# GEMM tile transition: trailing half goes from its last MFMA block straight into its epilogue; its rendezvous moved behind the accumulator reset; leading half no longer waits before epilogue
# baseline (speedup 1.0000x reference)
.LBB0_208:
	s_lshr_b32 s99, s91, 2
	s_cmp_eq_u32 s99, 1
	s_cselect_b32 s98, 12, 0x7fffffff
	s_add_i32 s84, s84, 1
	s_mul_i32 s4, s84, s56
	s_mul_hi_u32 s5, s84, s57
	s_add_i32 s5, s5, s4
	s_mul_i32 s4, s84, s57
	s_add_u32 s42, s4, s2
	s_addc_u32 s43, s5, s3
	v_cmp_gt_i64_e32 vcc, s[42:43], v[150:151]
	v_cmp_lt_i64_e64 s[4:5], s[42:43], v[148:149]
	s_cbranch_vccnz .LBB0_210
	s_ashr_i32 s7, s42, 31
	s_lshr_b32 s7, s7, 29
	s_add_i32 s7, s42, s7
	s_ashr_i32 s8, s7, 3
	s_and_b32 s7, s7, -8
	s_sub_i32 s7, s42, s7
	s_cmp_lt_i32 s7, 0
	s_cselect_b32 s12, s77, 0xc0
	s_mul_i32 s7, s7, s12
	s_add_i32 s7, s7, s8
	s_mul_hi_i32 s8, s7, 0x2aaaaaab
	s_lshr_b32 s12, s8, 31
	s_ashr_i32 s8, s8, 4
	s_add_i32 s8, s8, s12
	s_lshl_b32 s12, s8, 3
	s_sub_i32 s13, 0x80, s12
	s_min_i32 s13, s13, 8
	s_abs_i32 s28, s13
	v_cvt_f32_u32_e32 v0, s28
	s_sub_i32 s34, 0, s28
	s_mulk_i32 s8, 0x60
	s_sub_i32 s7, s7, s8
	v_rcp_iflag_f32_e32 v0, v0
	s_abs_i32 s8, s7
	s_xor_b32 s29, s7, s13
	s_ashr_i32 s29, s29, 31
	v_mul_f32_e32 v0, 0x4f7ffffe, v0
	v_cvt_u32_f32_e32 v0, v0
	s_mov_b32 s85, s84
	v_readfirstlane_b32 s35, v0
	s_mul_i32 s34, s34, s35
	s_mul_hi_u32 s34, s35, s34
	s_add_i32 s35, s35, s34
	s_mul_hi_u32 s34, s8, s35
	s_mul_i32 s35, s34, s28
	s_sub_i32 s8, s8, s35
	s_add_i32 s40, s34, 1
	s_sub_i32 s35, s8, s28
	s_cmp_ge_u32 s8, s28
	s_cselect_b32 s34, s40, s34
	s_cselect_b32 s8, s35, s8
	s_add_i32 s35, s34, 1
	s_cmp_ge_u32 s8, s28
	s_cselect_b32 s8, s35, s34
	s_xor_b32 s8, s8, s29
	s_sub_i32 s28, s8, s29
	s_mul_i32 s8, s28, s13
	s_sub_i32 s7, s7, s8
	s_add_i32 s40, s12, s7
.LBB0_210:
	s_ashr_i32 s41, s40, 31
	s_lshl_b64 s[12:13], s[40:41], 19
	s_add_u32 s42, s14, s12
	s_addc_u32 s43, s15, s13
	s_and_b64 s[12:13], s[4:5], exec
	s_cselect_b32 s7, s43, s51
	s_cselect_b32 s8, s42, s50
	s_ashr_i32 s29, s28, 31
	s_lshl_b64 s[12:13], s[28:29], 19
	s_add_u32 s48, s59, s12
	s_addc_u32 s49, s62, s13
	s_and_b64 s[12:13], s[4:5], exec
	s_cselect_b32 s12, s49, s53
	s_cselect_b32 s13, s48, s52
	s_add_u32 s50, s50, 0x40080
	s_addc_u32 s51, s51, 0
	s_add_u32 s29, s52, 0x100
	v_mov_b32_e32 v0, 0
	s_addc_u32 s41, s53, 0
	s_mov_b32 s86, -2
	v_mov_b32_e32 v1, v0
	v_mov_b32_e32 v2, v0
	v_mov_b32_e32 v3, v0
	v_mov_b32_e32 v4, v0
	v_mov_b32_e32 v5, v0
	v_mov_b32_e32 v6, v0
	v_mov_b32_e32 v7, v0
	v_mov_b32_e32 v16, v0
	v_mov_b32_e32 v17, v0
	s_waitcnt lgkmcnt(0)
	v_mov_b32_e32 v18, v0
	v_mov_b32_e32 v19, v0
	v_mov_b32_e32 v20, v0
	v_mov_b32_e32 v21, v0
	v_mov_b32_e32 v22, v0
	v_mov_b32_e32 v23, v0
	v_mov_b32_e32 v32, v0
	v_mov_b32_e32 v33, v0
	v_mov_b32_e32 v34, v0
	v_mov_b32_e32 v35, v0
	v_mov_b32_e32 v36, v0
	v_mov_b32_e32 v37, v0
	v_mov_b32_e32 v38, v0
	v_mov_b32_e32 v39, v0
	v_mov_b32_e32 v48, v0
	v_mov_b32_e32 v49, v0
	v_mov_b32_e32 v50, v0
	v_mov_b32_e32 v51, v0
	v_mov_b32_e32 v52, v0
	v_mov_b32_e32 v53, v0
	v_mov_b32_e32 v54, v0
	v_mov_b32_e32 v55, v0
	v_mov_b32_e32 v8, v0
	v_mov_b32_e32 v9, v0
	v_mov_b32_e32 v10, v0
	v_mov_b32_e32 v11, v0
	v_mov_b32_e32 v12, v0
	v_mov_b32_e32 v13, v0
	v_mov_b32_e32 v14, v0
	v_mov_b32_e32 v15, v0
	v_mov_b32_e32 v24, v0
	v_mov_b32_e32 v25, v0
	v_mov_b32_e32 v26, v0
	v_mov_b32_e32 v27, v0
	v_mov_b32_e32 v28, v0
	v_mov_b32_e32 v29, v0
	v_mov_b32_e32 v30, v0
	v_mov_b32_e32 v31, v0
	v_mov_b32_e32 v40, v0
	v_mov_b32_e32 v41, v0
	v_mov_b32_e32 v42, v0
	v_mov_b32_e32 v43, v0
	v_mov_b32_e32 v44, v0
	v_mov_b32_e32 v45, v0
	v_mov_b32_e32 v46, v0
	v_mov_b32_e32 v47, v0
	v_mov_b32_e32 v56, v0
	v_mov_b32_e32 v57, v0
	v_mov_b32_e32 v58, v0
	v_mov_b32_e32 v59, v0
	v_mov_b32_e32 v60, v0
	v_mov_b32_e32 v61, v0
	v_mov_b32_e32 v62, v0
	v_mov_b32_e32 v63, v0
	v_mov_b32_e32 v64, v0
	v_mov_b32_e32 v65, v0
	v_mov_b32_e32 v66, v0
	v_mov_b32_e32 v67, v0
	v_mov_b32_e32 v68, v0
	v_mov_b32_e32 v69, v0
	v_mov_b32_e32 v70, v0
	v_mov_b32_e32 v71, v0
	v_mov_b32_e32 v80, v0
	v_mov_b32_e32 v81, v0
	v_mov_b32_e32 v82, v0
	v_mov_b32_e32 v83, v0
	v_mov_b32_e32 v84, v0
	v_mov_b32_e32 v85, v0
	v_mov_b32_e32 v86, v0
	v_mov_b32_e32 v87, v0
	v_mov_b32_e32 v96, v0
	v_mov_b32_e32 v97, v0
	v_mov_b32_e32 v98, v0
	v_mov_b32_e32 v99, v0
	v_mov_b32_e32 v100, v0
	v_mov_b32_e32 v101, v0
	v_mov_b32_e32 v102, v0
	v_mov_b32_e32 v103, v0
	v_mov_b32_e32 v112, v0
	v_mov_b32_e32 v113, v0
	v_mov_b32_e32 v114, v0
	v_mov_b32_e32 v115, v0
	v_mov_b32_e32 v116, v0
	v_mov_b32_e32 v117, v0
	v_mov_b32_e32 v118, v0
	v_mov_b32_e32 v119, v0
	v_mov_b32_e32 v72, v0
	v_mov_b32_e32 v73, v0
	v_mov_b32_e32 v74, v0
	v_mov_b32_e32 v75, v0
	v_mov_b32_e32 v76, v0
	v_mov_b32_e32 v77, v0
	v_mov_b32_e32 v78, v0
	v_mov_b32_e32 v79, v0
	v_mov_b32_e32 v88, v0
	v_mov_b32_e32 v89, v0
	v_mov_b32_e32 v90, v0
	v_mov_b32_e32 v91, v0
	v_mov_b32_e32 v92, v0
	v_mov_b32_e32 v93, v0
	v_mov_b32_e32 v94, v0
	v_mov_b32_e32 v95, v0
	v_mov_b32_e32 v104, v0
	v_mov_b32_e32 v105, v0
	v_mov_b32_e32 v106, v0
	v_mov_b32_e32 v107, v0
	v_mov_b32_e32 v108, v0
	v_mov_b32_e32 v109, v0
	v_mov_b32_e32 v110, v0
	v_mov_b32_e32 v111, v0
	v_mov_b32_e32 v120, v0
	v_mov_b32_e32 v121, v0
	v_mov_b32_e32 v122, v0
	v_mov_b32_e32 v123, v0
	v_mov_b32_e32 v124, v0
	v_mov_b32_e32 v125, v0
	v_mov_b32_e32 v126, v0
	v_mov_b32_e32 v127, v0
	s_cmp_lg_u32 s84, 1
	s_cselect_b32 s100, s99, 0
	s_cmp_lg_u32 s100, 0
	s_cbranch_scc0 .Lmy_nobar2_2
	s_barrier
.Lmy_nobar2_2:
.LBB0_211:
	ds_read_b128 v[152:155], v157
	ds_read_b128 v[160:163], v157 offset:1024
	ds_read_b128 v[164:167], v157 offset:2048
	ds_read_b128 v[168:171], v157 offset:3072
	ds_read_b128 v[172:175], v158
	ds_read_b128 v[176:179], v158 offset:1024
	ds_read_b128 v[180:183], v158 offset:2048
	ds_read_b128 v[184:187], v158 offset:3072
	s_add_u32 s34, s50, 0xfffc0080
	s_addc_u32 s35, s51, -1
	s_cmp_eq_u32 s86, 12
	s_cselect_b32 s55, s7, s35
	s_cselect_b32 s54, s8, s34
	s_cselect_b32 s53, s12, s41
	s_cselect_b32 s52, s13, s29
	v_lshl_add_u64 v[220:221], s[50:51], 0, v[144:145]
	s_add_i32 m0, s63, 0xc000
	ds_read_b128 v[188:191], v159
	ds_read_b128 v[192:195], v159 offset:1024
	ds_read_b128 v[196:199], v159 offset:2048
	ds_read_b128 v[200:203], v159 offset:3072
	ds_read_b128 v[204:207], v159 offset:4096
	ds_read_b128 v[208:211], v159 offset:5120
	ds_read_b128 v[212:215], v159 offset:6144
	ds_read_b128 v[216:219], v159 offset:7168
	global_load_lds_dwordx4 v[220:221], off
	v_lshl_add_u64 v[220:221], s[50:51], 0, v[146:147]
	s_add_i32 m0, s63, 0xe000
	s_nop 0
	global_load_lds_dwordx4 v[220:221], off
	s_waitcnt vmcnt(8)
	s_waitcnt lgkmcnt(0)
	s_barrier
	s_setprio 1
	s_waitcnt lgkmcnt(0)
	v_mfma_f32_16x16x32_bf16 v[124:127], v[152:155], v[188:191], v[124:127]
	v_mfma_f32_16x16x32_bf16 v[120:123], v[164:167], v[188:191], v[120:123]
	v_mfma_f32_16x16x32_bf16 v[108:111], v[152:155], v[196:199], v[108:111]
	v_mfma_f32_16x16x32_bf16 v[104:107], v[164:167], v[196:199], v[104:107]
	v_mfma_f32_16x16x32_bf16 v[92:95], v[152:155], v[204:207], v[92:95]
	v_mfma_f32_16x16x32_bf16 v[88:91], v[164:167], v[204:207], v[88:91]
	v_mfma_f32_16x16x32_bf16 v[76:79], v[152:155], v[212:215], v[76:79]
	v_mfma_f32_16x16x32_bf16 v[72:75], v[164:167], v[212:215], v[72:75]
	v_mfma_f32_16x16x32_bf16 v[124:127], v[160:163], v[192:195], v[124:127]
	v_mfma_f32_16x16x32_bf16 v[120:123], v[168:171], v[192:195], v[120:123]
	v_mfma_f32_16x16x32_bf16 v[108:111], v[160:163], v[200:203], v[108:111]
	v_mfma_f32_16x16x32_bf16 v[104:107], v[168:171], v[200:203], v[104:107]
	v_mfma_f32_16x16x32_bf16 v[92:95], v[160:163], v[208:211], v[92:95]
	v_mfma_f32_16x16x32_bf16 v[88:91], v[168:171], v[208:211], v[88:91]
	v_mfma_f32_16x16x32_bf16 v[76:79], v[160:163], v[216:219], v[76:79]
	v_mfma_f32_16x16x32_bf16 v[72:75], v[168:171], v[216:219], v[72:75]
	s_setprio 0
	s_setprio 1
	v_mfma_f32_16x16x32_bf16 v[116:119], v[172:175], v[188:191], v[116:119]
	v_mfma_f32_16x16x32_bf16 v[112:115], v[180:183], v[188:191], v[112:115]
	v_mfma_f32_16x16x32_bf16 v[100:103], v[172:175], v[196:199], v[100:103]
	v_mfma_f32_16x16x32_bf16 v[96:99], v[180:183], v[196:199], v[96:99]
	v_mfma_f32_16x16x32_bf16 v[84:87], v[172:175], v[204:207], v[84:87]
	v_mfma_f32_16x16x32_bf16 v[80:83], v[180:183], v[204:207], v[80:83]
	v_mfma_f32_16x16x32_bf16 v[68:71], v[172:175], v[212:215], v[68:71]
	v_mfma_f32_16x16x32_bf16 v[64:67], v[180:183], v[212:215], v[64:67]
	v_mfma_f32_16x16x32_bf16 v[116:119], v[176:179], v[192:195], v[116:119]
	v_mfma_f32_16x16x32_bf16 v[112:115], v[184:187], v[192:195], v[112:115]
	v_mfma_f32_16x16x32_bf16 v[100:103], v[176:179], v[200:203], v[100:103]
	v_mfma_f32_16x16x32_bf16 v[96:99], v[184:187], v[200:203], v[96:99]
	v_mfma_f32_16x16x32_bf16 v[84:87], v[176:179], v[208:211], v[84:87]
	v_mfma_f32_16x16x32_bf16 v[80:83], v[184:187], v[208:211], v[80:83]
	v_mfma_f32_16x16x32_bf16 v[68:71], v[176:179], v[216:219], v[68:71]
	v_mfma_f32_16x16x32_bf16 v[64:67], v[184:187], v[216:219], v[64:67]
	s_setprio 0
	s_barrier
	s_add_i32 s34, s82, s58
	v_lshl_add_u64 v[220:221], s[52:53], 0, v[136:137]
	s_mov_b32 m0, s34
	ds_read_b128 v[188:191], v159 offset:16384
	ds_read_b128 v[192:195], v159 offset:17408
	ds_read_b128 v[196:199], v159 offset:18432
	ds_read_b128 v[200:203], v159 offset:19456
	ds_read_b128 v[204:207], v159 offset:20480
	ds_read_b128 v[208:211], v159 offset:21504
	ds_read_b128 v[212:215], v159 offset:22528
	ds_read_b128 v[216:219], v159 offset:23552
	global_load_lds_dwordx4 v[220:221], off
	s_add_i32 m0, s34, 0x2000
	s_add_u32 s34, s52, 0x40000
	v_lshl_add_u64 v[222:223], s[52:53], 0, v[140:141]
	s_addc_u32 s35, s53, 0
	s_add_i32 s87, s83, s58
	global_load_lds_dwordx4 v[222:223], off
	v_lshl_add_u64 v[224:225], s[34:35], 0, v[136:137]
	s_mov_b32 m0, s87
	v_lshl_add_u64 v[226:227], s[54:55], 0, v[138:139]
	global_load_lds_dwordx4 v[224:225], off
	v_lshl_add_u64 v[224:225], s[34:35], 0, v[140:141]
	s_add_i32 m0, s87, 0x2000
	s_nop 0
	global_load_lds_dwordx4 v[224:225], off
	v_lshl_add_u64 v[224:225], s[54:55], 0, v[134:135]
	s_mov_b32 m0, s63
	s_nop 0
	global_load_lds_dwordx4 v[224:225], off
	s_mov_b32 m0, s64
	s_nop 0
	global_load_lds_dwordx4 v[226:227], off
	s_waitcnt vmcnt(8)
	s_waitcnt lgkmcnt(0)
	s_barrier
	s_setprio 1
	s_waitcnt lgkmcnt(0)
	v_mfma_f32_16x16x32_bf16 v[60:63], v[152:155], v[188:191], v[60:63]
	v_mfma_f32_16x16x32_bf16 v[56:59], v[164:167], v[188:191], v[56:59]
	v_mfma_f32_16x16x32_bf16 v[44:47], v[152:155], v[196:199], v[44:47]
	v_mfma_f32_16x16x32_bf16 v[40:43], v[164:167], v[196:199], v[40:43]
	v_mfma_f32_16x16x32_bf16 v[28:31], v[152:155], v[204:207], v[28:31]
	v_mfma_f32_16x16x32_bf16 v[24:27], v[164:167], v[204:207], v[24:27]
	v_mfma_f32_16x16x32_bf16 v[12:15], v[152:155], v[212:215], v[12:15]
	v_mfma_f32_16x16x32_bf16 v[8:11], v[164:167], v[212:215], v[8:11]
	v_mfma_f32_16x16x32_bf16 v[60:63], v[160:163], v[192:195], v[60:63]
	v_mfma_f32_16x16x32_bf16 v[56:59], v[168:171], v[192:195], v[56:59]
	v_mfma_f32_16x16x32_bf16 v[44:47], v[160:163], v[200:203], v[44:47]
	v_mfma_f32_16x16x32_bf16 v[40:43], v[168:171], v[200:203], v[40:43]
	v_mfma_f32_16x16x32_bf16 v[28:31], v[160:163], v[208:211], v[28:31]
	v_mfma_f32_16x16x32_bf16 v[24:27], v[168:171], v[208:211], v[24:27]
	v_mfma_f32_16x16x32_bf16 v[12:15], v[160:163], v[216:219], v[12:15]
	v_mfma_f32_16x16x32_bf16 v[8:11], v[168:171], v[216:219], v[8:11]
	s_setprio 0
	s_setprio 1
	v_mfma_f32_16x16x32_bf16 v[52:55], v[172:175], v[188:191], v[52:55]
	v_mfma_f32_16x16x32_bf16 v[48:51], v[180:183], v[188:191], v[48:51]
	v_mfma_f32_16x16x32_bf16 v[36:39], v[172:175], v[196:199], v[36:39]
	v_mfma_f32_16x16x32_bf16 v[32:35], v[180:183], v[196:199], v[32:35]
	v_mfma_f32_16x16x32_bf16 v[20:23], v[172:175], v[204:207], v[20:23]
	v_mfma_f32_16x16x32_bf16 v[16:19], v[180:183], v[204:207], v[16:19]
	v_mfma_f32_16x16x32_bf16 v[4:7], v[172:175], v[212:215], v[4:7]
	v_mfma_f32_16x16x32_bf16 v[0:3], v[180:183], v[212:215], v[0:3]
	v_mfma_f32_16x16x32_bf16 v[52:55], v[176:179], v[192:195], v[52:55]
	v_mfma_f32_16x16x32_bf16 v[48:51], v[184:187], v[192:195], v[48:51]
	v_mfma_f32_16x16x32_bf16 v[36:39], v[176:179], v[200:203], v[36:39]
	v_mfma_f32_16x16x32_bf16 v[32:35], v[184:187], v[200:203], v[32:35]
	v_mfma_f32_16x16x32_bf16 v[20:23], v[176:179], v[208:211], v[20:23]
	v_mfma_f32_16x16x32_bf16 v[16:19], v[184:187], v[208:211], v[16:19]
	v_mfma_f32_16x16x32_bf16 v[4:7], v[176:179], v[216:219], v[4:7]
	v_mfma_f32_16x16x32_bf16 v[0:3], v[184:187], v[216:219], v[0:3]
	s_setprio 0
	s_barrier
	s_add_i32 s87, 0, 0x18000
	v_add_u32_e32 v142, s87, v133
	s_add_i32 s88, 0, 0x1c000
	ds_read_b128 v[152:155], v142
	ds_read_b128 v[160:163], v142 offset:1024
	ds_read_b128 v[164:167], v142 offset:2048
	ds_read_b128 v[168:171], v142 offset:3072
	v_add_u32_e32 v142, s88, v133
	ds_read_b128 v[172:175], v142
	ds_read_b128 v[176:179], v142 offset:1024
	ds_read_b128 v[180:183], v142 offset:2048
	ds_read_b128 v[184:187], v142 offset:3072
	s_add_u32 s34, s54, 0x40000
	s_addc_u32 s35, s55, 0
	s_mov_b32 m0, s65
	v_lshl_add_u64 v[228:229], s[34:35], 0, v[134:135]
	ds_read_b128 v[188:191], v159 offset:32768
	ds_read_b128 v[192:195], v159 offset:33792
	ds_read_b128 v[196:199], v159 offset:34816
	ds_read_b128 v[200:203], v159 offset:35840
	ds_read_b128 v[204:207], v159 offset:36864
	ds_read_b128 v[208:211], v159 offset:37888
	ds_read_b128 v[212:215], v159 offset:38912
	ds_read_b128 v[216:219], v159 offset:39936
	global_load_lds_dwordx4 v[228:229], off
	v_lshl_add_u64 v[228:229], s[34:35], 0, v[138:139]
	s_mov_b32 m0, s66
	s_nop 0
	global_load_lds_dwordx4 v[228:229], off
	s_waitcnt vmcnt(8)
	s_waitcnt lgkmcnt(0)
	s_barrier
	s_setprio 1
	s_waitcnt lgkmcnt(0)
	v_mfma_f32_16x16x32_bf16 v[124:127], v[152:155], v[188:191], v[124:127]
	v_mfma_f32_16x16x32_bf16 v[120:123], v[164:167], v[188:191], v[120:123]
	v_mfma_f32_16x16x32_bf16 v[108:111], v[152:155], v[196:199], v[108:111]
	v_mfma_f32_16x16x32_bf16 v[104:107], v[164:167], v[196:199], v[104:107]
	v_mfma_f32_16x16x32_bf16 v[92:95], v[152:155], v[204:207], v[92:95]
	v_mfma_f32_16x16x32_bf16 v[88:91], v[164:167], v[204:207], v[88:91]
	v_mfma_f32_16x16x32_bf16 v[76:79], v[152:155], v[212:215], v[76:79]
	v_mfma_f32_16x16x32_bf16 v[72:75], v[164:167], v[212:215], v[72:75]
	v_mfma_f32_16x16x32_bf16 v[124:127], v[160:163], v[192:195], v[124:127]
	v_mfma_f32_16x16x32_bf16 v[120:123], v[168:171], v[192:195], v[120:123]
	v_mfma_f32_16x16x32_bf16 v[108:111], v[160:163], v[200:203], v[108:111]
	v_mfma_f32_16x16x32_bf16 v[104:107], v[168:171], v[200:203], v[104:107]
	v_mfma_f32_16x16x32_bf16 v[92:95], v[160:163], v[208:211], v[92:95]
	v_mfma_f32_16x16x32_bf16 v[88:91], v[168:171], v[208:211], v[88:91]
	v_mfma_f32_16x16x32_bf16 v[76:79], v[160:163], v[216:219], v[76:79]
	v_mfma_f32_16x16x32_bf16 v[72:75], v[168:171], v[216:219], v[72:75]
	s_setprio 0
	s_setprio 1
	v_mfma_f32_16x16x32_bf16 v[116:119], v[172:175], v[188:191], v[116:119]
	v_mfma_f32_16x16x32_bf16 v[112:115], v[180:183], v[188:191], v[112:115]
	v_mfma_f32_16x16x32_bf16 v[100:103], v[172:175], v[196:199], v[100:103]
	v_mfma_f32_16x16x32_bf16 v[96:99], v[180:183], v[196:199], v[96:99]
	v_mfma_f32_16x16x32_bf16 v[84:87], v[172:175], v[204:207], v[84:87]
	v_mfma_f32_16x16x32_bf16 v[80:83], v[180:183], v[204:207], v[80:83]
	v_mfma_f32_16x16x32_bf16 v[68:71], v[172:175], v[212:215], v[68:71]
	v_mfma_f32_16x16x32_bf16 v[64:67], v[180:183], v[212:215], v[64:67]
	v_mfma_f32_16x16x32_bf16 v[116:119], v[176:179], v[192:195], v[116:119]
	v_mfma_f32_16x16x32_bf16 v[112:115], v[184:187], v[192:195], v[112:115]
	v_mfma_f32_16x16x32_bf16 v[100:103], v[176:179], v[200:203], v[100:103]
	v_mfma_f32_16x16x32_bf16 v[96:99], v[184:187], v[200:203], v[96:99]
	v_mfma_f32_16x16x32_bf16 v[84:87], v[176:179], v[208:211], v[84:87]
	v_mfma_f32_16x16x32_bf16 v[80:83], v[184:187], v[208:211], v[80:83]
	v_mfma_f32_16x16x32_bf16 v[68:71], v[176:179], v[216:219], v[68:71]
	v_mfma_f32_16x16x32_bf16 v[64:67], v[184:187], v[216:219], v[64:67]
	s_setprio 0
	s_barrier
	s_add_i32 s34, s87, s58
	v_lshl_add_u64 v[220:221], v[220:221], 0, s[22:23]
	s_mov_b32 m0, s34
	ds_read_b128 v[188:191], v159 offset:49152
	ds_read_b128 v[192:195], v159 offset:50176
	ds_read_b128 v[196:199], v159 offset:51200
	ds_read_b128 v[200:203], v159 offset:52224
	ds_read_b128 v[204:207], v159 offset:53248
	ds_read_b128 v[208:211], v159 offset:54272
	ds_read_b128 v[212:215], v159 offset:55296
	ds_read_b128 v[216:219], v159 offset:56320
	global_load_lds_dwordx4 v[220:221], off
	s_add_i32 m0, s34, 0x2000
	s_add_u32 s34, s52, 0x40080
	v_lshl_add_u64 v[220:221], v[222:223], 0, s[22:23]
	s_addc_u32 s35, s53, 0
	s_add_i32 s52, s88, s58
	global_load_lds_dwordx4 v[220:221], off
	v_lshl_add_u64 v[220:221], s[34:35], 0, v[136:137]
	s_mov_b32 m0, s52
	s_nop 0
	global_load_lds_dwordx4 v[220:221], off
	v_lshl_add_u64 v[220:221], s[34:35], 0, v[140:141]
	s_add_i32 m0, s52, 0x2000
	s_nop 0
	global_load_lds_dwordx4 v[220:221], off
	v_lshl_add_u64 v[220:221], v[224:225], 0, s[22:23]
	s_mov_b32 m0, s79
	s_nop 0
	global_load_lds_dwordx4 v[220:221], off
	v_lshl_add_u64 v[220:221], v[226:227], 0, s[22:23]
	s_mov_b32 m0, s81
	s_nop 0
	global_load_lds_dwordx4 v[220:221], off
	s_waitcnt vmcnt(8)
	s_waitcnt lgkmcnt(0)
	s_barrier
	s_setprio 1
	s_waitcnt lgkmcnt(0)
	v_mfma_f32_16x16x32_bf16 v[60:63], v[152:155], v[188:191], v[60:63]
	v_mfma_f32_16x16x32_bf16 v[56:59], v[164:167], v[188:191], v[56:59]
	v_mfma_f32_16x16x32_bf16 v[44:47], v[152:155], v[196:199], v[44:47]
	v_mfma_f32_16x16x32_bf16 v[40:43], v[164:167], v[196:199], v[40:43]
	v_mfma_f32_16x16x32_bf16 v[28:31], v[152:155], v[204:207], v[28:31]
	v_mfma_f32_16x16x32_bf16 v[24:27], v[164:167], v[204:207], v[24:27]
	v_mfma_f32_16x16x32_bf16 v[12:15], v[152:155], v[212:215], v[12:15]
	v_mfma_f32_16x16x32_bf16 v[8:11], v[164:167], v[212:215], v[8:11]
	v_mfma_f32_16x16x32_bf16 v[60:63], v[160:163], v[192:195], v[60:63]
	v_mfma_f32_16x16x32_bf16 v[56:59], v[168:171], v[192:195], v[56:59]
	v_mfma_f32_16x16x32_bf16 v[44:47], v[160:163], v[200:203], v[44:47]
	v_mfma_f32_16x16x32_bf16 v[40:43], v[168:171], v[200:203], v[40:43]
	v_mfma_f32_16x16x32_bf16 v[28:31], v[160:163], v[208:211], v[28:31]
	v_mfma_f32_16x16x32_bf16 v[24:27], v[168:171], v[208:211], v[24:27]
	v_mfma_f32_16x16x32_bf16 v[12:15], v[160:163], v[216:219], v[12:15]
	v_mfma_f32_16x16x32_bf16 v[8:11], v[168:171], v[216:219], v[8:11]
	s_setprio 0
	s_setprio 1
	v_mfma_f32_16x16x32_bf16 v[52:55], v[172:175], v[188:191], v[52:55]
	v_mfma_f32_16x16x32_bf16 v[48:51], v[180:183], v[188:191], v[48:51]
	v_mfma_f32_16x16x32_bf16 v[36:39], v[172:175], v[196:199], v[36:39]
	v_mfma_f32_16x16x32_bf16 v[32:35], v[180:183], v[196:199], v[32:35]
	v_mfma_f32_16x16x32_bf16 v[20:23], v[172:175], v[204:207], v[20:23]
	v_mfma_f32_16x16x32_bf16 v[16:19], v[180:183], v[204:207], v[16:19]
	v_mfma_f32_16x16x32_bf16 v[4:7], v[172:175], v[212:215], v[4:7]
	v_mfma_f32_16x16x32_bf16 v[0:3], v[180:183], v[212:215], v[0:3]
	v_mfma_f32_16x16x32_bf16 v[52:55], v[176:179], v[192:195], v[52:55]
	v_mfma_f32_16x16x32_bf16 v[48:51], v[184:187], v[192:195], v[48:51]
	v_mfma_f32_16x16x32_bf16 v[36:39], v[176:179], v[200:203], v[36:39]
	v_mfma_f32_16x16x32_bf16 v[32:35], v[184:187], v[200:203], v[32:35]
	v_mfma_f32_16x16x32_bf16 v[20:23], v[176:179], v[208:211], v[20:23]
	v_mfma_f32_16x16x32_bf16 v[16:19], v[184:187], v[208:211], v[16:19]
	v_mfma_f32_16x16x32_bf16 v[4:7], v[176:179], v[216:219], v[4:7]
	v_mfma_f32_16x16x32_bf16 v[0:3], v[184:187], v[216:219], v[0:3]
	s_setprio 0
	s_cmp_eq_u32 s86, s98
	s_cbranch_scc1 .Lmy_nobar_2
	s_barrier
.Lmy_nobar_2:
	s_add_i32 s86, s86, 2
	s_add_u32 s50, s50, 0x100
	s_addc_u32 s51, s51, 0
	s_add_u32 s29, s29, 0x100
	s_addc_u32 s41, s41, 0
	s_cmp_gt_u32 s86, 13
	s_cbranch_scc0 .LBB0_211
	s_and_b64 vcc, exec, s[26:27]
	s_cbranch_vccz .LBB0_214
	s_nop 0

.LBB0_247:
	s_andn2_b64 vcc, exec, s[10:11]
	s_cbranch_vccnz .LBB0_206
	s_nop 0
	s_branch .LBB0_206

.LBB0_379:
	s_lshr_b32 s99, s91, 2
	s_cmp_eq_u32 s99, 1
	s_cselect_b32 s98, 12, 0x7fffffff
	s_add_i32 s84, s84, 1
	s_mul_i32 s6, s84, s67
	s_mul_hi_u32 s7, s84, s79
	s_add_i32 s7, s7, s6
	s_mul_i32 s6, s84, s79
	s_add_u32 s40, s6, s2
	s_addc_u32 s41, s7, s81
	v_cmp_gt_i64_e32 vcc, s[40:41], v[146:147]
	v_cmp_lt_i64_e64 s[6:7], s[40:41], v[144:145]
	s_cbranch_vccnz .LBB0_385
	s_ashr_i32 s12, s40, 31
	s_lshr_b32 s12, s12, 29
	s_add_i32 s12, s40, s12
	s_and_b32 s13, s12, -8
	s_sub_i32 s13, s40, s13
	s_cmp_gt_i32 s13, -1
	s_mov_b64 s[26:27], -1
	s_cbranch_scc0 .LBB0_382
	s_lshl_b32 s28, s13, 6
	s_mov_b64 s[26:27], 0

.LBB0_385:
	s_ashr_i32 s29, s28, 31
	s_lshl_b64 s[12:13], s[28:29], 19
	s_add_u32 s40, s20, s12
	s_addc_u32 s41, s21, s13
	s_and_b64 s[12:13], s[6:7], exec
	s_cselect_b32 s12, s41, s51
	s_cselect_b32 s13, s40, s50
	s_ashr_i32 s27, s26, 31
	s_lshl_b64 s[34:35], s[26:27], 19
	s_add_u32 s42, s3, s34
	s_addc_u32 s43, s56, s35
	s_and_b64 s[34:35], s[6:7], exec
	s_cselect_b32 s27, s43, s53
	s_cselect_b32 s29, s42, s52
	s_add_u32 s50, s50, 0x40080
	s_addc_u32 s51, s51, 0
	s_add_u32 s49, s52, 0x100
	v_mov_b32_e32 v0, 0
	s_addc_u32 s77, s53, 0
	s_mov_b32 s85, -2
	s_waitcnt lgkmcnt(0)
	v_mov_b32_e32 v1, v0
	v_mov_b32_e32 v2, v0
	v_mov_b32_e32 v3, v0
	v_mov_b32_e32 v4, v0
	v_mov_b32_e32 v5, v0
	v_mov_b32_e32 v6, v0
	v_mov_b32_e32 v7, v0
	v_mov_b32_e32 v16, v0
	v_mov_b32_e32 v17, v0
	v_mov_b32_e32 v18, v0
	v_mov_b32_e32 v19, v0
	v_mov_b32_e32 v20, v0
	v_mov_b32_e32 v21, v0
	v_mov_b32_e32 v22, v0
	v_mov_b32_e32 v23, v0
	v_mov_b32_e32 v32, v0
	v_mov_b32_e32 v33, v0
	v_mov_b32_e32 v34, v0
	v_mov_b32_e32 v35, v0
	v_mov_b32_e32 v36, v0
	v_mov_b32_e32 v37, v0
	v_mov_b32_e32 v38, v0
	v_mov_b32_e32 v39, v0
	v_mov_b32_e32 v48, v0
	v_mov_b32_e32 v49, v0
	v_mov_b32_e32 v50, v0
	v_mov_b32_e32 v51, v0
	v_mov_b32_e32 v52, v0
	v_mov_b32_e32 v53, v0
	v_mov_b32_e32 v54, v0
	v_mov_b32_e32 v55, v0
	v_mov_b32_e32 v8, v0
	v_mov_b32_e32 v9, v0
	v_mov_b32_e32 v10, v0
	v_mov_b32_e32 v11, v0
	v_mov_b32_e32 v12, v0
	v_mov_b32_e32 v13, v0
	v_mov_b32_e32 v14, v0
	v_mov_b32_e32 v15, v0
	v_mov_b32_e32 v24, v0
	v_mov_b32_e32 v25, v0
	v_mov_b32_e32 v26, v0
	v_mov_b32_e32 v27, v0
	v_mov_b32_e32 v28, v0
	v_mov_b32_e32 v29, v0
	v_mov_b32_e32 v30, v0
	v_mov_b32_e32 v31, v0
	v_mov_b32_e32 v40, v0
	v_mov_b32_e32 v41, v0
	v_mov_b32_e32 v42, v0
	v_mov_b32_e32 v43, v0
	v_mov_b32_e32 v44, v0
	v_mov_b32_e32 v45, v0
	v_mov_b32_e32 v46, v0
	v_mov_b32_e32 v47, v0
	v_mov_b32_e32 v56, v0
	v_mov_b32_e32 v57, v0
	v_mov_b32_e32 v58, v0
	v_mov_b32_e32 v59, v0
	v_mov_b32_e32 v60, v0
	v_mov_b32_e32 v61, v0
	v_mov_b32_e32 v62, v0
	v_mov_b32_e32 v63, v0
	v_mov_b32_e32 v64, v0
	v_mov_b32_e32 v65, v0
	v_mov_b32_e32 v66, v0
	v_mov_b32_e32 v67, v0
	v_mov_b32_e32 v68, v0
	v_mov_b32_e32 v69, v0
	v_mov_b32_e32 v70, v0
	v_mov_b32_e32 v71, v0
	v_mov_b32_e32 v80, v0
	v_mov_b32_e32 v81, v0
	v_mov_b32_e32 v82, v0
	v_mov_b32_e32 v83, v0
	v_mov_b32_e32 v84, v0
	v_mov_b32_e32 v85, v0
	v_mov_b32_e32 v86, v0
	v_mov_b32_e32 v87, v0
	v_mov_b32_e32 v96, v0
	v_mov_b32_e32 v97, v0
	v_mov_b32_e32 v98, v0
	v_mov_b32_e32 v99, v0
	v_mov_b32_e32 v100, v0
	v_mov_b32_e32 v101, v0
	v_mov_b32_e32 v102, v0
	v_mov_b32_e32 v103, v0
	v_mov_b32_e32 v112, v0
	v_mov_b32_e32 v113, v0
	v_mov_b32_e32 v114, v0
	v_mov_b32_e32 v115, v0
	v_mov_b32_e32 v116, v0
	v_mov_b32_e32 v117, v0
	v_mov_b32_e32 v118, v0
	v_mov_b32_e32 v119, v0
	v_mov_b32_e32 v72, v0
	v_mov_b32_e32 v73, v0
	v_mov_b32_e32 v74, v0
	v_mov_b32_e32 v75, v0
	v_mov_b32_e32 v76, v0
	v_mov_b32_e32 v77, v0
	v_mov_b32_e32 v78, v0
	v_mov_b32_e32 v79, v0
	v_mov_b32_e32 v88, v0
	v_mov_b32_e32 v89, v0
	v_mov_b32_e32 v90, v0
	v_mov_b32_e32 v91, v0
	v_mov_b32_e32 v92, v0
	v_mov_b32_e32 v93, v0
	v_mov_b32_e32 v94, v0
	v_mov_b32_e32 v95, v0
	v_mov_b32_e32 v104, v0
	v_mov_b32_e32 v105, v0
	v_mov_b32_e32 v106, v0
	v_mov_b32_e32 v107, v0
	v_mov_b32_e32 v108, v0
	v_mov_b32_e32 v109, v0
	v_mov_b32_e32 v110, v0
	v_mov_b32_e32 v111, v0
	v_mov_b32_e32 v120, v0
	v_mov_b32_e32 v121, v0
	v_mov_b32_e32 v122, v0
	v_mov_b32_e32 v123, v0
	v_mov_b32_e32 v124, v0
	v_mov_b32_e32 v125, v0
	v_mov_b32_e32 v126, v0
	v_mov_b32_e32 v127, v0
	s_cmp_lg_u32 s84, 1
	s_cselect_b32 s100, s99, 0
	s_cmp_lg_u32 s100, 0
	s_cbranch_scc0 .Lmy_nobar2_4
	s_barrier
.Lmy_nobar2_4:
.LBB0_386:
	ds_read_b128 v[148:151], v154
	ds_read_b128 v[160:163], v154 offset:1024
	ds_read_b128 v[164:167], v154 offset:2048
	ds_read_b128 v[168:171], v154 offset:3072
	ds_read_b128 v[172:175], v155
	ds_read_b128 v[176:179], v155 offset:1024
	ds_read_b128 v[180:183], v155 offset:2048
	ds_read_b128 v[184:187], v155 offset:3072
	s_add_u32 s34, s50, 0xfffc0080
	s_addc_u32 s35, s51, -1
	s_cmp_eq_u32 s85, 12
	s_cselect_b32 s55, s12, s35
	s_cselect_b32 s54, s13, s34
	s_cselect_b32 s53, s27, s77
	s_cselect_b32 s52, s29, s49
	v_lshl_add_u64 v[220:221], s[50:51], 0, v[140:141]
	s_add_i32 m0, s58, 0xc000
	ds_read_b128 v[188:191], v157
	ds_read_b128 v[192:195], v157 offset:1024
	ds_read_b128 v[196:199], v157 offset:2048
	ds_read_b128 v[200:203], v157 offset:3072
	ds_read_b128 v[204:207], v157 offset:4096
	ds_read_b128 v[208:211], v157 offset:5120
	ds_read_b128 v[212:215], v157 offset:6144
	ds_read_b128 v[216:219], v157 offset:7168
	global_load_lds_dwordx4 v[220:221], off
	v_lshl_add_u64 v[220:221], s[50:51], 0, v[142:143]
	s_add_i32 m0, s58, 0xe000
	s_nop 0
	global_load_lds_dwordx4 v[220:221], off
	s_waitcnt vmcnt(8)
	s_waitcnt lgkmcnt(0)
	s_barrier
	s_setprio 1
	s_waitcnt lgkmcnt(0)
	v_mfma_f32_16x16x32_bf16 v[124:127], v[148:151], v[188:191], v[124:127]
	v_mfma_f32_16x16x32_bf16 v[120:123], v[164:167], v[188:191], v[120:123]
	v_mfma_f32_16x16x32_bf16 v[108:111], v[148:151], v[196:199], v[108:111]
	v_mfma_f32_16x16x32_bf16 v[104:107], v[164:167], v[196:199], v[104:107]
	v_mfma_f32_16x16x32_bf16 v[92:95], v[148:151], v[204:207], v[92:95]
	v_mfma_f32_16x16x32_bf16 v[88:91], v[164:167], v[204:207], v[88:91]
	v_mfma_f32_16x16x32_bf16 v[76:79], v[148:151], v[212:215], v[76:79]
	v_mfma_f32_16x16x32_bf16 v[72:75], v[164:167], v[212:215], v[72:75]
	v_mfma_f32_16x16x32_bf16 v[124:127], v[160:163], v[192:195], v[124:127]
	v_mfma_f32_16x16x32_bf16 v[120:123], v[168:171], v[192:195], v[120:123]
	v_mfma_f32_16x16x32_bf16 v[108:111], v[160:163], v[200:203], v[108:111]
	v_mfma_f32_16x16x32_bf16 v[104:107], v[168:171], v[200:203], v[104:107]
	v_mfma_f32_16x16x32_bf16 v[92:95], v[160:163], v[208:211], v[92:95]
	v_mfma_f32_16x16x32_bf16 v[88:91], v[168:171], v[208:211], v[88:91]
	v_mfma_f32_16x16x32_bf16 v[76:79], v[160:163], v[216:219], v[76:79]
	v_mfma_f32_16x16x32_bf16 v[72:75], v[168:171], v[216:219], v[72:75]
	s_setprio 0
	s_setprio 1
	v_mfma_f32_16x16x32_bf16 v[116:119], v[172:175], v[188:191], v[116:119]
	v_mfma_f32_16x16x32_bf16 v[112:115], v[180:183], v[188:191], v[112:115]
	v_mfma_f32_16x16x32_bf16 v[100:103], v[172:175], v[196:199], v[100:103]
	v_mfma_f32_16x16x32_bf16 v[96:99], v[180:183], v[196:199], v[96:99]
	v_mfma_f32_16x16x32_bf16 v[84:87], v[172:175], v[204:207], v[84:87]
	v_mfma_f32_16x16x32_bf16 v[80:83], v[180:183], v[204:207], v[80:83]
	v_mfma_f32_16x16x32_bf16 v[68:71], v[172:175], v[212:215], v[68:71]
	v_mfma_f32_16x16x32_bf16 v[64:67], v[180:183], v[212:215], v[64:67]
	v_mfma_f32_16x16x32_bf16 v[116:119], v[176:179], v[192:195], v[116:119]
	v_mfma_f32_16x16x32_bf16 v[112:115], v[184:187], v[192:195], v[112:115]
	v_mfma_f32_16x16x32_bf16 v[100:103], v[176:179], v[200:203], v[100:103]
	v_mfma_f32_16x16x32_bf16 v[96:99], v[184:187], v[200:203], v[96:99]
	v_mfma_f32_16x16x32_bf16 v[84:87], v[176:179], v[208:211], v[84:87]
	v_mfma_f32_16x16x32_bf16 v[80:83], v[184:187], v[208:211], v[80:83]
	v_mfma_f32_16x16x32_bf16 v[68:71], v[176:179], v[216:219], v[68:71]
	v_mfma_f32_16x16x32_bf16 v[64:67], v[184:187], v[216:219], v[64:67]
	s_setprio 0
	s_barrier
	s_add_i32 s34, s82, s57
	v_lshl_add_u64 v[220:221], s[52:53], 0, v[134:135]
	s_mov_b32 m0, s34
	ds_read_b128 v[188:191], v157 offset:16384
	ds_read_b128 v[192:195], v157 offset:17408
	ds_read_b128 v[196:199], v157 offset:18432
	ds_read_b128 v[200:203], v157 offset:19456
	ds_read_b128 v[204:207], v157 offset:20480
	ds_read_b128 v[208:211], v157 offset:21504
	ds_read_b128 v[212:215], v157 offset:22528
	ds_read_b128 v[216:219], v157 offset:23552
	global_load_lds_dwordx4 v[220:221], off
	s_add_i32 m0, s34, 0x2000
	s_add_u32 s34, s52, 0x40000
	v_lshl_add_u64 v[222:223], s[52:53], 0, v[138:139]
	s_addc_u32 s35, s53, 0
	s_add_i32 s86, s83, s57
	global_load_lds_dwordx4 v[222:223], off
	v_lshl_add_u64 v[224:225], s[34:35], 0, v[134:135]
	s_mov_b32 m0, s86
	v_lshl_add_u64 v[226:227], s[54:55], 0, v[136:137]
	global_load_lds_dwordx4 v[224:225], off
	v_lshl_add_u64 v[224:225], s[34:35], 0, v[138:139]
	s_add_i32 m0, s86, 0x2000
	s_nop 0
	global_load_lds_dwordx4 v[224:225], off
	v_lshl_add_u64 v[224:225], s[54:55], 0, v[132:133]
	s_mov_b32 m0, s58
	s_nop 0
	global_load_lds_dwordx4 v[224:225], off
	s_mov_b32 m0, s59
	s_nop 0
	global_load_lds_dwordx4 v[226:227], off
	s_waitcnt vmcnt(8)
	s_waitcnt lgkmcnt(0)
	s_barrier
	s_setprio 1
	s_waitcnt lgkmcnt(0)
	v_mfma_f32_16x16x32_bf16 v[60:63], v[148:151], v[188:191], v[60:63]
	v_mfma_f32_16x16x32_bf16 v[56:59], v[164:167], v[188:191], v[56:59]
	v_mfma_f32_16x16x32_bf16 v[44:47], v[148:151], v[196:199], v[44:47]
	v_mfma_f32_16x16x32_bf16 v[40:43], v[164:167], v[196:199], v[40:43]
	v_mfma_f32_16x16x32_bf16 v[28:31], v[148:151], v[204:207], v[28:31]
	v_mfma_f32_16x16x32_bf16 v[24:27], v[164:167], v[204:207], v[24:27]
	v_mfma_f32_16x16x32_bf16 v[12:15], v[148:151], v[212:215], v[12:15]
	v_mfma_f32_16x16x32_bf16 v[8:11], v[164:167], v[212:215], v[8:11]
	v_mfma_f32_16x16x32_bf16 v[60:63], v[160:163], v[192:195], v[60:63]
	v_mfma_f32_16x16x32_bf16 v[56:59], v[168:171], v[192:195], v[56:59]
	v_mfma_f32_16x16x32_bf16 v[44:47], v[160:163], v[200:203], v[44:47]
	v_mfma_f32_16x16x32_bf16 v[40:43], v[168:171], v[200:203], v[40:43]
	v_mfma_f32_16x16x32_bf16 v[28:31], v[160:163], v[208:211], v[28:31]
	v_mfma_f32_16x16x32_bf16 v[24:27], v[168:171], v[208:211], v[24:27]
	v_mfma_f32_16x16x32_bf16 v[12:15], v[160:163], v[216:219], v[12:15]
	v_mfma_f32_16x16x32_bf16 v[8:11], v[168:171], v[216:219], v[8:11]
	s_setprio 0
	s_setprio 1
	v_mfma_f32_16x16x32_bf16 v[52:55], v[172:175], v[188:191], v[52:55]
	v_mfma_f32_16x16x32_bf16 v[48:51], v[180:183], v[188:191], v[48:51]
	v_mfma_f32_16x16x32_bf16 v[36:39], v[172:175], v[196:199], v[36:39]
	v_mfma_f32_16x16x32_bf16 v[32:35], v[180:183], v[196:199], v[32:35]
	v_mfma_f32_16x16x32_bf16 v[20:23], v[172:175], v[204:207], v[20:23]
	v_mfma_f32_16x16x32_bf16 v[16:19], v[180:183], v[204:207], v[16:19]
	v_mfma_f32_16x16x32_bf16 v[4:7], v[172:175], v[212:215], v[4:7]
	v_mfma_f32_16x16x32_bf16 v[0:3], v[180:183], v[212:215], v[0:3]
	v_mfma_f32_16x16x32_bf16 v[52:55], v[176:179], v[192:195], v[52:55]
	v_mfma_f32_16x16x32_bf16 v[48:51], v[184:187], v[192:195], v[48:51]
	v_mfma_f32_16x16x32_bf16 v[36:39], v[176:179], v[200:203], v[36:39]
	v_mfma_f32_16x16x32_bf16 v[32:35], v[184:187], v[200:203], v[32:35]
	v_mfma_f32_16x16x32_bf16 v[20:23], v[176:179], v[208:211], v[20:23]
	v_mfma_f32_16x16x32_bf16 v[16:19], v[184:187], v[208:211], v[16:19]
	v_mfma_f32_16x16x32_bf16 v[4:7], v[176:179], v[216:219], v[4:7]
	v_mfma_f32_16x16x32_bf16 v[0:3], v[184:187], v[216:219], v[0:3]
	s_setprio 0
	s_barrier
	s_add_i32 s86, 0, 0x18000
	v_add_u32_e32 v159, s86, v152
	s_add_i32 s87, 0, 0x1c000
	ds_read_b128 v[148:151], v159
	ds_read_b128 v[160:163], v159 offset:1024
	ds_read_b128 v[164:167], v159 offset:2048
	ds_read_b128 v[168:171], v159 offset:3072
	v_add_u32_e32 v159, s87, v152
	ds_read_b128 v[172:175], v159
	ds_read_b128 v[176:179], v159 offset:1024
	ds_read_b128 v[180:183], v159 offset:2048
	ds_read_b128 v[184:187], v159 offset:3072
	s_add_u32 s34, s54, 0x40000
	s_addc_u32 s35, s55, 0
	s_mov_b32 m0, s62
	v_lshl_add_u64 v[228:229], s[34:35], 0, v[132:133]
	ds_read_b128 v[188:191], v157 offset:32768
	ds_read_b128 v[192:195], v157 offset:33792
	ds_read_b128 v[196:199], v157 offset:34816
	ds_read_b128 v[200:203], v157 offset:35840
	ds_read_b128 v[204:207], v157 offset:36864
	ds_read_b128 v[208:211], v157 offset:37888
	ds_read_b128 v[212:215], v157 offset:38912
	ds_read_b128 v[216:219], v157 offset:39936
	global_load_lds_dwordx4 v[228:229], off
	v_lshl_add_u64 v[228:229], s[34:35], 0, v[136:137]
	s_mov_b32 m0, s63
	s_nop 0
	global_load_lds_dwordx4 v[228:229], off
	s_waitcnt vmcnt(8)
	s_waitcnt lgkmcnt(0)
	s_barrier
	s_setprio 1
	s_waitcnt lgkmcnt(0)
	v_mfma_f32_16x16x32_bf16 v[124:127], v[148:151], v[188:191], v[124:127]
	v_mfma_f32_16x16x32_bf16 v[120:123], v[164:167], v[188:191], v[120:123]
	v_mfma_f32_16x16x32_bf16 v[108:111], v[148:151], v[196:199], v[108:111]
	v_mfma_f32_16x16x32_bf16 v[104:107], v[164:167], v[196:199], v[104:107]
	v_mfma_f32_16x16x32_bf16 v[92:95], v[148:151], v[204:207], v[92:95]
	v_mfma_f32_16x16x32_bf16 v[88:91], v[164:167], v[204:207], v[88:91]
	v_mfma_f32_16x16x32_bf16 v[76:79], v[148:151], v[212:215], v[76:79]
	v_mfma_f32_16x16x32_bf16 v[72:75], v[164:167], v[212:215], v[72:75]
	v_mfma_f32_16x16x32_bf16 v[124:127], v[160:163], v[192:195], v[124:127]
	v_mfma_f32_16x16x32_bf16 v[120:123], v[168:171], v[192:195], v[120:123]
	v_mfma_f32_16x16x32_bf16 v[108:111], v[160:163], v[200:203], v[108:111]
	v_mfma_f32_16x16x32_bf16 v[104:107], v[168:171], v[200:203], v[104:107]
	v_mfma_f32_16x16x32_bf16 v[92:95], v[160:163], v[208:211], v[92:95]
	v_mfma_f32_16x16x32_bf16 v[88:91], v[168:171], v[208:211], v[88:91]
	v_mfma_f32_16x16x32_bf16 v[76:79], v[160:163], v[216:219], v[76:79]
	v_mfma_f32_16x16x32_bf16 v[72:75], v[168:171], v[216:219], v[72:75]
	s_setprio 0
	s_setprio 1
	v_mfma_f32_16x16x32_bf16 v[116:119], v[172:175], v[188:191], v[116:119]
	v_mfma_f32_16x16x32_bf16 v[112:115], v[180:183], v[188:191], v[112:115]
	v_mfma_f32_16x16x32_bf16 v[100:103], v[172:175], v[196:199], v[100:103]
	v_mfma_f32_16x16x32_bf16 v[96:99], v[180:183], v[196:199], v[96:99]
	v_mfma_f32_16x16x32_bf16 v[84:87], v[172:175], v[204:207], v[84:87]
	v_mfma_f32_16x16x32_bf16 v[80:83], v[180:183], v[204:207], v[80:83]
	v_mfma_f32_16x16x32_bf16 v[68:71], v[172:175], v[212:215], v[68:71]
	v_mfma_f32_16x16x32_bf16 v[64:67], v[180:183], v[212:215], v[64:67]
	v_mfma_f32_16x16x32_bf16 v[116:119], v[176:179], v[192:195], v[116:119]
	v_mfma_f32_16x16x32_bf16 v[112:115], v[184:187], v[192:195], v[112:115]
	v_mfma_f32_16x16x32_bf16 v[100:103], v[176:179], v[200:203], v[100:103]
	v_mfma_f32_16x16x32_bf16 v[96:99], v[184:187], v[200:203], v[96:99]
	v_mfma_f32_16x16x32_bf16 v[84:87], v[176:179], v[208:211], v[84:87]
	v_mfma_f32_16x16x32_bf16 v[80:83], v[184:187], v[208:211], v[80:83]
	v_mfma_f32_16x16x32_bf16 v[68:71], v[176:179], v[216:219], v[68:71]
	v_mfma_f32_16x16x32_bf16 v[64:67], v[184:187], v[216:219], v[64:67]
	s_setprio 0
	s_barrier
	s_add_i32 s34, s86, s57
	v_lshl_add_u64 v[220:221], v[220:221], 0, s[10:11]
	s_mov_b32 m0, s34
	ds_read_b128 v[188:191], v157 offset:49152
	ds_read_b128 v[192:195], v157 offset:50176
	ds_read_b128 v[196:199], v157 offset:51200
	ds_read_b128 v[200:203], v157 offset:52224
	ds_read_b128 v[204:207], v157 offset:53248
	ds_read_b128 v[208:211], v157 offset:54272
	ds_read_b128 v[212:215], v157 offset:55296
	ds_read_b128 v[216:219], v157 offset:56320
	global_load_lds_dwordx4 v[220:221], off
	s_add_i32 m0, s34, 0x2000
	s_add_u32 s34, s52, 0x40080
	v_lshl_add_u64 v[220:221], v[222:223], 0, s[10:11]
	s_addc_u32 s35, s53, 0
	s_add_i32 s52, s87, s57
	global_load_lds_dwordx4 v[220:221], off
	v_lshl_add_u64 v[220:221], s[34:35], 0, v[134:135]
	s_mov_b32 m0, s52
	s_nop 0
	global_load_lds_dwordx4 v[220:221], off
	v_lshl_add_u64 v[220:221], s[34:35], 0, v[138:139]
	s_add_i32 m0, s52, 0x2000
	s_nop 0
	global_load_lds_dwordx4 v[220:221], off
	v_lshl_add_u64 v[220:221], v[224:225], 0, s[10:11]
	s_mov_b32 m0, s65
	s_nop 0
	global_load_lds_dwordx4 v[220:221], off
	v_lshl_add_u64 v[220:221], v[226:227], 0, s[10:11]
	s_mov_b32 m0, s66
	s_nop 0
	global_load_lds_dwordx4 v[220:221], off
	s_waitcnt vmcnt(8)
	s_waitcnt lgkmcnt(0)
	s_barrier
	s_setprio 1
	s_waitcnt lgkmcnt(0)
	v_mfma_f32_16x16x32_bf16 v[60:63], v[148:151], v[188:191], v[60:63]
	v_mfma_f32_16x16x32_bf16 v[56:59], v[164:167], v[188:191], v[56:59]
	v_mfma_f32_16x16x32_bf16 v[44:47], v[148:151], v[196:199], v[44:47]
	v_mfma_f32_16x16x32_bf16 v[40:43], v[164:167], v[196:199], v[40:43]
	v_mfma_f32_16x16x32_bf16 v[28:31], v[148:151], v[204:207], v[28:31]
	v_mfma_f32_16x16x32_bf16 v[24:27], v[164:167], v[204:207], v[24:27]
	v_mfma_f32_16x16x32_bf16 v[12:15], v[148:151], v[212:215], v[12:15]
	v_mfma_f32_16x16x32_bf16 v[8:11], v[164:167], v[212:215], v[8:11]
	v_mfma_f32_16x16x32_bf16 v[60:63], v[160:163], v[192:195], v[60:63]
	v_mfma_f32_16x16x32_bf16 v[56:59], v[168:171], v[192:195], v[56:59]
	v_mfma_f32_16x16x32_bf16 v[44:47], v[160:163], v[200:203], v[44:47]
	v_mfma_f32_16x16x32_bf16 v[40:43], v[168:171], v[200:203], v[40:43]
	v_mfma_f32_16x16x32_bf16 v[28:31], v[160:163], v[208:211], v[28:31]
	v_mfma_f32_16x16x32_bf16 v[24:27], v[168:171], v[208:211], v[24:27]
	v_mfma_f32_16x16x32_bf16 v[12:15], v[160:163], v[216:219], v[12:15]
	v_mfma_f32_16x16x32_bf16 v[8:11], v[168:171], v[216:219], v[8:11]
	s_setprio 0
	s_setprio 1
	v_mfma_f32_16x16x32_bf16 v[52:55], v[172:175], v[188:191], v[52:55]
	v_mfma_f32_16x16x32_bf16 v[48:51], v[180:183], v[188:191], v[48:51]
	v_mfma_f32_16x16x32_bf16 v[36:39], v[172:175], v[196:199], v[36:39]
	v_mfma_f32_16x16x32_bf16 v[32:35], v[180:183], v[196:199], v[32:35]
	v_mfma_f32_16x16x32_bf16 v[20:23], v[172:175], v[204:207], v[20:23]
	v_mfma_f32_16x16x32_bf16 v[16:19], v[180:183], v[204:207], v[16:19]
	v_mfma_f32_16x16x32_bf16 v[4:7], v[172:175], v[212:215], v[4:7]
	v_mfma_f32_16x16x32_bf16 v[0:3], v[180:183], v[212:215], v[0:3]
	v_mfma_f32_16x16x32_bf16 v[52:55], v[176:179], v[192:195], v[52:55]
	v_mfma_f32_16x16x32_bf16 v[48:51], v[184:187], v[192:195], v[48:51]
	v_mfma_f32_16x16x32_bf16 v[36:39], v[176:179], v[200:203], v[36:39]
	v_mfma_f32_16x16x32_bf16 v[32:35], v[184:187], v[200:203], v[32:35]
	v_mfma_f32_16x16x32_bf16 v[20:23], v[176:179], v[208:211], v[20:23]
	v_mfma_f32_16x16x32_bf16 v[16:19], v[184:187], v[208:211], v[16:19]
	v_mfma_f32_16x16x32_bf16 v[4:7], v[176:179], v[216:219], v[4:7]
	v_mfma_f32_16x16x32_bf16 v[0:3], v[184:187], v[216:219], v[0:3]
	s_setprio 0
	s_cmp_eq_u32 s85, s98
	s_cbranch_scc1 .Lmy_nobar_4
	s_barrier
.Lmy_nobar_4:
	s_add_i32 s85, s85, 2
	s_add_u32 s50, s50, 0x100
	s_addc_u32 s51, s51, 0
	s_add_u32 s49, s49, 0x100
	s_addc_u32 s77, s77, 0
	s_cmp_gt_u32 s85, 13
	s_cbranch_scc0 .LBB0_386
	s_and_b64 vcc, exec, s[22:23]
	s_cbranch_vccz .LBB0_389
	s_nop 0

.LBB0_405:
	s_or_b64 exec, exec, s[50:51]
	s_andn2_b64 vcc, exec, s[6:7]
	s_mov_b64 s[6:7], -1
	s_cbranch_vccnz .LBB0_378
	s_andn2_b64 vcc, exec, s[8:9]
	s_cbranch_vccnz .LBB0_377
	s_nop 0
	s_branch .LBB0_377

.LBB0_473:
	s_lshr_b32 s99, s91, 2
	s_cmp_eq_u32 s99, 1
	s_cselect_b32 s98, 12, 0x7fffffff
	s_add_i32 s77, s77, 1
	s_mul_i32 s4, s77, s52
	s_mul_hi_u32 s5, s77, s53
	s_add_i32 s5, s5, s4
	s_mul_i32 s4, s77, s53
	s_add_u32 s26, s4, s2
	s_addc_u32 s27, s5, s3
	v_cmp_gt_i64_e32 vcc, s[26:27], v[146:147]
	v_cmp_lt_i64_e64 s[4:5], s[26:27], v[144:145]
	s_cbranch_vccnz .LBB0_475
	s_ashr_i32 s10, s26, 31
	s_lshr_b32 s10, s10, 29
	s_add_i32 s10, s26, s10
	s_ashr_i32 s11, s10, 3
	s_and_b32 s10, s10, -8
	s_sub_i32 s10, s26, s10
	s_cmp_lt_i32 s10, 0
	s_cselect_b32 s22, s57, 0x160
	s_mul_i32 s10, s10, s22
	s_add_i32 s10, s10, s11
	s_mul_hi_i32 s11, s10, 0x2e8ba2e9
	s_lshr_b32 s22, s11, 31
	s_ashr_i32 s11, s11, 5
	s_add_i32 s11, s11, s22
	s_lshl_b32 s22, s11, 3
	s_sub_i32 s23, 0x80, s22
	s_min_i32 s23, s23, 8
	s_abs_i32 s26, s23
	v_cvt_f32_u32_e32 v0, s26
	s_sub_i32 s28, 0, s26
	s_mulk_i32 s11, 0xb0
	s_sub_i32 s11, s10, s11
	v_rcp_iflag_f32_e32 v0, v0
	s_abs_i32 s10, s11
	s_xor_b32 s27, s11, s23
	s_ashr_i32 s27, s27, 31
	v_mul_f32_e32 v0, 0x4f7ffffe, v0
	v_cvt_u32_f32_e32 v0, v0
	s_mov_b32 s79, s77
	v_readfirstlane_b32 s29, v0
	s_mul_i32 s28, s28, s29
	s_mul_hi_u32 s28, s29, s28
	s_add_i32 s29, s29, s28
	s_mul_hi_u32 s28, s10, s29
	s_mul_i32 s29, s28, s26
	s_sub_i32 s10, s10, s29
	s_add_i32 s34, s28, 1
	s_sub_i32 s29, s10, s26
	s_cmp_ge_u32 s10, s26
	s_cselect_b32 s28, s34, s28
	s_cselect_b32 s10, s29, s10
	s_add_i32 s29, s28, 1
	s_cmp_ge_u32 s10, s26
	s_cselect_b32 s10, s29, s28
	s_xor_b32 s10, s10, s27
	s_sub_i32 s10, s10, s27
	s_mul_i32 s23, s10, s23
	s_sub_i32 s11, s11, s23
	s_add_i32 s22, s22, s11
.LBB0_475:
	s_ashr_i32 s23, s22, 31
	s_lshl_b64 s[26:27], s[22:23], 19
	s_add_u32 s26, s14, s26
	s_addc_u32 s27, s15, s27
	s_and_b64 s[28:29], s[4:5], exec
	s_cselect_b32 s23, s27, s43
	s_cselect_b32 s81, s26, s42
	s_ashr_i32 s11, s10, 31
	s_lshl_b64 s[28:29], s[10:11], 19
	s_add_u32 s28, s55, s28
	s_addc_u32 s29, s56, s29
	s_and_b64 s[34:35], s[4:5], exec
	s_cselect_b32 s11, s29, s49
	s_cselect_b32 s82, s28, s48
	s_add_u32 s42, s42, 0x40080
	s_addc_u32 s43, s43, 0
	s_add_u32 s83, s48, 0x100
	v_mov_b32_e32 v0, 0
	s_addc_u32 s84, s49, 0
	s_mov_b32 s85, -2
	v_mov_b32_e32 v1, v0
	v_mov_b32_e32 v2, v0
	v_mov_b32_e32 v3, v0
	v_mov_b32_e32 v4, v0
	v_mov_b32_e32 v5, v0
	v_mov_b32_e32 v6, v0
	v_mov_b32_e32 v7, v0
	v_mov_b32_e32 v16, v0
	v_mov_b32_e32 v17, v0
	v_mov_b32_e32 v18, v0
	v_mov_b32_e32 v19, v0
	v_mov_b32_e32 v20, v0
	v_mov_b32_e32 v21, v0
	v_mov_b32_e32 v22, v0
	v_mov_b32_e32 v23, v0
	v_mov_b32_e32 v32, v0
	v_mov_b32_e32 v33, v0
	v_mov_b32_e32 v34, v0
	v_mov_b32_e32 v35, v0
	v_mov_b32_e32 v36, v0
	v_mov_b32_e32 v37, v0
	v_mov_b32_e32 v38, v0
	v_mov_b32_e32 v39, v0
	v_mov_b32_e32 v48, v0
	v_mov_b32_e32 v49, v0
	v_mov_b32_e32 v50, v0
	v_mov_b32_e32 v51, v0
	v_mov_b32_e32 v52, v0
	v_mov_b32_e32 v53, v0
	v_mov_b32_e32 v54, v0
	v_mov_b32_e32 v55, v0
	v_mov_b32_e32 v8, v0
	v_mov_b32_e32 v9, v0
	v_mov_b32_e32 v10, v0
	v_mov_b32_e32 v11, v0
	v_mov_b32_e32 v12, v0
	v_mov_b32_e32 v13, v0
	v_mov_b32_e32 v14, v0
	v_mov_b32_e32 v15, v0
	v_mov_b32_e32 v24, v0
	v_mov_b32_e32 v25, v0
	v_mov_b32_e32 v26, v0
	v_mov_b32_e32 v27, v0
	v_mov_b32_e32 v28, v0
	v_mov_b32_e32 v29, v0
	v_mov_b32_e32 v30, v0
	v_mov_b32_e32 v31, v0
	v_mov_b32_e32 v40, v0
	v_mov_b32_e32 v41, v0
	v_mov_b32_e32 v42, v0
	v_mov_b32_e32 v43, v0
	v_mov_b32_e32 v44, v0
	v_mov_b32_e32 v45, v0
	v_mov_b32_e32 v46, v0
	v_mov_b32_e32 v47, v0
	v_mov_b32_e32 v56, v0
	v_mov_b32_e32 v57, v0
	v_mov_b32_e32 v58, v0
	v_mov_b32_e32 v59, v0
	v_mov_b32_e32 v60, v0
	v_mov_b32_e32 v61, v0
	v_mov_b32_e32 v62, v0
	v_mov_b32_e32 v63, v0
	v_mov_b32_e32 v64, v0
	v_mov_b32_e32 v65, v0
	v_mov_b32_e32 v66, v0
	v_mov_b32_e32 v67, v0
	v_mov_b32_e32 v68, v0
	v_mov_b32_e32 v69, v0
	v_mov_b32_e32 v70, v0
	v_mov_b32_e32 v71, v0
	v_mov_b32_e32 v80, v0
	v_mov_b32_e32 v81, v0
	v_mov_b32_e32 v82, v0
	v_mov_b32_e32 v83, v0
	v_mov_b32_e32 v84, v0
	v_mov_b32_e32 v85, v0
	v_mov_b32_e32 v86, v0
	v_mov_b32_e32 v87, v0
	v_mov_b32_e32 v96, v0
	v_mov_b32_e32 v97, v0
	v_mov_b32_e32 v98, v0
	v_mov_b32_e32 v99, v0
	v_mov_b32_e32 v100, v0
	v_mov_b32_e32 v101, v0
	v_mov_b32_e32 v102, v0
	v_mov_b32_e32 v103, v0
	v_mov_b32_e32 v112, v0
	v_mov_b32_e32 v113, v0
	v_mov_b32_e32 v114, v0
	v_mov_b32_e32 v115, v0
	v_mov_b32_e32 v116, v0
	v_mov_b32_e32 v117, v0
	v_mov_b32_e32 v118, v0
	v_mov_b32_e32 v119, v0
	v_mov_b32_e32 v72, v0
	v_mov_b32_e32 v73, v0
	v_mov_b32_e32 v74, v0
	v_mov_b32_e32 v75, v0
	v_mov_b32_e32 v76, v0
	v_mov_b32_e32 v77, v0
	v_mov_b32_e32 v78, v0
	v_mov_b32_e32 v79, v0
	v_mov_b32_e32 v88, v0
	v_mov_b32_e32 v89, v0
	v_mov_b32_e32 v90, v0
	v_mov_b32_e32 v91, v0
	v_mov_b32_e32 v92, v0
	v_mov_b32_e32 v93, v0
	v_mov_b32_e32 v94, v0
	v_mov_b32_e32 v95, v0
	v_mov_b32_e32 v104, v0
	v_mov_b32_e32 v105, v0
	v_mov_b32_e32 v106, v0
	v_mov_b32_e32 v107, v0
	v_mov_b32_e32 v108, v0
	v_mov_b32_e32 v109, v0
	v_mov_b32_e32 v110, v0
	v_mov_b32_e32 v111, v0
	v_mov_b32_e32 v120, v0
	v_mov_b32_e32 v121, v0
	v_mov_b32_e32 v122, v0
	v_mov_b32_e32 v123, v0
	v_mov_b32_e32 v124, v0
	v_mov_b32_e32 v125, v0
	v_mov_b32_e32 v126, v0
	v_mov_b32_e32 v127, v0
	s_cmp_lg_u32 s77, 1
	s_cselect_b32 s100, s99, 0
	s_cmp_lg_u32 s100, 0
	s_cbranch_scc0 .Lmy_nobar2_5
	s_barrier
.Lmy_nobar2_5:
.LBB0_476:
	ds_read_b128 v[148:151], v155
	ds_read_b128 v[160:163], v155 offset:1024
	ds_read_b128 v[164:167], v155 offset:2048
	ds_read_b128 v[168:171], v155 offset:3072
	ds_read_b128 v[172:175], v157
	ds_read_b128 v[176:179], v157 offset:1024
	ds_read_b128 v[180:183], v157 offset:2048
	ds_read_b128 v[184:187], v157 offset:3072
	s_add_u32 s34, s42, 0xfffc0080
	s_addc_u32 s35, s43, -1
	s_cmp_eq_u32 s85, 12
	s_cselect_b32 s51, s23, s35
	s_cselect_b32 s50, s81, s34
	s_cselect_b32 s49, s11, s84
	s_cselect_b32 s48, s82, s83
	v_lshl_add_u64 v[220:221], s[42:43], 0, v[140:141]
	s_add_i32 m0, s41, 0xc000
	ds_read_b128 v[188:191], v158
	ds_read_b128 v[192:195], v158 offset:1024
	ds_read_b128 v[196:199], v158 offset:2048
	ds_read_b128 v[200:203], v158 offset:3072
	ds_read_b128 v[204:207], v158 offset:4096
	ds_read_b128 v[208:211], v158 offset:5120
	ds_read_b128 v[212:215], v158 offset:6144
	ds_read_b128 v[216:219], v158 offset:7168
	global_load_lds_dwordx4 v[220:221], off
	v_lshl_add_u64 v[220:221], s[42:43], 0, v[142:143]
	s_add_i32 m0, s41, 0xe000
	s_nop 0
	global_load_lds_dwordx4 v[220:221], off
	s_waitcnt vmcnt(8)
	s_waitcnt lgkmcnt(0)
	s_barrier
	s_setprio 1
	s_waitcnt lgkmcnt(0)
	v_mfma_f32_16x16x32_bf16 v[124:127], v[148:151], v[188:191], v[124:127]
	v_mfma_f32_16x16x32_bf16 v[120:123], v[164:167], v[188:191], v[120:123]
	v_mfma_f32_16x16x32_bf16 v[108:111], v[148:151], v[196:199], v[108:111]
	v_mfma_f32_16x16x32_bf16 v[104:107], v[164:167], v[196:199], v[104:107]
	v_mfma_f32_16x16x32_bf16 v[92:95], v[148:151], v[204:207], v[92:95]
	v_mfma_f32_16x16x32_bf16 v[88:91], v[164:167], v[204:207], v[88:91]
	v_mfma_f32_16x16x32_bf16 v[76:79], v[148:151], v[212:215], v[76:79]
	v_mfma_f32_16x16x32_bf16 v[72:75], v[164:167], v[212:215], v[72:75]
	v_mfma_f32_16x16x32_bf16 v[124:127], v[160:163], v[192:195], v[124:127]
	v_mfma_f32_16x16x32_bf16 v[120:123], v[168:171], v[192:195], v[120:123]
	v_mfma_f32_16x16x32_bf16 v[108:111], v[160:163], v[200:203], v[108:111]
	v_mfma_f32_16x16x32_bf16 v[104:107], v[168:171], v[200:203], v[104:107]
	v_mfma_f32_16x16x32_bf16 v[92:95], v[160:163], v[208:211], v[92:95]
	v_mfma_f32_16x16x32_bf16 v[88:91], v[168:171], v[208:211], v[88:91]
	v_mfma_f32_16x16x32_bf16 v[76:79], v[160:163], v[216:219], v[76:79]
	v_mfma_f32_16x16x32_bf16 v[72:75], v[168:171], v[216:219], v[72:75]
	s_setprio 0
	s_setprio 1
	v_mfma_f32_16x16x32_bf16 v[116:119], v[172:175], v[188:191], v[116:119]
	v_mfma_f32_16x16x32_bf16 v[112:115], v[180:183], v[188:191], v[112:115]
	v_mfma_f32_16x16x32_bf16 v[100:103], v[172:175], v[196:199], v[100:103]
	v_mfma_f32_16x16x32_bf16 v[96:99], v[180:183], v[196:199], v[96:99]
	v_mfma_f32_16x16x32_bf16 v[84:87], v[172:175], v[204:207], v[84:87]
	v_mfma_f32_16x16x32_bf16 v[80:83], v[180:183], v[204:207], v[80:83]
	v_mfma_f32_16x16x32_bf16 v[68:71], v[172:175], v[212:215], v[68:71]
	v_mfma_f32_16x16x32_bf16 v[64:67], v[180:183], v[212:215], v[64:67]
	v_mfma_f32_16x16x32_bf16 v[116:119], v[176:179], v[192:195], v[116:119]
	v_mfma_f32_16x16x32_bf16 v[112:115], v[184:187], v[192:195], v[112:115]
	v_mfma_f32_16x16x32_bf16 v[100:103], v[176:179], v[200:203], v[100:103]
	v_mfma_f32_16x16x32_bf16 v[96:99], v[184:187], v[200:203], v[96:99]
	v_mfma_f32_16x16x32_bf16 v[84:87], v[176:179], v[208:211], v[84:87]
	v_mfma_f32_16x16x32_bf16 v[80:83], v[184:187], v[208:211], v[80:83]
	v_mfma_f32_16x16x32_bf16 v[68:71], v[176:179], v[216:219], v[68:71]
	v_mfma_f32_16x16x32_bf16 v[64:67], v[184:187], v[216:219], v[64:67]
	s_setprio 0
	s_barrier
	s_add_i32 s34, s65, s54
	v_lshl_add_u64 v[220:221], s[48:49], 0, v[136:137]
	s_mov_b32 m0, s34
	ds_read_b128 v[188:191], v158 offset:16384
	ds_read_b128 v[192:195], v158 offset:17408
	ds_read_b128 v[196:199], v158 offset:18432
	ds_read_b128 v[200:203], v158 offset:19456
	ds_read_b128 v[204:207], v158 offset:20480
	ds_read_b128 v[208:211], v158 offset:21504
	ds_read_b128 v[212:215], v158 offset:22528
	ds_read_b128 v[216:219], v158 offset:23552
	global_load_lds_dwordx4 v[220:221], off
	s_add_i32 m0, s34, 0x2000
	s_add_u32 s34, s48, 0x40000
	v_lshl_add_u64 v[222:223], s[48:49], 0, v[132:133]
	s_addc_u32 s35, s49, 0
	s_add_i32 s86, s66, s54
	global_load_lds_dwordx4 v[222:223], off
	v_lshl_add_u64 v[224:225], s[34:35], 0, v[136:137]
	s_mov_b32 m0, s86
	v_lshl_add_u64 v[226:227], s[50:51], 0, v[134:135]
	global_load_lds_dwordx4 v[224:225], off
	v_lshl_add_u64 v[224:225], s[34:35], 0, v[132:133]
	s_add_i32 m0, s86, 0x2000
	s_nop 0
	global_load_lds_dwordx4 v[224:225], off
	v_lshl_add_u64 v[224:225], s[50:51], 0, v[138:139]
	s_mov_b32 m0, s41
	s_nop 0
	global_load_lds_dwordx4 v[224:225], off
	s_mov_b32 m0, s58
	s_nop 0
	global_load_lds_dwordx4 v[226:227], off
	s_waitcnt vmcnt(8)
	s_waitcnt lgkmcnt(0)
	s_barrier
	s_setprio 1
	s_waitcnt lgkmcnt(0)
	v_mfma_f32_16x16x32_bf16 v[60:63], v[148:151], v[188:191], v[60:63]
	v_mfma_f32_16x16x32_bf16 v[56:59], v[164:167], v[188:191], v[56:59]
	v_mfma_f32_16x16x32_bf16 v[44:47], v[148:151], v[196:199], v[44:47]
	v_mfma_f32_16x16x32_bf16 v[40:43], v[164:167], v[196:199], v[40:43]
	v_mfma_f32_16x16x32_bf16 v[28:31], v[148:151], v[204:207], v[28:31]
	v_mfma_f32_16x16x32_bf16 v[24:27], v[164:167], v[204:207], v[24:27]
	v_mfma_f32_16x16x32_bf16 v[12:15], v[148:151], v[212:215], v[12:15]
	v_mfma_f32_16x16x32_bf16 v[8:11], v[164:167], v[212:215], v[8:11]
	v_mfma_f32_16x16x32_bf16 v[60:63], v[160:163], v[192:195], v[60:63]
	v_mfma_f32_16x16x32_bf16 v[56:59], v[168:171], v[192:195], v[56:59]
	v_mfma_f32_16x16x32_bf16 v[44:47], v[160:163], v[200:203], v[44:47]
	v_mfma_f32_16x16x32_bf16 v[40:43], v[168:171], v[200:203], v[40:43]
	v_mfma_f32_16x16x32_bf16 v[28:31], v[160:163], v[208:211], v[28:31]
	v_mfma_f32_16x16x32_bf16 v[24:27], v[168:171], v[208:211], v[24:27]
	v_mfma_f32_16x16x32_bf16 v[12:15], v[160:163], v[216:219], v[12:15]
	v_mfma_f32_16x16x32_bf16 v[8:11], v[168:171], v[216:219], v[8:11]
	s_setprio 0
	s_setprio 1
	v_mfma_f32_16x16x32_bf16 v[52:55], v[172:175], v[188:191], v[52:55]
	v_mfma_f32_16x16x32_bf16 v[48:51], v[180:183], v[188:191], v[48:51]
	v_mfma_f32_16x16x32_bf16 v[36:39], v[172:175], v[196:199], v[36:39]
	v_mfma_f32_16x16x32_bf16 v[32:35], v[180:183], v[196:199], v[32:35]
	v_mfma_f32_16x16x32_bf16 v[20:23], v[172:175], v[204:207], v[20:23]
	v_mfma_f32_16x16x32_bf16 v[16:19], v[180:183], v[204:207], v[16:19]
	v_mfma_f32_16x16x32_bf16 v[4:7], v[172:175], v[212:215], v[4:7]
	v_mfma_f32_16x16x32_bf16 v[0:3], v[180:183], v[212:215], v[0:3]
	v_mfma_f32_16x16x32_bf16 v[52:55], v[176:179], v[192:195], v[52:55]
	v_mfma_f32_16x16x32_bf16 v[48:51], v[184:187], v[192:195], v[48:51]
	v_mfma_f32_16x16x32_bf16 v[36:39], v[176:179], v[200:203], v[36:39]
	v_mfma_f32_16x16x32_bf16 v[32:35], v[184:187], v[200:203], v[32:35]
	v_mfma_f32_16x16x32_bf16 v[20:23], v[176:179], v[208:211], v[20:23]
	v_mfma_f32_16x16x32_bf16 v[16:19], v[184:187], v[208:211], v[16:19]
	v_mfma_f32_16x16x32_bf16 v[4:7], v[176:179], v[216:219], v[4:7]
	v_mfma_f32_16x16x32_bf16 v[0:3], v[184:187], v[216:219], v[0:3]
	s_setprio 0
	s_barrier
	s_add_i32 s86, 0, 0x18000
	v_add_u32_e32 v159, s86, v152
	s_add_i32 s87, 0, 0x1c000
	ds_read_b128 v[148:151], v159
	ds_read_b128 v[160:163], v159 offset:1024
	ds_read_b128 v[164:167], v159 offset:2048
	ds_read_b128 v[168:171], v159 offset:3072
	v_add_u32_e32 v159, s87, v152
	ds_read_b128 v[172:175], v159
	ds_read_b128 v[176:179], v159 offset:1024
	ds_read_b128 v[180:183], v159 offset:2048
	ds_read_b128 v[184:187], v159 offset:3072
	s_add_u32 s34, s50, 0x40000
	s_addc_u32 s35, s51, 0
	s_mov_b32 m0, s59
	v_lshl_add_u64 v[228:229], s[34:35], 0, v[138:139]
	ds_read_b128 v[188:191], v158 offset:32768
	ds_read_b128 v[192:195], v158 offset:33792
	ds_read_b128 v[196:199], v158 offset:34816
	ds_read_b128 v[200:203], v158 offset:35840
	ds_read_b128 v[204:207], v158 offset:36864
	ds_read_b128 v[208:211], v158 offset:37888
	ds_read_b128 v[212:215], v158 offset:38912
	ds_read_b128 v[216:219], v158 offset:39936
	global_load_lds_dwordx4 v[228:229], off
	v_lshl_add_u64 v[228:229], s[34:35], 0, v[134:135]
	s_mov_b32 m0, s62
	s_nop 0
	global_load_lds_dwordx4 v[228:229], off
	s_waitcnt vmcnt(8)
	s_waitcnt lgkmcnt(0)
	s_barrier
	s_setprio 1
	s_waitcnt lgkmcnt(0)
	v_mfma_f32_16x16x32_bf16 v[124:127], v[148:151], v[188:191], v[124:127]
	v_mfma_f32_16x16x32_bf16 v[120:123], v[164:167], v[188:191], v[120:123]
	v_mfma_f32_16x16x32_bf16 v[108:111], v[148:151], v[196:199], v[108:111]
	v_mfma_f32_16x16x32_bf16 v[104:107], v[164:167], v[196:199], v[104:107]
	v_mfma_f32_16x16x32_bf16 v[92:95], v[148:151], v[204:207], v[92:95]
	v_mfma_f32_16x16x32_bf16 v[88:91], v[164:167], v[204:207], v[88:91]
	v_mfma_f32_16x16x32_bf16 v[76:79], v[148:151], v[212:215], v[76:79]
	v_mfma_f32_16x16x32_bf16 v[72:75], v[164:167], v[212:215], v[72:75]
	v_mfma_f32_16x16x32_bf16 v[124:127], v[160:163], v[192:195], v[124:127]
	v_mfma_f32_16x16x32_bf16 v[120:123], v[168:171], v[192:195], v[120:123]
	v_mfma_f32_16x16x32_bf16 v[108:111], v[160:163], v[200:203], v[108:111]
	v_mfma_f32_16x16x32_bf16 v[104:107], v[168:171], v[200:203], v[104:107]
	v_mfma_f32_16x16x32_bf16 v[92:95], v[160:163], v[208:211], v[92:95]
	v_mfma_f32_16x16x32_bf16 v[88:91], v[168:171], v[208:211], v[88:91]
	v_mfma_f32_16x16x32_bf16 v[76:79], v[160:163], v[216:219], v[76:79]
	v_mfma_f32_16x16x32_bf16 v[72:75], v[168:171], v[216:219], v[72:75]
	s_setprio 0
	s_setprio 1
	v_mfma_f32_16x16x32_bf16 v[116:119], v[172:175], v[188:191], v[116:119]
	v_mfma_f32_16x16x32_bf16 v[112:115], v[180:183], v[188:191], v[112:115]
	v_mfma_f32_16x16x32_bf16 v[100:103], v[172:175], v[196:199], v[100:103]
	v_mfma_f32_16x16x32_bf16 v[96:99], v[180:183], v[196:199], v[96:99]
	v_mfma_f32_16x16x32_bf16 v[84:87], v[172:175], v[204:207], v[84:87]
	v_mfma_f32_16x16x32_bf16 v[80:83], v[180:183], v[204:207], v[80:83]
	v_mfma_f32_16x16x32_bf16 v[68:71], v[172:175], v[212:215], v[68:71]
	v_mfma_f32_16x16x32_bf16 v[64:67], v[180:183], v[212:215], v[64:67]
	v_mfma_f32_16x16x32_bf16 v[116:119], v[176:179], v[192:195], v[116:119]
	v_mfma_f32_16x16x32_bf16 v[112:115], v[184:187], v[192:195], v[112:115]
	v_mfma_f32_16x16x32_bf16 v[100:103], v[176:179], v[200:203], v[100:103]
	v_mfma_f32_16x16x32_bf16 v[96:99], v[184:187], v[200:203], v[96:99]
	v_mfma_f32_16x16x32_bf16 v[84:87], v[176:179], v[208:211], v[84:87]
	v_mfma_f32_16x16x32_bf16 v[80:83], v[184:187], v[208:211], v[80:83]
	v_mfma_f32_16x16x32_bf16 v[68:71], v[176:179], v[216:219], v[68:71]
	v_mfma_f32_16x16x32_bf16 v[64:67], v[184:187], v[216:219], v[64:67]
	s_setprio 0
	s_barrier
	s_add_i32 s34, s86, s54
	v_lshl_add_u64 v[220:221], v[220:221], 0, s[6:7]
	s_mov_b32 m0, s34
	ds_read_b128 v[188:191], v158 offset:49152
	ds_read_b128 v[192:195], v158 offset:50176
	ds_read_b128 v[196:199], v158 offset:51200
	ds_read_b128 v[200:203], v158 offset:52224
	ds_read_b128 v[204:207], v158 offset:53248
	ds_read_b128 v[208:211], v158 offset:54272
	ds_read_b128 v[212:215], v158 offset:55296
	ds_read_b128 v[216:219], v158 offset:56320
	global_load_lds_dwordx4 v[220:221], off
	s_add_i32 m0, s34, 0x2000
	s_add_u32 s34, s48, 0x40080
	v_lshl_add_u64 v[220:221], v[222:223], 0, s[6:7]
	s_addc_u32 s35, s49, 0
	s_add_i32 s48, s87, s54
	global_load_lds_dwordx4 v[220:221], off
	v_lshl_add_u64 v[220:221], s[34:35], 0, v[136:137]
	s_mov_b32 m0, s48
	s_nop 0
	global_load_lds_dwordx4 v[220:221], off
	v_lshl_add_u64 v[220:221], s[34:35], 0, v[132:133]
	s_add_i32 m0, s48, 0x2000
	s_nop 0
	global_load_lds_dwordx4 v[220:221], off
	v_lshl_add_u64 v[220:221], v[224:225], 0, s[6:7]
	s_mov_b32 m0, s63
	s_nop 0
	global_load_lds_dwordx4 v[220:221], off
	v_lshl_add_u64 v[220:221], v[226:227], 0, s[6:7]
	s_mov_b32 m0, s64
	s_nop 0
	global_load_lds_dwordx4 v[220:221], off
	s_waitcnt vmcnt(8)
	s_waitcnt lgkmcnt(0)
	s_barrier
	s_setprio 1
	s_waitcnt lgkmcnt(0)
	v_mfma_f32_16x16x32_bf16 v[60:63], v[148:151], v[188:191], v[60:63]
	v_mfma_f32_16x16x32_bf16 v[56:59], v[164:167], v[188:191], v[56:59]
	v_mfma_f32_16x16x32_bf16 v[44:47], v[148:151], v[196:199], v[44:47]
	v_mfma_f32_16x16x32_bf16 v[40:43], v[164:167], v[196:199], v[40:43]
	v_mfma_f32_16x16x32_bf16 v[28:31], v[148:151], v[204:207], v[28:31]
	v_mfma_f32_16x16x32_bf16 v[24:27], v[164:167], v[204:207], v[24:27]
	v_mfma_f32_16x16x32_bf16 v[12:15], v[148:151], v[212:215], v[12:15]
	v_mfma_f32_16x16x32_bf16 v[8:11], v[164:167], v[212:215], v[8:11]
	v_mfma_f32_16x16x32_bf16 v[60:63], v[160:163], v[192:195], v[60:63]
	v_mfma_f32_16x16x32_bf16 v[56:59], v[168:171], v[192:195], v[56:59]
	v_mfma_f32_16x16x32_bf16 v[44:47], v[160:163], v[200:203], v[44:47]
	v_mfma_f32_16x16x32_bf16 v[40:43], v[168:171], v[200:203], v[40:43]
	v_mfma_f32_16x16x32_bf16 v[28:31], v[160:163], v[208:211], v[28:31]
	v_mfma_f32_16x16x32_bf16 v[24:27], v[168:171], v[208:211], v[24:27]
	v_mfma_f32_16x16x32_bf16 v[12:15], v[160:163], v[216:219], v[12:15]
	v_mfma_f32_16x16x32_bf16 v[8:11], v[168:171], v[216:219], v[8:11]
	s_setprio 0
	s_setprio 1
	v_mfma_f32_16x16x32_bf16 v[52:55], v[172:175], v[188:191], v[52:55]
	v_mfma_f32_16x16x32_bf16 v[48:51], v[180:183], v[188:191], v[48:51]
	v_mfma_f32_16x16x32_bf16 v[36:39], v[172:175], v[196:199], v[36:39]
	v_mfma_f32_16x16x32_bf16 v[32:35], v[180:183], v[196:199], v[32:35]
	v_mfma_f32_16x16x32_bf16 v[20:23], v[172:175], v[204:207], v[20:23]
	v_mfma_f32_16x16x32_bf16 v[16:19], v[180:183], v[204:207], v[16:19]
	v_mfma_f32_16x16x32_bf16 v[4:7], v[172:175], v[212:215], v[4:7]
	v_mfma_f32_16x16x32_bf16 v[0:3], v[180:183], v[212:215], v[0:3]
	v_mfma_f32_16x16x32_bf16 v[52:55], v[176:179], v[192:195], v[52:55]
	v_mfma_f32_16x16x32_bf16 v[48:51], v[184:187], v[192:195], v[48:51]
	v_mfma_f32_16x16x32_bf16 v[36:39], v[176:179], v[200:203], v[36:39]
	v_mfma_f32_16x16x32_bf16 v[32:35], v[184:187], v[200:203], v[32:35]
	v_mfma_f32_16x16x32_bf16 v[20:23], v[176:179], v[208:211], v[20:23]
	v_mfma_f32_16x16x32_bf16 v[16:19], v[184:187], v[208:211], v[16:19]
	v_mfma_f32_16x16x32_bf16 v[4:7], v[176:179], v[216:219], v[4:7]
	v_mfma_f32_16x16x32_bf16 v[0:3], v[184:187], v[216:219], v[0:3]
	s_setprio 0
	s_cmp_eq_u32 s85, s98
	s_cbranch_scc1 .Lmy_nobar_5
	s_barrier
.Lmy_nobar_5:
	s_add_i32 s85, s85, 2
	s_add_u32 s42, s42, 0x100
	s_addc_u32 s43, s43, 0
	s_add_u32 s83, s83, 0x100
	s_addc_u32 s84, s84, 0
	s_cmp_gt_u32 s85, 13
	s_cbranch_scc0 .LBB0_476
	s_and_b64 vcc, exec, s[8:9]
	s_cbranch_vccz .LBB0_479
	s_nop 0
.LBB0_479:
	v_lshl_add_u32 v160, s12, 10, v153
	ds_read_b32 v162, v160
	v_lshl_or_b32 v150, s13, 7, v154
	v_lshl_add_u32 v159, s40, 8, v131
	v_ashrrev_i32_e32 v151, 31, v150
	v_mov_b64_e32 v[148:149], s[16:17]
	s_waitcnt lgkmcnt(0)
	v_pk_mul_f32 v[124:125], v[124:125], v[162:163] op_sel_hi:[1,0]
	v_pk_mul_f32 v[126:127], v[126:127], v[162:163] op_sel_hi:[1,0]
	v_pk_mul_f32 v[122:123], v[122:123], v[162:163] op_sel_hi:[1,0]
	v_pk_mul_f32 v[120:121], v[120:121], v[162:163] op_sel_hi:[1,0]
	v_pk_mul_f32 v[118:119], v[118:119], v[162:163] op_sel_hi:[1,0]
	v_pk_mul_f32 v[116:117], v[116:117], v[162:163] op_sel_hi:[1,0]
	v_mul_f32_e32 v161, 0xbfb8aa3b, v124
	v_mul_f32_e32 v163, 0xbfb8aa3b, v125
	v_exp_f32_e32 v161, v161
	v_exp_f32_e32 v163, v163
	v_mad_i64_i32 v[164:165], s[12:13], v159, s67, v[148:149]
	v_lshlrev_b64 v[150:151], 1, v[150:151]
	v_pk_mul_f32 v[166:167], v[114:115], v[162:163] op_sel_hi:[1,0]
	v_add_f32_e32 v114, 1.0, v161
	v_rcp_f32_e32 v161, v114
	v_add_f32_e32 v114, 1.0, v163
	v_rcp_f32_e32 v163, v114
	v_lshl_add_u64 v[164:165], v[164:165], 0, v[150:151]
	s_andn2_b64 vcc, exec, s[4:5]
	s_mov_b64 s[4:5], -1
	v_pk_mul_f32 v[114:115], v[112:113], v[162:163] op_sel_hi:[1,0]
	v_mul_f32_e32 v112, v124, v161
	v_mul_f32_e32 v112, v116, v112
	v_mul_f32_e32 v116, 0xbfb8aa3b, v126
	v_mul_f32_e32 v124, 0xbfb8aa3b, v127
	v_exp_f32_e32 v116, v116
	v_exp_f32_e32 v124, v124
	v_mul_f32_e32 v113, v125, v163
	v_mul_f32_e32 v113, v117, v113
	v_add_f32_e32 v116, 1.0, v116
	v_add_f32_e32 v117, 1.0, v124
	v_rcp_f32_e32 v116, v116
	v_rcp_f32_e32 v117, v117
	v_cvt_pk_bf16_f32 v112, v112, v113
	v_mul_f32_e32 v113, v126, v116
	v_mul_f32_e32 v116, v127, v117
	v_mul_f32_e32 v117, 0xbfb8aa3b, v120
	v_mul_f32_e32 v113, v118, v113
	v_exp_f32_e32 v117, v117
	v_mul_f32_e32 v118, 0xbfb8aa3b, v121
	v_exp_f32_e32 v118, v118
	v_mul_f32_e32 v116, v119, v116
	v_add_f32_e32 v117, 1.0, v117
	v_rcp_f32_e32 v117, v117
	v_add_f32_e32 v118, 1.0, v118
	v_rcp_f32_e32 v118, v118
	v_cvt_pk_bf16_f32 v113, v113, v116
	v_mul_f32_e32 v116, v120, v117
	v_mul_f32_e32 v117, 0xbfb8aa3b, v122
	v_mul_f32_e32 v114, v114, v116
	v_mul_f32_e32 v116, v121, v118
	v_exp_f32_e32 v117, v117
	v_mul_f32_e32 v118, 0xbfb8aa3b, v123
	v_exp_f32_e32 v118, v118
	v_mul_f32_e32 v115, v115, v116
	v_add_f32_e32 v116, 1.0, v117
	v_rcp_f32_e32 v116, v116
	v_add_f32_e32 v117, 1.0, v118
	v_rcp_f32_e32 v117, v117
	v_cvt_pk_bf16_f32 v114, v114, v115
	v_mul_f32_e32 v115, v122, v116
	v_mul_f32_e32 v115, v166, v115
	v_mul_f32_e32 v116, v123, v117
	v_mul_f32_e32 v116, v167, v116
	v_cvt_pk_bf16_f32 v115, v115, v116
	global_store_dwordx4 v[164:165], v[112:115], off
	ds_read_b32 v112, v160 offset:64
	s_nop 0
	v_or_b32_e32 v113, 16, v159
	v_mad_i64_i32 v[114:115], s[12:13], v113, s67, v[148:149]
	s_waitcnt lgkmcnt(0)
	v_pk_mul_f32 v[108:109], v[108:109], v[112:113] op_sel_hi:[1,0]
	v_pk_mul_f32 v[110:111], v[110:111], v[112:113] op_sel_hi:[1,0]
	v_pk_mul_f32 v[106:107], v[106:107], v[112:113] op_sel_hi:[1,0]
	v_pk_mul_f32 v[104:105], v[104:105], v[112:113] op_sel_hi:[1,0]
	v_pk_mul_f32 v[102:103], v[102:103], v[112:113] op_sel_hi:[1,0]
	v_pk_mul_f32 v[100:101], v[100:101], v[112:113] op_sel_hi:[1,0]
	v_mul_f32_e32 v113, 0xbfb8aa3b, v108
	v_exp_f32_e32 v113, v113
	v_mul_f32_e32 v116, 0xbfb8aa3b, v109
	v_exp_f32_e32 v118, v116
	v_lshl_add_u64 v[114:115], v[114:115], 0, v[150:151]
	v_pk_mul_f32 v[116:117], v[98:99], v[112:113] op_sel_hi:[1,0]
	v_add_f32_e32 v98, 1.0, v113
	v_rcp_f32_e32 v113, v98
	v_add_f32_e32 v98, 1.0, v118
	v_rcp_f32_e32 v118, v98
	v_pk_mul_f32 v[98:99], v[96:97], v[112:113] op_sel_hi:[1,0]
	v_mul_f32_e32 v96, v108, v113
	v_mul_f32_e32 v96, v100, v96
	v_mul_f32_e32 v100, 0xbfb8aa3b, v110
	v_mul_f32_e32 v108, 0xbfb8aa3b, v111
	v_exp_f32_e32 v100, v100
	v_exp_f32_e32 v108, v108
	v_mul_f32_e32 v97, v109, v118
	v_mul_f32_e32 v97, v101, v97
	v_add_f32_e32 v100, 1.0, v100
	v_add_f32_e32 v101, 1.0, v108
	v_rcp_f32_e32 v100, v100
	v_rcp_f32_e32 v101, v101
	v_cvt_pk_bf16_f32 v96, v96, v97
	v_mul_f32_e32 v97, v110, v100
	v_mul_f32_e32 v100, v111, v101
	v_mul_f32_e32 v101, 0xbfb8aa3b, v104
	v_mul_f32_e32 v97, v102, v97
	v_exp_f32_e32 v101, v101
	v_mul_f32_e32 v102, 0xbfb8aa3b, v105
	v_exp_f32_e32 v102, v102
	v_mul_f32_e32 v100, v103, v100
	v_add_f32_e32 v101, 1.0, v101
	v_rcp_f32_e32 v101, v101
	v_add_f32_e32 v102, 1.0, v102
	v_rcp_f32_e32 v102, v102
	v_cvt_pk_bf16_f32 v97, v97, v100
	v_mul_f32_e32 v100, v104, v101
	v_mul_f32_e32 v101, 0xbfb8aa3b, v106
	v_mul_f32_e32 v98, v98, v100
	v_mul_f32_e32 v100, v105, v102
	v_exp_f32_e32 v101, v101
	v_mul_f32_e32 v102, 0xbfb8aa3b, v107
	v_exp_f32_e32 v102, v102
	v_mul_f32_e32 v99, v99, v100
	v_add_f32_e32 v100, 1.0, v101
	v_rcp_f32_e32 v100, v100
	v_add_f32_e32 v101, 1.0, v102
	v_rcp_f32_e32 v101, v101
	v_cvt_pk_bf16_f32 v98, v98, v99
	v_mul_f32_e32 v99, v106, v100
	v_mul_f32_e32 v99, v116, v99
	v_mul_f32_e32 v100, v107, v101
	v_mul_f32_e32 v100, v117, v100
	v_cvt_pk_bf16_f32 v99, v99, v100
	global_store_dwordx4 v[114:115], v[96:99], off
	ds_read_b32 v96, v160 offset:128
	s_nop 0
	v_or_b32_e32 v97, 32, v159
	v_mad_i64_i32 v[98:99], s[12:13], v97, s67, v[148:149]
	s_waitcnt lgkmcnt(0)
	v_pk_mul_f32 v[92:93], v[92:93], v[96:97] op_sel_hi:[1,0]
	v_pk_mul_f32 v[94:95], v[94:95], v[96:97] op_sel_hi:[1,0]
	v_pk_mul_f32 v[90:91], v[90:91], v[96:97] op_sel_hi:[1,0]
	v_pk_mul_f32 v[88:89], v[88:89], v[96:97] op_sel_hi:[1,0]
	v_pk_mul_f32 v[86:87], v[86:87], v[96:97] op_sel_hi:[1,0]
	v_pk_mul_f32 v[84:85], v[84:85], v[96:97] op_sel_hi:[1,0]
	v_mul_f32_e32 v97, 0xbfb8aa3b, v92
	v_exp_f32_e32 v97, v97
	v_mul_f32_e32 v100, 0xbfb8aa3b, v93
	v_exp_f32_e32 v102, v100
	v_lshl_add_u64 v[98:99], v[98:99], 0, v[150:151]
	v_pk_mul_f32 v[100:101], v[82:83], v[96:97] op_sel_hi:[1,0]
	v_add_f32_e32 v82, 1.0, v97
	v_rcp_f32_e32 v97, v82
	v_add_f32_e32 v82, 1.0, v102
	v_rcp_f32_e32 v102, v82
	v_pk_mul_f32 v[82:83], v[80:81], v[96:97] op_sel_hi:[1,0]
	v_mul_f32_e32 v80, v92, v97
	v_mul_f32_e32 v80, v84, v80
	v_mul_f32_e32 v84, 0xbfb8aa3b, v94
	v_mul_f32_e32 v92, 0xbfb8aa3b, v95
	v_exp_f32_e32 v84, v84
	v_exp_f32_e32 v92, v92
	v_mul_f32_e32 v81, v93, v102
	v_mul_f32_e32 v81, v85, v81
	v_add_f32_e32 v84, 1.0, v84
	v_add_f32_e32 v85, 1.0, v92
	v_rcp_f32_e32 v84, v84
	v_rcp_f32_e32 v85, v85
	v_cvt_pk_bf16_f32 v80, v80, v81
	v_mul_f32_e32 v81, v94, v84
	v_mul_f32_e32 v84, v95, v85
	v_mul_f32_e32 v85, 0xbfb8aa3b, v88
	v_mul_f32_e32 v81, v86, v81
	v_exp_f32_e32 v85, v85
	v_mul_f32_e32 v86, 0xbfb8aa3b, v89
	v_exp_f32_e32 v86, v86
	v_mul_f32_e32 v84, v87, v84
	v_add_f32_e32 v85, 1.0, v85
	v_rcp_f32_e32 v85, v85
	v_add_f32_e32 v86, 1.0, v86
	v_rcp_f32_e32 v86, v86
	v_cvt_pk_bf16_f32 v81, v81, v84
	v_mul_f32_e32 v84, v88, v85
	v_mul_f32_e32 v85, 0xbfb8aa3b, v90
	v_mul_f32_e32 v82, v82, v84
	v_mul_f32_e32 v84, v89, v86
	v_exp_f32_e32 v85, v85
	v_mul_f32_e32 v86, 0xbfb8aa3b, v91
	v_exp_f32_e32 v86, v86
	v_mul_f32_e32 v83, v83, v84
	v_add_f32_e32 v84, 1.0, v85
	v_rcp_f32_e32 v84, v84
	v_add_f32_e32 v85, 1.0, v86
	v_rcp_f32_e32 v85, v85
	v_cvt_pk_bf16_f32 v82, v82, v83
	v_mul_f32_e32 v83, v90, v84
	v_mul_f32_e32 v83, v100, v83
	v_mul_f32_e32 v84, v91, v85
	v_mul_f32_e32 v84, v101, v84
	v_cvt_pk_bf16_f32 v83, v83, v84
	global_store_dwordx4 v[98:99], v[80:83], off
	ds_read_b32 v80, v160 offset:192
	s_nop 0
	v_or_b32_e32 v81, 48, v159
	v_mad_i64_i32 v[82:83], s[12:13], v81, s67, v[148:149]
	s_waitcnt lgkmcnt(0)
	v_pk_mul_f32 v[76:77], v[76:77], v[80:81] op_sel_hi:[1,0]
	v_pk_mul_f32 v[78:79], v[78:79], v[80:81] op_sel_hi:[1,0]
	v_pk_mul_f32 v[74:75], v[74:75], v[80:81] op_sel_hi:[1,0]
	v_pk_mul_f32 v[72:73], v[72:73], v[80:81] op_sel_hi:[1,0]
	v_pk_mul_f32 v[70:71], v[70:71], v[80:81] op_sel_hi:[1,0]
	v_pk_mul_f32 v[68:69], v[68:69], v[80:81] op_sel_hi:[1,0]
	v_mul_f32_e32 v81, 0xbfb8aa3b, v76
	v_exp_f32_e32 v81, v81
	v_mul_f32_e32 v84, 0xbfb8aa3b, v77
	v_exp_f32_e32 v86, v84
	v_lshl_add_u64 v[82:83], v[82:83], 0, v[150:151]
	v_pk_mul_f32 v[84:85], v[66:67], v[80:81] op_sel_hi:[1,0]
	v_add_f32_e32 v66, 1.0, v81
	v_rcp_f32_e32 v81, v66
	v_add_f32_e32 v66, 1.0, v86
	v_rcp_f32_e32 v86, v66
	v_pk_mul_f32 v[66:67], v[64:65], v[80:81] op_sel_hi:[1,0]
	v_mul_f32_e32 v64, v76, v81
	v_mul_f32_e32 v64, v68, v64
	v_mul_f32_e32 v68, 0xbfb8aa3b, v78
	v_mul_f32_e32 v76, 0xbfb8aa3b, v79
	v_exp_f32_e32 v68, v68
	v_exp_f32_e32 v76, v76
	v_mul_f32_e32 v65, v77, v86
	v_mul_f32_e32 v65, v69, v65
	v_add_f32_e32 v68, 1.0, v68
	v_add_f32_e32 v69, 1.0, v76
	v_rcp_f32_e32 v68, v68
	v_rcp_f32_e32 v69, v69
	v_cvt_pk_bf16_f32 v64, v64, v65
	v_mul_f32_e32 v65, v78, v68
	v_mul_f32_e32 v68, v79, v69
	v_mul_f32_e32 v69, 0xbfb8aa3b, v72
	v_mul_f32_e32 v65, v70, v65
	v_exp_f32_e32 v69, v69
	v_mul_f32_e32 v70, 0xbfb8aa3b, v73
	v_exp_f32_e32 v70, v70
	v_mul_f32_e32 v68, v71, v68
	v_add_f32_e32 v69, 1.0, v69
	v_rcp_f32_e32 v69, v69
	v_add_f32_e32 v70, 1.0, v70
	v_rcp_f32_e32 v70, v70
	v_cvt_pk_bf16_f32 v65, v65, v68
	v_mul_f32_e32 v68, v72, v69
	v_mul_f32_e32 v69, 0xbfb8aa3b, v74
	v_mul_f32_e32 v66, v66, v68
	v_mul_f32_e32 v68, v73, v70
	v_exp_f32_e32 v69, v69
	v_mul_f32_e32 v70, 0xbfb8aa3b, v75
	v_exp_f32_e32 v70, v70
	v_mul_f32_e32 v67, v67, v68
	v_add_f32_e32 v68, 1.0, v69
	v_rcp_f32_e32 v68, v68
	v_add_f32_e32 v69, 1.0, v70
	v_rcp_f32_e32 v69, v69
	v_cvt_pk_bf16_f32 v66, v66, v67
	v_mul_f32_e32 v67, v74, v68
	v_mul_f32_e32 v67, v84, v67
	v_mul_f32_e32 v68, v75, v69
	v_mul_f32_e32 v68, v85, v68
	v_cvt_pk_bf16_f32 v67, v67, v68
	global_store_dwordx4 v[82:83], v[64:67], off
	ds_read_b32 v64, v160 offset:512
	s_nop 0
	v_add_u32_e32 v65, 0x80, v159
	v_mad_i64_i32 v[66:67], s[12:13], v65, s67, v[148:149]
	s_waitcnt lgkmcnt(0)
	v_pk_mul_f32 v[60:61], v[60:61], v[64:65] op_sel_hi:[1,0]
	v_pk_mul_f32 v[62:63], v[62:63], v[64:65] op_sel_hi:[1,0]
	v_pk_mul_f32 v[58:59], v[58:59], v[64:65] op_sel_hi:[1,0]
	v_pk_mul_f32 v[56:57], v[56:57], v[64:65] op_sel_hi:[1,0]
	v_pk_mul_f32 v[54:55], v[54:55], v[64:65] op_sel_hi:[1,0]
	v_pk_mul_f32 v[52:53], v[52:53], v[64:65] op_sel_hi:[1,0]
	v_mul_f32_e32 v65, 0xbfb8aa3b, v60
	v_exp_f32_e32 v65, v65
	v_mul_f32_e32 v68, 0xbfb8aa3b, v61
	v_exp_f32_e32 v70, v68
	v_lshl_add_u64 v[66:67], v[66:67], 0, v[150:151]
	v_pk_mul_f32 v[68:69], v[50:51], v[64:65] op_sel_hi:[1,0]
	v_add_f32_e32 v50, 1.0, v65
	v_rcp_f32_e32 v65, v50
	v_add_f32_e32 v50, 1.0, v70
	v_rcp_f32_e32 v70, v50
	v_pk_mul_f32 v[50:51], v[48:49], v[64:65] op_sel_hi:[1,0]
	v_mul_f32_e32 v48, v60, v65
	v_mul_f32_e32 v48, v52, v48
	v_mul_f32_e32 v52, 0xbfb8aa3b, v62
	v_mul_f32_e32 v60, 0xbfb8aa3b, v63
	v_exp_f32_e32 v52, v52
	v_exp_f32_e32 v60, v60
	v_mul_f32_e32 v49, v61, v70
	v_mul_f32_e32 v49, v53, v49
	v_add_f32_e32 v52, 1.0, v52
	v_add_f32_e32 v53, 1.0, v60
	v_rcp_f32_e32 v52, v52
	v_rcp_f32_e32 v53, v53
	v_cvt_pk_bf16_f32 v48, v48, v49
	v_mul_f32_e32 v49, v62, v52
	v_mul_f32_e32 v52, v63, v53
	v_mul_f32_e32 v53, 0xbfb8aa3b, v56
	v_mul_f32_e32 v49, v54, v49
	v_exp_f32_e32 v53, v53
	v_mul_f32_e32 v54, 0xbfb8aa3b, v57
	v_exp_f32_e32 v54, v54
	v_mul_f32_e32 v52, v55, v52
	v_add_f32_e32 v53, 1.0, v53
	v_rcp_f32_e32 v53, v53
	v_add_f32_e32 v54, 1.0, v54
	v_rcp_f32_e32 v54, v54
	v_cvt_pk_bf16_f32 v49, v49, v52
	v_mul_f32_e32 v52, v56, v53
	v_mul_f32_e32 v53, 0xbfb8aa3b, v58
	v_mul_f32_e32 v50, v50, v52
	v_mul_f32_e32 v52, v57, v54
	v_exp_f32_e32 v53, v53
	v_mul_f32_e32 v54, 0xbfb8aa3b, v59
	v_exp_f32_e32 v54, v54
	v_mul_f32_e32 v51, v51, v52
	v_add_f32_e32 v52, 1.0, v53
	v_rcp_f32_e32 v52, v52
	v_add_f32_e32 v53, 1.0, v54
	v_rcp_f32_e32 v53, v53
	v_cvt_pk_bf16_f32 v50, v50, v51
	v_mul_f32_e32 v51, v58, v52
	v_mul_f32_e32 v51, v68, v51
	v_mul_f32_e32 v52, v59, v53
	v_mul_f32_e32 v52, v69, v52
	v_cvt_pk_bf16_f32 v51, v51, v52
	global_store_dwordx4 v[66:67], v[48:51], off
	ds_read_b32 v48, v160 offset:576
	s_nop 0
	v_add_u32_e32 v49, 0x90, v159
	v_mad_i64_i32 v[50:51], s[12:13], v49, s67, v[148:149]
	s_waitcnt lgkmcnt(0)
	v_pk_mul_f32 v[44:45], v[44:45], v[48:49] op_sel_hi:[1,0]
	v_pk_mul_f32 v[46:47], v[46:47], v[48:49] op_sel_hi:[1,0]
	v_pk_mul_f32 v[42:43], v[42:43], v[48:49] op_sel_hi:[1,0]
	v_pk_mul_f32 v[40:41], v[40:41], v[48:49] op_sel_hi:[1,0]
	v_pk_mul_f32 v[38:39], v[38:39], v[48:49] op_sel_hi:[1,0]
	v_pk_mul_f32 v[36:37], v[36:37], v[48:49] op_sel_hi:[1,0]
	v_mul_f32_e32 v49, 0xbfb8aa3b, v44
	v_exp_f32_e32 v49, v49
	v_mul_f32_e32 v52, 0xbfb8aa3b, v45
	v_exp_f32_e32 v54, v52
	v_lshl_add_u64 v[50:51], v[50:51], 0, v[150:151]
	v_pk_mul_f32 v[52:53], v[34:35], v[48:49] op_sel_hi:[1,0]
	v_add_f32_e32 v34, 1.0, v49
	v_rcp_f32_e32 v49, v34
	v_add_f32_e32 v34, 1.0, v54
	v_rcp_f32_e32 v54, v34
	v_pk_mul_f32 v[34:35], v[32:33], v[48:49] op_sel_hi:[1,0]
	v_mul_f32_e32 v32, v44, v49
	v_mul_f32_e32 v32, v36, v32
	v_mul_f32_e32 v36, 0xbfb8aa3b, v46
	v_mul_f32_e32 v44, 0xbfb8aa3b, v47
	v_exp_f32_e32 v36, v36
	v_exp_f32_e32 v44, v44
	v_mul_f32_e32 v33, v45, v54
	v_mul_f32_e32 v33, v37, v33
	v_add_f32_e32 v36, 1.0, v36
	v_add_f32_e32 v37, 1.0, v44
	v_rcp_f32_e32 v36, v36
	v_rcp_f32_e32 v37, v37
	v_cvt_pk_bf16_f32 v32, v32, v33
	v_mul_f32_e32 v33, v46, v36
	v_mul_f32_e32 v36, v47, v37
	v_mul_f32_e32 v37, 0xbfb8aa3b, v40
	v_mul_f32_e32 v33, v38, v33
	v_exp_f32_e32 v37, v37
	v_mul_f32_e32 v38, 0xbfb8aa3b, v41
	v_exp_f32_e32 v38, v38
	v_mul_f32_e32 v36, v39, v36
	v_add_f32_e32 v37, 1.0, v37
	v_rcp_f32_e32 v37, v37
	v_add_f32_e32 v38, 1.0, v38
	v_rcp_f32_e32 v38, v38
	v_cvt_pk_bf16_f32 v33, v33, v36
	v_mul_f32_e32 v36, v40, v37
	v_mul_f32_e32 v37, 0xbfb8aa3b, v42
	v_mul_f32_e32 v34, v34, v36
	v_mul_f32_e32 v36, v41, v38
	v_exp_f32_e32 v37, v37
	v_mul_f32_e32 v38, 0xbfb8aa3b, v43
	v_exp_f32_e32 v38, v38
	v_mul_f32_e32 v35, v35, v36
	v_add_f32_e32 v36, 1.0, v37
	v_rcp_f32_e32 v36, v36
	v_add_f32_e32 v37, 1.0, v38
	v_rcp_f32_e32 v37, v37
	v_cvt_pk_bf16_f32 v34, v34, v35
	v_mul_f32_e32 v35, v42, v36
	v_mul_f32_e32 v35, v52, v35
	v_mul_f32_e32 v36, v43, v37
	v_mul_f32_e32 v36, v53, v36
	v_cvt_pk_bf16_f32 v35, v35, v36
	global_store_dwordx4 v[50:51], v[32:35], off
	ds_read_b32 v32, v160 offset:640
	s_nop 0
	v_add_u32_e32 v33, 0xa0, v159
	v_mad_i64_i32 v[34:35], s[12:13], v33, s67, v[148:149]
	s_waitcnt lgkmcnt(0)
	v_pk_mul_f32 v[28:29], v[28:29], v[32:33] op_sel_hi:[1,0]
	v_pk_mul_f32 v[30:31], v[30:31], v[32:33] op_sel_hi:[1,0]
	v_pk_mul_f32 v[26:27], v[26:27], v[32:33] op_sel_hi:[1,0]
	v_pk_mul_f32 v[24:25], v[24:25], v[32:33] op_sel_hi:[1,0]
	v_pk_mul_f32 v[22:23], v[22:23], v[32:33] op_sel_hi:[1,0]
	v_pk_mul_f32 v[20:21], v[20:21], v[32:33] op_sel_hi:[1,0]
	v_mul_f32_e32 v33, 0xbfb8aa3b, v28
	v_exp_f32_e32 v33, v33
	v_mul_f32_e32 v36, 0xbfb8aa3b, v29
	v_exp_f32_e32 v38, v36
	v_lshl_add_u64 v[34:35], v[34:35], 0, v[150:151]
	v_pk_mul_f32 v[36:37], v[18:19], v[32:33] op_sel_hi:[1,0]
	v_add_f32_e32 v18, 1.0, v33
	v_rcp_f32_e32 v33, v18
	v_add_f32_e32 v18, 1.0, v38
	v_rcp_f32_e32 v38, v18
	v_pk_mul_f32 v[18:19], v[16:17], v[32:33] op_sel_hi:[1,0]
	v_mul_f32_e32 v16, v28, v33
	v_mul_f32_e32 v16, v20, v16
	v_mul_f32_e32 v20, 0xbfb8aa3b, v30
	v_mul_f32_e32 v28, 0xbfb8aa3b, v31
	v_exp_f32_e32 v20, v20
	v_exp_f32_e32 v28, v28
	v_mul_f32_e32 v17, v29, v38
	v_mul_f32_e32 v17, v21, v17
	v_add_f32_e32 v20, 1.0, v20
	v_add_f32_e32 v21, 1.0, v28
	v_rcp_f32_e32 v20, v20
	v_rcp_f32_e32 v21, v21
	v_cvt_pk_bf16_f32 v16, v16, v17
	v_mul_f32_e32 v17, v30, v20
	v_mul_f32_e32 v20, v31, v21
	v_mul_f32_e32 v21, 0xbfb8aa3b, v24
	v_mul_f32_e32 v17, v22, v17
	v_exp_f32_e32 v21, v21
	v_mul_f32_e32 v22, 0xbfb8aa3b, v25
	v_exp_f32_e32 v22, v22
	v_mul_f32_e32 v20, v23, v20
	v_add_f32_e32 v21, 1.0, v21
	v_rcp_f32_e32 v21, v21
	v_add_f32_e32 v22, 1.0, v22
	v_rcp_f32_e32 v22, v22
	v_cvt_pk_bf16_f32 v17, v17, v20
	v_mul_f32_e32 v20, v24, v21
	v_mul_f32_e32 v21, 0xbfb8aa3b, v26
	v_mul_f32_e32 v18, v18, v20
	v_mul_f32_e32 v20, v25, v22
	v_exp_f32_e32 v21, v21
	v_mul_f32_e32 v22, 0xbfb8aa3b, v27
	v_exp_f32_e32 v22, v22
	v_mul_f32_e32 v19, v19, v20
	v_add_f32_e32 v20, 1.0, v21
	v_rcp_f32_e32 v20, v20
	v_add_f32_e32 v21, 1.0, v22
	v_rcp_f32_e32 v21, v21
	v_cvt_pk_bf16_f32 v18, v18, v19
	v_mul_f32_e32 v19, v26, v20
	v_mul_f32_e32 v19, v36, v19
	v_mul_f32_e32 v20, v27, v21
	v_mul_f32_e32 v20, v37, v20
	v_cvt_pk_bf16_f32 v19, v19, v20
	global_store_dwordx4 v[34:35], v[16:19], off
	ds_read_b32 v16, v160 offset:704
	s_nop 0
	v_add_u32_e32 v17, 0xb0, v159
	v_mad_i64_i32 v[18:19], s[12:13], v17, s67, v[148:149]
	s_waitcnt lgkmcnt(0)
	v_pk_mul_f32 v[12:13], v[12:13], v[16:17] op_sel_hi:[1,0]
	v_pk_mul_f32 v[14:15], v[14:15], v[16:17] op_sel_hi:[1,0]
	v_pk_mul_f32 v[10:11], v[10:11], v[16:17] op_sel_hi:[1,0]
	v_pk_mul_f32 v[8:9], v[8:9], v[16:17] op_sel_hi:[1,0]
	v_pk_mul_f32 v[6:7], v[6:7], v[16:17] op_sel_hi:[1,0]
	v_pk_mul_f32 v[4:5], v[4:5], v[16:17] op_sel_hi:[1,0]
	v_mul_f32_e32 v17, 0xbfb8aa3b, v12
	v_exp_f32_e32 v17, v17
	v_mul_f32_e32 v20, 0xbfb8aa3b, v13
	v_exp_f32_e32 v22, v20
	v_lshl_add_u64 v[18:19], v[18:19], 0, v[150:151]
	v_pk_mul_f32 v[20:21], v[2:3], v[16:17] op_sel_hi:[1,0]
	v_add_f32_e32 v2, 1.0, v17
	v_rcp_f32_e32 v17, v2
	v_add_f32_e32 v2, 1.0, v22
	v_rcp_f32_e32 v22, v2
	v_pk_mul_f32 v[2:3], v[0:1], v[16:17] op_sel_hi:[1,0]
	v_mul_f32_e32 v0, v12, v17
	v_mul_f32_e32 v0, v4, v0
	v_mul_f32_e32 v4, 0xbfb8aa3b, v14
	v_mul_f32_e32 v12, 0xbfb8aa3b, v15
	v_exp_f32_e32 v4, v4
	v_exp_f32_e32 v12, v12
	v_mul_f32_e32 v1, v13, v22
	v_mul_f32_e32 v1, v5, v1
	v_add_f32_e32 v4, 1.0, v4
	v_add_f32_e32 v5, 1.0, v12
	v_rcp_f32_e32 v4, v4
	v_rcp_f32_e32 v5, v5
	v_cvt_pk_bf16_f32 v0, v0, v1
	v_mul_f32_e32 v1, v14, v4
	v_mul_f32_e32 v4, v15, v5
	v_mul_f32_e32 v5, 0xbfb8aa3b, v8
	v_mul_f32_e32 v1, v6, v1
	v_exp_f32_e32 v5, v5
	v_mul_f32_e32 v6, 0xbfb8aa3b, v9
	v_exp_f32_e32 v6, v6
	v_mul_f32_e32 v4, v7, v4
	v_add_f32_e32 v5, 1.0, v5
	v_rcp_f32_e32 v5, v5
	v_add_f32_e32 v6, 1.0, v6
	v_rcp_f32_e32 v6, v6
	v_cvt_pk_bf16_f32 v1, v1, v4
	v_mul_f32_e32 v4, v8, v5
	v_mul_f32_e32 v5, 0xbfb8aa3b, v10
	v_mul_f32_e32 v2, v2, v4
	v_mul_f32_e32 v4, v9, v6
	v_exp_f32_e32 v5, v5
	v_mul_f32_e32 v6, 0xbfb8aa3b, v11
	v_exp_f32_e32 v6, v6
	v_mul_f32_e32 v3, v3, v4
	v_add_f32_e32 v4, 1.0, v5
	v_rcp_f32_e32 v4, v4
	v_add_f32_e32 v5, 1.0, v6
	v_rcp_f32_e32 v5, v5
	v_cvt_pk_bf16_f32 v2, v2, v3
	v_mul_f32_e32 v3, v10, v4
	v_mul_f32_e32 v3, v20, v3
	v_mul_f32_e32 v4, v11, v5
	v_mul_f32_e32 v4, v21, v4
	v_cvt_pk_bf16_f32 v3, v3, v4
	global_store_dwordx4 v[18:19], v[0:3], off
	s_cbranch_vccnz .LBB0_472
	s_andn2_b64 vcc, exec, s[0:1]
	s_cbranch_vccnz .LBB0_471
	s_nop 0
	s_branch .LBB0_471

.LBB0_551:
	s_lshr_b32 s99, s91, 2
	s_cmp_eq_u32 s99, 1
	s_cselect_b32 s98, 40, 0x7fffffff
	s_add_i32 s66, s66, 1
	s_mul_i32 s0, s66, s59
	s_mul_hi_u32 s1, s66, s62
	s_add_i32 s1, s1, s0
	s_mul_i32 s0, s66, s62
	s_add_u32 s6, s0, s2
	s_addc_u32 s7, s1, s63
	v_cmp_gt_i64_e32 vcc, s[6:7], v[146:147]
	v_cmp_lt_i64_e64 s[0:1], s[6:7], v[144:145]
	s_cbranch_vccnz .LBB0_557
	s_ashr_i32 s7, s6, 31
	s_lshr_b32 s7, s7, 29
	s_add_i32 s13, s6, s7
	s_and_b32 s7, s13, -8
	s_sub_i32 s28, s6, s7
	s_cmp_gt_i32 s28, -1
	s_mov_b64 s[6:7], -1
	s_cbranch_scc0 .LBB0_554
	s_lshl_b32 s29, s28, 6
	s_mov_b64 s[6:7], 0

.LBB0_561:
	s_add_u32 s40, s40, 0xb0080
	s_addc_u32 s41, s41, 0
	s_add_u32 s13, s42, 0x100
	v_mov_b32_e32 v0, 0
	s_addc_u32 s77, s43, 0
	s_mov_b32 s81, -2
	s_waitcnt lgkmcnt(0)
	v_mov_b32_e32 v1, v0
	v_mov_b32_e32 v2, v0
	v_mov_b32_e32 v3, v0
	v_mov_b32_e32 v4, v0
	v_mov_b32_e32 v5, v0
	v_mov_b32_e32 v6, v0
	v_mov_b32_e32 v7, v0
	v_mov_b32_e32 v16, v0
	v_mov_b32_e32 v17, v0
	v_mov_b32_e32 v18, v0
	v_mov_b32_e32 v19, v0
	v_mov_b32_e32 v20, v0
	v_mov_b32_e32 v21, v0
	v_mov_b32_e32 v22, v0
	v_mov_b32_e32 v23, v0
	v_mov_b32_e32 v32, v0
	v_mov_b32_e32 v33, v0
	v_mov_b32_e32 v34, v0
	v_mov_b32_e32 v35, v0
	v_mov_b32_e32 v36, v0
	v_mov_b32_e32 v37, v0
	v_mov_b32_e32 v38, v0
	v_mov_b32_e32 v39, v0
	v_mov_b32_e32 v48, v0
	v_mov_b32_e32 v49, v0
	v_mov_b32_e32 v50, v0
	v_mov_b32_e32 v51, v0
	v_mov_b32_e32 v52, v0
	v_mov_b32_e32 v53, v0
	v_mov_b32_e32 v54, v0
	v_mov_b32_e32 v55, v0
	v_mov_b32_e32 v8, v0
	v_mov_b32_e32 v9, v0
	v_mov_b32_e32 v10, v0
	v_mov_b32_e32 v11, v0
	v_mov_b32_e32 v12, v0
	v_mov_b32_e32 v13, v0
	v_mov_b32_e32 v14, v0
	v_mov_b32_e32 v15, v0
	v_mov_b32_e32 v24, v0
	v_mov_b32_e32 v25, v0
	v_mov_b32_e32 v26, v0
	v_mov_b32_e32 v27, v0
	v_mov_b32_e32 v28, v0
	v_mov_b32_e32 v29, v0
	v_mov_b32_e32 v30, v0
	v_mov_b32_e32 v31, v0
	v_mov_b32_e32 v40, v0
	v_mov_b32_e32 v41, v0
	v_mov_b32_e32 v42, v0
	v_mov_b32_e32 v43, v0
	v_mov_b32_e32 v44, v0
	v_mov_b32_e32 v45, v0
	v_mov_b32_e32 v46, v0
	v_mov_b32_e32 v47, v0
	v_mov_b32_e32 v56, v0
	v_mov_b32_e32 v57, v0
	v_mov_b32_e32 v58, v0
	v_mov_b32_e32 v59, v0
	v_mov_b32_e32 v60, v0
	v_mov_b32_e32 v61, v0
	v_mov_b32_e32 v62, v0
	v_mov_b32_e32 v63, v0
	v_mov_b32_e32 v64, v0
	v_mov_b32_e32 v65, v0
	v_mov_b32_e32 v66, v0
	v_mov_b32_e32 v67, v0
	v_mov_b32_e32 v68, v0
	v_mov_b32_e32 v69, v0
	v_mov_b32_e32 v70, v0
	v_mov_b32_e32 v71, v0
	v_mov_b32_e32 v80, v0
	v_mov_b32_e32 v81, v0
	v_mov_b32_e32 v82, v0
	v_mov_b32_e32 v83, v0
	v_mov_b32_e32 v84, v0
	v_mov_b32_e32 v85, v0
	v_mov_b32_e32 v86, v0
	v_mov_b32_e32 v87, v0
	v_mov_b32_e32 v96, v0
	v_mov_b32_e32 v97, v0
	v_mov_b32_e32 v98, v0
	v_mov_b32_e32 v99, v0
	v_mov_b32_e32 v100, v0
	v_mov_b32_e32 v101, v0
	v_mov_b32_e32 v102, v0
	v_mov_b32_e32 v103, v0
	v_mov_b32_e32 v112, v0
	v_mov_b32_e32 v113, v0
	v_mov_b32_e32 v114, v0
	v_mov_b32_e32 v115, v0
	v_mov_b32_e32 v116, v0
	v_mov_b32_e32 v117, v0
	v_mov_b32_e32 v118, v0
	v_mov_b32_e32 v119, v0
	v_mov_b32_e32 v72, v0
	v_mov_b32_e32 v73, v0
	v_mov_b32_e32 v74, v0
	v_mov_b32_e32 v75, v0
	v_mov_b32_e32 v76, v0
	v_mov_b32_e32 v77, v0
	v_mov_b32_e32 v78, v0
	v_mov_b32_e32 v79, v0
	v_mov_b32_e32 v88, v0
	v_mov_b32_e32 v89, v0
	v_mov_b32_e32 v90, v0
	v_mov_b32_e32 v91, v0
	v_mov_b32_e32 v92, v0
	v_mov_b32_e32 v93, v0
	v_mov_b32_e32 v94, v0
	v_mov_b32_e32 v95, v0
	v_mov_b32_e32 v104, v0
	v_mov_b32_e32 v105, v0
	v_mov_b32_e32 v106, v0
	v_mov_b32_e32 v107, v0
	v_mov_b32_e32 v108, v0
	v_mov_b32_e32 v109, v0
	v_mov_b32_e32 v110, v0
	v_mov_b32_e32 v111, v0
	v_mov_b32_e32 v120, v0
	v_mov_b32_e32 v121, v0
	v_mov_b32_e32 v122, v0
	v_mov_b32_e32 v123, v0
	v_mov_b32_e32 v124, v0
	v_mov_b32_e32 v125, v0
	v_mov_b32_e32 v126, v0
	v_mov_b32_e32 v127, v0
	s_cmp_lg_u32 s66, 1
	s_cselect_b32 s100, s99, 0
	s_cmp_lg_u32 s100, 0
	s_cbranch_scc0 .Lmy_nobar2_6
	s_barrier
.Lmy_nobar2_6:
.LBB0_562:
	ds_read_b128 v[148:151], v154
	ds_read_b128 v[160:163], v154 offset:1024
	ds_read_b128 v[164:167], v154 offset:2048
	ds_read_b128 v[168:171], v154 offset:3072
	ds_read_b128 v[172:175], v155
	ds_read_b128 v[176:179], v155 offset:1024
	ds_read_b128 v[180:183], v155 offset:2048
	ds_read_b128 v[184:187], v155 offset:3072
	s_add_u32 s34, s40, 0xfff50080
	s_addc_u32 s35, s41, -1
	s_cmp_eq_u32 s81, 40
	s_cselect_b32 s49, s1, s35
	s_cselect_b32 s48, s0, s34
	s_cselect_b32 s43, s29, s77
	s_cselect_b32 s42, s28, s13
	v_lshl_add_u64 v[220:221], s[40:41], 0, v[140:141]
	s_add_i32 m0, s52, 0xc000
	ds_read_b128 v[188:191], v157
	ds_read_b128 v[192:195], v157 offset:1024
	ds_read_b128 v[196:199], v157 offset:2048
	ds_read_b128 v[200:203], v157 offset:3072
	ds_read_b128 v[204:207], v157 offset:4096
	ds_read_b128 v[208:211], v157 offset:5120
	ds_read_b128 v[212:215], v157 offset:6144
	ds_read_b128 v[216:219], v157 offset:7168
	global_load_lds_dwordx4 v[220:221], off
	v_lshl_add_u64 v[220:221], s[40:41], 0, v[142:143]
	s_add_i32 m0, s52, 0xe000
	s_nop 0
	global_load_lds_dwordx4 v[220:221], off
	s_waitcnt vmcnt(8)
	s_waitcnt lgkmcnt(0)
	s_barrier
	s_setprio 1
	s_waitcnt lgkmcnt(0)
	v_mfma_f32_16x16x32_bf16 v[124:127], v[148:151], v[188:191], v[124:127]
	v_mfma_f32_16x16x32_bf16 v[120:123], v[164:167], v[188:191], v[120:123]
	v_mfma_f32_16x16x32_bf16 v[108:111], v[148:151], v[196:199], v[108:111]
	v_mfma_f32_16x16x32_bf16 v[104:107], v[164:167], v[196:199], v[104:107]
	v_mfma_f32_16x16x32_bf16 v[92:95], v[148:151], v[204:207], v[92:95]
	v_mfma_f32_16x16x32_bf16 v[88:91], v[164:167], v[204:207], v[88:91]
	v_mfma_f32_16x16x32_bf16 v[76:79], v[148:151], v[212:215], v[76:79]
	v_mfma_f32_16x16x32_bf16 v[72:75], v[164:167], v[212:215], v[72:75]
	v_mfma_f32_16x16x32_bf16 v[124:127], v[160:163], v[192:195], v[124:127]
	v_mfma_f32_16x16x32_bf16 v[120:123], v[168:171], v[192:195], v[120:123]
	v_mfma_f32_16x16x32_bf16 v[108:111], v[160:163], v[200:203], v[108:111]
	v_mfma_f32_16x16x32_bf16 v[104:107], v[168:171], v[200:203], v[104:107]
	v_mfma_f32_16x16x32_bf16 v[92:95], v[160:163], v[208:211], v[92:95]
	v_mfma_f32_16x16x32_bf16 v[88:91], v[168:171], v[208:211], v[88:91]
	v_mfma_f32_16x16x32_bf16 v[76:79], v[160:163], v[216:219], v[76:79]
	v_mfma_f32_16x16x32_bf16 v[72:75], v[168:171], v[216:219], v[72:75]
	s_setprio 0
	s_setprio 1
	v_mfma_f32_16x16x32_bf16 v[116:119], v[172:175], v[188:191], v[116:119]
	v_mfma_f32_16x16x32_bf16 v[112:115], v[180:183], v[188:191], v[112:115]
	v_mfma_f32_16x16x32_bf16 v[100:103], v[172:175], v[196:199], v[100:103]
	v_mfma_f32_16x16x32_bf16 v[96:99], v[180:183], v[196:199], v[96:99]
	v_mfma_f32_16x16x32_bf16 v[84:87], v[172:175], v[204:207], v[84:87]
	v_mfma_f32_16x16x32_bf16 v[80:83], v[180:183], v[204:207], v[80:83]
	v_mfma_f32_16x16x32_bf16 v[68:71], v[172:175], v[212:215], v[68:71]
	v_mfma_f32_16x16x32_bf16 v[64:67], v[180:183], v[212:215], v[64:67]
	v_mfma_f32_16x16x32_bf16 v[116:119], v[176:179], v[192:195], v[116:119]
	v_mfma_f32_16x16x32_bf16 v[112:115], v[184:187], v[192:195], v[112:115]
	v_mfma_f32_16x16x32_bf16 v[100:103], v[176:179], v[200:203], v[100:103]
	v_mfma_f32_16x16x32_bf16 v[96:99], v[184:187], v[200:203], v[96:99]
	v_mfma_f32_16x16x32_bf16 v[84:87], v[176:179], v[208:211], v[84:87]
	v_mfma_f32_16x16x32_bf16 v[80:83], v[184:187], v[208:211], v[80:83]
	v_mfma_f32_16x16x32_bf16 v[68:71], v[176:179], v[216:219], v[68:71]
	v_mfma_f32_16x16x32_bf16 v[64:67], v[184:187], v[216:219], v[64:67]
	s_setprio 0
	s_barrier
	s_add_i32 s34, s64, s51
	v_lshl_add_u64 v[220:221], s[42:43], 0, v[134:135]
	s_mov_b32 m0, s34
	ds_read_b128 v[188:191], v157 offset:16384
	ds_read_b128 v[192:195], v157 offset:17408
	ds_read_b128 v[196:199], v157 offset:18432
	ds_read_b128 v[200:203], v157 offset:19456
	ds_read_b128 v[204:207], v157 offset:20480
	ds_read_b128 v[208:211], v157 offset:21504
	ds_read_b128 v[212:215], v157 offset:22528
	ds_read_b128 v[216:219], v157 offset:23552
	global_load_lds_dwordx4 v[220:221], off
	s_add_i32 m0, s34, 0x2000
	s_add_u32 s34, s42, 0xb0000
	v_lshl_add_u64 v[222:223], s[42:43], 0, v[138:139]
	s_addc_u32 s35, s43, 0
	s_add_i32 s82, s65, s51
	global_load_lds_dwordx4 v[222:223], off
	v_lshl_add_u64 v[224:225], s[34:35], 0, v[134:135]
	s_mov_b32 m0, s82
	v_lshl_add_u64 v[226:227], s[48:49], 0, v[136:137]
	global_load_lds_dwordx4 v[224:225], off
	v_lshl_add_u64 v[224:225], s[34:35], 0, v[138:139]
	s_add_i32 m0, s82, 0x2000
	s_nop 0
	global_load_lds_dwordx4 v[224:225], off
	v_lshl_add_u64 v[224:225], s[48:49], 0, v[132:133]
	s_mov_b32 m0, s52
	s_nop 0
	global_load_lds_dwordx4 v[224:225], off
	s_mov_b32 m0, s53
	s_nop 0
	global_load_lds_dwordx4 v[226:227], off
	s_waitcnt vmcnt(8)
	s_waitcnt lgkmcnt(0)
	s_barrier
	s_setprio 1
	s_waitcnt lgkmcnt(0)
	v_mfma_f32_16x16x32_bf16 v[60:63], v[148:151], v[188:191], v[60:63]
	v_mfma_f32_16x16x32_bf16 v[56:59], v[164:167], v[188:191], v[56:59]
	v_mfma_f32_16x16x32_bf16 v[44:47], v[148:151], v[196:199], v[44:47]
	v_mfma_f32_16x16x32_bf16 v[40:43], v[164:167], v[196:199], v[40:43]
	v_mfma_f32_16x16x32_bf16 v[28:31], v[148:151], v[204:207], v[28:31]
	v_mfma_f32_16x16x32_bf16 v[24:27], v[164:167], v[204:207], v[24:27]
	v_mfma_f32_16x16x32_bf16 v[12:15], v[148:151], v[212:215], v[12:15]
	v_mfma_f32_16x16x32_bf16 v[8:11], v[164:167], v[212:215], v[8:11]
	v_mfma_f32_16x16x32_bf16 v[60:63], v[160:163], v[192:195], v[60:63]
	v_mfma_f32_16x16x32_bf16 v[56:59], v[168:171], v[192:195], v[56:59]
	v_mfma_f32_16x16x32_bf16 v[44:47], v[160:163], v[200:203], v[44:47]
	v_mfma_f32_16x16x32_bf16 v[40:43], v[168:171], v[200:203], v[40:43]
	v_mfma_f32_16x16x32_bf16 v[28:31], v[160:163], v[208:211], v[28:31]
	v_mfma_f32_16x16x32_bf16 v[24:27], v[168:171], v[208:211], v[24:27]
	v_mfma_f32_16x16x32_bf16 v[12:15], v[160:163], v[216:219], v[12:15]
	v_mfma_f32_16x16x32_bf16 v[8:11], v[168:171], v[216:219], v[8:11]
	s_setprio 0
	s_setprio 1
	v_mfma_f32_16x16x32_bf16 v[52:55], v[172:175], v[188:191], v[52:55]
	v_mfma_f32_16x16x32_bf16 v[48:51], v[180:183], v[188:191], v[48:51]
	v_mfma_f32_16x16x32_bf16 v[36:39], v[172:175], v[196:199], v[36:39]
	v_mfma_f32_16x16x32_bf16 v[32:35], v[180:183], v[196:199], v[32:35]
	v_mfma_f32_16x16x32_bf16 v[20:23], v[172:175], v[204:207], v[20:23]
	v_mfma_f32_16x16x32_bf16 v[16:19], v[180:183], v[204:207], v[16:19]
	v_mfma_f32_16x16x32_bf16 v[4:7], v[172:175], v[212:215], v[4:7]
	v_mfma_f32_16x16x32_bf16 v[0:3], v[180:183], v[212:215], v[0:3]
	v_mfma_f32_16x16x32_bf16 v[52:55], v[176:179], v[192:195], v[52:55]
	v_mfma_f32_16x16x32_bf16 v[48:51], v[184:187], v[192:195], v[48:51]
	v_mfma_f32_16x16x32_bf16 v[36:39], v[176:179], v[200:203], v[36:39]
	v_mfma_f32_16x16x32_bf16 v[32:35], v[184:187], v[200:203], v[32:35]
	v_mfma_f32_16x16x32_bf16 v[20:23], v[176:179], v[208:211], v[20:23]
	v_mfma_f32_16x16x32_bf16 v[16:19], v[184:187], v[208:211], v[16:19]
	v_mfma_f32_16x16x32_bf16 v[4:7], v[176:179], v[216:219], v[4:7]
	v_mfma_f32_16x16x32_bf16 v[0:3], v[184:187], v[216:219], v[0:3]
	s_setprio 0
	s_barrier
	s_add_i32 s82, 0, 0x18000
	v_add_u32_e32 v159, s82, v152
	s_add_i32 s83, 0, 0x1c000
	ds_read_b128 v[148:151], v159
	ds_read_b128 v[160:163], v159 offset:1024
	ds_read_b128 v[164:167], v159 offset:2048
	ds_read_b128 v[168:171], v159 offset:3072
	v_add_u32_e32 v159, s83, v152
	ds_read_b128 v[172:175], v159
	ds_read_b128 v[176:179], v159 offset:1024
	ds_read_b128 v[180:183], v159 offset:2048
	ds_read_b128 v[184:187], v159 offset:3072
	s_add_u32 s34, s48, 0xb0000
	s_addc_u32 s35, s49, 0
	s_mov_b32 m0, s54
	v_lshl_add_u64 v[228:229], s[34:35], 0, v[132:133]
	ds_read_b128 v[188:191], v157 offset:32768
	ds_read_b128 v[192:195], v157 offset:33792
	ds_read_b128 v[196:199], v157 offset:34816
	ds_read_b128 v[200:203], v157 offset:35840
	ds_read_b128 v[204:207], v157 offset:36864
	ds_read_b128 v[208:211], v157 offset:37888
	ds_read_b128 v[212:215], v157 offset:38912
	ds_read_b128 v[216:219], v157 offset:39936
	global_load_lds_dwordx4 v[228:229], off
	v_lshl_add_u64 v[228:229], s[34:35], 0, v[136:137]
	s_mov_b32 m0, s55
	s_nop 0
	global_load_lds_dwordx4 v[228:229], off
	s_waitcnt vmcnt(8)
	s_waitcnt lgkmcnt(0)
	s_barrier
	s_setprio 1
	s_waitcnt lgkmcnt(0)
	v_mfma_f32_16x16x32_bf16 v[124:127], v[148:151], v[188:191], v[124:127]
	v_mfma_f32_16x16x32_bf16 v[120:123], v[164:167], v[188:191], v[120:123]
	v_mfma_f32_16x16x32_bf16 v[108:111], v[148:151], v[196:199], v[108:111]
	v_mfma_f32_16x16x32_bf16 v[104:107], v[164:167], v[196:199], v[104:107]
	v_mfma_f32_16x16x32_bf16 v[92:95], v[148:151], v[204:207], v[92:95]
	v_mfma_f32_16x16x32_bf16 v[88:91], v[164:167], v[204:207], v[88:91]
	v_mfma_f32_16x16x32_bf16 v[76:79], v[148:151], v[212:215], v[76:79]
	v_mfma_f32_16x16x32_bf16 v[72:75], v[164:167], v[212:215], v[72:75]
	v_mfma_f32_16x16x32_bf16 v[124:127], v[160:163], v[192:195], v[124:127]
	v_mfma_f32_16x16x32_bf16 v[120:123], v[168:171], v[192:195], v[120:123]
	v_mfma_f32_16x16x32_bf16 v[108:111], v[160:163], v[200:203], v[108:111]
	v_mfma_f32_16x16x32_bf16 v[104:107], v[168:171], v[200:203], v[104:107]
	v_mfma_f32_16x16x32_bf16 v[92:95], v[160:163], v[208:211], v[92:95]
	v_mfma_f32_16x16x32_bf16 v[88:91], v[168:171], v[208:211], v[88:91]
	v_mfma_f32_16x16x32_bf16 v[76:79], v[160:163], v[216:219], v[76:79]
	v_mfma_f32_16x16x32_bf16 v[72:75], v[168:171], v[216:219], v[72:75]
	s_setprio 0
	s_setprio 1
	v_mfma_f32_16x16x32_bf16 v[116:119], v[172:175], v[188:191], v[116:119]
	v_mfma_f32_16x16x32_bf16 v[112:115], v[180:183], v[188:191], v[112:115]
	v_mfma_f32_16x16x32_bf16 v[100:103], v[172:175], v[196:199], v[100:103]
	v_mfma_f32_16x16x32_bf16 v[96:99], v[180:183], v[196:199], v[96:99]
	v_mfma_f32_16x16x32_bf16 v[84:87], v[172:175], v[204:207], v[84:87]
	v_mfma_f32_16x16x32_bf16 v[80:83], v[180:183], v[204:207], v[80:83]
	v_mfma_f32_16x16x32_bf16 v[68:71], v[172:175], v[212:215], v[68:71]
	v_mfma_f32_16x16x32_bf16 v[64:67], v[180:183], v[212:215], v[64:67]
	v_mfma_f32_16x16x32_bf16 v[116:119], v[176:179], v[192:195], v[116:119]
	v_mfma_f32_16x16x32_bf16 v[112:115], v[184:187], v[192:195], v[112:115]
	v_mfma_f32_16x16x32_bf16 v[100:103], v[176:179], v[200:203], v[100:103]
	v_mfma_f32_16x16x32_bf16 v[96:99], v[184:187], v[200:203], v[96:99]
	v_mfma_f32_16x16x32_bf16 v[84:87], v[176:179], v[208:211], v[84:87]
	v_mfma_f32_16x16x32_bf16 v[80:83], v[184:187], v[208:211], v[80:83]
	v_mfma_f32_16x16x32_bf16 v[68:71], v[176:179], v[216:219], v[68:71]
	v_mfma_f32_16x16x32_bf16 v[64:67], v[184:187], v[216:219], v[64:67]
	s_setprio 0
	s_barrier
	s_add_i32 s34, s82, s51
	v_lshl_add_u64 v[220:221], v[220:221], 0, s[22:23]
	s_mov_b32 m0, s34
	ds_read_b128 v[188:191], v157 offset:49152
	ds_read_b128 v[192:195], v157 offset:50176
	ds_read_b128 v[196:199], v157 offset:51200
	ds_read_b128 v[200:203], v157 offset:52224
	ds_read_b128 v[204:207], v157 offset:53248
	ds_read_b128 v[208:211], v157 offset:54272
	ds_read_b128 v[212:215], v157 offset:55296
	ds_read_b128 v[216:219], v157 offset:56320
	global_load_lds_dwordx4 v[220:221], off
	s_add_i32 m0, s34, 0x2000
	s_add_u32 s34, s42, 0xb0080
	v_lshl_add_u64 v[220:221], v[222:223], 0, s[22:23]
	s_addc_u32 s35, s43, 0
	s_add_i32 s42, s83, s51
	global_load_lds_dwordx4 v[220:221], off
	v_lshl_add_u64 v[220:221], s[34:35], 0, v[134:135]
	s_mov_b32 m0, s42
	s_nop 0
	global_load_lds_dwordx4 v[220:221], off
	v_lshl_add_u64 v[220:221], s[34:35], 0, v[138:139]
	s_add_i32 m0, s42, 0x2000
	s_nop 0
	global_load_lds_dwordx4 v[220:221], off
	v_lshl_add_u64 v[220:221], v[224:225], 0, s[22:23]
	s_mov_b32 m0, s57
	s_nop 0
	global_load_lds_dwordx4 v[220:221], off
	v_lshl_add_u64 v[220:221], v[226:227], 0, s[22:23]
	s_mov_b32 m0, s58
	s_nop 0
	global_load_lds_dwordx4 v[220:221], off
	s_waitcnt vmcnt(8)
	s_waitcnt lgkmcnt(0)
	s_barrier
	s_setprio 1
	s_waitcnt lgkmcnt(0)
	v_mfma_f32_16x16x32_bf16 v[60:63], v[148:151], v[188:191], v[60:63]
	v_mfma_f32_16x16x32_bf16 v[56:59], v[164:167], v[188:191], v[56:59]
	v_mfma_f32_16x16x32_bf16 v[44:47], v[148:151], v[196:199], v[44:47]
	v_mfma_f32_16x16x32_bf16 v[40:43], v[164:167], v[196:199], v[40:43]
	v_mfma_f32_16x16x32_bf16 v[28:31], v[148:151], v[204:207], v[28:31]
	v_mfma_f32_16x16x32_bf16 v[24:27], v[164:167], v[204:207], v[24:27]
	v_mfma_f32_16x16x32_bf16 v[12:15], v[148:151], v[212:215], v[12:15]
	v_mfma_f32_16x16x32_bf16 v[8:11], v[164:167], v[212:215], v[8:11]
	v_mfma_f32_16x16x32_bf16 v[60:63], v[160:163], v[192:195], v[60:63]
	v_mfma_f32_16x16x32_bf16 v[56:59], v[168:171], v[192:195], v[56:59]
	v_mfma_f32_16x16x32_bf16 v[44:47], v[160:163], v[200:203], v[44:47]
	v_mfma_f32_16x16x32_bf16 v[40:43], v[168:171], v[200:203], v[40:43]
	v_mfma_f32_16x16x32_bf16 v[28:31], v[160:163], v[208:211], v[28:31]
	v_mfma_f32_16x16x32_bf16 v[24:27], v[168:171], v[208:211], v[24:27]
	v_mfma_f32_16x16x32_bf16 v[12:15], v[160:163], v[216:219], v[12:15]
	v_mfma_f32_16x16x32_bf16 v[8:11], v[168:171], v[216:219], v[8:11]
	s_setprio 0
	s_setprio 1
	v_mfma_f32_16x16x32_bf16 v[52:55], v[172:175], v[188:191], v[52:55]
	v_mfma_f32_16x16x32_bf16 v[48:51], v[180:183], v[188:191], v[48:51]
	v_mfma_f32_16x16x32_bf16 v[36:39], v[172:175], v[196:199], v[36:39]
	v_mfma_f32_16x16x32_bf16 v[32:35], v[180:183], v[196:199], v[32:35]
	v_mfma_f32_16x16x32_bf16 v[20:23], v[172:175], v[204:207], v[20:23]
	v_mfma_f32_16x16x32_bf16 v[16:19], v[180:183], v[204:207], v[16:19]
	v_mfma_f32_16x16x32_bf16 v[4:7], v[172:175], v[212:215], v[4:7]
	v_mfma_f32_16x16x32_bf16 v[0:3], v[180:183], v[212:215], v[0:3]
	v_mfma_f32_16x16x32_bf16 v[52:55], v[176:179], v[192:195], v[52:55]
	v_mfma_f32_16x16x32_bf16 v[48:51], v[184:187], v[192:195], v[48:51]
	v_mfma_f32_16x16x32_bf16 v[36:39], v[176:179], v[200:203], v[36:39]
	v_mfma_f32_16x16x32_bf16 v[32:35], v[184:187], v[200:203], v[32:35]
	v_mfma_f32_16x16x32_bf16 v[20:23], v[176:179], v[208:211], v[20:23]
	v_mfma_f32_16x16x32_bf16 v[16:19], v[184:187], v[208:211], v[16:19]
	v_mfma_f32_16x16x32_bf16 v[4:7], v[176:179], v[216:219], v[4:7]
	v_mfma_f32_16x16x32_bf16 v[0:3], v[184:187], v[216:219], v[0:3]
	s_setprio 0
	s_cmp_eq_u32 s81, s98
	s_cbranch_scc1 .Lmy_nobar_6
	s_barrier
.Lmy_nobar_6:
	s_add_i32 s81, s81, 2
	s_add_u32 s40, s40, 0x100
	s_addc_u32 s41, s41, 0
	s_add_u32 s13, s13, 0x100
	s_addc_u32 s77, s77, 0
	s_cmp_gt_u32 s81, 41
	s_cbranch_scc0 .LBB0_562
	s_and_b64 vcc, exec, s[26:27]
	s_cbranch_vccz .LBB0_565
	s_nop 0

.LBB0_581:
	s_or_b64 exec, exec, s[42:43]
	s_and_b64 vcc, exec, s[6:7]
	s_mov_b64 s[6:7], -1
	s_cbranch_vccnz .LBB0_550
	s_andn2_b64 vcc, exec, s[10:11]
	s_cbranch_vccnz .LBB0_549
	s_nop 0
	s_branch .LBB0_549

.LBB0_652:
	s_lshr_b32 s99, s91, 2
	s_cmp_eq_u32 s99, 1
	s_cselect_b32 s98, 12, 0x7fffffff
	s_add_i32 s93, s93, 1
	s_mul_i32 s6, s93, s58
	s_mul_hi_u32 s7, s93, s59
	s_add_i32 s7, s7, s6
	s_mul_i32 s6, s93, s59
	s_add_u32 s48, s6, s2
	s_addc_u32 s49, s7, s3
	v_cmp_gt_i64_e32 vcc, s[48:49], v[146:147]
	v_cmp_lt_i64_e64 s[6:7], s[48:49], v[144:145]
	s_cbranch_vccnz .LBB0_654
	s_ashr_i32 s9, s48, 31
	s_lshr_b32 s9, s9, 29
	s_add_i32 s9, s48, s9
	s_ashr_i32 s10, s9, 3
	s_and_b32 s9, s9, -8
	s_sub_i32 s9, s48, s9
	s_cmp_lt_i32 s9, 0
	s_cselect_b32 s12, s87, 0xc0
	s_mul_i32 s9, s9, s12
	s_add_i32 s9, s9, s10
	s_mul_hi_i32 s10, s9, 0x2aaaaaab
	s_lshr_b32 s12, s10, 31
	s_ashr_i32 s10, s10, 4
	s_add_i32 s10, s10, s12
	s_lshl_b32 s12, s10, 3
	s_sub_i32 s13, 0x80, s12
	s_min_i32 s13, s13, 8
	s_abs_i32 s34, s13
	v_cvt_f32_u32_e32 v0, s34
	s_sub_i32 s40, 0, s34
	s_mulk_i32 s10, 0x60
	s_sub_i32 s9, s9, s10
	v_rcp_iflag_f32_e32 v0, v0
	s_abs_i32 s10, s9
	s_xor_b32 s35, s9, s13
	s_ashr_i32 s35, s35, 31
	v_mul_f32_e32 v0, 0x4f7ffffe, v0
	v_cvt_u32_f32_e32 v0, v0
	s_mov_b32 s94, s93
	v_readfirstlane_b32 s41, v0
	s_mul_i32 s40, s40, s41
	s_mul_hi_u32 s40, s41, s40
	s_add_i32 s41, s41, s40
	s_mul_hi_u32 s40, s10, s41
	s_mul_i32 s41, s40, s34
	s_sub_i32 s10, s10, s41
	s_add_i32 s42, s40, 1
	s_sub_i32 s41, s10, s34
	s_cmp_ge_u32 s10, s34
	s_cselect_b32 s40, s42, s40
	s_cselect_b32 s10, s41, s10
	s_add_i32 s41, s40, 1
	s_cmp_ge_u32 s10, s34
	s_cselect_b32 s10, s41, s40
	s_xor_b32 s10, s10, s35
	s_sub_i32 s40, s10, s35
	s_mul_i32 s10, s40, s13
	s_sub_i32 s9, s9, s10
	s_add_i32 s42, s12, s9
.LBB0_654:
	s_ashr_i32 s43, s42, 31
	s_lshl_b64 s[12:13], s[42:43], 19
	s_add_u32 s48, s14, s12
	s_addc_u32 s49, s15, s13
	s_and_b64 s[12:13], s[6:7], exec
	s_cselect_b32 s9, s49, s53
	s_cselect_b32 s10, s48, s52
	s_ashr_i32 s41, s40, 31
	s_lshl_b64 s[12:13], s[40:41], 19
	s_add_u32 s50, s63, s12
	s_addc_u32 s51, s64, s13
	s_and_b64 s[12:13], s[6:7], exec
	s_cselect_b32 s12, s51, s55
	s_cselect_b32 s13, s50, s54
	s_add_u32 s52, s52, 0x40080
	s_addc_u32 s53, s53, 0
	s_add_u32 s41, s54, 0x100
	v_mov_b32_e32 v0, 0
	s_addc_u32 s43, s55, 0
	s_mov_b32 s77, -2
	s_waitcnt lgkmcnt(0)
	v_mov_b32_e32 v1, v0
	v_mov_b32_e32 v2, v0
	v_mov_b32_e32 v3, v0
	v_mov_b32_e32 v4, v0
	v_mov_b32_e32 v5, v0
	v_mov_b32_e32 v6, v0
	v_mov_b32_e32 v7, v0
	v_mov_b32_e32 v16, v0
	v_mov_b32_e32 v17, v0
	v_mov_b32_e32 v18, v0
	v_mov_b32_e32 v19, v0
	v_mov_b32_e32 v20, v0
	v_mov_b32_e32 v21, v0
	v_mov_b32_e32 v22, v0
	v_mov_b32_e32 v23, v0
	v_mov_b32_e32 v32, v0
	v_mov_b32_e32 v33, v0
	v_mov_b32_e32 v34, v0
	v_mov_b32_e32 v35, v0
	v_mov_b32_e32 v36, v0
	v_mov_b32_e32 v37, v0
	v_mov_b32_e32 v38, v0
	v_mov_b32_e32 v39, v0
	v_mov_b32_e32 v48, v0
	v_mov_b32_e32 v49, v0
	v_mov_b32_e32 v50, v0
	v_mov_b32_e32 v51, v0
	v_mov_b32_e32 v52, v0
	v_mov_b32_e32 v53, v0
	v_mov_b32_e32 v54, v0
	v_mov_b32_e32 v55, v0
	v_mov_b32_e32 v8, v0
	v_mov_b32_e32 v9, v0
	v_mov_b32_e32 v10, v0
	v_mov_b32_e32 v11, v0
	v_mov_b32_e32 v12, v0
	v_mov_b32_e32 v13, v0
	v_mov_b32_e32 v14, v0
	v_mov_b32_e32 v15, v0
	v_mov_b32_e32 v24, v0
	v_mov_b32_e32 v25, v0
	v_mov_b32_e32 v26, v0
	v_mov_b32_e32 v27, v0
	v_mov_b32_e32 v28, v0
	v_mov_b32_e32 v29, v0
	v_mov_b32_e32 v30, v0
	v_mov_b32_e32 v31, v0
	v_mov_b32_e32 v40, v0
	v_mov_b32_e32 v41, v0
	v_mov_b32_e32 v42, v0
	v_mov_b32_e32 v43, v0
	v_mov_b32_e32 v44, v0
	v_mov_b32_e32 v45, v0
	v_mov_b32_e32 v46, v0
	v_mov_b32_e32 v47, v0
	v_mov_b32_e32 v56, v0
	v_mov_b32_e32 v57, v0
	v_mov_b32_e32 v58, v0
	v_mov_b32_e32 v59, v0
	v_mov_b32_e32 v60, v0
	v_mov_b32_e32 v61, v0
	v_mov_b32_e32 v62, v0
	v_mov_b32_e32 v63, v0
	v_mov_b32_e32 v64, v0
	v_mov_b32_e32 v65, v0
	v_mov_b32_e32 v66, v0
	v_mov_b32_e32 v67, v0
	v_mov_b32_e32 v68, v0
	v_mov_b32_e32 v69, v0
	v_mov_b32_e32 v70, v0
	v_mov_b32_e32 v71, v0
	v_mov_b32_e32 v80, v0
	v_mov_b32_e32 v81, v0
	v_mov_b32_e32 v82, v0
	v_mov_b32_e32 v83, v0
	v_mov_b32_e32 v84, v0
	v_mov_b32_e32 v85, v0
	v_mov_b32_e32 v86, v0
	v_mov_b32_e32 v87, v0
	v_mov_b32_e32 v96, v0
	v_mov_b32_e32 v97, v0
	v_mov_b32_e32 v98, v0
	v_mov_b32_e32 v99, v0
	v_mov_b32_e32 v100, v0
	v_mov_b32_e32 v101, v0
	v_mov_b32_e32 v102, v0
	v_mov_b32_e32 v103, v0
	v_mov_b32_e32 v112, v0
	v_mov_b32_e32 v113, v0
	v_mov_b32_e32 v114, v0
	v_mov_b32_e32 v115, v0
	v_mov_b32_e32 v116, v0
	v_mov_b32_e32 v117, v0
	v_mov_b32_e32 v118, v0
	v_mov_b32_e32 v119, v0
	v_mov_b32_e32 v72, v0
	v_mov_b32_e32 v73, v0
	v_mov_b32_e32 v74, v0
	v_mov_b32_e32 v75, v0
	v_mov_b32_e32 v76, v0
	v_mov_b32_e32 v77, v0
	v_mov_b32_e32 v78, v0
	v_mov_b32_e32 v79, v0
	v_mov_b32_e32 v88, v0
	v_mov_b32_e32 v89, v0
	v_mov_b32_e32 v90, v0
	v_mov_b32_e32 v91, v0
	v_mov_b32_e32 v92, v0
	v_mov_b32_e32 v93, v0
	v_mov_b32_e32 v94, v0
	v_mov_b32_e32 v95, v0
	v_mov_b32_e32 v104, v0
	v_mov_b32_e32 v105, v0
	v_mov_b32_e32 v106, v0
	v_mov_b32_e32 v107, v0
	v_mov_b32_e32 v108, v0
	v_mov_b32_e32 v109, v0
	v_mov_b32_e32 v110, v0
	v_mov_b32_e32 v111, v0
	v_mov_b32_e32 v120, v0
	v_mov_b32_e32 v121, v0
	v_mov_b32_e32 v122, v0
	v_mov_b32_e32 v123, v0
	v_mov_b32_e32 v124, v0
	v_mov_b32_e32 v125, v0
	v_mov_b32_e32 v126, v0
	v_mov_b32_e32 v127, v0
	s_cmp_lg_u32 s93, 1
	s_cselect_b32 s100, s99, 0
	s_cmp_lg_u32 s100, 0
	s_cbranch_scc0 .Lmy_nobar2_7
	s_barrier
.Lmy_nobar2_7:
.LBB0_655:
	ds_read_b128 v[148:151], v160
	ds_read_b128 v[152:155], v160 offset:1024
	ds_read_b128 v[164:167], v160 offset:2048
	ds_read_b128 v[168:171], v160 offset:3072
	ds_read_b128 v[172:175], v161
	ds_read_b128 v[176:179], v161 offset:1024
	ds_read_b128 v[180:183], v161 offset:2048
	ds_read_b128 v[184:187], v161 offset:3072
	s_add_u32 s34, s52, 0xfffc0080
	s_addc_u32 s35, s53, -1
	s_cmp_eq_u32 s77, 12
	s_cselect_b32 s57, s9, s35
	s_cselect_b32 s56, s10, s34
	s_cselect_b32 s55, s12, s43
	s_cselect_b32 s54, s13, s41
	v_lshl_add_u64 v[220:221], s[52:53], 0, v[140:141]
	s_add_i32 m0, s65, 0xc000
	ds_read_b128 v[188:191], v162
	ds_read_b128 v[192:195], v162 offset:1024
	ds_read_b128 v[196:199], v162 offset:2048
	ds_read_b128 v[200:203], v162 offset:3072
	ds_read_b128 v[204:207], v162 offset:4096
	ds_read_b128 v[208:211], v162 offset:5120
	ds_read_b128 v[212:215], v162 offset:6144
	ds_read_b128 v[216:219], v162 offset:7168
	global_load_lds_dwordx4 v[220:221], off
	v_lshl_add_u64 v[220:221], s[52:53], 0, v[142:143]
	s_add_i32 m0, s65, 0xe000
	s_nop 0
	global_load_lds_dwordx4 v[220:221], off
	s_waitcnt vmcnt(8)
	s_waitcnt lgkmcnt(0)
	s_barrier
	s_setprio 1
	s_waitcnt lgkmcnt(0)
	v_mfma_f32_16x16x32_bf16 v[124:127], v[148:151], v[188:191], v[124:127]
	v_mfma_f32_16x16x32_bf16 v[120:123], v[164:167], v[188:191], v[120:123]
	v_mfma_f32_16x16x32_bf16 v[108:111], v[148:151], v[196:199], v[108:111]
	v_mfma_f32_16x16x32_bf16 v[104:107], v[164:167], v[196:199], v[104:107]
	v_mfma_f32_16x16x32_bf16 v[92:95], v[148:151], v[204:207], v[92:95]
	v_mfma_f32_16x16x32_bf16 v[88:91], v[164:167], v[204:207], v[88:91]
	v_mfma_f32_16x16x32_bf16 v[76:79], v[148:151], v[212:215], v[76:79]
	v_mfma_f32_16x16x32_bf16 v[72:75], v[164:167], v[212:215], v[72:75]
	v_mfma_f32_16x16x32_bf16 v[124:127], v[152:155], v[192:195], v[124:127]
	v_mfma_f32_16x16x32_bf16 v[120:123], v[168:171], v[192:195], v[120:123]
	v_mfma_f32_16x16x32_bf16 v[108:111], v[152:155], v[200:203], v[108:111]
	v_mfma_f32_16x16x32_bf16 v[104:107], v[168:171], v[200:203], v[104:107]
	v_mfma_f32_16x16x32_bf16 v[92:95], v[152:155], v[208:211], v[92:95]
	v_mfma_f32_16x16x32_bf16 v[88:91], v[168:171], v[208:211], v[88:91]
	v_mfma_f32_16x16x32_bf16 v[76:79], v[152:155], v[216:219], v[76:79]
	v_mfma_f32_16x16x32_bf16 v[72:75], v[168:171], v[216:219], v[72:75]
	s_setprio 0
	s_setprio 1
	v_mfma_f32_16x16x32_bf16 v[116:119], v[172:175], v[188:191], v[116:119]
	v_mfma_f32_16x16x32_bf16 v[112:115], v[180:183], v[188:191], v[112:115]
	v_mfma_f32_16x16x32_bf16 v[100:103], v[172:175], v[196:199], v[100:103]
	v_mfma_f32_16x16x32_bf16 v[96:99], v[180:183], v[196:199], v[96:99]
	v_mfma_f32_16x16x32_bf16 v[84:87], v[172:175], v[204:207], v[84:87]
	v_mfma_f32_16x16x32_bf16 v[80:83], v[180:183], v[204:207], v[80:83]
	v_mfma_f32_16x16x32_bf16 v[68:71], v[172:175], v[212:215], v[68:71]
	v_mfma_f32_16x16x32_bf16 v[64:67], v[180:183], v[212:215], v[64:67]
	v_mfma_f32_16x16x32_bf16 v[116:119], v[176:179], v[192:195], v[116:119]
	v_mfma_f32_16x16x32_bf16 v[112:115], v[184:187], v[192:195], v[112:115]
	v_mfma_f32_16x16x32_bf16 v[100:103], v[176:179], v[200:203], v[100:103]
	v_mfma_f32_16x16x32_bf16 v[96:99], v[184:187], v[200:203], v[96:99]
	v_mfma_f32_16x16x32_bf16 v[84:87], v[176:179], v[208:211], v[84:87]
	v_mfma_f32_16x16x32_bf16 v[80:83], v[184:187], v[208:211], v[80:83]
	v_mfma_f32_16x16x32_bf16 v[68:71], v[176:179], v[216:219], v[68:71]
	v_mfma_f32_16x16x32_bf16 v[64:67], v[184:187], v[216:219], v[64:67]
	s_setprio 0
	s_barrier
	s_add_i32 s34, s88, s62
	v_lshl_add_u64 v[220:221], s[54:55], 0, v[134:135]
	s_mov_b32 m0, s34
	ds_read_b128 v[188:191], v162 offset:16384
	ds_read_b128 v[192:195], v162 offset:17408
	ds_read_b128 v[196:199], v162 offset:18432
	ds_read_b128 v[200:203], v162 offset:19456
	ds_read_b128 v[204:207], v162 offset:20480
	ds_read_b128 v[208:211], v162 offset:21504
	ds_read_b128 v[212:215], v162 offset:22528
	ds_read_b128 v[216:219], v162 offset:23552
	global_load_lds_dwordx4 v[220:221], off
	s_add_i32 m0, s34, 0x2000
	s_add_u32 s34, s54, 0x40000
	v_lshl_add_u64 v[222:223], s[54:55], 0, v[138:139]
	s_addc_u32 s35, s55, 0
	s_add_i32 s90, s89, s62
	global_load_lds_dwordx4 v[222:223], off
	v_lshl_add_u64 v[224:225], s[34:35], 0, v[134:135]
	s_mov_b32 m0, s90
	v_lshl_add_u64 v[226:227], s[56:57], 0, v[136:137]
	global_load_lds_dwordx4 v[224:225], off
	v_lshl_add_u64 v[224:225], s[34:35], 0, v[138:139]
	s_add_i32 m0, s90, 0x2000
	s_nop 0
	global_load_lds_dwordx4 v[224:225], off
	v_lshl_add_u64 v[224:225], s[56:57], 0, v[132:133]
	s_mov_b32 m0, s65
	s_nop 0
	global_load_lds_dwordx4 v[224:225], off
	s_mov_b32 m0, s66
	s_nop 0
	global_load_lds_dwordx4 v[226:227], off
	s_waitcnt vmcnt(8)
	s_waitcnt lgkmcnt(0)
	s_barrier
	s_setprio 1
	s_waitcnt lgkmcnt(0)
	v_mfma_f32_16x16x32_bf16 v[60:63], v[148:151], v[188:191], v[60:63]
	v_mfma_f32_16x16x32_bf16 v[56:59], v[164:167], v[188:191], v[56:59]
	v_mfma_f32_16x16x32_bf16 v[44:47], v[148:151], v[196:199], v[44:47]
	v_mfma_f32_16x16x32_bf16 v[40:43], v[164:167], v[196:199], v[40:43]
	v_mfma_f32_16x16x32_bf16 v[28:31], v[148:151], v[204:207], v[28:31]
	v_mfma_f32_16x16x32_bf16 v[24:27], v[164:167], v[204:207], v[24:27]
	v_mfma_f32_16x16x32_bf16 v[12:15], v[148:151], v[212:215], v[12:15]
	v_mfma_f32_16x16x32_bf16 v[8:11], v[164:167], v[212:215], v[8:11]
	v_mfma_f32_16x16x32_bf16 v[60:63], v[152:155], v[192:195], v[60:63]
	v_mfma_f32_16x16x32_bf16 v[56:59], v[168:171], v[192:195], v[56:59]
	v_mfma_f32_16x16x32_bf16 v[44:47], v[152:155], v[200:203], v[44:47]
	v_mfma_f32_16x16x32_bf16 v[40:43], v[168:171], v[200:203], v[40:43]
	v_mfma_f32_16x16x32_bf16 v[28:31], v[152:155], v[208:211], v[28:31]
	v_mfma_f32_16x16x32_bf16 v[24:27], v[168:171], v[208:211], v[24:27]
	v_mfma_f32_16x16x32_bf16 v[12:15], v[152:155], v[216:219], v[12:15]
	v_mfma_f32_16x16x32_bf16 v[8:11], v[168:171], v[216:219], v[8:11]
	s_setprio 0
	s_setprio 1
	v_mfma_f32_16x16x32_bf16 v[52:55], v[172:175], v[188:191], v[52:55]
	v_mfma_f32_16x16x32_bf16 v[48:51], v[180:183], v[188:191], v[48:51]
	v_mfma_f32_16x16x32_bf16 v[36:39], v[172:175], v[196:199], v[36:39]
	v_mfma_f32_16x16x32_bf16 v[32:35], v[180:183], v[196:199], v[32:35]
	v_mfma_f32_16x16x32_bf16 v[20:23], v[172:175], v[204:207], v[20:23]
	v_mfma_f32_16x16x32_bf16 v[16:19], v[180:183], v[204:207], v[16:19]
	v_mfma_f32_16x16x32_bf16 v[4:7], v[172:175], v[212:215], v[4:7]
	v_mfma_f32_16x16x32_bf16 v[0:3], v[180:183], v[212:215], v[0:3]
	v_mfma_f32_16x16x32_bf16 v[52:55], v[176:179], v[192:195], v[52:55]
	v_mfma_f32_16x16x32_bf16 v[48:51], v[184:187], v[192:195], v[48:51]
	v_mfma_f32_16x16x32_bf16 v[36:39], v[176:179], v[200:203], v[36:39]
	v_mfma_f32_16x16x32_bf16 v[32:35], v[184:187], v[200:203], v[32:35]
	v_mfma_f32_16x16x32_bf16 v[20:23], v[176:179], v[208:211], v[20:23]
	v_mfma_f32_16x16x32_bf16 v[16:19], v[184:187], v[208:211], v[16:19]
	v_mfma_f32_16x16x32_bf16 v[4:7], v[176:179], v[216:219], v[4:7]
	v_mfma_f32_16x16x32_bf16 v[0:3], v[184:187], v[216:219], v[0:3]
	s_setprio 0
	s_barrier
	s_add_i32 s90, 0, 0x18000
	s_add_i32 s95, 0, 0x1c000
	v_add_u32_e32 v168, s90, v157
	v_add_u32_e32 v184, s95, v157
	ds_read_b128 v[148:151], v168
	ds_read_b128 v[152:155], v168 offset:1024
	ds_read_b128 v[164:167], v168 offset:2048
	ds_read_b128 v[168:171], v168 offset:3072
	ds_read_b128 v[172:175], v184
	ds_read_b128 v[176:179], v184 offset:1024
	ds_read_b128 v[180:183], v184 offset:2048
	ds_read_b128 v[184:187], v184 offset:3072
	s_add_u32 s34, s56, 0x40000
	s_addc_u32 s35, s57, 0
	s_mov_b32 m0, s67
	v_lshl_add_u64 v[228:229], s[34:35], 0, v[132:133]
	ds_read_b128 v[188:191], v162 offset:32768
	ds_read_b128 v[192:195], v162 offset:33792
	ds_read_b128 v[196:199], v162 offset:34816
	ds_read_b128 v[200:203], v162 offset:35840
	ds_read_b128 v[204:207], v162 offset:36864
	ds_read_b128 v[208:211], v162 offset:37888
	ds_read_b128 v[212:215], v162 offset:38912
	ds_read_b128 v[216:219], v162 offset:39936
	global_load_lds_dwordx4 v[228:229], off
	v_lshl_add_u64 v[228:229], s[34:35], 0, v[136:137]
	s_mov_b32 m0, s79
	s_nop 0
	global_load_lds_dwordx4 v[228:229], off
	s_waitcnt vmcnt(8)
	s_waitcnt lgkmcnt(0)
	s_barrier
	s_setprio 1
	s_waitcnt lgkmcnt(0)
	v_mfma_f32_16x16x32_bf16 v[124:127], v[148:151], v[188:191], v[124:127]
	v_mfma_f32_16x16x32_bf16 v[120:123], v[164:167], v[188:191], v[120:123]
	v_mfma_f32_16x16x32_bf16 v[108:111], v[148:151], v[196:199], v[108:111]
	v_mfma_f32_16x16x32_bf16 v[104:107], v[164:167], v[196:199], v[104:107]
	v_mfma_f32_16x16x32_bf16 v[92:95], v[148:151], v[204:207], v[92:95]
	v_mfma_f32_16x16x32_bf16 v[88:91], v[164:167], v[204:207], v[88:91]
	v_mfma_f32_16x16x32_bf16 v[76:79], v[148:151], v[212:215], v[76:79]
	v_mfma_f32_16x16x32_bf16 v[72:75], v[164:167], v[212:215], v[72:75]
	v_mfma_f32_16x16x32_bf16 v[124:127], v[152:155], v[192:195], v[124:127]
	v_mfma_f32_16x16x32_bf16 v[120:123], v[168:171], v[192:195], v[120:123]
	v_mfma_f32_16x16x32_bf16 v[108:111], v[152:155], v[200:203], v[108:111]
	v_mfma_f32_16x16x32_bf16 v[104:107], v[168:171], v[200:203], v[104:107]
	v_mfma_f32_16x16x32_bf16 v[92:95], v[152:155], v[208:211], v[92:95]
	v_mfma_f32_16x16x32_bf16 v[88:91], v[168:171], v[208:211], v[88:91]
	v_mfma_f32_16x16x32_bf16 v[76:79], v[152:155], v[216:219], v[76:79]
	v_mfma_f32_16x16x32_bf16 v[72:75], v[168:171], v[216:219], v[72:75]
	s_setprio 0
	s_setprio 1
	v_mfma_f32_16x16x32_bf16 v[116:119], v[172:175], v[188:191], v[116:119]
	v_mfma_f32_16x16x32_bf16 v[112:115], v[180:183], v[188:191], v[112:115]
	v_mfma_f32_16x16x32_bf16 v[100:103], v[172:175], v[196:199], v[100:103]
	v_mfma_f32_16x16x32_bf16 v[96:99], v[180:183], v[196:199], v[96:99]
	v_mfma_f32_16x16x32_bf16 v[84:87], v[172:175], v[204:207], v[84:87]
	v_mfma_f32_16x16x32_bf16 v[80:83], v[180:183], v[204:207], v[80:83]
	v_mfma_f32_16x16x32_bf16 v[68:71], v[172:175], v[212:215], v[68:71]
	v_mfma_f32_16x16x32_bf16 v[64:67], v[180:183], v[212:215], v[64:67]
	v_mfma_f32_16x16x32_bf16 v[116:119], v[176:179], v[192:195], v[116:119]
	v_mfma_f32_16x16x32_bf16 v[112:115], v[184:187], v[192:195], v[112:115]
	v_mfma_f32_16x16x32_bf16 v[100:103], v[176:179], v[200:203], v[100:103]
	v_mfma_f32_16x16x32_bf16 v[96:99], v[184:187], v[200:203], v[96:99]
	v_mfma_f32_16x16x32_bf16 v[84:87], v[176:179], v[208:211], v[84:87]
	v_mfma_f32_16x16x32_bf16 v[80:83], v[184:187], v[208:211], v[80:83]
	v_mfma_f32_16x16x32_bf16 v[68:71], v[176:179], v[216:219], v[68:71]
	v_mfma_f32_16x16x32_bf16 v[64:67], v[184:187], v[216:219], v[64:67]
	s_setprio 0
	s_barrier
	s_add_i32 s34, s90, s62
	v_lshl_add_u64 v[220:221], v[220:221], 0, s[26:27]
	s_mov_b32 m0, s34
	ds_read_b128 v[188:191], v162 offset:49152
	ds_read_b128 v[192:195], v162 offset:50176
	ds_read_b128 v[196:199], v162 offset:51200
	ds_read_b128 v[200:203], v162 offset:52224
	ds_read_b128 v[204:207], v162 offset:53248
	ds_read_b128 v[208:211], v162 offset:54272
	ds_read_b128 v[212:215], v162 offset:55296
	ds_read_b128 v[216:219], v162 offset:56320
	global_load_lds_dwordx4 v[220:221], off
	s_add_i32 m0, s34, 0x2000
	s_add_u32 s34, s54, 0x40080
	v_lshl_add_u64 v[220:221], v[222:223], 0, s[26:27]
	s_addc_u32 s35, s55, 0
	s_add_i32 s54, s95, s62
	global_load_lds_dwordx4 v[220:221], off
	v_lshl_add_u64 v[220:221], s[34:35], 0, v[134:135]
	s_mov_b32 m0, s54
	s_nop 0
	global_load_lds_dwordx4 v[220:221], off
	v_lshl_add_u64 v[220:221], s[34:35], 0, v[138:139]
	s_add_i32 m0, s54, 0x2000
	s_nop 0
	global_load_lds_dwordx4 v[220:221], off
	v_lshl_add_u64 v[220:221], v[224:225], 0, s[26:27]
	s_mov_b32 m0, s83
	s_nop 0
	global_load_lds_dwordx4 v[220:221], off
	v_lshl_add_u64 v[220:221], v[226:227], 0, s[26:27]
	s_mov_b32 m0, s84
	s_nop 0
	global_load_lds_dwordx4 v[220:221], off
	s_waitcnt vmcnt(8)
	s_waitcnt lgkmcnt(0)
	s_barrier
	s_setprio 1
	s_waitcnt lgkmcnt(0)
	v_mfma_f32_16x16x32_bf16 v[60:63], v[148:151], v[188:191], v[60:63]
	v_mfma_f32_16x16x32_bf16 v[56:59], v[164:167], v[188:191], v[56:59]
	v_mfma_f32_16x16x32_bf16 v[44:47], v[148:151], v[196:199], v[44:47]
	v_mfma_f32_16x16x32_bf16 v[40:43], v[164:167], v[196:199], v[40:43]
	v_mfma_f32_16x16x32_bf16 v[28:31], v[148:151], v[204:207], v[28:31]
	v_mfma_f32_16x16x32_bf16 v[24:27], v[164:167], v[204:207], v[24:27]
	v_mfma_f32_16x16x32_bf16 v[12:15], v[148:151], v[212:215], v[12:15]
	v_mfma_f32_16x16x32_bf16 v[8:11], v[164:167], v[212:215], v[8:11]
	v_mfma_f32_16x16x32_bf16 v[60:63], v[152:155], v[192:195], v[60:63]
	v_mfma_f32_16x16x32_bf16 v[56:59], v[168:171], v[192:195], v[56:59]
	v_mfma_f32_16x16x32_bf16 v[44:47], v[152:155], v[200:203], v[44:47]
	v_mfma_f32_16x16x32_bf16 v[40:43], v[168:171], v[200:203], v[40:43]
	v_mfma_f32_16x16x32_bf16 v[28:31], v[152:155], v[208:211], v[28:31]
	v_mfma_f32_16x16x32_bf16 v[24:27], v[168:171], v[208:211], v[24:27]
	v_mfma_f32_16x16x32_bf16 v[12:15], v[152:155], v[216:219], v[12:15]
	v_mfma_f32_16x16x32_bf16 v[8:11], v[168:171], v[216:219], v[8:11]
	s_setprio 0
	s_setprio 1
	v_mfma_f32_16x16x32_bf16 v[52:55], v[172:175], v[188:191], v[52:55]
	v_mfma_f32_16x16x32_bf16 v[48:51], v[180:183], v[188:191], v[48:51]
	v_mfma_f32_16x16x32_bf16 v[36:39], v[172:175], v[196:199], v[36:39]
	v_mfma_f32_16x16x32_bf16 v[32:35], v[180:183], v[196:199], v[32:35]
	v_mfma_f32_16x16x32_bf16 v[20:23], v[172:175], v[204:207], v[20:23]
	v_mfma_f32_16x16x32_bf16 v[16:19], v[180:183], v[204:207], v[16:19]
	v_mfma_f32_16x16x32_bf16 v[4:7], v[172:175], v[212:215], v[4:7]
	v_mfma_f32_16x16x32_bf16 v[0:3], v[180:183], v[212:215], v[0:3]
	v_mfma_f32_16x16x32_bf16 v[52:55], v[176:179], v[192:195], v[52:55]
	v_mfma_f32_16x16x32_bf16 v[48:51], v[184:187], v[192:195], v[48:51]
	v_mfma_f32_16x16x32_bf16 v[36:39], v[176:179], v[200:203], v[36:39]
	v_mfma_f32_16x16x32_bf16 v[32:35], v[184:187], v[200:203], v[32:35]
	v_mfma_f32_16x16x32_bf16 v[20:23], v[176:179], v[208:211], v[20:23]
	v_mfma_f32_16x16x32_bf16 v[16:19], v[184:187], v[208:211], v[16:19]
	v_mfma_f32_16x16x32_bf16 v[4:7], v[176:179], v[216:219], v[4:7]
	v_mfma_f32_16x16x32_bf16 v[0:3], v[184:187], v[216:219], v[0:3]
	s_setprio 0
	s_cmp_eq_u32 s77, s98
	s_cbranch_scc1 .Lmy_nobar_7
	s_barrier
.Lmy_nobar_7:
	s_add_i32 s77, s77, 2
	s_add_u32 s52, s52, 0x100
	s_addc_u32 s53, s53, 0
	s_add_u32 s41, s41, 0x100
	s_addc_u32 s43, s43, 0
	s_cmp_gt_u32 s77, 13
	s_cbranch_scc0 .LBB0_655
	s_and_b64 vcc, exec, s[28:29]
	s_cbranch_vccz .LBB0_658
	s_nop 0

.LBB0_722:
	s_andn2_b64 vcc, exec, s[6:7]
	s_mov_b64 s[0:1], -1
	s_cbranch_vccnz .LBB0_651
	s_andn2_b64 vcc, exec, s[22:23]
	s_cbranch_vccnz .LBB0_650
	s_nop 0
	s_branch .LBB0_650

.LBB0_962:
	s_lshr_b32 s99, s91, 2
	s_cmp_eq_u32 s99, 1
	s_cselect_b32 s98, 12, 0x7fffffff
	s_add_i32 s66, s66, 1
	s_mul_i32 s6, s66, s59
	s_mul_hi_u32 s7, s66, s62
	s_add_i32 s7, s7, s6
	s_mul_i32 s6, s66, s62
	s_add_u32 s30, s6, s2
	s_addc_u32 s31, s7, s63
	v_cmp_gt_i64_e32 vcc, s[30:31], v[146:147]
	v_cmp_lt_i64_e64 s[6:7], s[30:31], v[144:145]
	s_cbranch_vccnz .LBB0_968
	s_ashr_i32 s12, s30, 31
	s_lshr_b32 s12, s12, 29
	s_add_i32 s12, s30, s12
	s_and_b32 s13, s12, -8
	s_sub_i32 s13, s30, s13
	s_cmp_gt_i32 s13, -1
	s_mov_b64 s[26:27], -1
	s_cbranch_scc0 .LBB0_965
	s_lshl_b32 s28, s13, 6
	s_mov_b64 s[26:27], 0

.LBB0_968:
	s_ashr_i32 s29, s28, 31
	s_lshl_b64 s[12:13], s[28:29], 19
	s_add_u32 s30, s20, s12
	s_addc_u32 s31, s21, s13
	s_and_b64 s[12:13], s[6:7], exec
	s_cselect_b32 s12, s31, s41
	s_cselect_b32 s13, s30, s40
	s_ashr_i32 s27, s26, 31
	s_lshl_b64 s[34:35], s[26:27], 19
	s_add_u32 s36, s3, s34
	s_addc_u32 s37, s50, s35
	s_and_b64 s[34:35], s[6:7], exec
	s_cselect_b32 s27, s37, s43
	s_cselect_b32 s29, s36, s42
	s_add_u32 s40, s40, 0x40080
	s_addc_u32 s41, s41, 0
	s_add_u32 s39, s42, 0x100
	v_mov_b32_e32 v0, 0
	s_addc_u32 s67, s43, 0
	s_mov_b32 s77, -2
	s_waitcnt lgkmcnt(0)
	v_mov_b32_e32 v1, v0
	v_mov_b32_e32 v2, v0
	v_mov_b32_e32 v3, v0
	v_mov_b32_e32 v4, v0
	v_mov_b32_e32 v5, v0
	v_mov_b32_e32 v6, v0
	v_mov_b32_e32 v7, v0
	v_mov_b32_e32 v16, v0
	v_mov_b32_e32 v17, v0
	v_mov_b32_e32 v18, v0
	v_mov_b32_e32 v19, v0
	v_mov_b32_e32 v20, v0
	v_mov_b32_e32 v21, v0
	v_mov_b32_e32 v22, v0
	v_mov_b32_e32 v23, v0
	v_mov_b32_e32 v32, v0
	v_mov_b32_e32 v33, v0
	v_mov_b32_e32 v34, v0
	v_mov_b32_e32 v35, v0
	v_mov_b32_e32 v36, v0
	v_mov_b32_e32 v37, v0
	v_mov_b32_e32 v38, v0
	v_mov_b32_e32 v39, v0
	v_mov_b32_e32 v48, v0
	v_mov_b32_e32 v49, v0
	v_mov_b32_e32 v50, v0
	v_mov_b32_e32 v51, v0
	v_mov_b32_e32 v52, v0
	v_mov_b32_e32 v53, v0
	v_mov_b32_e32 v54, v0
	v_mov_b32_e32 v55, v0
	v_mov_b32_e32 v8, v0
	v_mov_b32_e32 v9, v0
	v_mov_b32_e32 v10, v0
	v_mov_b32_e32 v11, v0
	v_mov_b32_e32 v12, v0
	v_mov_b32_e32 v13, v0
	v_mov_b32_e32 v14, v0
	v_mov_b32_e32 v15, v0
	v_mov_b32_e32 v24, v0
	v_mov_b32_e32 v25, v0
	v_mov_b32_e32 v26, v0
	v_mov_b32_e32 v27, v0
	v_mov_b32_e32 v28, v0
	v_mov_b32_e32 v29, v0
	v_mov_b32_e32 v30, v0
	v_mov_b32_e32 v31, v0
	v_mov_b32_e32 v40, v0
	v_mov_b32_e32 v41, v0
	v_mov_b32_e32 v42, v0
	v_mov_b32_e32 v43, v0
	v_mov_b32_e32 v44, v0
	v_mov_b32_e32 v45, v0
	v_mov_b32_e32 v46, v0
	v_mov_b32_e32 v47, v0
	v_mov_b32_e32 v56, v0
	v_mov_b32_e32 v57, v0
	v_mov_b32_e32 v58, v0
	v_mov_b32_e32 v59, v0
	v_mov_b32_e32 v60, v0
	v_mov_b32_e32 v61, v0
	v_mov_b32_e32 v62, v0
	v_mov_b32_e32 v63, v0
	v_mov_b32_e32 v64, v0
	v_mov_b32_e32 v65, v0
	v_mov_b32_e32 v66, v0
	v_mov_b32_e32 v67, v0
	v_mov_b32_e32 v68, v0
	v_mov_b32_e32 v69, v0
	v_mov_b32_e32 v70, v0
	v_mov_b32_e32 v71, v0
	v_mov_b32_e32 v80, v0
	v_mov_b32_e32 v81, v0
	v_mov_b32_e32 v82, v0
	v_mov_b32_e32 v83, v0
	v_mov_b32_e32 v84, v0
	v_mov_b32_e32 v85, v0
	v_mov_b32_e32 v86, v0
	v_mov_b32_e32 v87, v0
	v_mov_b32_e32 v96, v0
	v_mov_b32_e32 v97, v0
	v_mov_b32_e32 v98, v0
	v_mov_b32_e32 v99, v0
	v_mov_b32_e32 v100, v0
	v_mov_b32_e32 v101, v0
	v_mov_b32_e32 v102, v0
	v_mov_b32_e32 v103, v0
	v_mov_b32_e32 v112, v0
	v_mov_b32_e32 v113, v0
	v_mov_b32_e32 v114, v0
	v_mov_b32_e32 v115, v0
	v_mov_b32_e32 v116, v0
	v_mov_b32_e32 v117, v0
	v_mov_b32_e32 v118, v0
	v_mov_b32_e32 v119, v0
	v_mov_b32_e32 v72, v0
	v_mov_b32_e32 v73, v0
	v_mov_b32_e32 v74, v0
	v_mov_b32_e32 v75, v0
	v_mov_b32_e32 v76, v0
	v_mov_b32_e32 v77, v0
	v_mov_b32_e32 v78, v0
	v_mov_b32_e32 v79, v0
	v_mov_b32_e32 v88, v0
	v_mov_b32_e32 v89, v0
	v_mov_b32_e32 v90, v0
	v_mov_b32_e32 v91, v0
	v_mov_b32_e32 v92, v0
	v_mov_b32_e32 v93, v0
	v_mov_b32_e32 v94, v0
	v_mov_b32_e32 v95, v0
	v_mov_b32_e32 v104, v0
	v_mov_b32_e32 v105, v0
	v_mov_b32_e32 v106, v0
	v_mov_b32_e32 v107, v0
	v_mov_b32_e32 v108, v0
	v_mov_b32_e32 v109, v0
	v_mov_b32_e32 v110, v0
	v_mov_b32_e32 v111, v0
	v_mov_b32_e32 v120, v0
	v_mov_b32_e32 v121, v0
	v_mov_b32_e32 v122, v0
	v_mov_b32_e32 v123, v0
	v_mov_b32_e32 v124, v0
	v_mov_b32_e32 v125, v0
	v_mov_b32_e32 v126, v0
	v_mov_b32_e32 v127, v0
	s_cmp_lg_u32 s66, 1
	s_cselect_b32 s100, s99, 0
	s_cmp_lg_u32 s100, 0
	s_cbranch_scc0 .Lmy_nobar2_9
	s_barrier
.Lmy_nobar2_9:
.LBB0_969:
	ds_read_b128 v[148:151], v154
	ds_read_b128 v[160:163], v154 offset:1024
	ds_read_b128 v[164:167], v154 offset:2048
	ds_read_b128 v[168:171], v154 offset:3072
	ds_read_b128 v[172:175], v155
	ds_read_b128 v[176:179], v155 offset:1024
	ds_read_b128 v[180:183], v155 offset:2048
	ds_read_b128 v[184:187], v155 offset:3072
	s_add_u32 s34, s40, 0xfffc0080
	s_addc_u32 s35, s41, -1
	s_cmp_eq_u32 s77, 12
	s_cselect_b32 s49, s12, s35
	s_cselect_b32 s48, s13, s34
	s_cselect_b32 s43, s27, s67
	s_cselect_b32 s42, s29, s39
	v_lshl_add_u64 v[220:221], s[40:41], 0, v[140:141]
	s_add_i32 m0, s52, 0xc000
	ds_read_b128 v[188:191], v157
	ds_read_b128 v[192:195], v157 offset:1024
	ds_read_b128 v[196:199], v157 offset:2048
	ds_read_b128 v[200:203], v157 offset:3072
	ds_read_b128 v[204:207], v157 offset:4096
	ds_read_b128 v[208:211], v157 offset:5120
	ds_read_b128 v[212:215], v157 offset:6144
	ds_read_b128 v[216:219], v157 offset:7168
	global_load_lds_dwordx4 v[220:221], off
	v_lshl_add_u64 v[220:221], s[40:41], 0, v[142:143]
	s_add_i32 m0, s52, 0xe000
	s_nop 0
	global_load_lds_dwordx4 v[220:221], off
	s_waitcnt vmcnt(8)
	s_waitcnt lgkmcnt(0)
	s_barrier
	s_setprio 1
	s_waitcnt lgkmcnt(0)
	v_mfma_f32_16x16x32_bf16 v[124:127], v[148:151], v[188:191], v[124:127]
	v_mfma_f32_16x16x32_bf16 v[120:123], v[164:167], v[188:191], v[120:123]
	v_mfma_f32_16x16x32_bf16 v[108:111], v[148:151], v[196:199], v[108:111]
	v_mfma_f32_16x16x32_bf16 v[104:107], v[164:167], v[196:199], v[104:107]
	v_mfma_f32_16x16x32_bf16 v[92:95], v[148:151], v[204:207], v[92:95]
	v_mfma_f32_16x16x32_bf16 v[88:91], v[164:167], v[204:207], v[88:91]
	v_mfma_f32_16x16x32_bf16 v[76:79], v[148:151], v[212:215], v[76:79]
	v_mfma_f32_16x16x32_bf16 v[72:75], v[164:167], v[212:215], v[72:75]
	v_mfma_f32_16x16x32_bf16 v[124:127], v[160:163], v[192:195], v[124:127]
	v_mfma_f32_16x16x32_bf16 v[120:123], v[168:171], v[192:195], v[120:123]
	v_mfma_f32_16x16x32_bf16 v[108:111], v[160:163], v[200:203], v[108:111]
	v_mfma_f32_16x16x32_bf16 v[104:107], v[168:171], v[200:203], v[104:107]
	v_mfma_f32_16x16x32_bf16 v[92:95], v[160:163], v[208:211], v[92:95]
	v_mfma_f32_16x16x32_bf16 v[88:91], v[168:171], v[208:211], v[88:91]
	v_mfma_f32_16x16x32_bf16 v[76:79], v[160:163], v[216:219], v[76:79]
	v_mfma_f32_16x16x32_bf16 v[72:75], v[168:171], v[216:219], v[72:75]
	s_setprio 0
	s_setprio 1
	v_mfma_f32_16x16x32_bf16 v[116:119], v[172:175], v[188:191], v[116:119]
	v_mfma_f32_16x16x32_bf16 v[112:115], v[180:183], v[188:191], v[112:115]
	v_mfma_f32_16x16x32_bf16 v[100:103], v[172:175], v[196:199], v[100:103]
	v_mfma_f32_16x16x32_bf16 v[96:99], v[180:183], v[196:199], v[96:99]
	v_mfma_f32_16x16x32_bf16 v[84:87], v[172:175], v[204:207], v[84:87]
	v_mfma_f32_16x16x32_bf16 v[80:83], v[180:183], v[204:207], v[80:83]
	v_mfma_f32_16x16x32_bf16 v[68:71], v[172:175], v[212:215], v[68:71]
	v_mfma_f32_16x16x32_bf16 v[64:67], v[180:183], v[212:215], v[64:67]
	v_mfma_f32_16x16x32_bf16 v[116:119], v[176:179], v[192:195], v[116:119]
	v_mfma_f32_16x16x32_bf16 v[112:115], v[184:187], v[192:195], v[112:115]
	v_mfma_f32_16x16x32_bf16 v[100:103], v[176:179], v[200:203], v[100:103]
	v_mfma_f32_16x16x32_bf16 v[96:99], v[184:187], v[200:203], v[96:99]
	v_mfma_f32_16x16x32_bf16 v[84:87], v[176:179], v[208:211], v[84:87]
	v_mfma_f32_16x16x32_bf16 v[80:83], v[184:187], v[208:211], v[80:83]
	v_mfma_f32_16x16x32_bf16 v[68:71], v[176:179], v[216:219], v[68:71]
	v_mfma_f32_16x16x32_bf16 v[64:67], v[184:187], v[216:219], v[64:67]
	s_setprio 0
	s_barrier
	s_add_i32 s34, s64, s51
	v_lshl_add_u64 v[220:221], s[42:43], 0, v[134:135]
	s_mov_b32 m0, s34
	ds_read_b128 v[188:191], v157 offset:16384
	ds_read_b128 v[192:195], v157 offset:17408
	ds_read_b128 v[196:199], v157 offset:18432
	ds_read_b128 v[200:203], v157 offset:19456
	ds_read_b128 v[204:207], v157 offset:20480
	ds_read_b128 v[208:211], v157 offset:21504
	ds_read_b128 v[212:215], v157 offset:22528
	ds_read_b128 v[216:219], v157 offset:23552
	global_load_lds_dwordx4 v[220:221], off
	s_add_i32 m0, s34, 0x2000
	s_add_u32 s34, s42, 0x40000
	v_lshl_add_u64 v[222:223], s[42:43], 0, v[138:139]
	s_addc_u32 s35, s43, 0
	s_add_i32 s79, s65, s51
	global_load_lds_dwordx4 v[222:223], off
	v_lshl_add_u64 v[224:225], s[34:35], 0, v[134:135]
	s_mov_b32 m0, s79
	v_lshl_add_u64 v[226:227], s[48:49], 0, v[136:137]
	global_load_lds_dwordx4 v[224:225], off
	v_lshl_add_u64 v[224:225], s[34:35], 0, v[138:139]
	s_add_i32 m0, s79, 0x2000
	s_nop 0
	global_load_lds_dwordx4 v[224:225], off
	v_lshl_add_u64 v[224:225], s[48:49], 0, v[132:133]
	s_mov_b32 m0, s52
	s_nop 0
	global_load_lds_dwordx4 v[224:225], off
	s_mov_b32 m0, s53
	s_nop 0
	global_load_lds_dwordx4 v[226:227], off
	s_waitcnt vmcnt(8)
	s_waitcnt lgkmcnt(0)
	s_barrier
	s_setprio 1
	s_waitcnt lgkmcnt(0)
	v_mfma_f32_16x16x32_bf16 v[60:63], v[148:151], v[188:191], v[60:63]
	v_mfma_f32_16x16x32_bf16 v[56:59], v[164:167], v[188:191], v[56:59]
	v_mfma_f32_16x16x32_bf16 v[44:47], v[148:151], v[196:199], v[44:47]
	v_mfma_f32_16x16x32_bf16 v[40:43], v[164:167], v[196:199], v[40:43]
	v_mfma_f32_16x16x32_bf16 v[28:31], v[148:151], v[204:207], v[28:31]
	v_mfma_f32_16x16x32_bf16 v[24:27], v[164:167], v[204:207], v[24:27]
	v_mfma_f32_16x16x32_bf16 v[12:15], v[148:151], v[212:215], v[12:15]
	v_mfma_f32_16x16x32_bf16 v[8:11], v[164:167], v[212:215], v[8:11]
	v_mfma_f32_16x16x32_bf16 v[60:63], v[160:163], v[192:195], v[60:63]
	v_mfma_f32_16x16x32_bf16 v[56:59], v[168:171], v[192:195], v[56:59]
	v_mfma_f32_16x16x32_bf16 v[44:47], v[160:163], v[200:203], v[44:47]
	v_mfma_f32_16x16x32_bf16 v[40:43], v[168:171], v[200:203], v[40:43]
	v_mfma_f32_16x16x32_bf16 v[28:31], v[160:163], v[208:211], v[28:31]
	v_mfma_f32_16x16x32_bf16 v[24:27], v[168:171], v[208:211], v[24:27]
	v_mfma_f32_16x16x32_bf16 v[12:15], v[160:163], v[216:219], v[12:15]
	v_mfma_f32_16x16x32_bf16 v[8:11], v[168:171], v[216:219], v[8:11]
	s_setprio 0
	s_setprio 1
	v_mfma_f32_16x16x32_bf16 v[52:55], v[172:175], v[188:191], v[52:55]
	v_mfma_f32_16x16x32_bf16 v[48:51], v[180:183], v[188:191], v[48:51]
	v_mfma_f32_16x16x32_bf16 v[36:39], v[172:175], v[196:199], v[36:39]
	v_mfma_f32_16x16x32_bf16 v[32:35], v[180:183], v[196:199], v[32:35]
	v_mfma_f32_16x16x32_bf16 v[20:23], v[172:175], v[204:207], v[20:23]
	v_mfma_f32_16x16x32_bf16 v[16:19], v[180:183], v[204:207], v[16:19]
	v_mfma_f32_16x16x32_bf16 v[4:7], v[172:175], v[212:215], v[4:7]
	v_mfma_f32_16x16x32_bf16 v[0:3], v[180:183], v[212:215], v[0:3]
	v_mfma_f32_16x16x32_bf16 v[52:55], v[176:179], v[192:195], v[52:55]
	v_mfma_f32_16x16x32_bf16 v[48:51], v[184:187], v[192:195], v[48:51]
	v_mfma_f32_16x16x32_bf16 v[36:39], v[176:179], v[200:203], v[36:39]
	v_mfma_f32_16x16x32_bf16 v[32:35], v[184:187], v[200:203], v[32:35]
	v_mfma_f32_16x16x32_bf16 v[20:23], v[176:179], v[208:211], v[20:23]
	v_mfma_f32_16x16x32_bf16 v[16:19], v[184:187], v[208:211], v[16:19]
	v_mfma_f32_16x16x32_bf16 v[4:7], v[176:179], v[216:219], v[4:7]
	v_mfma_f32_16x16x32_bf16 v[0:3], v[184:187], v[216:219], v[0:3]
	s_setprio 0
	s_barrier
	s_add_i32 s79, 0, 0x18000
	v_add_u32_e32 v159, s79, v152
	s_add_i32 s81, 0, 0x1c000
	ds_read_b128 v[148:151], v159
	ds_read_b128 v[160:163], v159 offset:1024
	ds_read_b128 v[164:167], v159 offset:2048
	ds_read_b128 v[168:171], v159 offset:3072
	v_add_u32_e32 v159, s81, v152
	ds_read_b128 v[172:175], v159
	ds_read_b128 v[176:179], v159 offset:1024
	ds_read_b128 v[180:183], v159 offset:2048
	ds_read_b128 v[184:187], v159 offset:3072
	s_add_u32 s34, s48, 0x40000
	s_addc_u32 s35, s49, 0
	s_mov_b32 m0, s54
	v_lshl_add_u64 v[228:229], s[34:35], 0, v[132:133]
	ds_read_b128 v[188:191], v157 offset:32768
	ds_read_b128 v[192:195], v157 offset:33792
	ds_read_b128 v[196:199], v157 offset:34816
	ds_read_b128 v[200:203], v157 offset:35840
	ds_read_b128 v[204:207], v157 offset:36864
	ds_read_b128 v[208:211], v157 offset:37888
	ds_read_b128 v[212:215], v157 offset:38912
	ds_read_b128 v[216:219], v157 offset:39936
	global_load_lds_dwordx4 v[228:229], off
	v_lshl_add_u64 v[228:229], s[34:35], 0, v[136:137]
	s_mov_b32 m0, s55
	s_nop 0
	global_load_lds_dwordx4 v[228:229], off
	s_waitcnt vmcnt(8)
	s_waitcnt lgkmcnt(0)
	s_barrier
	s_setprio 1
	s_waitcnt lgkmcnt(0)
	v_mfma_f32_16x16x32_bf16 v[124:127], v[148:151], v[188:191], v[124:127]
	v_mfma_f32_16x16x32_bf16 v[120:123], v[164:167], v[188:191], v[120:123]
	v_mfma_f32_16x16x32_bf16 v[108:111], v[148:151], v[196:199], v[108:111]
	v_mfma_f32_16x16x32_bf16 v[104:107], v[164:167], v[196:199], v[104:107]
	v_mfma_f32_16x16x32_bf16 v[92:95], v[148:151], v[204:207], v[92:95]
	v_mfma_f32_16x16x32_bf16 v[88:91], v[164:167], v[204:207], v[88:91]
	v_mfma_f32_16x16x32_bf16 v[76:79], v[148:151], v[212:215], v[76:79]
	v_mfma_f32_16x16x32_bf16 v[72:75], v[164:167], v[212:215], v[72:75]
	v_mfma_f32_16x16x32_bf16 v[124:127], v[160:163], v[192:195], v[124:127]
	v_mfma_f32_16x16x32_bf16 v[120:123], v[168:171], v[192:195], v[120:123]
	v_mfma_f32_16x16x32_bf16 v[108:111], v[160:163], v[200:203], v[108:111]
	v_mfma_f32_16x16x32_bf16 v[104:107], v[168:171], v[200:203], v[104:107]
	v_mfma_f32_16x16x32_bf16 v[92:95], v[160:163], v[208:211], v[92:95]
	v_mfma_f32_16x16x32_bf16 v[88:91], v[168:171], v[208:211], v[88:91]
	v_mfma_f32_16x16x32_bf16 v[76:79], v[160:163], v[216:219], v[76:79]
	v_mfma_f32_16x16x32_bf16 v[72:75], v[168:171], v[216:219], v[72:75]
	s_setprio 0
	s_setprio 1
	v_mfma_f32_16x16x32_bf16 v[116:119], v[172:175], v[188:191], v[116:119]
	v_mfma_f32_16x16x32_bf16 v[112:115], v[180:183], v[188:191], v[112:115]
	v_mfma_f32_16x16x32_bf16 v[100:103], v[172:175], v[196:199], v[100:103]
	v_mfma_f32_16x16x32_bf16 v[96:99], v[180:183], v[196:199], v[96:99]
	v_mfma_f32_16x16x32_bf16 v[84:87], v[172:175], v[204:207], v[84:87]
	v_mfma_f32_16x16x32_bf16 v[80:83], v[180:183], v[204:207], v[80:83]
	v_mfma_f32_16x16x32_bf16 v[68:71], v[172:175], v[212:215], v[68:71]
	v_mfma_f32_16x16x32_bf16 v[64:67], v[180:183], v[212:215], v[64:67]
	v_mfma_f32_16x16x32_bf16 v[116:119], v[176:179], v[192:195], v[116:119]
	v_mfma_f32_16x16x32_bf16 v[112:115], v[184:187], v[192:195], v[112:115]
	v_mfma_f32_16x16x32_bf16 v[100:103], v[176:179], v[200:203], v[100:103]
	v_mfma_f32_16x16x32_bf16 v[96:99], v[184:187], v[200:203], v[96:99]
	v_mfma_f32_16x16x32_bf16 v[84:87], v[176:179], v[208:211], v[84:87]
	v_mfma_f32_16x16x32_bf16 v[80:83], v[184:187], v[208:211], v[80:83]
	v_mfma_f32_16x16x32_bf16 v[68:71], v[176:179], v[216:219], v[68:71]
	v_mfma_f32_16x16x32_bf16 v[64:67], v[184:187], v[216:219], v[64:67]
	s_setprio 0
	s_barrier
	s_add_i32 s34, s79, s51
	v_lshl_add_u64 v[220:221], v[220:221], 0, s[10:11]
	s_mov_b32 m0, s34
	ds_read_b128 v[188:191], v157 offset:49152
	ds_read_b128 v[192:195], v157 offset:50176
	ds_read_b128 v[196:199], v157 offset:51200
	ds_read_b128 v[200:203], v157 offset:52224
	ds_read_b128 v[204:207], v157 offset:53248
	ds_read_b128 v[208:211], v157 offset:54272
	ds_read_b128 v[212:215], v157 offset:55296
	ds_read_b128 v[216:219], v157 offset:56320
	global_load_lds_dwordx4 v[220:221], off
	s_add_i32 m0, s34, 0x2000
	s_add_u32 s34, s42, 0x40080
	v_lshl_add_u64 v[220:221], v[222:223], 0, s[10:11]
	s_addc_u32 s35, s43, 0
	s_add_i32 s42, s81, s51
	global_load_lds_dwordx4 v[220:221], off
	v_lshl_add_u64 v[220:221], s[34:35], 0, v[134:135]
	s_mov_b32 m0, s42
	s_nop 0
	global_load_lds_dwordx4 v[220:221], off
	v_lshl_add_u64 v[220:221], s[34:35], 0, v[138:139]
	s_add_i32 m0, s42, 0x2000
	s_nop 0
	global_load_lds_dwordx4 v[220:221], off
	v_lshl_add_u64 v[220:221], v[224:225], 0, s[10:11]
	s_mov_b32 m0, s57
	s_nop 0
	global_load_lds_dwordx4 v[220:221], off
	v_lshl_add_u64 v[220:221], v[226:227], 0, s[10:11]
	s_mov_b32 m0, s58
	s_nop 0
	global_load_lds_dwordx4 v[220:221], off
	s_waitcnt vmcnt(8)
	s_waitcnt lgkmcnt(0)
	s_barrier
	s_setprio 1
	s_waitcnt lgkmcnt(0)
	v_mfma_f32_16x16x32_bf16 v[60:63], v[148:151], v[188:191], v[60:63]
	v_mfma_f32_16x16x32_bf16 v[56:59], v[164:167], v[188:191], v[56:59]
	v_mfma_f32_16x16x32_bf16 v[44:47], v[148:151], v[196:199], v[44:47]
	v_mfma_f32_16x16x32_bf16 v[40:43], v[164:167], v[196:199], v[40:43]
	v_mfma_f32_16x16x32_bf16 v[28:31], v[148:151], v[204:207], v[28:31]
	v_mfma_f32_16x16x32_bf16 v[24:27], v[164:167], v[204:207], v[24:27]
	v_mfma_f32_16x16x32_bf16 v[12:15], v[148:151], v[212:215], v[12:15]
	v_mfma_f32_16x16x32_bf16 v[8:11], v[164:167], v[212:215], v[8:11]
	v_mfma_f32_16x16x32_bf16 v[60:63], v[160:163], v[192:195], v[60:63]
	v_mfma_f32_16x16x32_bf16 v[56:59], v[168:171], v[192:195], v[56:59]
	v_mfma_f32_16x16x32_bf16 v[44:47], v[160:163], v[200:203], v[44:47]
	v_mfma_f32_16x16x32_bf16 v[40:43], v[168:171], v[200:203], v[40:43]
	v_mfma_f32_16x16x32_bf16 v[28:31], v[160:163], v[208:211], v[28:31]
	v_mfma_f32_16x16x32_bf16 v[24:27], v[168:171], v[208:211], v[24:27]
	v_mfma_f32_16x16x32_bf16 v[12:15], v[160:163], v[216:219], v[12:15]
	v_mfma_f32_16x16x32_bf16 v[8:11], v[168:171], v[216:219], v[8:11]
	s_setprio 0
	s_setprio 1
	v_mfma_f32_16x16x32_bf16 v[52:55], v[172:175], v[188:191], v[52:55]
	v_mfma_f32_16x16x32_bf16 v[48:51], v[180:183], v[188:191], v[48:51]
	v_mfma_f32_16x16x32_bf16 v[36:39], v[172:175], v[196:199], v[36:39]
	v_mfma_f32_16x16x32_bf16 v[32:35], v[180:183], v[196:199], v[32:35]
	v_mfma_f32_16x16x32_bf16 v[20:23], v[172:175], v[204:207], v[20:23]
	v_mfma_f32_16x16x32_bf16 v[16:19], v[180:183], v[204:207], v[16:19]
	v_mfma_f32_16x16x32_bf16 v[4:7], v[172:175], v[212:215], v[4:7]
	v_mfma_f32_16x16x32_bf16 v[0:3], v[180:183], v[212:215], v[0:3]
	v_mfma_f32_16x16x32_bf16 v[52:55], v[176:179], v[192:195], v[52:55]
	v_mfma_f32_16x16x32_bf16 v[48:51], v[184:187], v[192:195], v[48:51]
	v_mfma_f32_16x16x32_bf16 v[36:39], v[176:179], v[200:203], v[36:39]
	v_mfma_f32_16x16x32_bf16 v[32:35], v[184:187], v[200:203], v[32:35]
	v_mfma_f32_16x16x32_bf16 v[20:23], v[176:179], v[208:211], v[20:23]
	v_mfma_f32_16x16x32_bf16 v[16:19], v[184:187], v[208:211], v[16:19]
	v_mfma_f32_16x16x32_bf16 v[4:7], v[176:179], v[216:219], v[4:7]
	v_mfma_f32_16x16x32_bf16 v[0:3], v[184:187], v[216:219], v[0:3]
	s_setprio 0
	s_cmp_eq_u32 s77, s98
	s_cbranch_scc1 .Lmy_nobar_9
	s_barrier
.Lmy_nobar_9:
	s_add_i32 s77, s77, 2
	s_add_u32 s40, s40, 0x100
	s_addc_u32 s41, s41, 0
	s_add_u32 s39, s39, 0x100
	s_addc_u32 s67, s67, 0
	s_cmp_gt_u32 s77, 13
	s_cbranch_scc0 .LBB0_969
	s_and_b64 vcc, exec, s[22:23]
	s_cbranch_vccz .LBB0_972
	s_nop 0

.LBB0_988:
	s_or_b64 exec, exec, s[40:41]
	s_andn2_b64 vcc, exec, s[6:7]
	s_mov_b64 s[6:7], -1
	s_cbranch_vccnz .LBB0_961
	s_andn2_b64 vcc, exec, s[8:9]
	s_cbranch_vccnz .LBB0_960
	s_nop 0
	s_branch .LBB0_960

.LBB0_1056:
	s_lshr_b32 s99, s91, 2
	s_cmp_eq_u32 s99, 1
	s_cselect_b32 s98, 12, 0x7fffffff
	s_add_i32 s62, s62, 1
	s_mul_i32 s4, s62, s42
	s_mul_hi_u32 s5, s62, s43
	s_add_i32 s5, s5, s4
	s_mul_i32 s4, s62, s43
	s_add_u32 s26, s4, s2
	s_addc_u32 s27, s5, s3
	v_cmp_gt_i64_e32 vcc, s[26:27], v[146:147]
	v_cmp_lt_i64_e64 s[4:5], s[26:27], v[144:145]
	s_cbranch_vccnz .LBB0_1058
	s_ashr_i32 s10, s26, 31
	s_lshr_b32 s10, s10, 29
	s_add_i32 s10, s26, s10
	s_ashr_i32 s11, s10, 3
	s_and_b32 s10, s10, -8
	s_sub_i32 s10, s26, s10
	s_cmp_lt_i32 s10, 0
	s_cselect_b32 s22, s51, 0x160
	s_mul_i32 s10, s10, s22
	s_add_i32 s10, s10, s11
	s_mul_hi_i32 s11, s10, 0x2e8ba2e9
	s_lshr_b32 s22, s11, 31
	s_ashr_i32 s11, s11, 5
	s_add_i32 s11, s11, s22
	s_lshl_b32 s22, s11, 3
	s_sub_i32 s23, 0x80, s22
	s_min_i32 s23, s23, 8
	s_abs_i32 s26, s23
	v_cvt_f32_u32_e32 v0, s26
	s_sub_i32 s28, 0, s26
	s_mulk_i32 s11, 0xb0
	s_sub_i32 s11, s10, s11
	v_rcp_iflag_f32_e32 v0, v0
	s_abs_i32 s10, s11
	s_xor_b32 s27, s11, s23
	s_ashr_i32 s27, s27, 31
	v_mul_f32_e32 v0, 0x4f7ffffe, v0
	v_cvt_u32_f32_e32 v0, v0
	s_mov_b32 s63, s62
	v_readfirstlane_b32 s29, v0
	s_mul_i32 s28, s28, s29
	s_mul_hi_u32 s28, s29, s28
	s_add_i32 s29, s29, s28
	s_mul_hi_u32 s28, s10, s29
	s_mul_i32 s29, s28, s26
	s_sub_i32 s10, s10, s29
	s_add_i32 s34, s28, 1
	s_sub_i32 s29, s10, s26
	s_cmp_ge_u32 s10, s26
	s_cselect_b32 s28, s34, s28
	s_cselect_b32 s10, s29, s10
	s_add_i32 s29, s28, 1
	s_cmp_ge_u32 s10, s26
	s_cselect_b32 s10, s29, s28
	s_xor_b32 s10, s10, s27
	s_sub_i32 s10, s10, s27
	s_mul_i32 s23, s10, s23
	s_sub_i32 s11, s11, s23
	s_add_i32 s22, s22, s11
.LBB0_1058:
	s_ashr_i32 s23, s22, 31
	s_lshl_b64 s[26:27], s[22:23], 19
	s_add_u32 s26, s14, s26
	s_addc_u32 s27, s15, s27
	s_and_b64 s[28:29], s[4:5], exec
	s_cselect_b32 s23, s27, s37
	s_cselect_b32 s64, s26, s36
	s_ashr_i32 s11, s10, 31
	s_lshl_b64 s[28:29], s[10:11], 19
	s_add_u32 s28, s49, s28
	s_addc_u32 s29, s50, s29
	s_and_b64 s[34:35], s[4:5], exec
	s_cselect_b32 s11, s29, s39
	s_cselect_b32 s65, s28, s38
	s_add_u32 s36, s36, 0x40080
	s_addc_u32 s37, s37, 0
	s_add_u32 s66, s38, 0x100
	v_mov_b32_e32 v0, 0
	s_addc_u32 s67, s39, 0
	s_mov_b32 s77, -2
	v_mov_b32_e32 v1, v0
	v_mov_b32_e32 v2, v0
	v_mov_b32_e32 v3, v0
	v_mov_b32_e32 v4, v0
	v_mov_b32_e32 v5, v0
	v_mov_b32_e32 v6, v0
	v_mov_b32_e32 v7, v0
	v_mov_b32_e32 v16, v0
	v_mov_b32_e32 v17, v0
	v_mov_b32_e32 v18, v0
	v_mov_b32_e32 v19, v0
	v_mov_b32_e32 v20, v0
	v_mov_b32_e32 v21, v0
	v_mov_b32_e32 v22, v0
	v_mov_b32_e32 v23, v0
	v_mov_b32_e32 v32, v0
	v_mov_b32_e32 v33, v0
	v_mov_b32_e32 v34, v0
	v_mov_b32_e32 v35, v0
	v_mov_b32_e32 v36, v0
	v_mov_b32_e32 v37, v0
	v_mov_b32_e32 v38, v0
	v_mov_b32_e32 v39, v0
	v_mov_b32_e32 v48, v0
	v_mov_b32_e32 v49, v0
	v_mov_b32_e32 v50, v0
	v_mov_b32_e32 v51, v0
	v_mov_b32_e32 v52, v0
	v_mov_b32_e32 v53, v0
	v_mov_b32_e32 v54, v0
	v_mov_b32_e32 v55, v0
	v_mov_b32_e32 v8, v0
	v_mov_b32_e32 v9, v0
	v_mov_b32_e32 v10, v0
	v_mov_b32_e32 v11, v0
	v_mov_b32_e32 v12, v0
	v_mov_b32_e32 v13, v0
	v_mov_b32_e32 v14, v0
	v_mov_b32_e32 v15, v0
	v_mov_b32_e32 v24, v0
	v_mov_b32_e32 v25, v0
	v_mov_b32_e32 v26, v0
	v_mov_b32_e32 v27, v0
	v_mov_b32_e32 v28, v0
	v_mov_b32_e32 v29, v0
	v_mov_b32_e32 v30, v0
	v_mov_b32_e32 v31, v0
	v_mov_b32_e32 v40, v0
	v_mov_b32_e32 v41, v0
	v_mov_b32_e32 v42, v0
	v_mov_b32_e32 v43, v0
	v_mov_b32_e32 v44, v0
	v_mov_b32_e32 v45, v0
	v_mov_b32_e32 v46, v0
	v_mov_b32_e32 v47, v0
	v_mov_b32_e32 v56, v0
	v_mov_b32_e32 v57, v0
	v_mov_b32_e32 v58, v0
	v_mov_b32_e32 v59, v0
	v_mov_b32_e32 v60, v0
	v_mov_b32_e32 v61, v0
	v_mov_b32_e32 v62, v0
	v_mov_b32_e32 v63, v0
	v_mov_b32_e32 v64, v0
	v_mov_b32_e32 v65, v0
	v_mov_b32_e32 v66, v0
	v_mov_b32_e32 v67, v0
	v_mov_b32_e32 v68, v0
	v_mov_b32_e32 v69, v0
	v_mov_b32_e32 v70, v0
	v_mov_b32_e32 v71, v0
	v_mov_b32_e32 v80, v0
	v_mov_b32_e32 v81, v0
	v_mov_b32_e32 v82, v0
	v_mov_b32_e32 v83, v0
	v_mov_b32_e32 v84, v0
	v_mov_b32_e32 v85, v0
	v_mov_b32_e32 v86, v0
	v_mov_b32_e32 v87, v0
	v_mov_b32_e32 v96, v0
	v_mov_b32_e32 v97, v0
	v_mov_b32_e32 v98, v0
	v_mov_b32_e32 v99, v0
	v_mov_b32_e32 v100, v0
	v_mov_b32_e32 v101, v0
	v_mov_b32_e32 v102, v0
	v_mov_b32_e32 v103, v0
	v_mov_b32_e32 v112, v0
	v_mov_b32_e32 v113, v0
	v_mov_b32_e32 v114, v0
	v_mov_b32_e32 v115, v0
	v_mov_b32_e32 v116, v0
	v_mov_b32_e32 v117, v0
	v_mov_b32_e32 v118, v0
	v_mov_b32_e32 v119, v0
	v_mov_b32_e32 v72, v0
	v_mov_b32_e32 v73, v0
	v_mov_b32_e32 v74, v0
	v_mov_b32_e32 v75, v0
	v_mov_b32_e32 v76, v0
	v_mov_b32_e32 v77, v0
	v_mov_b32_e32 v78, v0
	v_mov_b32_e32 v79, v0
	v_mov_b32_e32 v88, v0
	v_mov_b32_e32 v89, v0
	v_mov_b32_e32 v90, v0
	v_mov_b32_e32 v91, v0
	v_mov_b32_e32 v92, v0
	v_mov_b32_e32 v93, v0
	v_mov_b32_e32 v94, v0
	v_mov_b32_e32 v95, v0
	v_mov_b32_e32 v104, v0
	v_mov_b32_e32 v105, v0
	v_mov_b32_e32 v106, v0
	v_mov_b32_e32 v107, v0
	v_mov_b32_e32 v108, v0
	v_mov_b32_e32 v109, v0
	v_mov_b32_e32 v110, v0
	v_mov_b32_e32 v111, v0
	v_mov_b32_e32 v120, v0
	v_mov_b32_e32 v121, v0
	v_mov_b32_e32 v122, v0
	v_mov_b32_e32 v123, v0
	v_mov_b32_e32 v124, v0
	v_mov_b32_e32 v125, v0
	v_mov_b32_e32 v126, v0
	v_mov_b32_e32 v127, v0
	s_cmp_lg_u32 s62, 1
	s_cselect_b32 s100, s99, 0
	s_cmp_lg_u32 s100, 0
	s_cbranch_scc0 .Lmy_nobar2_10
	s_barrier
.Lmy_nobar2_10:
.LBB0_1059:
	ds_read_b128 v[148:151], v155
	ds_read_b128 v[160:163], v155 offset:1024
	ds_read_b128 v[164:167], v155 offset:2048
	ds_read_b128 v[168:171], v155 offset:3072
	ds_read_b128 v[172:175], v157
	ds_read_b128 v[176:179], v157 offset:1024
	ds_read_b128 v[180:183], v157 offset:2048
	ds_read_b128 v[184:187], v157 offset:3072
	s_add_u32 s34, s36, 0xfffc0080
	s_addc_u32 s35, s37, -1
	s_cmp_eq_u32 s77, 12
	s_cselect_b32 s41, s23, s35
	s_cselect_b32 s40, s64, s34
	s_cselect_b32 s39, s11, s67
	s_cselect_b32 s38, s65, s66
	v_lshl_add_u64 v[220:221], s[36:37], 0, v[140:141]
	s_add_i32 m0, s31, 0xc000
	ds_read_b128 v[188:191], v158
	ds_read_b128 v[192:195], v158 offset:1024
	ds_read_b128 v[196:199], v158 offset:2048
	ds_read_b128 v[200:203], v158 offset:3072
	ds_read_b128 v[204:207], v158 offset:4096
	ds_read_b128 v[208:211], v158 offset:5120
	ds_read_b128 v[212:215], v158 offset:6144
	ds_read_b128 v[216:219], v158 offset:7168
	global_load_lds_dwordx4 v[220:221], off
	v_lshl_add_u64 v[220:221], s[36:37], 0, v[142:143]
	s_add_i32 m0, s31, 0xe000
	s_nop 0
	global_load_lds_dwordx4 v[220:221], off
	s_waitcnt vmcnt(8)
	s_waitcnt lgkmcnt(0)
	s_barrier
	s_setprio 1
	s_waitcnt lgkmcnt(0)
	v_mfma_f32_16x16x32_bf16 v[124:127], v[148:151], v[188:191], v[124:127]
	v_mfma_f32_16x16x32_bf16 v[120:123], v[164:167], v[188:191], v[120:123]
	v_mfma_f32_16x16x32_bf16 v[108:111], v[148:151], v[196:199], v[108:111]
	v_mfma_f32_16x16x32_bf16 v[104:107], v[164:167], v[196:199], v[104:107]
	v_mfma_f32_16x16x32_bf16 v[92:95], v[148:151], v[204:207], v[92:95]
	v_mfma_f32_16x16x32_bf16 v[88:91], v[164:167], v[204:207], v[88:91]
	v_mfma_f32_16x16x32_bf16 v[76:79], v[148:151], v[212:215], v[76:79]
	v_mfma_f32_16x16x32_bf16 v[72:75], v[164:167], v[212:215], v[72:75]
	v_mfma_f32_16x16x32_bf16 v[124:127], v[160:163], v[192:195], v[124:127]
	v_mfma_f32_16x16x32_bf16 v[120:123], v[168:171], v[192:195], v[120:123]
	v_mfma_f32_16x16x32_bf16 v[108:111], v[160:163], v[200:203], v[108:111]
	v_mfma_f32_16x16x32_bf16 v[104:107], v[168:171], v[200:203], v[104:107]
	v_mfma_f32_16x16x32_bf16 v[92:95], v[160:163], v[208:211], v[92:95]
	v_mfma_f32_16x16x32_bf16 v[88:91], v[168:171], v[208:211], v[88:91]
	v_mfma_f32_16x16x32_bf16 v[76:79], v[160:163], v[216:219], v[76:79]
	v_mfma_f32_16x16x32_bf16 v[72:75], v[168:171], v[216:219], v[72:75]
	s_setprio 0
	s_setprio 1
	v_mfma_f32_16x16x32_bf16 v[116:119], v[172:175], v[188:191], v[116:119]
	v_mfma_f32_16x16x32_bf16 v[112:115], v[180:183], v[188:191], v[112:115]
	v_mfma_f32_16x16x32_bf16 v[100:103], v[172:175], v[196:199], v[100:103]
	v_mfma_f32_16x16x32_bf16 v[96:99], v[180:183], v[196:199], v[96:99]
	v_mfma_f32_16x16x32_bf16 v[84:87], v[172:175], v[204:207], v[84:87]
	v_mfma_f32_16x16x32_bf16 v[80:83], v[180:183], v[204:207], v[80:83]
	v_mfma_f32_16x16x32_bf16 v[68:71], v[172:175], v[212:215], v[68:71]
	v_mfma_f32_16x16x32_bf16 v[64:67], v[180:183], v[212:215], v[64:67]
	v_mfma_f32_16x16x32_bf16 v[116:119], v[176:179], v[192:195], v[116:119]
	v_mfma_f32_16x16x32_bf16 v[112:115], v[184:187], v[192:195], v[112:115]
	v_mfma_f32_16x16x32_bf16 v[100:103], v[176:179], v[200:203], v[100:103]
	v_mfma_f32_16x16x32_bf16 v[96:99], v[184:187], v[200:203], v[96:99]
	v_mfma_f32_16x16x32_bf16 v[84:87], v[176:179], v[208:211], v[84:87]
	v_mfma_f32_16x16x32_bf16 v[80:83], v[184:187], v[208:211], v[80:83]
	v_mfma_f32_16x16x32_bf16 v[68:71], v[176:179], v[216:219], v[68:71]
	v_mfma_f32_16x16x32_bf16 v[64:67], v[184:187], v[216:219], v[64:67]
	s_setprio 0
	s_barrier
	s_add_i32 s34, s57, s48
	v_lshl_add_u64 v[220:221], s[38:39], 0, v[136:137]
	s_mov_b32 m0, s34
	ds_read_b128 v[188:191], v158 offset:16384
	ds_read_b128 v[192:195], v158 offset:17408
	ds_read_b128 v[196:199], v158 offset:18432
	ds_read_b128 v[200:203], v158 offset:19456
	ds_read_b128 v[204:207], v158 offset:20480
	ds_read_b128 v[208:211], v158 offset:21504
	ds_read_b128 v[212:215], v158 offset:22528
	ds_read_b128 v[216:219], v158 offset:23552
	global_load_lds_dwordx4 v[220:221], off
	s_add_i32 m0, s34, 0x2000
	s_add_u32 s34, s38, 0x40000
	v_lshl_add_u64 v[222:223], s[38:39], 0, v[132:133]
	s_addc_u32 s35, s39, 0
	s_add_i32 s79, s58, s48
	global_load_lds_dwordx4 v[222:223], off
	v_lshl_add_u64 v[224:225], s[34:35], 0, v[136:137]
	s_mov_b32 m0, s79
	v_lshl_add_u64 v[226:227], s[40:41], 0, v[134:135]
	global_load_lds_dwordx4 v[224:225], off
	v_lshl_add_u64 v[224:225], s[34:35], 0, v[132:133]
	s_add_i32 m0, s79, 0x2000
	s_nop 0
	global_load_lds_dwordx4 v[224:225], off
	v_lshl_add_u64 v[224:225], s[40:41], 0, v[138:139]
	s_mov_b32 m0, s31
	s_nop 0
	global_load_lds_dwordx4 v[224:225], off
	s_mov_b32 m0, s52
	s_nop 0
	global_load_lds_dwordx4 v[226:227], off
	s_waitcnt vmcnt(8)
	s_waitcnt lgkmcnt(0)
	s_barrier
	s_setprio 1
	s_waitcnt lgkmcnt(0)
	v_mfma_f32_16x16x32_bf16 v[60:63], v[148:151], v[188:191], v[60:63]
	v_mfma_f32_16x16x32_bf16 v[56:59], v[164:167], v[188:191], v[56:59]
	v_mfma_f32_16x16x32_bf16 v[44:47], v[148:151], v[196:199], v[44:47]
	v_mfma_f32_16x16x32_bf16 v[40:43], v[164:167], v[196:199], v[40:43]
	v_mfma_f32_16x16x32_bf16 v[28:31], v[148:151], v[204:207], v[28:31]
	v_mfma_f32_16x16x32_bf16 v[24:27], v[164:167], v[204:207], v[24:27]
	v_mfma_f32_16x16x32_bf16 v[12:15], v[148:151], v[212:215], v[12:15]
	v_mfma_f32_16x16x32_bf16 v[8:11], v[164:167], v[212:215], v[8:11]
	v_mfma_f32_16x16x32_bf16 v[60:63], v[160:163], v[192:195], v[60:63]
	v_mfma_f32_16x16x32_bf16 v[56:59], v[168:171], v[192:195], v[56:59]
	v_mfma_f32_16x16x32_bf16 v[44:47], v[160:163], v[200:203], v[44:47]
	v_mfma_f32_16x16x32_bf16 v[40:43], v[168:171], v[200:203], v[40:43]
	v_mfma_f32_16x16x32_bf16 v[28:31], v[160:163], v[208:211], v[28:31]
	v_mfma_f32_16x16x32_bf16 v[24:27], v[168:171], v[208:211], v[24:27]
	v_mfma_f32_16x16x32_bf16 v[12:15], v[160:163], v[216:219], v[12:15]
	v_mfma_f32_16x16x32_bf16 v[8:11], v[168:171], v[216:219], v[8:11]
	s_setprio 0
	s_setprio 1
	v_mfma_f32_16x16x32_bf16 v[52:55], v[172:175], v[188:191], v[52:55]
	v_mfma_f32_16x16x32_bf16 v[48:51], v[180:183], v[188:191], v[48:51]
	v_mfma_f32_16x16x32_bf16 v[36:39], v[172:175], v[196:199], v[36:39]
	v_mfma_f32_16x16x32_bf16 v[32:35], v[180:183], v[196:199], v[32:35]
	v_mfma_f32_16x16x32_bf16 v[20:23], v[172:175], v[204:207], v[20:23]
	v_mfma_f32_16x16x32_bf16 v[16:19], v[180:183], v[204:207], v[16:19]
	v_mfma_f32_16x16x32_bf16 v[4:7], v[172:175], v[212:215], v[4:7]
	v_mfma_f32_16x16x32_bf16 v[0:3], v[180:183], v[212:215], v[0:3]
	v_mfma_f32_16x16x32_bf16 v[52:55], v[176:179], v[192:195], v[52:55]
	v_mfma_f32_16x16x32_bf16 v[48:51], v[184:187], v[192:195], v[48:51]
	v_mfma_f32_16x16x32_bf16 v[36:39], v[176:179], v[200:203], v[36:39]
	v_mfma_f32_16x16x32_bf16 v[32:35], v[184:187], v[200:203], v[32:35]
	v_mfma_f32_16x16x32_bf16 v[20:23], v[176:179], v[208:211], v[20:23]
	v_mfma_f32_16x16x32_bf16 v[16:19], v[184:187], v[208:211], v[16:19]
	v_mfma_f32_16x16x32_bf16 v[4:7], v[176:179], v[216:219], v[4:7]
	v_mfma_f32_16x16x32_bf16 v[0:3], v[184:187], v[216:219], v[0:3]
	s_setprio 0
	s_barrier
	s_add_i32 s79, 0, 0x18000
	v_add_u32_e32 v159, s79, v152
	s_add_i32 s81, 0, 0x1c000
	ds_read_b128 v[148:151], v159
	ds_read_b128 v[160:163], v159 offset:1024
	ds_read_b128 v[164:167], v159 offset:2048
	ds_read_b128 v[168:171], v159 offset:3072
	v_add_u32_e32 v159, s81, v152
	ds_read_b128 v[172:175], v159
	ds_read_b128 v[176:179], v159 offset:1024
	ds_read_b128 v[180:183], v159 offset:2048
	ds_read_b128 v[184:187], v159 offset:3072
	s_add_u32 s34, s40, 0x40000
	s_addc_u32 s35, s41, 0
	s_mov_b32 m0, s53
	v_lshl_add_u64 v[228:229], s[34:35], 0, v[138:139]
	ds_read_b128 v[188:191], v158 offset:32768
	ds_read_b128 v[192:195], v158 offset:33792
	ds_read_b128 v[196:199], v158 offset:34816
	ds_read_b128 v[200:203], v158 offset:35840
	ds_read_b128 v[204:207], v158 offset:36864
	ds_read_b128 v[208:211], v158 offset:37888
	ds_read_b128 v[212:215], v158 offset:38912
	ds_read_b128 v[216:219], v158 offset:39936
	global_load_lds_dwordx4 v[228:229], off
	v_lshl_add_u64 v[228:229], s[34:35], 0, v[134:135]
	s_mov_b32 m0, s54
	s_nop 0
	global_load_lds_dwordx4 v[228:229], off
	s_waitcnt vmcnt(8)
	s_waitcnt lgkmcnt(0)
	s_barrier
	s_setprio 1
	s_waitcnt lgkmcnt(0)
	v_mfma_f32_16x16x32_bf16 v[124:127], v[148:151], v[188:191], v[124:127]
	v_mfma_f32_16x16x32_bf16 v[120:123], v[164:167], v[188:191], v[120:123]
	v_mfma_f32_16x16x32_bf16 v[108:111], v[148:151], v[196:199], v[108:111]
	v_mfma_f32_16x16x32_bf16 v[104:107], v[164:167], v[196:199], v[104:107]
	v_mfma_f32_16x16x32_bf16 v[92:95], v[148:151], v[204:207], v[92:95]
	v_mfma_f32_16x16x32_bf16 v[88:91], v[164:167], v[204:207], v[88:91]
	v_mfma_f32_16x16x32_bf16 v[76:79], v[148:151], v[212:215], v[76:79]
	v_mfma_f32_16x16x32_bf16 v[72:75], v[164:167], v[212:215], v[72:75]
	v_mfma_f32_16x16x32_bf16 v[124:127], v[160:163], v[192:195], v[124:127]
	v_mfma_f32_16x16x32_bf16 v[120:123], v[168:171], v[192:195], v[120:123]
	v_mfma_f32_16x16x32_bf16 v[108:111], v[160:163], v[200:203], v[108:111]
	v_mfma_f32_16x16x32_bf16 v[104:107], v[168:171], v[200:203], v[104:107]
	v_mfma_f32_16x16x32_bf16 v[92:95], v[160:163], v[208:211], v[92:95]
	v_mfma_f32_16x16x32_bf16 v[88:91], v[168:171], v[208:211], v[88:91]
	v_mfma_f32_16x16x32_bf16 v[76:79], v[160:163], v[216:219], v[76:79]
	v_mfma_f32_16x16x32_bf16 v[72:75], v[168:171], v[216:219], v[72:75]
	s_setprio 0
	s_setprio 1
	v_mfma_f32_16x16x32_bf16 v[116:119], v[172:175], v[188:191], v[116:119]
	v_mfma_f32_16x16x32_bf16 v[112:115], v[180:183], v[188:191], v[112:115]
	v_mfma_f32_16x16x32_bf16 v[100:103], v[172:175], v[196:199], v[100:103]
	v_mfma_f32_16x16x32_bf16 v[96:99], v[180:183], v[196:199], v[96:99]
	v_mfma_f32_16x16x32_bf16 v[84:87], v[172:175], v[204:207], v[84:87]
	v_mfma_f32_16x16x32_bf16 v[80:83], v[180:183], v[204:207], v[80:83]
	v_mfma_f32_16x16x32_bf16 v[68:71], v[172:175], v[212:215], v[68:71]
	v_mfma_f32_16x16x32_bf16 v[64:67], v[180:183], v[212:215], v[64:67]
	v_mfma_f32_16x16x32_bf16 v[116:119], v[176:179], v[192:195], v[116:119]
	v_mfma_f32_16x16x32_bf16 v[112:115], v[184:187], v[192:195], v[112:115]
	v_mfma_f32_16x16x32_bf16 v[100:103], v[176:179], v[200:203], v[100:103]
	v_mfma_f32_16x16x32_bf16 v[96:99], v[184:187], v[200:203], v[96:99]
	v_mfma_f32_16x16x32_bf16 v[84:87], v[176:179], v[208:211], v[84:87]
	v_mfma_f32_16x16x32_bf16 v[80:83], v[184:187], v[208:211], v[80:83]
	v_mfma_f32_16x16x32_bf16 v[68:71], v[176:179], v[216:219], v[68:71]
	v_mfma_f32_16x16x32_bf16 v[64:67], v[184:187], v[216:219], v[64:67]
	s_setprio 0
	s_barrier
	s_add_i32 s34, s79, s48
	v_lshl_add_u64 v[220:221], v[220:221], 0, s[6:7]
	s_mov_b32 m0, s34
	ds_read_b128 v[188:191], v158 offset:49152
	ds_read_b128 v[192:195], v158 offset:50176
	ds_read_b128 v[196:199], v158 offset:51200
	ds_read_b128 v[200:203], v158 offset:52224
	ds_read_b128 v[204:207], v158 offset:53248
	ds_read_b128 v[208:211], v158 offset:54272
	ds_read_b128 v[212:215], v158 offset:55296
	ds_read_b128 v[216:219], v158 offset:56320
	global_load_lds_dwordx4 v[220:221], off
	s_add_i32 m0, s34, 0x2000
	s_add_u32 s34, s38, 0x40080
	v_lshl_add_u64 v[220:221], v[222:223], 0, s[6:7]
	s_addc_u32 s35, s39, 0
	s_add_i32 s38, s81, s48
	global_load_lds_dwordx4 v[220:221], off
	v_lshl_add_u64 v[220:221], s[34:35], 0, v[136:137]
	s_mov_b32 m0, s38
	s_nop 0
	global_load_lds_dwordx4 v[220:221], off
	v_lshl_add_u64 v[220:221], s[34:35], 0, v[132:133]
	s_add_i32 m0, s38, 0x2000
	s_nop 0
	global_load_lds_dwordx4 v[220:221], off
	v_lshl_add_u64 v[220:221], v[224:225], 0, s[6:7]
	s_mov_b32 m0, s55
	s_nop 0
	global_load_lds_dwordx4 v[220:221], off
	v_lshl_add_u64 v[220:221], v[226:227], 0, s[6:7]
	s_mov_b32 m0, s56
	s_nop 0
	global_load_lds_dwordx4 v[220:221], off
	s_waitcnt vmcnt(8)
	s_waitcnt lgkmcnt(0)
	s_barrier
	s_setprio 1
	s_waitcnt lgkmcnt(0)
	v_mfma_f32_16x16x32_bf16 v[60:63], v[148:151], v[188:191], v[60:63]
	v_mfma_f32_16x16x32_bf16 v[56:59], v[164:167], v[188:191], v[56:59]
	v_mfma_f32_16x16x32_bf16 v[44:47], v[148:151], v[196:199], v[44:47]
	v_mfma_f32_16x16x32_bf16 v[40:43], v[164:167], v[196:199], v[40:43]
	v_mfma_f32_16x16x32_bf16 v[28:31], v[148:151], v[204:207], v[28:31]
	v_mfma_f32_16x16x32_bf16 v[24:27], v[164:167], v[204:207], v[24:27]
	v_mfma_f32_16x16x32_bf16 v[12:15], v[148:151], v[212:215], v[12:15]
	v_mfma_f32_16x16x32_bf16 v[8:11], v[164:167], v[212:215], v[8:11]
	v_mfma_f32_16x16x32_bf16 v[60:63], v[160:163], v[192:195], v[60:63]
	v_mfma_f32_16x16x32_bf16 v[56:59], v[168:171], v[192:195], v[56:59]
	v_mfma_f32_16x16x32_bf16 v[44:47], v[160:163], v[200:203], v[44:47]
	v_mfma_f32_16x16x32_bf16 v[40:43], v[168:171], v[200:203], v[40:43]
	v_mfma_f32_16x16x32_bf16 v[28:31], v[160:163], v[208:211], v[28:31]
	v_mfma_f32_16x16x32_bf16 v[24:27], v[168:171], v[208:211], v[24:27]
	v_mfma_f32_16x16x32_bf16 v[12:15], v[160:163], v[216:219], v[12:15]
	v_mfma_f32_16x16x32_bf16 v[8:11], v[168:171], v[216:219], v[8:11]
	s_setprio 0
	s_setprio 1
	v_mfma_f32_16x16x32_bf16 v[52:55], v[172:175], v[188:191], v[52:55]
	v_mfma_f32_16x16x32_bf16 v[48:51], v[180:183], v[188:191], v[48:51]
	v_mfma_f32_16x16x32_bf16 v[36:39], v[172:175], v[196:199], v[36:39]
	v_mfma_f32_16x16x32_bf16 v[32:35], v[180:183], v[196:199], v[32:35]
	v_mfma_f32_16x16x32_bf16 v[20:23], v[172:175], v[204:207], v[20:23]
	v_mfma_f32_16x16x32_bf16 v[16:19], v[180:183], v[204:207], v[16:19]
	v_mfma_f32_16x16x32_bf16 v[4:7], v[172:175], v[212:215], v[4:7]
	v_mfma_f32_16x16x32_bf16 v[0:3], v[180:183], v[212:215], v[0:3]
	v_mfma_f32_16x16x32_bf16 v[52:55], v[176:179], v[192:195], v[52:55]
	v_mfma_f32_16x16x32_bf16 v[48:51], v[184:187], v[192:195], v[48:51]
	v_mfma_f32_16x16x32_bf16 v[36:39], v[176:179], v[200:203], v[36:39]
	v_mfma_f32_16x16x32_bf16 v[32:35], v[184:187], v[200:203], v[32:35]
	v_mfma_f32_16x16x32_bf16 v[20:23], v[176:179], v[208:211], v[20:23]
	v_mfma_f32_16x16x32_bf16 v[16:19], v[184:187], v[208:211], v[16:19]
	v_mfma_f32_16x16x32_bf16 v[4:7], v[176:179], v[216:219], v[4:7]
	v_mfma_f32_16x16x32_bf16 v[0:3], v[184:187], v[216:219], v[0:3]
	s_setprio 0
	s_cmp_eq_u32 s77, s98
	s_cbranch_scc1 .Lmy_nobar_10
	s_barrier
.Lmy_nobar_10:
	s_add_i32 s77, s77, 2
	s_add_u32 s36, s36, 0x100
	s_addc_u32 s37, s37, 0
	s_add_u32 s66, s66, 0x100
	s_addc_u32 s67, s67, 0
	s_cmp_gt_u32 s77, 13
	s_cbranch_scc0 .LBB0_1059
	s_and_b64 vcc, exec, s[8:9]
	s_cbranch_vccz .LBB0_1062
	s_nop 0
.LBB0_1062:
	v_lshl_add_u32 v160, s12, 10, v153
	ds_read_b32 v162, v160
	v_lshl_or_b32 v150, s13, 7, v154
	v_lshl_add_u32 v159, s30, 8, v131
	v_ashrrev_i32_e32 v151, 31, v150
	v_mov_b64_e32 v[148:149], s[16:17]
	s_waitcnt lgkmcnt(0)
	v_pk_mul_f32 v[124:125], v[124:125], v[162:163] op_sel_hi:[1,0]
	v_pk_mul_f32 v[126:127], v[126:127], v[162:163] op_sel_hi:[1,0]
	v_pk_mul_f32 v[122:123], v[122:123], v[162:163] op_sel_hi:[1,0]
	v_pk_mul_f32 v[120:121], v[120:121], v[162:163] op_sel_hi:[1,0]
	v_pk_mul_f32 v[118:119], v[118:119], v[162:163] op_sel_hi:[1,0]
	v_pk_mul_f32 v[116:117], v[116:117], v[162:163] op_sel_hi:[1,0]
	v_mul_f32_e32 v161, 0xbfb8aa3b, v124
	v_mul_f32_e32 v163, 0xbfb8aa3b, v125
	v_exp_f32_e32 v161, v161
	v_exp_f32_e32 v163, v163
	v_mad_i64_i32 v[164:165], s[12:13], v159, s59, v[148:149]
	v_lshlrev_b64 v[150:151], 1, v[150:151]
	v_pk_mul_f32 v[166:167], v[114:115], v[162:163] op_sel_hi:[1,0]
	v_add_f32_e32 v114, 1.0, v161
	v_rcp_f32_e32 v161, v114
	v_add_f32_e32 v114, 1.0, v163
	v_rcp_f32_e32 v163, v114
	v_lshl_add_u64 v[164:165], v[164:165], 0, v[150:151]
	s_andn2_b64 vcc, exec, s[4:5]
	s_mov_b64 s[4:5], -1
	v_pk_mul_f32 v[114:115], v[112:113], v[162:163] op_sel_hi:[1,0]
	v_mul_f32_e32 v112, v124, v161
	v_mul_f32_e32 v112, v116, v112
	v_mul_f32_e32 v116, 0xbfb8aa3b, v126
	v_mul_f32_e32 v124, 0xbfb8aa3b, v127
	v_exp_f32_e32 v116, v116
	v_exp_f32_e32 v124, v124
	v_mul_f32_e32 v113, v125, v163
	v_mul_f32_e32 v113, v117, v113
	v_add_f32_e32 v116, 1.0, v116
	v_add_f32_e32 v117, 1.0, v124
	v_rcp_f32_e32 v116, v116
	v_rcp_f32_e32 v117, v117
	v_cvt_pk_bf16_f32 v112, v112, v113
	v_mul_f32_e32 v113, v126, v116
	v_mul_f32_e32 v116, v127, v117
	v_mul_f32_e32 v117, 0xbfb8aa3b, v120
	v_mul_f32_e32 v113, v118, v113
	v_exp_f32_e32 v117, v117
	v_mul_f32_e32 v118, 0xbfb8aa3b, v121
	v_exp_f32_e32 v118, v118
	v_mul_f32_e32 v116, v119, v116
	v_add_f32_e32 v117, 1.0, v117
	v_rcp_f32_e32 v117, v117
	v_add_f32_e32 v118, 1.0, v118
	v_rcp_f32_e32 v118, v118
	v_cvt_pk_bf16_f32 v113, v113, v116
	v_mul_f32_e32 v116, v120, v117
	v_mul_f32_e32 v117, 0xbfb8aa3b, v122
	v_mul_f32_e32 v114, v114, v116
	v_mul_f32_e32 v116, v121, v118
	v_exp_f32_e32 v117, v117
	v_mul_f32_e32 v118, 0xbfb8aa3b, v123
	v_exp_f32_e32 v118, v118
	v_mul_f32_e32 v115, v115, v116
	v_add_f32_e32 v116, 1.0, v117
	v_rcp_f32_e32 v116, v116
	v_add_f32_e32 v117, 1.0, v118
	v_rcp_f32_e32 v117, v117
	v_cvt_pk_bf16_f32 v114, v114, v115
	v_mul_f32_e32 v115, v122, v116
	v_mul_f32_e32 v115, v166, v115
	v_mul_f32_e32 v116, v123, v117
	v_mul_f32_e32 v116, v167, v116
	v_cvt_pk_bf16_f32 v115, v115, v116
	global_store_dwordx4 v[164:165], v[112:115], off
	ds_read_b32 v112, v160 offset:64
	s_nop 0
	v_or_b32_e32 v113, 16, v159
	v_mad_i64_i32 v[114:115], s[12:13], v113, s59, v[148:149]
	s_waitcnt lgkmcnt(0)
	v_pk_mul_f32 v[108:109], v[108:109], v[112:113] op_sel_hi:[1,0]
	v_pk_mul_f32 v[110:111], v[110:111], v[112:113] op_sel_hi:[1,0]
	v_pk_mul_f32 v[106:107], v[106:107], v[112:113] op_sel_hi:[1,0]
	v_pk_mul_f32 v[104:105], v[104:105], v[112:113] op_sel_hi:[1,0]
	v_pk_mul_f32 v[102:103], v[102:103], v[112:113] op_sel_hi:[1,0]
	v_pk_mul_f32 v[100:101], v[100:101], v[112:113] op_sel_hi:[1,0]
	v_mul_f32_e32 v113, 0xbfb8aa3b, v108
	v_exp_f32_e32 v113, v113
	v_mul_f32_e32 v116, 0xbfb8aa3b, v109
	v_exp_f32_e32 v118, v116
	v_lshl_add_u64 v[114:115], v[114:115], 0, v[150:151]
	v_pk_mul_f32 v[116:117], v[98:99], v[112:113] op_sel_hi:[1,0]
	v_add_f32_e32 v98, 1.0, v113
	v_rcp_f32_e32 v113, v98
	v_add_f32_e32 v98, 1.0, v118
	v_rcp_f32_e32 v118, v98
	v_pk_mul_f32 v[98:99], v[96:97], v[112:113] op_sel_hi:[1,0]
	v_mul_f32_e32 v96, v108, v113
	v_mul_f32_e32 v96, v100, v96
	v_mul_f32_e32 v100, 0xbfb8aa3b, v110
	v_mul_f32_e32 v108, 0xbfb8aa3b, v111
	v_exp_f32_e32 v100, v100
	v_exp_f32_e32 v108, v108
	v_mul_f32_e32 v97, v109, v118
	v_mul_f32_e32 v97, v101, v97
	v_add_f32_e32 v100, 1.0, v100
	v_add_f32_e32 v101, 1.0, v108
	v_rcp_f32_e32 v100, v100
	v_rcp_f32_e32 v101, v101
	v_cvt_pk_bf16_f32 v96, v96, v97
	v_mul_f32_e32 v97, v110, v100
	v_mul_f32_e32 v100, v111, v101
	v_mul_f32_e32 v101, 0xbfb8aa3b, v104
	v_mul_f32_e32 v97, v102, v97
	v_exp_f32_e32 v101, v101
	v_mul_f32_e32 v102, 0xbfb8aa3b, v105
	v_exp_f32_e32 v102, v102
	v_mul_f32_e32 v100, v103, v100
	v_add_f32_e32 v101, 1.0, v101
	v_rcp_f32_e32 v101, v101
	v_add_f32_e32 v102, 1.0, v102
	v_rcp_f32_e32 v102, v102
	v_cvt_pk_bf16_f32 v97, v97, v100
	v_mul_f32_e32 v100, v104, v101
	v_mul_f32_e32 v101, 0xbfb8aa3b, v106
	v_mul_f32_e32 v98, v98, v100
	v_mul_f32_e32 v100, v105, v102
	v_exp_f32_e32 v101, v101
	v_mul_f32_e32 v102, 0xbfb8aa3b, v107
	v_exp_f32_e32 v102, v102
	v_mul_f32_e32 v99, v99, v100
	v_add_f32_e32 v100, 1.0, v101
	v_rcp_f32_e32 v100, v100
	v_add_f32_e32 v101, 1.0, v102
	v_rcp_f32_e32 v101, v101
	v_cvt_pk_bf16_f32 v98, v98, v99
	v_mul_f32_e32 v99, v106, v100
	v_mul_f32_e32 v99, v116, v99
	v_mul_f32_e32 v100, v107, v101
	v_mul_f32_e32 v100, v117, v100
	v_cvt_pk_bf16_f32 v99, v99, v100
	global_store_dwordx4 v[114:115], v[96:99], off
	ds_read_b32 v96, v160 offset:128
	s_nop 0
	v_or_b32_e32 v97, 32, v159
	v_mad_i64_i32 v[98:99], s[12:13], v97, s59, v[148:149]
	s_waitcnt lgkmcnt(0)
	v_pk_mul_f32 v[92:93], v[92:93], v[96:97] op_sel_hi:[1,0]
	v_pk_mul_f32 v[94:95], v[94:95], v[96:97] op_sel_hi:[1,0]
	v_pk_mul_f32 v[90:91], v[90:91], v[96:97] op_sel_hi:[1,0]
	v_pk_mul_f32 v[88:89], v[88:89], v[96:97] op_sel_hi:[1,0]
	v_pk_mul_f32 v[86:87], v[86:87], v[96:97] op_sel_hi:[1,0]
	v_pk_mul_f32 v[84:85], v[84:85], v[96:97] op_sel_hi:[1,0]
	v_mul_f32_e32 v97, 0xbfb8aa3b, v92
	v_exp_f32_e32 v97, v97
	v_mul_f32_e32 v100, 0xbfb8aa3b, v93
	v_exp_f32_e32 v102, v100
	v_lshl_add_u64 v[98:99], v[98:99], 0, v[150:151]
	v_pk_mul_f32 v[100:101], v[82:83], v[96:97] op_sel_hi:[1,0]
	v_add_f32_e32 v82, 1.0, v97
	v_rcp_f32_e32 v97, v82
	v_add_f32_e32 v82, 1.0, v102
	v_rcp_f32_e32 v102, v82
	v_pk_mul_f32 v[82:83], v[80:81], v[96:97] op_sel_hi:[1,0]
	v_mul_f32_e32 v80, v92, v97
	v_mul_f32_e32 v80, v84, v80
	v_mul_f32_e32 v84, 0xbfb8aa3b, v94
	v_mul_f32_e32 v92, 0xbfb8aa3b, v95
	v_exp_f32_e32 v84, v84
	v_exp_f32_e32 v92, v92
	v_mul_f32_e32 v81, v93, v102
	v_mul_f32_e32 v81, v85, v81
	v_add_f32_e32 v84, 1.0, v84
	v_add_f32_e32 v85, 1.0, v92
	v_rcp_f32_e32 v84, v84
	v_rcp_f32_e32 v85, v85
	v_cvt_pk_bf16_f32 v80, v80, v81
	v_mul_f32_e32 v81, v94, v84
	v_mul_f32_e32 v84, v95, v85
	v_mul_f32_e32 v85, 0xbfb8aa3b, v88
	v_mul_f32_e32 v81, v86, v81
	v_exp_f32_e32 v85, v85
	v_mul_f32_e32 v86, 0xbfb8aa3b, v89
	v_exp_f32_e32 v86, v86
	v_mul_f32_e32 v84, v87, v84
	v_add_f32_e32 v85, 1.0, v85
	v_rcp_f32_e32 v85, v85
	v_add_f32_e32 v86, 1.0, v86
	v_rcp_f32_e32 v86, v86
	v_cvt_pk_bf16_f32 v81, v81, v84
	v_mul_f32_e32 v84, v88, v85
	v_mul_f32_e32 v85, 0xbfb8aa3b, v90
	v_mul_f32_e32 v82, v82, v84
	v_mul_f32_e32 v84, v89, v86
	v_exp_f32_e32 v85, v85
	v_mul_f32_e32 v86, 0xbfb8aa3b, v91
	v_exp_f32_e32 v86, v86
	v_mul_f32_e32 v83, v83, v84
	v_add_f32_e32 v84, 1.0, v85
	v_rcp_f32_e32 v84, v84
	v_add_f32_e32 v85, 1.0, v86
	v_rcp_f32_e32 v85, v85
	v_cvt_pk_bf16_f32 v82, v82, v83
	v_mul_f32_e32 v83, v90, v84
	v_mul_f32_e32 v83, v100, v83
	v_mul_f32_e32 v84, v91, v85
	v_mul_f32_e32 v84, v101, v84
	v_cvt_pk_bf16_f32 v83, v83, v84
	global_store_dwordx4 v[98:99], v[80:83], off
	ds_read_b32 v80, v160 offset:192
	s_nop 0
	v_or_b32_e32 v81, 48, v159
	v_mad_i64_i32 v[82:83], s[12:13], v81, s59, v[148:149]
	s_waitcnt lgkmcnt(0)
	v_pk_mul_f32 v[76:77], v[76:77], v[80:81] op_sel_hi:[1,0]
	v_pk_mul_f32 v[78:79], v[78:79], v[80:81] op_sel_hi:[1,0]
	v_pk_mul_f32 v[74:75], v[74:75], v[80:81] op_sel_hi:[1,0]
	v_pk_mul_f32 v[72:73], v[72:73], v[80:81] op_sel_hi:[1,0]
	v_pk_mul_f32 v[70:71], v[70:71], v[80:81] op_sel_hi:[1,0]
	v_pk_mul_f32 v[68:69], v[68:69], v[80:81] op_sel_hi:[1,0]
	v_mul_f32_e32 v81, 0xbfb8aa3b, v76
	v_exp_f32_e32 v81, v81
	v_mul_f32_e32 v84, 0xbfb8aa3b, v77
	v_exp_f32_e32 v86, v84
	v_lshl_add_u64 v[82:83], v[82:83], 0, v[150:151]
	v_pk_mul_f32 v[84:85], v[66:67], v[80:81] op_sel_hi:[1,0]
	v_add_f32_e32 v66, 1.0, v81
	v_rcp_f32_e32 v81, v66
	v_add_f32_e32 v66, 1.0, v86
	v_rcp_f32_e32 v86, v66
	v_pk_mul_f32 v[66:67], v[64:65], v[80:81] op_sel_hi:[1,0]
	v_mul_f32_e32 v64, v76, v81
	v_mul_f32_e32 v64, v68, v64
	v_mul_f32_e32 v68, 0xbfb8aa3b, v78
	v_mul_f32_e32 v76, 0xbfb8aa3b, v79
	v_exp_f32_e32 v68, v68
	v_exp_f32_e32 v76, v76
	v_mul_f32_e32 v65, v77, v86
	v_mul_f32_e32 v65, v69, v65
	v_add_f32_e32 v68, 1.0, v68
	v_add_f32_e32 v69, 1.0, v76
	v_rcp_f32_e32 v68, v68
	v_rcp_f32_e32 v69, v69
	v_cvt_pk_bf16_f32 v64, v64, v65
	v_mul_f32_e32 v65, v78, v68
	v_mul_f32_e32 v68, v79, v69
	v_mul_f32_e32 v69, 0xbfb8aa3b, v72
	v_mul_f32_e32 v65, v70, v65
	v_exp_f32_e32 v69, v69
	v_mul_f32_e32 v70, 0xbfb8aa3b, v73
	v_exp_f32_e32 v70, v70
	v_mul_f32_e32 v68, v71, v68
	v_add_f32_e32 v69, 1.0, v69
	v_rcp_f32_e32 v69, v69
	v_add_f32_e32 v70, 1.0, v70
	v_rcp_f32_e32 v70, v70
	v_cvt_pk_bf16_f32 v65, v65, v68
	v_mul_f32_e32 v68, v72, v69
	v_mul_f32_e32 v69, 0xbfb8aa3b, v74
	v_mul_f32_e32 v66, v66, v68
	v_mul_f32_e32 v68, v73, v70
	v_exp_f32_e32 v69, v69
	v_mul_f32_e32 v70, 0xbfb8aa3b, v75
	v_exp_f32_e32 v70, v70
	v_mul_f32_e32 v67, v67, v68
	v_add_f32_e32 v68, 1.0, v69
	v_rcp_f32_e32 v68, v68
	v_add_f32_e32 v69, 1.0, v70
	v_rcp_f32_e32 v69, v69
	v_cvt_pk_bf16_f32 v66, v66, v67
	v_mul_f32_e32 v67, v74, v68
	v_mul_f32_e32 v67, v84, v67
	v_mul_f32_e32 v68, v75, v69
	v_mul_f32_e32 v68, v85, v68
	v_cvt_pk_bf16_f32 v67, v67, v68
	global_store_dwordx4 v[82:83], v[64:67], off
	ds_read_b32 v64, v160 offset:512
	s_nop 0
	v_add_u32_e32 v65, 0x80, v159
	v_mad_i64_i32 v[66:67], s[12:13], v65, s59, v[148:149]
	s_waitcnt lgkmcnt(0)
	v_pk_mul_f32 v[60:61], v[60:61], v[64:65] op_sel_hi:[1,0]
	v_pk_mul_f32 v[62:63], v[62:63], v[64:65] op_sel_hi:[1,0]
	v_pk_mul_f32 v[58:59], v[58:59], v[64:65] op_sel_hi:[1,0]
	v_pk_mul_f32 v[56:57], v[56:57], v[64:65] op_sel_hi:[1,0]
	v_pk_mul_f32 v[54:55], v[54:55], v[64:65] op_sel_hi:[1,0]
	v_pk_mul_f32 v[52:53], v[52:53], v[64:65] op_sel_hi:[1,0]
	v_mul_f32_e32 v65, 0xbfb8aa3b, v60
	v_exp_f32_e32 v65, v65
	v_mul_f32_e32 v68, 0xbfb8aa3b, v61
	v_exp_f32_e32 v70, v68
	v_lshl_add_u64 v[66:67], v[66:67], 0, v[150:151]
	v_pk_mul_f32 v[68:69], v[50:51], v[64:65] op_sel_hi:[1,0]
	v_add_f32_e32 v50, 1.0, v65
	v_rcp_f32_e32 v65, v50
	v_add_f32_e32 v50, 1.0, v70
	v_rcp_f32_e32 v70, v50
	v_pk_mul_f32 v[50:51], v[48:49], v[64:65] op_sel_hi:[1,0]
	v_mul_f32_e32 v48, v60, v65
	v_mul_f32_e32 v48, v52, v48
	v_mul_f32_e32 v52, 0xbfb8aa3b, v62
	v_mul_f32_e32 v60, 0xbfb8aa3b, v63
	v_exp_f32_e32 v52, v52
	v_exp_f32_e32 v60, v60
	v_mul_f32_e32 v49, v61, v70
	v_mul_f32_e32 v49, v53, v49
	v_add_f32_e32 v52, 1.0, v52
	v_add_f32_e32 v53, 1.0, v60
	v_rcp_f32_e32 v52, v52
	v_rcp_f32_e32 v53, v53
	v_cvt_pk_bf16_f32 v48, v48, v49
	v_mul_f32_e32 v49, v62, v52
	v_mul_f32_e32 v52, v63, v53
	v_mul_f32_e32 v53, 0xbfb8aa3b, v56
	v_mul_f32_e32 v49, v54, v49
	v_exp_f32_e32 v53, v53
	v_mul_f32_e32 v54, 0xbfb8aa3b, v57
	v_exp_f32_e32 v54, v54
	v_mul_f32_e32 v52, v55, v52
	v_add_f32_e32 v53, 1.0, v53
	v_rcp_f32_e32 v53, v53
	v_add_f32_e32 v54, 1.0, v54
	v_rcp_f32_e32 v54, v54
	v_cvt_pk_bf16_f32 v49, v49, v52
	v_mul_f32_e32 v52, v56, v53
	v_mul_f32_e32 v53, 0xbfb8aa3b, v58
	v_mul_f32_e32 v50, v50, v52
	v_mul_f32_e32 v52, v57, v54
	v_exp_f32_e32 v53, v53
	v_mul_f32_e32 v54, 0xbfb8aa3b, v59
	v_exp_f32_e32 v54, v54
	v_mul_f32_e32 v51, v51, v52
	v_add_f32_e32 v52, 1.0, v53
	v_rcp_f32_e32 v52, v52
	v_add_f32_e32 v53, 1.0, v54
	v_rcp_f32_e32 v53, v53
	v_cvt_pk_bf16_f32 v50, v50, v51
	v_mul_f32_e32 v51, v58, v52
	v_mul_f32_e32 v51, v68, v51
	v_mul_f32_e32 v52, v59, v53
	v_mul_f32_e32 v52, v69, v52
	v_cvt_pk_bf16_f32 v51, v51, v52
	global_store_dwordx4 v[66:67], v[48:51], off
	ds_read_b32 v48, v160 offset:576
	s_nop 0
	v_add_u32_e32 v49, 0x90, v159
	v_mad_i64_i32 v[50:51], s[12:13], v49, s59, v[148:149]
	s_waitcnt lgkmcnt(0)
	v_pk_mul_f32 v[44:45], v[44:45], v[48:49] op_sel_hi:[1,0]
	v_pk_mul_f32 v[46:47], v[46:47], v[48:49] op_sel_hi:[1,0]
	v_pk_mul_f32 v[42:43], v[42:43], v[48:49] op_sel_hi:[1,0]
	v_pk_mul_f32 v[40:41], v[40:41], v[48:49] op_sel_hi:[1,0]
	v_pk_mul_f32 v[38:39], v[38:39], v[48:49] op_sel_hi:[1,0]
	v_pk_mul_f32 v[36:37], v[36:37], v[48:49] op_sel_hi:[1,0]
	v_mul_f32_e32 v49, 0xbfb8aa3b, v44
	v_exp_f32_e32 v49, v49
	v_mul_f32_e32 v52, 0xbfb8aa3b, v45
	v_exp_f32_e32 v54, v52
	v_lshl_add_u64 v[50:51], v[50:51], 0, v[150:151]
	v_pk_mul_f32 v[52:53], v[34:35], v[48:49] op_sel_hi:[1,0]
	v_add_f32_e32 v34, 1.0, v49
	v_rcp_f32_e32 v49, v34
	v_add_f32_e32 v34, 1.0, v54
	v_rcp_f32_e32 v54, v34
	v_pk_mul_f32 v[34:35], v[32:33], v[48:49] op_sel_hi:[1,0]
	v_mul_f32_e32 v32, v44, v49
	v_mul_f32_e32 v32, v36, v32
	v_mul_f32_e32 v36, 0xbfb8aa3b, v46
	v_mul_f32_e32 v44, 0xbfb8aa3b, v47
	v_exp_f32_e32 v36, v36
	v_exp_f32_e32 v44, v44
	v_mul_f32_e32 v33, v45, v54
	v_mul_f32_e32 v33, v37, v33
	v_add_f32_e32 v36, 1.0, v36
	v_add_f32_e32 v37, 1.0, v44
	v_rcp_f32_e32 v36, v36
	v_rcp_f32_e32 v37, v37
	v_cvt_pk_bf16_f32 v32, v32, v33
	v_mul_f32_e32 v33, v46, v36
	v_mul_f32_e32 v36, v47, v37
	v_mul_f32_e32 v37, 0xbfb8aa3b, v40
	v_mul_f32_e32 v33, v38, v33
	v_exp_f32_e32 v37, v37
	v_mul_f32_e32 v38, 0xbfb8aa3b, v41
	v_exp_f32_e32 v38, v38
	v_mul_f32_e32 v36, v39, v36
	v_add_f32_e32 v37, 1.0, v37
	v_rcp_f32_e32 v37, v37
	v_add_f32_e32 v38, 1.0, v38
	v_rcp_f32_e32 v38, v38
	v_cvt_pk_bf16_f32 v33, v33, v36
	v_mul_f32_e32 v36, v40, v37
	v_mul_f32_e32 v37, 0xbfb8aa3b, v42
	v_mul_f32_e32 v34, v34, v36
	v_mul_f32_e32 v36, v41, v38
	v_exp_f32_e32 v37, v37
	v_mul_f32_e32 v38, 0xbfb8aa3b, v43
	v_exp_f32_e32 v38, v38
	v_mul_f32_e32 v35, v35, v36
	v_add_f32_e32 v36, 1.0, v37
	v_rcp_f32_e32 v36, v36
	v_add_f32_e32 v37, 1.0, v38
	v_rcp_f32_e32 v37, v37
	v_cvt_pk_bf16_f32 v34, v34, v35
	v_mul_f32_e32 v35, v42, v36
	v_mul_f32_e32 v35, v52, v35
	v_mul_f32_e32 v36, v43, v37
	v_mul_f32_e32 v36, v53, v36
	v_cvt_pk_bf16_f32 v35, v35, v36
	global_store_dwordx4 v[50:51], v[32:35], off
	ds_read_b32 v32, v160 offset:640
	s_nop 0
	v_add_u32_e32 v33, 0xa0, v159
	v_mad_i64_i32 v[34:35], s[12:13], v33, s59, v[148:149]
	s_waitcnt lgkmcnt(0)
	v_pk_mul_f32 v[28:29], v[28:29], v[32:33] op_sel_hi:[1,0]
	v_pk_mul_f32 v[30:31], v[30:31], v[32:33] op_sel_hi:[1,0]
	v_pk_mul_f32 v[26:27], v[26:27], v[32:33] op_sel_hi:[1,0]
	v_pk_mul_f32 v[24:25], v[24:25], v[32:33] op_sel_hi:[1,0]
	v_pk_mul_f32 v[22:23], v[22:23], v[32:33] op_sel_hi:[1,0]
	v_pk_mul_f32 v[20:21], v[20:21], v[32:33] op_sel_hi:[1,0]
	v_mul_f32_e32 v33, 0xbfb8aa3b, v28
	v_exp_f32_e32 v33, v33
	v_mul_f32_e32 v36, 0xbfb8aa3b, v29
	v_exp_f32_e32 v38, v36
	v_lshl_add_u64 v[34:35], v[34:35], 0, v[150:151]
	v_pk_mul_f32 v[36:37], v[18:19], v[32:33] op_sel_hi:[1,0]
	v_add_f32_e32 v18, 1.0, v33
	v_rcp_f32_e32 v33, v18
	v_add_f32_e32 v18, 1.0, v38
	v_rcp_f32_e32 v38, v18
	v_pk_mul_f32 v[18:19], v[16:17], v[32:33] op_sel_hi:[1,0]
	v_mul_f32_e32 v16, v28, v33
	v_mul_f32_e32 v16, v20, v16
	v_mul_f32_e32 v20, 0xbfb8aa3b, v30
	v_mul_f32_e32 v28, 0xbfb8aa3b, v31
	v_exp_f32_e32 v20, v20
	v_exp_f32_e32 v28, v28
	v_mul_f32_e32 v17, v29, v38
	v_mul_f32_e32 v17, v21, v17
	v_add_f32_e32 v20, 1.0, v20
	v_add_f32_e32 v21, 1.0, v28
	v_rcp_f32_e32 v20, v20
	v_rcp_f32_e32 v21, v21
	v_cvt_pk_bf16_f32 v16, v16, v17
	v_mul_f32_e32 v17, v30, v20
	v_mul_f32_e32 v20, v31, v21
	v_mul_f32_e32 v21, 0xbfb8aa3b, v24
	v_mul_f32_e32 v17, v22, v17
	v_exp_f32_e32 v21, v21
	v_mul_f32_e32 v22, 0xbfb8aa3b, v25
	v_exp_f32_e32 v22, v22
	v_mul_f32_e32 v20, v23, v20
	v_add_f32_e32 v21, 1.0, v21
	v_rcp_f32_e32 v21, v21
	v_add_f32_e32 v22, 1.0, v22
	v_rcp_f32_e32 v22, v22
	v_cvt_pk_bf16_f32 v17, v17, v20
	v_mul_f32_e32 v20, v24, v21
	v_mul_f32_e32 v21, 0xbfb8aa3b, v26
	v_mul_f32_e32 v18, v18, v20
	v_mul_f32_e32 v20, v25, v22
	v_exp_f32_e32 v21, v21
	v_mul_f32_e32 v22, 0xbfb8aa3b, v27
	v_exp_f32_e32 v22, v22
	v_mul_f32_e32 v19, v19, v20
	v_add_f32_e32 v20, 1.0, v21
	v_rcp_f32_e32 v20, v20
	v_add_f32_e32 v21, 1.0, v22
	v_rcp_f32_e32 v21, v21
	v_cvt_pk_bf16_f32 v18, v18, v19
	v_mul_f32_e32 v19, v26, v20
	v_mul_f32_e32 v19, v36, v19
	v_mul_f32_e32 v20, v27, v21
	v_mul_f32_e32 v20, v37, v20
	v_cvt_pk_bf16_f32 v19, v19, v20
	global_store_dwordx4 v[34:35], v[16:19], off
	ds_read_b32 v16, v160 offset:704
	s_nop 0
	v_add_u32_e32 v17, 0xb0, v159
	v_mad_i64_i32 v[18:19], s[12:13], v17, s59, v[148:149]
	s_waitcnt lgkmcnt(0)
	v_pk_mul_f32 v[12:13], v[12:13], v[16:17] op_sel_hi:[1,0]
	v_pk_mul_f32 v[14:15], v[14:15], v[16:17] op_sel_hi:[1,0]
	v_pk_mul_f32 v[10:11], v[10:11], v[16:17] op_sel_hi:[1,0]
	v_pk_mul_f32 v[8:9], v[8:9], v[16:17] op_sel_hi:[1,0]
	v_pk_mul_f32 v[6:7], v[6:7], v[16:17] op_sel_hi:[1,0]
	v_pk_mul_f32 v[4:5], v[4:5], v[16:17] op_sel_hi:[1,0]
	v_mul_f32_e32 v17, 0xbfb8aa3b, v12
	v_exp_f32_e32 v17, v17
	v_mul_f32_e32 v20, 0xbfb8aa3b, v13
	v_exp_f32_e32 v22, v20
	v_lshl_add_u64 v[18:19], v[18:19], 0, v[150:151]
	v_pk_mul_f32 v[20:21], v[2:3], v[16:17] op_sel_hi:[1,0]
	v_add_f32_e32 v2, 1.0, v17
	v_rcp_f32_e32 v17, v2
	v_add_f32_e32 v2, 1.0, v22
	v_rcp_f32_e32 v22, v2
	v_pk_mul_f32 v[2:3], v[0:1], v[16:17] op_sel_hi:[1,0]
	v_mul_f32_e32 v0, v12, v17
	v_mul_f32_e32 v0, v4, v0
	v_mul_f32_e32 v4, 0xbfb8aa3b, v14
	v_mul_f32_e32 v12, 0xbfb8aa3b, v15
	v_exp_f32_e32 v4, v4
	v_exp_f32_e32 v12, v12
	v_mul_f32_e32 v1, v13, v22
	v_mul_f32_e32 v1, v5, v1
	v_add_f32_e32 v4, 1.0, v4
	v_add_f32_e32 v5, 1.0, v12
	v_rcp_f32_e32 v4, v4
	v_rcp_f32_e32 v5, v5
	v_cvt_pk_bf16_f32 v0, v0, v1
	v_mul_f32_e32 v1, v14, v4
	v_mul_f32_e32 v4, v15, v5
	v_mul_f32_e32 v5, 0xbfb8aa3b, v8
	v_mul_f32_e32 v1, v6, v1
	v_exp_f32_e32 v5, v5
	v_mul_f32_e32 v6, 0xbfb8aa3b, v9
	v_exp_f32_e32 v6, v6
	v_mul_f32_e32 v4, v7, v4
	v_add_f32_e32 v5, 1.0, v5
	v_rcp_f32_e32 v5, v5
	v_add_f32_e32 v6, 1.0, v6
	v_rcp_f32_e32 v6, v6
	v_cvt_pk_bf16_f32 v1, v1, v4
	v_mul_f32_e32 v4, v8, v5
	v_mul_f32_e32 v5, 0xbfb8aa3b, v10
	v_mul_f32_e32 v2, v2, v4
	v_mul_f32_e32 v4, v9, v6
	v_exp_f32_e32 v5, v5
	v_mul_f32_e32 v6, 0xbfb8aa3b, v11
	v_exp_f32_e32 v6, v6
	v_mul_f32_e32 v3, v3, v4
	v_add_f32_e32 v4, 1.0, v5
	v_rcp_f32_e32 v4, v4
	v_add_f32_e32 v5, 1.0, v6
	v_rcp_f32_e32 v5, v5
	v_cvt_pk_bf16_f32 v2, v2, v3
	v_mul_f32_e32 v3, v10, v4
	v_mul_f32_e32 v3, v20, v3
	v_mul_f32_e32 v4, v11, v5
	v_mul_f32_e32 v4, v21, v4
	v_cvt_pk_bf16_f32 v3, v3, v4
	global_store_dwordx4 v[18:19], v[0:3], off
	s_cbranch_vccnz .LBB0_1055
	s_andn2_b64 vcc, exec, s[0:1]
	s_cbranch_vccnz .LBB0_1054
	s_nop 0
	s_branch .LBB0_1054

.LBB0_1134:
	s_lshr_b32 s99, s91, 2
	s_cmp_eq_u32 s99, 1
	s_cselect_b32 s98, 40, 0x7fffffff
	s_add_i32 s58, s58, 1
	s_mul_i32 s0, s58, s53
	s_mul_hi_u32 s1, s58, s54
	s_add_i32 s1, s1, s0
	s_mul_i32 s0, s58, s54
	s_add_u32 s6, s0, s2
	s_addc_u32 s7, s1, s55
	v_cmp_gt_i64_e32 vcc, s[6:7], v[146:147]
	v_cmp_lt_i64_e64 s[0:1], s[6:7], v[144:145]
	s_cbranch_vccnz .LBB0_1140
	s_ashr_i32 s7, s6, 31
	s_lshr_b32 s7, s7, 29
	s_add_i32 s13, s6, s7
	s_and_b32 s7, s13, -8
	s_sub_i32 s28, s6, s7
	s_cmp_gt_i32 s28, -1
	s_mov_b64 s[6:7], -1
	s_cbranch_scc0 .LBB0_1137
	s_lshl_b32 s29, s28, 6
	s_mov_b64 s[6:7], 0

.LBB0_1144:
	s_add_u32 s30, s30, 0xb0080
	s_addc_u32 s31, s31, 0
	s_add_u32 s13, s36, 0x100
	v_mov_b32_e32 v0, 0
	s_addc_u32 s63, s37, 0
	s_mov_b32 s64, -2
	s_waitcnt lgkmcnt(0)
	v_mov_b32_e32 v1, v0
	v_mov_b32_e32 v2, v0
	v_mov_b32_e32 v3, v0
	v_mov_b32_e32 v4, v0
	v_mov_b32_e32 v5, v0
	v_mov_b32_e32 v6, v0
	v_mov_b32_e32 v7, v0
	v_mov_b32_e32 v16, v0
	v_mov_b32_e32 v17, v0
	v_mov_b32_e32 v18, v0
	v_mov_b32_e32 v19, v0
	v_mov_b32_e32 v20, v0
	v_mov_b32_e32 v21, v0
	v_mov_b32_e32 v22, v0
	v_mov_b32_e32 v23, v0
	v_mov_b32_e32 v32, v0
	v_mov_b32_e32 v33, v0
	v_mov_b32_e32 v34, v0
	v_mov_b32_e32 v35, v0
	v_mov_b32_e32 v36, v0
	v_mov_b32_e32 v37, v0
	v_mov_b32_e32 v38, v0
	v_mov_b32_e32 v39, v0
	v_mov_b32_e32 v48, v0
	v_mov_b32_e32 v49, v0
	v_mov_b32_e32 v50, v0
	v_mov_b32_e32 v51, v0
	v_mov_b32_e32 v52, v0
	v_mov_b32_e32 v53, v0
	v_mov_b32_e32 v54, v0
	v_mov_b32_e32 v55, v0
	v_mov_b32_e32 v8, v0
	v_mov_b32_e32 v9, v0
	v_mov_b32_e32 v10, v0
	v_mov_b32_e32 v11, v0
	v_mov_b32_e32 v12, v0
	v_mov_b32_e32 v13, v0
	v_mov_b32_e32 v14, v0
	v_mov_b32_e32 v15, v0
	v_mov_b32_e32 v24, v0
	v_mov_b32_e32 v25, v0
	v_mov_b32_e32 v26, v0
	v_mov_b32_e32 v27, v0
	v_mov_b32_e32 v28, v0
	v_mov_b32_e32 v29, v0
	v_mov_b32_e32 v30, v0
	v_mov_b32_e32 v31, v0
	v_mov_b32_e32 v40, v0
	v_mov_b32_e32 v41, v0
	v_mov_b32_e32 v42, v0
	v_mov_b32_e32 v43, v0
	v_mov_b32_e32 v44, v0
	v_mov_b32_e32 v45, v0
	v_mov_b32_e32 v46, v0
	v_mov_b32_e32 v47, v0
	v_mov_b32_e32 v56, v0
	v_mov_b32_e32 v57, v0
	v_mov_b32_e32 v58, v0
	v_mov_b32_e32 v59, v0
	v_mov_b32_e32 v60, v0
	v_mov_b32_e32 v61, v0
	v_mov_b32_e32 v62, v0
	v_mov_b32_e32 v63, v0
	v_mov_b32_e32 v64, v0
	v_mov_b32_e32 v65, v0
	v_mov_b32_e32 v66, v0
	v_mov_b32_e32 v67, v0
	v_mov_b32_e32 v68, v0
	v_mov_b32_e32 v69, v0
	v_mov_b32_e32 v70, v0
	v_mov_b32_e32 v71, v0
	v_mov_b32_e32 v80, v0
	v_mov_b32_e32 v81, v0
	v_mov_b32_e32 v82, v0
	v_mov_b32_e32 v83, v0
	v_mov_b32_e32 v84, v0
	v_mov_b32_e32 v85, v0
	v_mov_b32_e32 v86, v0
	v_mov_b32_e32 v87, v0
	v_mov_b32_e32 v96, v0
	v_mov_b32_e32 v97, v0
	v_mov_b32_e32 v98, v0
	v_mov_b32_e32 v99, v0
	v_mov_b32_e32 v100, v0
	v_mov_b32_e32 v101, v0
	v_mov_b32_e32 v102, v0
	v_mov_b32_e32 v103, v0
	v_mov_b32_e32 v112, v0
	v_mov_b32_e32 v113, v0
	v_mov_b32_e32 v114, v0
	v_mov_b32_e32 v115, v0
	v_mov_b32_e32 v116, v0
	v_mov_b32_e32 v117, v0
	v_mov_b32_e32 v118, v0
	v_mov_b32_e32 v119, v0
	v_mov_b32_e32 v72, v0
	v_mov_b32_e32 v73, v0
	v_mov_b32_e32 v74, v0
	v_mov_b32_e32 v75, v0
	v_mov_b32_e32 v76, v0
	v_mov_b32_e32 v77, v0
	v_mov_b32_e32 v78, v0
	v_mov_b32_e32 v79, v0
	v_mov_b32_e32 v88, v0
	v_mov_b32_e32 v89, v0
	v_mov_b32_e32 v90, v0
	v_mov_b32_e32 v91, v0
	v_mov_b32_e32 v92, v0
	v_mov_b32_e32 v93, v0
	v_mov_b32_e32 v94, v0
	v_mov_b32_e32 v95, v0
	v_mov_b32_e32 v104, v0
	v_mov_b32_e32 v105, v0
	v_mov_b32_e32 v106, v0
	v_mov_b32_e32 v107, v0
	v_mov_b32_e32 v108, v0
	v_mov_b32_e32 v109, v0
	v_mov_b32_e32 v110, v0
	v_mov_b32_e32 v111, v0
	v_mov_b32_e32 v120, v0
	v_mov_b32_e32 v121, v0
	v_mov_b32_e32 v122, v0
	v_mov_b32_e32 v123, v0
	v_mov_b32_e32 v124, v0
	v_mov_b32_e32 v125, v0
	v_mov_b32_e32 v126, v0
	v_mov_b32_e32 v127, v0
	s_cmp_lg_u32 s58, 1
	s_cselect_b32 s100, s99, 0
	s_cmp_lg_u32 s100, 0
	s_cbranch_scc0 .Lmy_nobar2_11
	s_barrier
.Lmy_nobar2_11:
.LBB0_1145:
	ds_read_b128 v[148:151], v154
	ds_read_b128 v[160:163], v154 offset:1024
	ds_read_b128 v[164:167], v154 offset:2048
	ds_read_b128 v[168:171], v154 offset:3072
	ds_read_b128 v[172:175], v155
	ds_read_b128 v[176:179], v155 offset:1024
	ds_read_b128 v[180:183], v155 offset:2048
	ds_read_b128 v[184:187], v155 offset:3072
	s_add_u32 s34, s30, 0xfff50080
	s_addc_u32 s35, s31, -1
	s_cmp_eq_u32 s64, 40
	s_cselect_b32 s39, s1, s35
	s_cselect_b32 s38, s0, s34
	s_cselect_b32 s37, s29, s63
	s_cselect_b32 s36, s28, s13
	v_lshl_add_u64 v[220:221], s[30:31], 0, v[140:141]
	s_add_i32 m0, s42, 0xc000
	ds_read_b128 v[188:191], v157
	ds_read_b128 v[192:195], v157 offset:1024
	ds_read_b128 v[196:199], v157 offset:2048
	ds_read_b128 v[200:203], v157 offset:3072
	ds_read_b128 v[204:207], v157 offset:4096
	ds_read_b128 v[208:211], v157 offset:5120
	ds_read_b128 v[212:215], v157 offset:6144
	ds_read_b128 v[216:219], v157 offset:7168
	global_load_lds_dwordx4 v[220:221], off
	v_lshl_add_u64 v[220:221], s[30:31], 0, v[142:143]
	s_add_i32 m0, s42, 0xe000
	s_nop 0
	global_load_lds_dwordx4 v[220:221], off
	s_waitcnt vmcnt(8)
	s_waitcnt lgkmcnt(0)
	s_barrier
	s_setprio 1
	s_waitcnt lgkmcnt(0)
	v_mfma_f32_16x16x32_bf16 v[124:127], v[148:151], v[188:191], v[124:127]
	v_mfma_f32_16x16x32_bf16 v[120:123], v[164:167], v[188:191], v[120:123]
	v_mfma_f32_16x16x32_bf16 v[108:111], v[148:151], v[196:199], v[108:111]
	v_mfma_f32_16x16x32_bf16 v[104:107], v[164:167], v[196:199], v[104:107]
	v_mfma_f32_16x16x32_bf16 v[92:95], v[148:151], v[204:207], v[92:95]
	v_mfma_f32_16x16x32_bf16 v[88:91], v[164:167], v[204:207], v[88:91]
	v_mfma_f32_16x16x32_bf16 v[76:79], v[148:151], v[212:215], v[76:79]
	v_mfma_f32_16x16x32_bf16 v[72:75], v[164:167], v[212:215], v[72:75]
	v_mfma_f32_16x16x32_bf16 v[124:127], v[160:163], v[192:195], v[124:127]
	v_mfma_f32_16x16x32_bf16 v[120:123], v[168:171], v[192:195], v[120:123]
	v_mfma_f32_16x16x32_bf16 v[108:111], v[160:163], v[200:203], v[108:111]
	v_mfma_f32_16x16x32_bf16 v[104:107], v[168:171], v[200:203], v[104:107]
	v_mfma_f32_16x16x32_bf16 v[92:95], v[160:163], v[208:211], v[92:95]
	v_mfma_f32_16x16x32_bf16 v[88:91], v[168:171], v[208:211], v[88:91]
	v_mfma_f32_16x16x32_bf16 v[76:79], v[160:163], v[216:219], v[76:79]
	v_mfma_f32_16x16x32_bf16 v[72:75], v[168:171], v[216:219], v[72:75]
	s_setprio 0
	s_setprio 1
	v_mfma_f32_16x16x32_bf16 v[116:119], v[172:175], v[188:191], v[116:119]
	v_mfma_f32_16x16x32_bf16 v[112:115], v[180:183], v[188:191], v[112:115]
	v_mfma_f32_16x16x32_bf16 v[100:103], v[172:175], v[196:199], v[100:103]
	v_mfma_f32_16x16x32_bf16 v[96:99], v[180:183], v[196:199], v[96:99]
	v_mfma_f32_16x16x32_bf16 v[84:87], v[172:175], v[204:207], v[84:87]
	v_mfma_f32_16x16x32_bf16 v[80:83], v[180:183], v[204:207], v[80:83]
	v_mfma_f32_16x16x32_bf16 v[68:71], v[172:175], v[212:215], v[68:71]
	v_mfma_f32_16x16x32_bf16 v[64:67], v[180:183], v[212:215], v[64:67]
	v_mfma_f32_16x16x32_bf16 v[116:119], v[176:179], v[192:195], v[116:119]
	v_mfma_f32_16x16x32_bf16 v[112:115], v[184:187], v[192:195], v[112:115]
	v_mfma_f32_16x16x32_bf16 v[100:103], v[176:179], v[200:203], v[100:103]
	v_mfma_f32_16x16x32_bf16 v[96:99], v[184:187], v[200:203], v[96:99]
	v_mfma_f32_16x16x32_bf16 v[84:87], v[176:179], v[208:211], v[84:87]
	v_mfma_f32_16x16x32_bf16 v[80:83], v[184:187], v[208:211], v[80:83]
	v_mfma_f32_16x16x32_bf16 v[68:71], v[176:179], v[216:219], v[68:71]
	v_mfma_f32_16x16x32_bf16 v[64:67], v[184:187], v[216:219], v[64:67]
	s_setprio 0
	s_barrier
	s_add_i32 s34, s56, s41
	v_lshl_add_u64 v[220:221], s[36:37], 0, v[134:135]
	s_mov_b32 m0, s34
	ds_read_b128 v[188:191], v157 offset:16384
	ds_read_b128 v[192:195], v157 offset:17408
	ds_read_b128 v[196:199], v157 offset:18432
	ds_read_b128 v[200:203], v157 offset:19456
	ds_read_b128 v[204:207], v157 offset:20480
	ds_read_b128 v[208:211], v157 offset:21504
	ds_read_b128 v[212:215], v157 offset:22528
	ds_read_b128 v[216:219], v157 offset:23552
	global_load_lds_dwordx4 v[220:221], off
	s_add_i32 m0, s34, 0x2000
	s_add_u32 s34, s36, 0xb0000
	v_lshl_add_u64 v[222:223], s[36:37], 0, v[138:139]
	s_addc_u32 s35, s37, 0
	s_add_i32 s65, s57, s41
	global_load_lds_dwordx4 v[222:223], off
	v_lshl_add_u64 v[224:225], s[34:35], 0, v[134:135]
	s_mov_b32 m0, s65
	v_lshl_add_u64 v[226:227], s[38:39], 0, v[136:137]
	global_load_lds_dwordx4 v[224:225], off
	v_lshl_add_u64 v[224:225], s[34:35], 0, v[138:139]
	s_add_i32 m0, s65, 0x2000
	s_nop 0
	global_load_lds_dwordx4 v[224:225], off
	v_lshl_add_u64 v[224:225], s[38:39], 0, v[132:133]
	s_mov_b32 m0, s42
	s_nop 0
	global_load_lds_dwordx4 v[224:225], off
	s_mov_b32 m0, s43
	s_nop 0
	global_load_lds_dwordx4 v[226:227], off
	s_waitcnt vmcnt(8)
	s_waitcnt lgkmcnt(0)
	s_barrier
	s_setprio 1
	s_waitcnt lgkmcnt(0)
	v_mfma_f32_16x16x32_bf16 v[60:63], v[148:151], v[188:191], v[60:63]
	v_mfma_f32_16x16x32_bf16 v[56:59], v[164:167], v[188:191], v[56:59]
	v_mfma_f32_16x16x32_bf16 v[44:47], v[148:151], v[196:199], v[44:47]
	v_mfma_f32_16x16x32_bf16 v[40:43], v[164:167], v[196:199], v[40:43]
	v_mfma_f32_16x16x32_bf16 v[28:31], v[148:151], v[204:207], v[28:31]
	v_mfma_f32_16x16x32_bf16 v[24:27], v[164:167], v[204:207], v[24:27]
	v_mfma_f32_16x16x32_bf16 v[12:15], v[148:151], v[212:215], v[12:15]
	v_mfma_f32_16x16x32_bf16 v[8:11], v[164:167], v[212:215], v[8:11]
	v_mfma_f32_16x16x32_bf16 v[60:63], v[160:163], v[192:195], v[60:63]
	v_mfma_f32_16x16x32_bf16 v[56:59], v[168:171], v[192:195], v[56:59]
	v_mfma_f32_16x16x32_bf16 v[44:47], v[160:163], v[200:203], v[44:47]
	v_mfma_f32_16x16x32_bf16 v[40:43], v[168:171], v[200:203], v[40:43]
	v_mfma_f32_16x16x32_bf16 v[28:31], v[160:163], v[208:211], v[28:31]
	v_mfma_f32_16x16x32_bf16 v[24:27], v[168:171], v[208:211], v[24:27]
	v_mfma_f32_16x16x32_bf16 v[12:15], v[160:163], v[216:219], v[12:15]
	v_mfma_f32_16x16x32_bf16 v[8:11], v[168:171], v[216:219], v[8:11]
	s_setprio 0
	s_setprio 1
	v_mfma_f32_16x16x32_bf16 v[52:55], v[172:175], v[188:191], v[52:55]
	v_mfma_f32_16x16x32_bf16 v[48:51], v[180:183], v[188:191], v[48:51]
	v_mfma_f32_16x16x32_bf16 v[36:39], v[172:175], v[196:199], v[36:39]
	v_mfma_f32_16x16x32_bf16 v[32:35], v[180:183], v[196:199], v[32:35]
	v_mfma_f32_16x16x32_bf16 v[20:23], v[172:175], v[204:207], v[20:23]
	v_mfma_f32_16x16x32_bf16 v[16:19], v[180:183], v[204:207], v[16:19]
	v_mfma_f32_16x16x32_bf16 v[4:7], v[172:175], v[212:215], v[4:7]
	v_mfma_f32_16x16x32_bf16 v[0:3], v[180:183], v[212:215], v[0:3]
	v_mfma_f32_16x16x32_bf16 v[52:55], v[176:179], v[192:195], v[52:55]
	v_mfma_f32_16x16x32_bf16 v[48:51], v[184:187], v[192:195], v[48:51]
	v_mfma_f32_16x16x32_bf16 v[36:39], v[176:179], v[200:203], v[36:39]
	v_mfma_f32_16x16x32_bf16 v[32:35], v[184:187], v[200:203], v[32:35]
	v_mfma_f32_16x16x32_bf16 v[20:23], v[176:179], v[208:211], v[20:23]
	v_mfma_f32_16x16x32_bf16 v[16:19], v[184:187], v[208:211], v[16:19]
	v_mfma_f32_16x16x32_bf16 v[4:7], v[176:179], v[216:219], v[4:7]
	v_mfma_f32_16x16x32_bf16 v[0:3], v[184:187], v[216:219], v[0:3]
	s_setprio 0
	s_barrier
	s_add_i32 s65, 0, 0x18000
	v_add_u32_e32 v159, s65, v152
	s_add_i32 s66, 0, 0x1c000
	ds_read_b128 v[148:151], v159
	ds_read_b128 v[160:163], v159 offset:1024
	ds_read_b128 v[164:167], v159 offset:2048
	ds_read_b128 v[168:171], v159 offset:3072
	v_add_u32_e32 v159, s66, v152
	ds_read_b128 v[172:175], v159
	ds_read_b128 v[176:179], v159 offset:1024
	ds_read_b128 v[180:183], v159 offset:2048
	ds_read_b128 v[184:187], v159 offset:3072
	s_add_u32 s34, s38, 0xb0000
	s_addc_u32 s35, s39, 0
	s_mov_b32 m0, s48
	v_lshl_add_u64 v[228:229], s[34:35], 0, v[132:133]
	ds_read_b128 v[188:191], v157 offset:32768
	ds_read_b128 v[192:195], v157 offset:33792
	ds_read_b128 v[196:199], v157 offset:34816
	ds_read_b128 v[200:203], v157 offset:35840
	ds_read_b128 v[204:207], v157 offset:36864
	ds_read_b128 v[208:211], v157 offset:37888
	ds_read_b128 v[212:215], v157 offset:38912
	ds_read_b128 v[216:219], v157 offset:39936
	global_load_lds_dwordx4 v[228:229], off
	v_lshl_add_u64 v[228:229], s[34:35], 0, v[136:137]
	s_mov_b32 m0, s49
	s_nop 0
	global_load_lds_dwordx4 v[228:229], off
	s_waitcnt vmcnt(8)
	s_waitcnt lgkmcnt(0)
	s_barrier
	s_setprio 1
	s_waitcnt lgkmcnt(0)
	v_mfma_f32_16x16x32_bf16 v[124:127], v[148:151], v[188:191], v[124:127]
	v_mfma_f32_16x16x32_bf16 v[120:123], v[164:167], v[188:191], v[120:123]
	v_mfma_f32_16x16x32_bf16 v[108:111], v[148:151], v[196:199], v[108:111]
	v_mfma_f32_16x16x32_bf16 v[104:107], v[164:167], v[196:199], v[104:107]
	v_mfma_f32_16x16x32_bf16 v[92:95], v[148:151], v[204:207], v[92:95]
	v_mfma_f32_16x16x32_bf16 v[88:91], v[164:167], v[204:207], v[88:91]
	v_mfma_f32_16x16x32_bf16 v[76:79], v[148:151], v[212:215], v[76:79]
	v_mfma_f32_16x16x32_bf16 v[72:75], v[164:167], v[212:215], v[72:75]
	v_mfma_f32_16x16x32_bf16 v[124:127], v[160:163], v[192:195], v[124:127]
	v_mfma_f32_16x16x32_bf16 v[120:123], v[168:171], v[192:195], v[120:123]
	v_mfma_f32_16x16x32_bf16 v[108:111], v[160:163], v[200:203], v[108:111]
	v_mfma_f32_16x16x32_bf16 v[104:107], v[168:171], v[200:203], v[104:107]
	v_mfma_f32_16x16x32_bf16 v[92:95], v[160:163], v[208:211], v[92:95]
	v_mfma_f32_16x16x32_bf16 v[88:91], v[168:171], v[208:211], v[88:91]
	v_mfma_f32_16x16x32_bf16 v[76:79], v[160:163], v[216:219], v[76:79]
	v_mfma_f32_16x16x32_bf16 v[72:75], v[168:171], v[216:219], v[72:75]
	s_setprio 0
	s_setprio 1
	v_mfma_f32_16x16x32_bf16 v[116:119], v[172:175], v[188:191], v[116:119]
	v_mfma_f32_16x16x32_bf16 v[112:115], v[180:183], v[188:191], v[112:115]
	v_mfma_f32_16x16x32_bf16 v[100:103], v[172:175], v[196:199], v[100:103]
	v_mfma_f32_16x16x32_bf16 v[96:99], v[180:183], v[196:199], v[96:99]
	v_mfma_f32_16x16x32_bf16 v[84:87], v[172:175], v[204:207], v[84:87]
	v_mfma_f32_16x16x32_bf16 v[80:83], v[180:183], v[204:207], v[80:83]
	v_mfma_f32_16x16x32_bf16 v[68:71], v[172:175], v[212:215], v[68:71]
	v_mfma_f32_16x16x32_bf16 v[64:67], v[180:183], v[212:215], v[64:67]
	v_mfma_f32_16x16x32_bf16 v[116:119], v[176:179], v[192:195], v[116:119]
	v_mfma_f32_16x16x32_bf16 v[112:115], v[184:187], v[192:195], v[112:115]
	v_mfma_f32_16x16x32_bf16 v[100:103], v[176:179], v[200:203], v[100:103]
	v_mfma_f32_16x16x32_bf16 v[96:99], v[184:187], v[200:203], v[96:99]
	v_mfma_f32_16x16x32_bf16 v[84:87], v[176:179], v[208:211], v[84:87]
	v_mfma_f32_16x16x32_bf16 v[80:83], v[184:187], v[208:211], v[80:83]
	v_mfma_f32_16x16x32_bf16 v[68:71], v[176:179], v[216:219], v[68:71]
	v_mfma_f32_16x16x32_bf16 v[64:67], v[184:187], v[216:219], v[64:67]
	s_setprio 0
	s_barrier
	s_add_i32 s34, s65, s41
	v_lshl_add_u64 v[220:221], v[220:221], 0, s[22:23]
	s_mov_b32 m0, s34
	ds_read_b128 v[188:191], v157 offset:49152
	ds_read_b128 v[192:195], v157 offset:50176
	ds_read_b128 v[196:199], v157 offset:51200
	ds_read_b128 v[200:203], v157 offset:52224
	ds_read_b128 v[204:207], v157 offset:53248
	ds_read_b128 v[208:211], v157 offset:54272
	ds_read_b128 v[212:215], v157 offset:55296
	ds_read_b128 v[216:219], v157 offset:56320
	global_load_lds_dwordx4 v[220:221], off
	s_add_i32 m0, s34, 0x2000
	s_add_u32 s34, s36, 0xb0080
	v_lshl_add_u64 v[220:221], v[222:223], 0, s[22:23]
	s_addc_u32 s35, s37, 0
	s_add_i32 s36, s66, s41
	global_load_lds_dwordx4 v[220:221], off
	v_lshl_add_u64 v[220:221], s[34:35], 0, v[134:135]
	s_mov_b32 m0, s36
	s_nop 0
	global_load_lds_dwordx4 v[220:221], off
	v_lshl_add_u64 v[220:221], s[34:35], 0, v[138:139]
	s_add_i32 m0, s36, 0x2000
	s_nop 0
	global_load_lds_dwordx4 v[220:221], off
	v_lshl_add_u64 v[220:221], v[224:225], 0, s[22:23]
	s_mov_b32 m0, s51
	s_nop 0
	global_load_lds_dwordx4 v[220:221], off
	v_lshl_add_u64 v[220:221], v[226:227], 0, s[22:23]
	s_mov_b32 m0, s52
	s_nop 0
	global_load_lds_dwordx4 v[220:221], off
	s_waitcnt vmcnt(8)
	s_waitcnt lgkmcnt(0)
	s_barrier
	s_setprio 1
	s_waitcnt lgkmcnt(0)
	v_mfma_f32_16x16x32_bf16 v[60:63], v[148:151], v[188:191], v[60:63]
	v_mfma_f32_16x16x32_bf16 v[56:59], v[164:167], v[188:191], v[56:59]
	v_mfma_f32_16x16x32_bf16 v[44:47], v[148:151], v[196:199], v[44:47]
	v_mfma_f32_16x16x32_bf16 v[40:43], v[164:167], v[196:199], v[40:43]
	v_mfma_f32_16x16x32_bf16 v[28:31], v[148:151], v[204:207], v[28:31]
	v_mfma_f32_16x16x32_bf16 v[24:27], v[164:167], v[204:207], v[24:27]
	v_mfma_f32_16x16x32_bf16 v[12:15], v[148:151], v[212:215], v[12:15]
	v_mfma_f32_16x16x32_bf16 v[8:11], v[164:167], v[212:215], v[8:11]
	v_mfma_f32_16x16x32_bf16 v[60:63], v[160:163], v[192:195], v[60:63]
	v_mfma_f32_16x16x32_bf16 v[56:59], v[168:171], v[192:195], v[56:59]
	v_mfma_f32_16x16x32_bf16 v[44:47], v[160:163], v[200:203], v[44:47]
	v_mfma_f32_16x16x32_bf16 v[40:43], v[168:171], v[200:203], v[40:43]
	v_mfma_f32_16x16x32_bf16 v[28:31], v[160:163], v[208:211], v[28:31]
	v_mfma_f32_16x16x32_bf16 v[24:27], v[168:171], v[208:211], v[24:27]
	v_mfma_f32_16x16x32_bf16 v[12:15], v[160:163], v[216:219], v[12:15]
	v_mfma_f32_16x16x32_bf16 v[8:11], v[168:171], v[216:219], v[8:11]
	s_setprio 0
	s_setprio 1
	v_mfma_f32_16x16x32_bf16 v[52:55], v[172:175], v[188:191], v[52:55]
	v_mfma_f32_16x16x32_bf16 v[48:51], v[180:183], v[188:191], v[48:51]
	v_mfma_f32_16x16x32_bf16 v[36:39], v[172:175], v[196:199], v[36:39]
	v_mfma_f32_16x16x32_bf16 v[32:35], v[180:183], v[196:199], v[32:35]
	v_mfma_f32_16x16x32_bf16 v[20:23], v[172:175], v[204:207], v[20:23]
	v_mfma_f32_16x16x32_bf16 v[16:19], v[180:183], v[204:207], v[16:19]
	v_mfma_f32_16x16x32_bf16 v[4:7], v[172:175], v[212:215], v[4:7]
	v_mfma_f32_16x16x32_bf16 v[0:3], v[180:183], v[212:215], v[0:3]
	v_mfma_f32_16x16x32_bf16 v[52:55], v[176:179], v[192:195], v[52:55]
	v_mfma_f32_16x16x32_bf16 v[48:51], v[184:187], v[192:195], v[48:51]
	v_mfma_f32_16x16x32_bf16 v[36:39], v[176:179], v[200:203], v[36:39]
	v_mfma_f32_16x16x32_bf16 v[32:35], v[184:187], v[200:203], v[32:35]
	v_mfma_f32_16x16x32_bf16 v[20:23], v[176:179], v[208:211], v[20:23]
	v_mfma_f32_16x16x32_bf16 v[16:19], v[184:187], v[208:211], v[16:19]
	v_mfma_f32_16x16x32_bf16 v[4:7], v[176:179], v[216:219], v[4:7]
	v_mfma_f32_16x16x32_bf16 v[0:3], v[184:187], v[216:219], v[0:3]
	s_setprio 0
	s_cmp_eq_u32 s64, s98
	s_cbranch_scc1 .Lmy_nobar_11
	s_barrier
.Lmy_nobar_11:
	s_add_i32 s64, s64, 2
	s_add_u32 s30, s30, 0x100
	s_addc_u32 s31, s31, 0
	s_add_u32 s13, s13, 0x100
	s_addc_u32 s63, s63, 0
	s_cmp_gt_u32 s64, 41
	s_cbranch_scc0 .LBB0_1145
	s_and_b64 vcc, exec, s[26:27]
	s_cbranch_vccz .LBB0_1148
	s_nop 0

.LBB0_1164:
	s_or_b64 exec, exec, s[36:37]
	s_and_b64 vcc, exec, s[6:7]
	s_mov_b64 s[6:7], -1
	s_cbranch_vccnz .LBB0_1133
	s_andn2_b64 vcc, exec, s[10:11]
	s_cbranch_vccnz .LBB0_1132
	s_nop 0
	s_branch .LBB0_1132

.LBB0_1232:
	s_lshr_b32 s99, s91, 2
	s_cmp_eq_u32 s99, 1
	s_cselect_b32 s98, 12, 0x7fffffff
	s_add_i32 s58, s58, 1
	s_mul_i32 s4, s58, s42
	s_mul_hi_u32 s5, s58, s43
	s_add_i32 s5, s5, s4
	s_mul_i32 s4, s58, s43
	s_add_u32 s26, s4, s2
	s_addc_u32 s27, s5, s3
	v_cmp_gt_i64_e32 vcc, s[26:27], v[146:147]
	v_cmp_lt_i64_e64 s[4:5], s[26:27], v[144:145]
	s_cbranch_vccnz .LBB0_1234
	s_ashr_i32 s10, s26, 31
	s_lshr_b32 s10, s10, 29
	s_add_i32 s10, s26, s10
	s_ashr_i32 s11, s10, 3
	s_and_b32 s10, s10, -8
	s_sub_i32 s10, s26, s10
	s_cmp_lt_i32 s10, 0
	s_cselect_b32 s22, s51, 0xc0
	s_mul_i32 s10, s10, s22
	s_add_i32 s10, s10, s11
	s_mul_hi_i32 s11, s10, 0x2aaaaaab
	s_lshr_b32 s22, s11, 31
	s_ashr_i32 s11, s11, 4
	s_add_i32 s11, s11, s22
	s_lshl_b32 s22, s11, 3
	s_sub_i32 s23, 0x80, s22
	s_min_i32 s23, s23, 8
	s_abs_i32 s26, s23
	v_cvt_f32_u32_e32 v0, s26
	s_sub_i32 s28, 0, s26
	s_mulk_i32 s11, 0x60
	s_sub_i32 s11, s10, s11
	v_rcp_iflag_f32_e32 v0, v0
	s_abs_i32 s10, s11
	s_xor_b32 s27, s11, s23
	s_ashr_i32 s27, s27, 31
	v_mul_f32_e32 v0, 0x4f7ffffe, v0
	v_cvt_u32_f32_e32 v0, v0
	s_mov_b32 s59, s58
	v_readfirstlane_b32 s29, v0
	s_mul_i32 s28, s28, s29
	s_mul_hi_u32 s28, s29, s28
	s_add_i32 s29, s29, s28
	s_mul_hi_u32 s28, s10, s29
	s_mul_i32 s29, s28, s26
	s_sub_i32 s10, s10, s29
	s_add_i32 s34, s28, 1
	s_sub_i32 s29, s10, s26
	s_cmp_ge_u32 s10, s26
	s_cselect_b32 s28, s34, s28
	s_cselect_b32 s10, s29, s10
	s_add_i32 s29, s28, 1
	s_cmp_ge_u32 s10, s26
	s_cselect_b32 s10, s29, s28
	s_xor_b32 s10, s10, s27
	s_sub_i32 s10, s10, s27
	s_mul_i32 s23, s10, s23
	s_sub_i32 s11, s11, s23
	s_add_i32 s22, s22, s11
.LBB0_1234:
	s_ashr_i32 s23, s22, 31
	s_lshl_b64 s[26:27], s[22:23], 19
	s_add_u32 s26, s14, s26
	s_addc_u32 s27, s15, s27
	s_and_b64 s[28:29], s[4:5], exec
	s_cselect_b32 s23, s27, s37
	s_cselect_b32 s64, s26, s36
	s_ashr_i32 s11, s10, 31
	s_lshl_b64 s[28:29], s[10:11], 19
	s_add_u32 s28, s49, s28
	s_addc_u32 s29, s50, s29
	s_and_b64 s[34:35], s[4:5], exec
	s_cselect_b32 s11, s29, s39
	s_cselect_b32 s65, s28, s38
	s_add_u32 s36, s36, 0x40080
	s_addc_u32 s37, s37, 0
	s_add_u32 s66, s38, 0x100
	v_mov_b32_e32 v0, 0
	s_addc_u32 s67, s39, 0
	s_mov_b32 s77, -2
	v_mov_b32_e32 v1, v0
	v_mov_b32_e32 v2, v0
	v_mov_b32_e32 v3, v0
	v_mov_b32_e32 v4, v0
	v_mov_b32_e32 v5, v0
	v_mov_b32_e32 v6, v0
	v_mov_b32_e32 v7, v0
	v_mov_b32_e32 v16, v0
	v_mov_b32_e32 v17, v0
	v_mov_b32_e32 v18, v0
	v_mov_b32_e32 v19, v0
	v_mov_b32_e32 v20, v0
	v_mov_b32_e32 v21, v0
	v_mov_b32_e32 v22, v0
	v_mov_b32_e32 v23, v0
	v_mov_b32_e32 v32, v0
	v_mov_b32_e32 v33, v0
	v_mov_b32_e32 v34, v0
	v_mov_b32_e32 v35, v0
	v_mov_b32_e32 v36, v0
	v_mov_b32_e32 v37, v0
	v_mov_b32_e32 v38, v0
	v_mov_b32_e32 v39, v0
	v_mov_b32_e32 v48, v0
	v_mov_b32_e32 v49, v0
	v_mov_b32_e32 v50, v0
	v_mov_b32_e32 v51, v0
	v_mov_b32_e32 v52, v0
	v_mov_b32_e32 v53, v0
	v_mov_b32_e32 v54, v0
	v_mov_b32_e32 v55, v0
	v_mov_b32_e32 v8, v0
	v_mov_b32_e32 v9, v0
	v_mov_b32_e32 v10, v0
	v_mov_b32_e32 v11, v0
	v_mov_b32_e32 v12, v0
	v_mov_b32_e32 v13, v0
	v_mov_b32_e32 v14, v0
	v_mov_b32_e32 v15, v0
	v_mov_b32_e32 v24, v0
	v_mov_b32_e32 v25, v0
	v_mov_b32_e32 v26, v0
	v_mov_b32_e32 v27, v0
	v_mov_b32_e32 v28, v0
	v_mov_b32_e32 v29, v0
	v_mov_b32_e32 v30, v0
	v_mov_b32_e32 v31, v0
	v_mov_b32_e32 v40, v0
	v_mov_b32_e32 v41, v0
	v_mov_b32_e32 v42, v0
	v_mov_b32_e32 v43, v0
	v_mov_b32_e32 v44, v0
	v_mov_b32_e32 v45, v0
	v_mov_b32_e32 v46, v0
	v_mov_b32_e32 v47, v0
	v_mov_b32_e32 v56, v0
	v_mov_b32_e32 v57, v0
	v_mov_b32_e32 v58, v0
	v_mov_b32_e32 v59, v0
	v_mov_b32_e32 v60, v0
	v_mov_b32_e32 v61, v0
	v_mov_b32_e32 v62, v0
	v_mov_b32_e32 v63, v0
	v_mov_b32_e32 v64, v0
	v_mov_b32_e32 v65, v0
	v_mov_b32_e32 v66, v0
	v_mov_b32_e32 v67, v0
	v_mov_b32_e32 v68, v0
	v_mov_b32_e32 v69, v0
	v_mov_b32_e32 v70, v0
	v_mov_b32_e32 v71, v0
	v_mov_b32_e32 v80, v0
	v_mov_b32_e32 v81, v0
	v_mov_b32_e32 v82, v0
	v_mov_b32_e32 v83, v0
	v_mov_b32_e32 v84, v0
	v_mov_b32_e32 v85, v0
	v_mov_b32_e32 v86, v0
	v_mov_b32_e32 v87, v0
	v_mov_b32_e32 v96, v0
	v_mov_b32_e32 v97, v0
	v_mov_b32_e32 v98, v0
	v_mov_b32_e32 v99, v0
	v_mov_b32_e32 v100, v0
	v_mov_b32_e32 v101, v0
	v_mov_b32_e32 v102, v0
	v_mov_b32_e32 v103, v0
	v_mov_b32_e32 v112, v0
	v_mov_b32_e32 v113, v0
	v_mov_b32_e32 v114, v0
	v_mov_b32_e32 v115, v0
	v_mov_b32_e32 v116, v0
	v_mov_b32_e32 v117, v0
	v_mov_b32_e32 v118, v0
	v_mov_b32_e32 v119, v0
	v_mov_b32_e32 v72, v0
	v_mov_b32_e32 v73, v0
	v_mov_b32_e32 v74, v0
	v_mov_b32_e32 v75, v0
	v_mov_b32_e32 v76, v0
	v_mov_b32_e32 v77, v0
	v_mov_b32_e32 v78, v0
	v_mov_b32_e32 v79, v0
	v_mov_b32_e32 v88, v0
	v_mov_b32_e32 v89, v0
	v_mov_b32_e32 v90, v0
	v_mov_b32_e32 v91, v0
	v_mov_b32_e32 v92, v0
	v_mov_b32_e32 v93, v0
	v_mov_b32_e32 v94, v0
	v_mov_b32_e32 v95, v0
	v_mov_b32_e32 v104, v0
	v_mov_b32_e32 v105, v0
	v_mov_b32_e32 v106, v0
	v_mov_b32_e32 v107, v0
	v_mov_b32_e32 v108, v0
	v_mov_b32_e32 v109, v0
	v_mov_b32_e32 v110, v0
	v_mov_b32_e32 v111, v0
	v_mov_b32_e32 v120, v0
	v_mov_b32_e32 v121, v0
	v_mov_b32_e32 v122, v0
	v_mov_b32_e32 v123, v0
	v_mov_b32_e32 v124, v0
	v_mov_b32_e32 v125, v0
	v_mov_b32_e32 v126, v0
	v_mov_b32_e32 v127, v0
	s_cmp_lg_u32 s58, 1
	s_cselect_b32 s100, s99, 0
	s_cmp_lg_u32 s100, 0
	s_cbranch_scc0 .Lmy_nobar2_12
	s_barrier
.Lmy_nobar2_12:
.LBB0_1235:
	ds_read_b128 v[148:151], v155
	ds_read_b128 v[160:163], v155 offset:1024
	ds_read_b128 v[164:167], v155 offset:2048
	ds_read_b128 v[168:171], v155 offset:3072
	ds_read_b128 v[172:175], v157
	ds_read_b128 v[176:179], v157 offset:1024
	ds_read_b128 v[180:183], v157 offset:2048
	ds_read_b128 v[184:187], v157 offset:3072
	s_add_u32 s34, s36, 0xfffc0080
	s_addc_u32 s35, s37, -1
	s_cmp_eq_u32 s77, 12
	s_cselect_b32 s41, s23, s35
	s_cselect_b32 s40, s64, s34
	s_cselect_b32 s39, s11, s67
	s_cselect_b32 s38, s65, s66
	v_lshl_add_u64 v[220:221], s[36:37], 0, v[140:141]
	s_add_i32 m0, s31, 0xc000
	ds_read_b128 v[188:191], v158
	ds_read_b128 v[192:195], v158 offset:1024
	ds_read_b128 v[196:199], v158 offset:2048
	ds_read_b128 v[200:203], v158 offset:3072
	ds_read_b128 v[204:207], v158 offset:4096
	ds_read_b128 v[208:211], v158 offset:5120
	ds_read_b128 v[212:215], v158 offset:6144
	ds_read_b128 v[216:219], v158 offset:7168
	global_load_lds_dwordx4 v[220:221], off
	v_lshl_add_u64 v[220:221], s[36:37], 0, v[142:143]
	s_add_i32 m0, s31, 0xe000
	s_nop 0
	global_load_lds_dwordx4 v[220:221], off
	s_waitcnt vmcnt(8)
	s_waitcnt lgkmcnt(0)
	s_barrier
	s_setprio 1
	s_waitcnt lgkmcnt(0)
	v_mfma_f32_16x16x32_bf16 v[124:127], v[148:151], v[188:191], v[124:127]
	v_mfma_f32_16x16x32_bf16 v[120:123], v[164:167], v[188:191], v[120:123]
	v_mfma_f32_16x16x32_bf16 v[108:111], v[148:151], v[196:199], v[108:111]
	v_mfma_f32_16x16x32_bf16 v[104:107], v[164:167], v[196:199], v[104:107]
	v_mfma_f32_16x16x32_bf16 v[92:95], v[148:151], v[204:207], v[92:95]
	v_mfma_f32_16x16x32_bf16 v[88:91], v[164:167], v[204:207], v[88:91]
	v_mfma_f32_16x16x32_bf16 v[76:79], v[148:151], v[212:215], v[76:79]
	v_mfma_f32_16x16x32_bf16 v[72:75], v[164:167], v[212:215], v[72:75]
	v_mfma_f32_16x16x32_bf16 v[124:127], v[160:163], v[192:195], v[124:127]
	v_mfma_f32_16x16x32_bf16 v[120:123], v[168:171], v[192:195], v[120:123]
	v_mfma_f32_16x16x32_bf16 v[108:111], v[160:163], v[200:203], v[108:111]
	v_mfma_f32_16x16x32_bf16 v[104:107], v[168:171], v[200:203], v[104:107]
	v_mfma_f32_16x16x32_bf16 v[92:95], v[160:163], v[208:211], v[92:95]
	v_mfma_f32_16x16x32_bf16 v[88:91], v[168:171], v[208:211], v[88:91]
	v_mfma_f32_16x16x32_bf16 v[76:79], v[160:163], v[216:219], v[76:79]
	v_mfma_f32_16x16x32_bf16 v[72:75], v[168:171], v[216:219], v[72:75]
	s_setprio 0
	s_setprio 1
	v_mfma_f32_16x16x32_bf16 v[116:119], v[172:175], v[188:191], v[116:119]
	v_mfma_f32_16x16x32_bf16 v[112:115], v[180:183], v[188:191], v[112:115]
	v_mfma_f32_16x16x32_bf16 v[100:103], v[172:175], v[196:199], v[100:103]
	v_mfma_f32_16x16x32_bf16 v[96:99], v[180:183], v[196:199], v[96:99]
	v_mfma_f32_16x16x32_bf16 v[84:87], v[172:175], v[204:207], v[84:87]
	v_mfma_f32_16x16x32_bf16 v[80:83], v[180:183], v[204:207], v[80:83]
	v_mfma_f32_16x16x32_bf16 v[68:71], v[172:175], v[212:215], v[68:71]
	v_mfma_f32_16x16x32_bf16 v[64:67], v[180:183], v[212:215], v[64:67]
	v_mfma_f32_16x16x32_bf16 v[116:119], v[176:179], v[192:195], v[116:119]
	v_mfma_f32_16x16x32_bf16 v[112:115], v[184:187], v[192:195], v[112:115]
	v_mfma_f32_16x16x32_bf16 v[100:103], v[176:179], v[200:203], v[100:103]
	v_mfma_f32_16x16x32_bf16 v[96:99], v[184:187], v[200:203], v[96:99]
	v_mfma_f32_16x16x32_bf16 v[84:87], v[176:179], v[208:211], v[84:87]
	v_mfma_f32_16x16x32_bf16 v[80:83], v[184:187], v[208:211], v[80:83]
	v_mfma_f32_16x16x32_bf16 v[68:71], v[176:179], v[216:219], v[68:71]
	v_mfma_f32_16x16x32_bf16 v[64:67], v[184:187], v[216:219], v[64:67]
	s_setprio 0
	s_barrier
	s_add_i32 s34, s55, s48
	v_lshl_add_u64 v[220:221], s[38:39], 0, v[136:137]
	s_mov_b32 m0, s34
	ds_read_b128 v[188:191], v158 offset:16384
	ds_read_b128 v[192:195], v158 offset:17408
	ds_read_b128 v[196:199], v158 offset:18432
	ds_read_b128 v[200:203], v158 offset:19456
	ds_read_b128 v[204:207], v158 offset:20480
	ds_read_b128 v[208:211], v158 offset:21504
	ds_read_b128 v[212:215], v158 offset:22528
	ds_read_b128 v[216:219], v158 offset:23552
	global_load_lds_dwordx4 v[220:221], off
	s_add_i32 m0, s34, 0x2000
	s_add_u32 s34, s38, 0x40000
	v_lshl_add_u64 v[222:223], s[38:39], 0, v[132:133]
	s_addc_u32 s35, s39, 0
	s_add_i32 s79, s56, s48
	global_load_lds_dwordx4 v[222:223], off
	v_lshl_add_u64 v[224:225], s[34:35], 0, v[136:137]
	s_mov_b32 m0, s79
	v_lshl_add_u64 v[226:227], s[40:41], 0, v[134:135]
	global_load_lds_dwordx4 v[224:225], off
	v_lshl_add_u64 v[224:225], s[34:35], 0, v[132:133]
	s_add_i32 m0, s79, 0x2000
	s_nop 0
	global_load_lds_dwordx4 v[224:225], off
	v_lshl_add_u64 v[224:225], s[40:41], 0, v[138:139]
	s_mov_b32 m0, s31
	s_nop 0
	global_load_lds_dwordx4 v[224:225], off
	s_mov_b32 m0, s52
	s_nop 0
	global_load_lds_dwordx4 v[226:227], off
	s_waitcnt vmcnt(8)
	s_waitcnt lgkmcnt(0)
	s_barrier
	s_setprio 1
	s_waitcnt lgkmcnt(0)
	v_mfma_f32_16x16x32_bf16 v[60:63], v[148:151], v[188:191], v[60:63]
	v_mfma_f32_16x16x32_bf16 v[56:59], v[164:167], v[188:191], v[56:59]
	v_mfma_f32_16x16x32_bf16 v[44:47], v[148:151], v[196:199], v[44:47]
	v_mfma_f32_16x16x32_bf16 v[40:43], v[164:167], v[196:199], v[40:43]
	v_mfma_f32_16x16x32_bf16 v[28:31], v[148:151], v[204:207], v[28:31]
	v_mfma_f32_16x16x32_bf16 v[24:27], v[164:167], v[204:207], v[24:27]
	v_mfma_f32_16x16x32_bf16 v[12:15], v[148:151], v[212:215], v[12:15]
	v_mfma_f32_16x16x32_bf16 v[8:11], v[164:167], v[212:215], v[8:11]
	v_mfma_f32_16x16x32_bf16 v[60:63], v[160:163], v[192:195], v[60:63]
	v_mfma_f32_16x16x32_bf16 v[56:59], v[168:171], v[192:195], v[56:59]
	v_mfma_f32_16x16x32_bf16 v[44:47], v[160:163], v[200:203], v[44:47]
	v_mfma_f32_16x16x32_bf16 v[40:43], v[168:171], v[200:203], v[40:43]
	v_mfma_f32_16x16x32_bf16 v[28:31], v[160:163], v[208:211], v[28:31]
	v_mfma_f32_16x16x32_bf16 v[24:27], v[168:171], v[208:211], v[24:27]
	v_mfma_f32_16x16x32_bf16 v[12:15], v[160:163], v[216:219], v[12:15]
	v_mfma_f32_16x16x32_bf16 v[8:11], v[168:171], v[216:219], v[8:11]
	s_setprio 0
	s_setprio 1
	v_mfma_f32_16x16x32_bf16 v[52:55], v[172:175], v[188:191], v[52:55]
	v_mfma_f32_16x16x32_bf16 v[48:51], v[180:183], v[188:191], v[48:51]
	v_mfma_f32_16x16x32_bf16 v[36:39], v[172:175], v[196:199], v[36:39]
	v_mfma_f32_16x16x32_bf16 v[32:35], v[180:183], v[196:199], v[32:35]
	v_mfma_f32_16x16x32_bf16 v[20:23], v[172:175], v[204:207], v[20:23]
	v_mfma_f32_16x16x32_bf16 v[16:19], v[180:183], v[204:207], v[16:19]
	v_mfma_f32_16x16x32_bf16 v[4:7], v[172:175], v[212:215], v[4:7]
	v_mfma_f32_16x16x32_bf16 v[0:3], v[180:183], v[212:215], v[0:3]
	v_mfma_f32_16x16x32_bf16 v[52:55], v[176:179], v[192:195], v[52:55]
	v_mfma_f32_16x16x32_bf16 v[48:51], v[184:187], v[192:195], v[48:51]
	v_mfma_f32_16x16x32_bf16 v[36:39], v[176:179], v[200:203], v[36:39]
	v_mfma_f32_16x16x32_bf16 v[32:35], v[184:187], v[200:203], v[32:35]
	v_mfma_f32_16x16x32_bf16 v[20:23], v[176:179], v[208:211], v[20:23]
	v_mfma_f32_16x16x32_bf16 v[16:19], v[184:187], v[208:211], v[16:19]
	v_mfma_f32_16x16x32_bf16 v[4:7], v[176:179], v[216:219], v[4:7]
	v_mfma_f32_16x16x32_bf16 v[0:3], v[184:187], v[216:219], v[0:3]
	s_setprio 0
	s_barrier
	s_add_i32 s79, 0, 0x18000
	v_add_u32_e32 v159, s79, v152
	s_add_i32 s81, 0, 0x1c000
	ds_read_b128 v[148:151], v159
	ds_read_b128 v[160:163], v159 offset:1024
	ds_read_b128 v[164:167], v159 offset:2048
	ds_read_b128 v[168:171], v159 offset:3072
	v_add_u32_e32 v159, s81, v152
	ds_read_b128 v[172:175], v159
	ds_read_b128 v[176:179], v159 offset:1024
	ds_read_b128 v[180:183], v159 offset:2048
	ds_read_b128 v[184:187], v159 offset:3072
	s_add_u32 s34, s40, 0x40000
	s_addc_u32 s35, s41, 0
	s_mov_b32 m0, s53
	v_lshl_add_u64 v[228:229], s[34:35], 0, v[138:139]
	ds_read_b128 v[188:191], v158 offset:32768
	ds_read_b128 v[192:195], v158 offset:33792
	ds_read_b128 v[196:199], v158 offset:34816
	ds_read_b128 v[200:203], v158 offset:35840
	ds_read_b128 v[204:207], v158 offset:36864
	ds_read_b128 v[208:211], v158 offset:37888
	ds_read_b128 v[212:215], v158 offset:38912
	ds_read_b128 v[216:219], v158 offset:39936
	global_load_lds_dwordx4 v[228:229], off
	v_lshl_add_u64 v[228:229], s[34:35], 0, v[134:135]
	s_mov_b32 m0, s54
	s_nop 0
	global_load_lds_dwordx4 v[228:229], off
	s_waitcnt vmcnt(8)
	s_waitcnt lgkmcnt(0)
	s_barrier
	s_setprio 1
	s_waitcnt lgkmcnt(0)
	v_mfma_f32_16x16x32_bf16 v[124:127], v[148:151], v[188:191], v[124:127]
	v_mfma_f32_16x16x32_bf16 v[120:123], v[164:167], v[188:191], v[120:123]
	v_mfma_f32_16x16x32_bf16 v[108:111], v[148:151], v[196:199], v[108:111]
	v_mfma_f32_16x16x32_bf16 v[104:107], v[164:167], v[196:199], v[104:107]
	v_mfma_f32_16x16x32_bf16 v[92:95], v[148:151], v[204:207], v[92:95]
	v_mfma_f32_16x16x32_bf16 v[88:91], v[164:167], v[204:207], v[88:91]
	v_mfma_f32_16x16x32_bf16 v[76:79], v[148:151], v[212:215], v[76:79]
	v_mfma_f32_16x16x32_bf16 v[72:75], v[164:167], v[212:215], v[72:75]
	v_mfma_f32_16x16x32_bf16 v[124:127], v[160:163], v[192:195], v[124:127]
	v_mfma_f32_16x16x32_bf16 v[120:123], v[168:171], v[192:195], v[120:123]
	v_mfma_f32_16x16x32_bf16 v[108:111], v[160:163], v[200:203], v[108:111]
	v_mfma_f32_16x16x32_bf16 v[104:107], v[168:171], v[200:203], v[104:107]
	v_mfma_f32_16x16x32_bf16 v[92:95], v[160:163], v[208:211], v[92:95]
	v_mfma_f32_16x16x32_bf16 v[88:91], v[168:171], v[208:211], v[88:91]
	v_mfma_f32_16x16x32_bf16 v[76:79], v[160:163], v[216:219], v[76:79]
	v_mfma_f32_16x16x32_bf16 v[72:75], v[168:171], v[216:219], v[72:75]
	s_setprio 0
	s_setprio 1
	v_mfma_f32_16x16x32_bf16 v[116:119], v[172:175], v[188:191], v[116:119]
	v_mfma_f32_16x16x32_bf16 v[112:115], v[180:183], v[188:191], v[112:115]
	v_mfma_f32_16x16x32_bf16 v[100:103], v[172:175], v[196:199], v[100:103]
	v_mfma_f32_16x16x32_bf16 v[96:99], v[180:183], v[196:199], v[96:99]
	v_mfma_f32_16x16x32_bf16 v[84:87], v[172:175], v[204:207], v[84:87]
	v_mfma_f32_16x16x32_bf16 v[80:83], v[180:183], v[204:207], v[80:83]
	v_mfma_f32_16x16x32_bf16 v[68:71], v[172:175], v[212:215], v[68:71]
	v_mfma_f32_16x16x32_bf16 v[64:67], v[180:183], v[212:215], v[64:67]
	v_mfma_f32_16x16x32_bf16 v[116:119], v[176:179], v[192:195], v[116:119]
	v_mfma_f32_16x16x32_bf16 v[112:115], v[184:187], v[192:195], v[112:115]
	v_mfma_f32_16x16x32_bf16 v[100:103], v[176:179], v[200:203], v[100:103]
	v_mfma_f32_16x16x32_bf16 v[96:99], v[184:187], v[200:203], v[96:99]
	v_mfma_f32_16x16x32_bf16 v[84:87], v[176:179], v[208:211], v[84:87]
	v_mfma_f32_16x16x32_bf16 v[80:83], v[184:187], v[208:211], v[80:83]
	v_mfma_f32_16x16x32_bf16 v[68:71], v[176:179], v[216:219], v[68:71]
	v_mfma_f32_16x16x32_bf16 v[64:67], v[184:187], v[216:219], v[64:67]
	s_setprio 0
	s_barrier
	s_add_i32 s34, s79, s48
	v_lshl_add_u64 v[220:221], v[220:221], 0, s[6:7]
	s_mov_b32 m0, s34
	ds_read_b128 v[188:191], v158 offset:49152
	ds_read_b128 v[192:195], v158 offset:50176
	ds_read_b128 v[196:199], v158 offset:51200
	ds_read_b128 v[200:203], v158 offset:52224
	ds_read_b128 v[204:207], v158 offset:53248
	ds_read_b128 v[208:211], v158 offset:54272
	ds_read_b128 v[212:215], v158 offset:55296
	ds_read_b128 v[216:219], v158 offset:56320
	global_load_lds_dwordx4 v[220:221], off
	s_add_i32 m0, s34, 0x2000
	s_add_u32 s34, s38, 0x40080
	v_lshl_add_u64 v[220:221], v[222:223], 0, s[6:7]
	s_addc_u32 s35, s39, 0
	s_add_i32 s38, s81, s48
	global_load_lds_dwordx4 v[220:221], off
	v_lshl_add_u64 v[220:221], s[34:35], 0, v[136:137]
	s_mov_b32 m0, s38
	s_nop 0
	global_load_lds_dwordx4 v[220:221], off
	v_lshl_add_u64 v[220:221], s[34:35], 0, v[132:133]
	s_add_i32 m0, s38, 0x2000
	s_nop 0
	global_load_lds_dwordx4 v[220:221], off
	v_lshl_add_u64 v[220:221], v[224:225], 0, s[6:7]
	s_mov_b32 m0, s12
	s_nop 0
	global_load_lds_dwordx4 v[220:221], off
	v_lshl_add_u64 v[220:221], v[226:227], 0, s[6:7]
	s_mov_b32 m0, s13
	s_nop 0
	global_load_lds_dwordx4 v[220:221], off
	s_waitcnt vmcnt(8)
	s_waitcnt lgkmcnt(0)
	s_barrier
	s_setprio 1
	s_waitcnt lgkmcnt(0)
	v_mfma_f32_16x16x32_bf16 v[60:63], v[148:151], v[188:191], v[60:63]
	v_mfma_f32_16x16x32_bf16 v[56:59], v[164:167], v[188:191], v[56:59]
	v_mfma_f32_16x16x32_bf16 v[44:47], v[148:151], v[196:199], v[44:47]
	v_mfma_f32_16x16x32_bf16 v[40:43], v[164:167], v[196:199], v[40:43]
	v_mfma_f32_16x16x32_bf16 v[28:31], v[148:151], v[204:207], v[28:31]
	v_mfma_f32_16x16x32_bf16 v[24:27], v[164:167], v[204:207], v[24:27]
	v_mfma_f32_16x16x32_bf16 v[12:15], v[148:151], v[212:215], v[12:15]
	v_mfma_f32_16x16x32_bf16 v[8:11], v[164:167], v[212:215], v[8:11]
	v_mfma_f32_16x16x32_bf16 v[60:63], v[160:163], v[192:195], v[60:63]
	v_mfma_f32_16x16x32_bf16 v[56:59], v[168:171], v[192:195], v[56:59]
	v_mfma_f32_16x16x32_bf16 v[44:47], v[160:163], v[200:203], v[44:47]
	v_mfma_f32_16x16x32_bf16 v[40:43], v[168:171], v[200:203], v[40:43]
	v_mfma_f32_16x16x32_bf16 v[28:31], v[160:163], v[208:211], v[28:31]
	v_mfma_f32_16x16x32_bf16 v[24:27], v[168:171], v[208:211], v[24:27]
	v_mfma_f32_16x16x32_bf16 v[12:15], v[160:163], v[216:219], v[12:15]
	v_mfma_f32_16x16x32_bf16 v[8:11], v[168:171], v[216:219], v[8:11]
	s_setprio 0
	s_setprio 1
	v_mfma_f32_16x16x32_bf16 v[52:55], v[172:175], v[188:191], v[52:55]
	v_mfma_f32_16x16x32_bf16 v[48:51], v[180:183], v[188:191], v[48:51]
	v_mfma_f32_16x16x32_bf16 v[36:39], v[172:175], v[196:199], v[36:39]
	v_mfma_f32_16x16x32_bf16 v[32:35], v[180:183], v[196:199], v[32:35]
	v_mfma_f32_16x16x32_bf16 v[20:23], v[172:175], v[204:207], v[20:23]
	v_mfma_f32_16x16x32_bf16 v[16:19], v[180:183], v[204:207], v[16:19]
	v_mfma_f32_16x16x32_bf16 v[4:7], v[172:175], v[212:215], v[4:7]
	v_mfma_f32_16x16x32_bf16 v[0:3], v[180:183], v[212:215], v[0:3]
	v_mfma_f32_16x16x32_bf16 v[52:55], v[176:179], v[192:195], v[52:55]
	v_mfma_f32_16x16x32_bf16 v[48:51], v[184:187], v[192:195], v[48:51]
	v_mfma_f32_16x16x32_bf16 v[36:39], v[176:179], v[200:203], v[36:39]
	v_mfma_f32_16x16x32_bf16 v[32:35], v[184:187], v[200:203], v[32:35]
	v_mfma_f32_16x16x32_bf16 v[20:23], v[176:179], v[208:211], v[20:23]
	v_mfma_f32_16x16x32_bf16 v[16:19], v[184:187], v[208:211], v[16:19]
	v_mfma_f32_16x16x32_bf16 v[4:7], v[176:179], v[216:219], v[4:7]
	v_mfma_f32_16x16x32_bf16 v[0:3], v[184:187], v[216:219], v[0:3]
	s_setprio 0
	s_cmp_eq_u32 s77, s98
	s_cbranch_scc1 .Lmy_nobar_12
	s_barrier

.LBB0_1238:
	v_lshl_add_u32 v161, s62, 10, v153
	ds_read_b32 v160, v161
	v_lshl_or_b32 v150, s63, 8, v154
	v_lshl_add_u32 v159, s30, 8, v131
	v_ashrrev_i32_e32 v151, 31, v150
	v_mov_b64_e32 v[148:149], s[16:17]
	v_mad_i64_i32 v[162:163], s[34:35], v159, s57, v[148:149]
	v_lshlrev_b64 v[150:151], 1, v[150:151]
	v_lshl_add_u64 v[162:163], v[162:163], 0, v[150:151]
	s_waitcnt lgkmcnt(0)
	v_pk_mul_f32 v[126:127], v[126:127], v[160:161] op_sel_hi:[1,0]
	v_pk_mul_f32 v[124:125], v[124:125], v[160:161] op_sel_hi:[1,0]
	v_pk_mul_f32 v[164:165], v[122:123], v[160:161] op_sel_hi:[1,0]
	v_pk_mul_f32 v[122:123], v[120:121], v[160:161] op_sel_hi:[1,0]
	v_cvt_pk_bf16_f32 v120, v124, v125
	v_cvt_pk_bf16_f32 v121, v126, v127
	v_pk_mul_f32 v[116:117], v[116:117], v[160:161] op_sel_hi:[1,0]
	v_cvt_pk_bf16_f32 v122, v122, v123
	v_cvt_pk_bf16_f32 v123, v164, v165
	global_store_dwordx4 v[162:163], v[120:123], off
	v_pk_mul_f32 v[118:119], v[118:119], v[160:161] op_sel_hi:[1,0]
	s_andn2_b64 vcc, exec, s[4:5]
	v_pk_mul_f32 v[120:121], v[114:115], v[160:161] op_sel_hi:[1,0]
	v_pk_mul_f32 v[114:115], v[112:113], v[160:161] op_sel_hi:[1,0]
	v_cvt_pk_bf16_f32 v112, v116, v117
	v_cvt_pk_bf16_f32 v113, v118, v119
	s_mov_b64 s[4:5], -1
	v_cvt_pk_bf16_f32 v114, v114, v115
	v_cvt_pk_bf16_f32 v115, v120, v121
	global_store_dwordx4 v[162:163], v[112:115], off offset:256
	ds_read_b32 v112, v161 offset:64
	s_nop 0
	v_or_b32_e32 v113, 16, v159
	v_mad_i64_i32 v[114:115], s[34:35], v113, s57, v[148:149]
	v_lshl_add_u64 v[114:115], v[114:115], 0, v[150:151]
	s_waitcnt lgkmcnt(0)
	v_pk_mul_f32 v[110:111], v[110:111], v[112:113] op_sel_hi:[1,0]
	v_pk_mul_f32 v[108:109], v[108:109], v[112:113] op_sel_hi:[1,0]
	v_pk_mul_f32 v[116:117], v[106:107], v[112:113] op_sel_hi:[1,0]
	v_pk_mul_f32 v[106:107], v[104:105], v[112:113] op_sel_hi:[1,0]
	v_cvt_pk_bf16_f32 v104, v108, v109
	v_cvt_pk_bf16_f32 v105, v110, v111
	v_pk_mul_f32 v[100:101], v[100:101], v[112:113] op_sel_hi:[1,0]
	v_cvt_pk_bf16_f32 v106, v106, v107
	v_cvt_pk_bf16_f32 v107, v116, v117
	global_store_dwordx4 v[114:115], v[104:107], off
	v_pk_mul_f32 v[102:103], v[102:103], v[112:113] op_sel_hi:[1,0]
	s_nop 0
	v_pk_mul_f32 v[104:105], v[98:99], v[112:113] op_sel_hi:[1,0]
	v_pk_mul_f32 v[98:99], v[96:97], v[112:113] op_sel_hi:[1,0]
	v_cvt_pk_bf16_f32 v96, v100, v101
	v_cvt_pk_bf16_f32 v97, v102, v103
	s_nop 0
	v_cvt_pk_bf16_f32 v98, v98, v99
	v_cvt_pk_bf16_f32 v99, v104, v105
	global_store_dwordx4 v[114:115], v[96:99], off offset:256
	ds_read_b32 v96, v161 offset:128
	s_nop 0
	v_or_b32_e32 v97, 32, v159
	v_mad_i64_i32 v[98:99], s[34:35], v97, s57, v[148:149]
	v_lshl_add_u64 v[98:99], v[98:99], 0, v[150:151]
	s_waitcnt lgkmcnt(0)
	v_pk_mul_f32 v[94:95], v[94:95], v[96:97] op_sel_hi:[1,0]
	v_pk_mul_f32 v[92:93], v[92:93], v[96:97] op_sel_hi:[1,0]
	v_pk_mul_f32 v[100:101], v[90:91], v[96:97] op_sel_hi:[1,0]
	v_pk_mul_f32 v[90:91], v[88:89], v[96:97] op_sel_hi:[1,0]
	v_cvt_pk_bf16_f32 v88, v92, v93
	v_cvt_pk_bf16_f32 v89, v94, v95
	v_pk_mul_f32 v[84:85], v[84:85], v[96:97] op_sel_hi:[1,0]
	v_cvt_pk_bf16_f32 v90, v90, v91
	v_cvt_pk_bf16_f32 v91, v100, v101
	global_store_dwordx4 v[98:99], v[88:91], off
	v_pk_mul_f32 v[86:87], v[86:87], v[96:97] op_sel_hi:[1,0]
	s_nop 0
	v_pk_mul_f32 v[88:89], v[82:83], v[96:97] op_sel_hi:[1,0]
	v_pk_mul_f32 v[82:83], v[80:81], v[96:97] op_sel_hi:[1,0]
	v_cvt_pk_bf16_f32 v80, v84, v85
	v_cvt_pk_bf16_f32 v81, v86, v87
	s_nop 0
	v_cvt_pk_bf16_f32 v82, v82, v83
	v_cvt_pk_bf16_f32 v83, v88, v89
	global_store_dwordx4 v[98:99], v[80:83], off offset:256
	ds_read_b32 v80, v161 offset:192
	s_nop 0
	v_or_b32_e32 v81, 48, v159
	v_mad_i64_i32 v[82:83], s[34:35], v81, s57, v[148:149]
	v_lshl_add_u64 v[82:83], v[82:83], 0, v[150:151]
	s_waitcnt lgkmcnt(0)
	v_pk_mul_f32 v[78:79], v[78:79], v[80:81] op_sel_hi:[1,0]
	v_pk_mul_f32 v[76:77], v[76:77], v[80:81] op_sel_hi:[1,0]
	v_pk_mul_f32 v[84:85], v[74:75], v[80:81] op_sel_hi:[1,0]
	v_pk_mul_f32 v[74:75], v[72:73], v[80:81] op_sel_hi:[1,0]
	v_cvt_pk_bf16_f32 v72, v76, v77
	v_cvt_pk_bf16_f32 v73, v78, v79
	v_pk_mul_f32 v[68:69], v[68:69], v[80:81] op_sel_hi:[1,0]
	v_cvt_pk_bf16_f32 v74, v74, v75
	v_cvt_pk_bf16_f32 v75, v84, v85
	global_store_dwordx4 v[82:83], v[72:75], off
	v_pk_mul_f32 v[70:71], v[70:71], v[80:81] op_sel_hi:[1,0]
	s_nop 0
	v_pk_mul_f32 v[72:73], v[66:67], v[80:81] op_sel_hi:[1,0]
	v_pk_mul_f32 v[66:67], v[64:65], v[80:81] op_sel_hi:[1,0]
	v_cvt_pk_bf16_f32 v64, v68, v69
	v_cvt_pk_bf16_f32 v65, v70, v71
	s_nop 0
	v_cvt_pk_bf16_f32 v66, v66, v67
	v_cvt_pk_bf16_f32 v67, v72, v73
	global_store_dwordx4 v[82:83], v[64:67], off offset:256
	ds_read_b32 v64, v161 offset:512
	s_nop 0
	v_add_u32_e32 v65, 0x80, v159
	v_mad_i64_i32 v[66:67], s[34:35], v65, s57, v[148:149]
	v_lshl_add_u64 v[66:67], v[66:67], 0, v[150:151]
	s_waitcnt lgkmcnt(0)
	v_pk_mul_f32 v[62:63], v[62:63], v[64:65] op_sel_hi:[1,0]
	v_pk_mul_f32 v[60:61], v[60:61], v[64:65] op_sel_hi:[1,0]
	v_pk_mul_f32 v[68:69], v[58:59], v[64:65] op_sel_hi:[1,0]
	v_pk_mul_f32 v[58:59], v[56:57], v[64:65] op_sel_hi:[1,0]
	v_cvt_pk_bf16_f32 v56, v60, v61
	v_cvt_pk_bf16_f32 v57, v62, v63
	v_pk_mul_f32 v[52:53], v[52:53], v[64:65] op_sel_hi:[1,0]
	v_cvt_pk_bf16_f32 v58, v58, v59
	v_cvt_pk_bf16_f32 v59, v68, v69
	global_store_dwordx4 v[66:67], v[56:59], off
	v_pk_mul_f32 v[54:55], v[54:55], v[64:65] op_sel_hi:[1,0]
	s_nop 0
	v_pk_mul_f32 v[56:57], v[50:51], v[64:65] op_sel_hi:[1,0]
	v_pk_mul_f32 v[50:51], v[48:49], v[64:65] op_sel_hi:[1,0]
	v_cvt_pk_bf16_f32 v48, v52, v53
	v_cvt_pk_bf16_f32 v49, v54, v55
	s_nop 0
	v_cvt_pk_bf16_f32 v50, v50, v51
	v_cvt_pk_bf16_f32 v51, v56, v57
	global_store_dwordx4 v[66:67], v[48:51], off offset:256
	ds_read_b32 v48, v161 offset:576
	s_nop 0
	v_add_u32_e32 v49, 0x90, v159
	v_mad_i64_i32 v[50:51], s[34:35], v49, s57, v[148:149]
	v_lshl_add_u64 v[50:51], v[50:51], 0, v[150:151]
	s_waitcnt lgkmcnt(0)
	v_pk_mul_f32 v[46:47], v[46:47], v[48:49] op_sel_hi:[1,0]
	v_pk_mul_f32 v[44:45], v[44:45], v[48:49] op_sel_hi:[1,0]
	v_pk_mul_f32 v[52:53], v[42:43], v[48:49] op_sel_hi:[1,0]
	v_pk_mul_f32 v[42:43], v[40:41], v[48:49] op_sel_hi:[1,0]
	v_cvt_pk_bf16_f32 v40, v44, v45
	v_cvt_pk_bf16_f32 v41, v46, v47
	v_pk_mul_f32 v[36:37], v[36:37], v[48:49] op_sel_hi:[1,0]
	v_cvt_pk_bf16_f32 v42, v42, v43
	v_cvt_pk_bf16_f32 v43, v52, v53
	global_store_dwordx4 v[50:51], v[40:43], off
	v_pk_mul_f32 v[38:39], v[38:39], v[48:49] op_sel_hi:[1,0]
	s_nop 0
	v_pk_mul_f32 v[40:41], v[34:35], v[48:49] op_sel_hi:[1,0]
	v_pk_mul_f32 v[34:35], v[32:33], v[48:49] op_sel_hi:[1,0]
	v_cvt_pk_bf16_f32 v32, v36, v37
	v_cvt_pk_bf16_f32 v33, v38, v39
	s_nop 0
	v_cvt_pk_bf16_f32 v34, v34, v35
	v_cvt_pk_bf16_f32 v35, v40, v41
	global_store_dwordx4 v[50:51], v[32:35], off offset:256
	ds_read_b32 v32, v161 offset:640
	s_nop 0
	v_add_u32_e32 v33, 0xa0, v159
	v_mad_i64_i32 v[34:35], s[34:35], v33, s57, v[148:149]
	v_lshl_add_u64 v[34:35], v[34:35], 0, v[150:151]
	s_waitcnt lgkmcnt(0)
	v_pk_mul_f32 v[30:31], v[30:31], v[32:33] op_sel_hi:[1,0]
	v_pk_mul_f32 v[28:29], v[28:29], v[32:33] op_sel_hi:[1,0]
	v_pk_mul_f32 v[36:37], v[26:27], v[32:33] op_sel_hi:[1,0]
	v_pk_mul_f32 v[26:27], v[24:25], v[32:33] op_sel_hi:[1,0]
	v_cvt_pk_bf16_f32 v24, v28, v29
	v_cvt_pk_bf16_f32 v25, v30, v31
	v_pk_mul_f32 v[20:21], v[20:21], v[32:33] op_sel_hi:[1,0]
	v_cvt_pk_bf16_f32 v26, v26, v27
	v_cvt_pk_bf16_f32 v27, v36, v37
	global_store_dwordx4 v[34:35], v[24:27], off
	v_pk_mul_f32 v[22:23], v[22:23], v[32:33] op_sel_hi:[1,0]
	s_nop 0
	v_pk_mul_f32 v[24:25], v[18:19], v[32:33] op_sel_hi:[1,0]
	v_pk_mul_f32 v[18:19], v[16:17], v[32:33] op_sel_hi:[1,0]
	v_cvt_pk_bf16_f32 v16, v20, v21
	v_cvt_pk_bf16_f32 v17, v22, v23
	s_nop 0
	v_cvt_pk_bf16_f32 v18, v18, v19
	v_cvt_pk_bf16_f32 v19, v24, v25
	global_store_dwordx4 v[34:35], v[16:19], off offset:256
	ds_read_b32 v16, v161 offset:704
	s_nop 0
	v_add_u32_e32 v17, 0xb0, v159
	v_mad_i64_i32 v[18:19], s[34:35], v17, s57, v[148:149]
	v_lshl_add_u64 v[18:19], v[18:19], 0, v[150:151]
	s_waitcnt lgkmcnt(0)
	v_pk_mul_f32 v[14:15], v[14:15], v[16:17] op_sel_hi:[1,0]
	v_pk_mul_f32 v[12:13], v[12:13], v[16:17] op_sel_hi:[1,0]
	v_pk_mul_f32 v[20:21], v[10:11], v[16:17] op_sel_hi:[1,0]
	v_pk_mul_f32 v[10:11], v[8:9], v[16:17] op_sel_hi:[1,0]
	v_cvt_pk_bf16_f32 v8, v12, v13
	v_cvt_pk_bf16_f32 v9, v14, v15
	v_pk_mul_f32 v[6:7], v[6:7], v[16:17] op_sel_hi:[1,0]
	v_cvt_pk_bf16_f32 v10, v10, v11
	v_cvt_pk_bf16_f32 v11, v20, v21
	global_store_dwordx4 v[18:19], v[8:11], off
	v_pk_mul_f32 v[4:5], v[4:5], v[16:17] op_sel_hi:[1,0]
	s_nop 0
	v_pk_mul_f32 v[8:9], v[2:3], v[16:17] op_sel_hi:[1,0]
	v_pk_mul_f32 v[2:3], v[0:1], v[16:17] op_sel_hi:[1,0]
	v_cvt_pk_bf16_f32 v0, v4, v5
	v_cvt_pk_bf16_f32 v1, v6, v7
	s_nop 0
	v_cvt_pk_bf16_f32 v2, v2, v3
	v_cvt_pk_bf16_f32 v3, v8, v9
	global_store_dwordx4 v[18:19], v[0:3], off offset:256
	s_cbranch_vccnz .LBB0_1231
	s_andn2_b64 vcc, exec, s[0:1]
	s_cbranch_vccnz .LBB0_1230
	s_nop 0
	s_branch .LBB0_1230

.LBB0_1550:
	s_lshr_b32 s99, s91, 2
	s_cmp_eq_u32 s99, 1
	s_cselect_b32 s98, 12, 0x7fffffff
	s_add_i32 s60, s60, 1
	s_mul_i32 s6, s60, s55
	s_mul_hi_u32 s7, s60, s56
	s_add_i32 s7, s7, s6
	s_mul_i32 s6, s60, s56
	s_add_u32 s30, s6, s2
	s_addc_u32 s31, s7, s57
	v_cmp_gt_i64_e32 vcc, s[30:31], v[144:145]
	v_cmp_lt_i64_e64 s[6:7], s[30:31], v[142:143]
	s_cbranch_vccnz .LBB0_1556
	s_ashr_i32 s12, s30, 31
	s_lshr_b32 s12, s12, 29
	s_add_i32 s12, s30, s12
	s_and_b32 s13, s12, -8
	s_sub_i32 s13, s30, s13
	s_cmp_gt_i32 s13, -1
	s_mov_b64 s[26:27], -1
	s_cbranch_scc0 .LBB0_1553
	s_lshl_b32 s28, s13, 6
	s_mov_b64 s[26:27], 0

.LBB0_1556:
	s_ashr_i32 s29, s28, 31
	s_lshl_b64 s[12:13], s[28:29], 19
	s_add_u32 s30, s20, s12
	s_addc_u32 s31, s21, s13
	s_and_b64 s[12:13], s[6:7], exec
	s_cselect_b32 s12, s31, s41
	s_cselect_b32 s13, s30, s40
	s_ashr_i32 s27, s26, 31
	s_lshl_b64 s[34:35], s[26:27], 19
	s_add_u32 s36, s3, s34
	s_addc_u32 s37, s46, s35
	s_and_b64 s[34:35], s[6:7], exec
	s_cselect_b32 s27, s37, s43
	s_cselect_b32 s29, s36, s42
	s_add_u32 s40, s40, 0x40080
	s_addc_u32 s41, s41, 0
	s_add_u32 s39, s42, 0x100
	v_mov_b32_e32 v0, 0
	s_addc_u32 s61, s43, 0
	s_mov_b32 s62, -2
	s_waitcnt lgkmcnt(0)
	v_mov_b32_e32 v1, v0
	v_mov_b32_e32 v2, v0
	v_mov_b32_e32 v3, v0
	v_mov_b32_e32 v4, v0
	v_mov_b32_e32 v5, v0
	v_mov_b32_e32 v6, v0
	v_mov_b32_e32 v7, v0
	v_mov_b32_e32 v16, v0
	v_mov_b32_e32 v17, v0
	v_mov_b32_e32 v18, v0
	v_mov_b32_e32 v19, v0
	v_mov_b32_e32 v20, v0
	v_mov_b32_e32 v21, v0
	v_mov_b32_e32 v22, v0
	v_mov_b32_e32 v23, v0
	v_mov_b32_e32 v32, v0
	v_mov_b32_e32 v33, v0
	v_mov_b32_e32 v34, v0
	v_mov_b32_e32 v35, v0
	v_mov_b32_e32 v36, v0
	v_mov_b32_e32 v37, v0
	v_mov_b32_e32 v38, v0
	v_mov_b32_e32 v39, v0
	v_mov_b32_e32 v48, v0
	v_mov_b32_e32 v49, v0
	v_mov_b32_e32 v50, v0
	v_mov_b32_e32 v51, v0
	v_mov_b32_e32 v52, v0
	v_mov_b32_e32 v53, v0
	v_mov_b32_e32 v54, v0
	v_mov_b32_e32 v55, v0
	v_mov_b32_e32 v8, v0
	v_mov_b32_e32 v9, v0
	v_mov_b32_e32 v10, v0
	v_mov_b32_e32 v11, v0
	v_mov_b32_e32 v12, v0
	v_mov_b32_e32 v13, v0
	v_mov_b32_e32 v14, v0
	v_mov_b32_e32 v15, v0
	v_mov_b32_e32 v24, v0
	v_mov_b32_e32 v25, v0
	v_mov_b32_e32 v26, v0
	v_mov_b32_e32 v27, v0
	v_mov_b32_e32 v28, v0
	v_mov_b32_e32 v29, v0
	v_mov_b32_e32 v30, v0
	v_mov_b32_e32 v31, v0
	v_mov_b32_e32 v40, v0
	v_mov_b32_e32 v41, v0
	v_mov_b32_e32 v42, v0
	v_mov_b32_e32 v43, v0
	v_mov_b32_e32 v44, v0
	v_mov_b32_e32 v45, v0
	v_mov_b32_e32 v46, v0
	v_mov_b32_e32 v47, v0
	v_mov_b32_e32 v56, v0
	v_mov_b32_e32 v57, v0
	v_mov_b32_e32 v58, v0
	v_mov_b32_e32 v59, v0
	v_mov_b32_e32 v60, v0
	v_mov_b32_e32 v61, v0
	v_mov_b32_e32 v62, v0
	v_mov_b32_e32 v63, v0
	v_mov_b32_e32 v64, v0
	v_mov_b32_e32 v65, v0
	v_mov_b32_e32 v66, v0
	v_mov_b32_e32 v67, v0
	v_mov_b32_e32 v68, v0
	v_mov_b32_e32 v69, v0
	v_mov_b32_e32 v70, v0
	v_mov_b32_e32 v71, v0
	v_mov_b32_e32 v80, v0
	v_mov_b32_e32 v81, v0
	v_mov_b32_e32 v82, v0
	v_mov_b32_e32 v83, v0
	v_mov_b32_e32 v84, v0
	v_mov_b32_e32 v85, v0
	v_mov_b32_e32 v86, v0
	v_mov_b32_e32 v87, v0
	v_mov_b32_e32 v96, v0
	v_mov_b32_e32 v97, v0
	v_mov_b32_e32 v98, v0
	v_mov_b32_e32 v99, v0
	v_mov_b32_e32 v100, v0
	v_mov_b32_e32 v101, v0
	v_mov_b32_e32 v102, v0
	v_mov_b32_e32 v103, v0
	v_mov_b32_e32 v112, v0
	v_mov_b32_e32 v113, v0
	v_mov_b32_e32 v114, v0
	v_mov_b32_e32 v115, v0
	v_mov_b32_e32 v116, v0
	v_mov_b32_e32 v117, v0
	v_mov_b32_e32 v118, v0
	v_mov_b32_e32 v119, v0
	v_mov_b32_e32 v72, v0
	v_mov_b32_e32 v73, v0
	v_mov_b32_e32 v74, v0
	v_mov_b32_e32 v75, v0
	v_mov_b32_e32 v76, v0
	v_mov_b32_e32 v77, v0
	v_mov_b32_e32 v78, v0
	v_mov_b32_e32 v79, v0
	v_mov_b32_e32 v88, v0
	v_mov_b32_e32 v89, v0
	v_mov_b32_e32 v90, v0
	v_mov_b32_e32 v91, v0
	v_mov_b32_e32 v92, v0
	v_mov_b32_e32 v93, v0
	v_mov_b32_e32 v94, v0
	v_mov_b32_e32 v95, v0
	v_mov_b32_e32 v104, v0
	v_mov_b32_e32 v105, v0
	v_mov_b32_e32 v106, v0
	v_mov_b32_e32 v107, v0
	v_mov_b32_e32 v108, v0
	v_mov_b32_e32 v109, v0
	v_mov_b32_e32 v110, v0
	v_mov_b32_e32 v111, v0
	v_mov_b32_e32 v120, v0
	v_mov_b32_e32 v121, v0
	v_mov_b32_e32 v122, v0
	v_mov_b32_e32 v123, v0
	v_mov_b32_e32 v124, v0
	v_mov_b32_e32 v125, v0
	v_mov_b32_e32 v126, v0
	v_mov_b32_e32 v127, v0
	s_cmp_lg_u32 s60, 1
	s_cselect_b32 s100, s99, 0
	s_cmp_lg_u32 s100, 0
	s_cbranch_scc0 .Lmy_nobar2_16
	s_barrier
.Lmy_nobar2_16:
.LBB0_1557:
	ds_read_b128 v[146:149], v153
	ds_read_b128 v[158:161], v153 offset:1024
	ds_read_b128 v[162:165], v153 offset:2048
	ds_read_b128 v[166:169], v153 offset:3072
	ds_read_b128 v[170:173], v154
	ds_read_b128 v[174:177], v154 offset:1024
	ds_read_b128 v[178:181], v154 offset:2048
	ds_read_b128 v[182:185], v154 offset:3072
	s_add_u32 s34, s40, 0xfffc0080
	s_addc_u32 s35, s41, -1
	s_cmp_eq_u32 s62, 12
	s_cselect_b32 s45, s12, s35
	s_cselect_b32 s44, s13, s34
	s_cselect_b32 s43, s27, s61
	s_cselect_b32 s42, s29, s39
	v_lshl_add_u64 v[218:219], s[40:41], 0, v[138:139]
	s_add_i32 m0, s48, 0xc000
	ds_read_b128 v[186:189], v155
	ds_read_b128 v[190:193], v155 offset:1024
	ds_read_b128 v[194:197], v155 offset:2048
	ds_read_b128 v[198:201], v155 offset:3072
	ds_read_b128 v[202:205], v155 offset:4096
	ds_read_b128 v[206:209], v155 offset:5120
	ds_read_b128 v[210:213], v155 offset:6144
	ds_read_b128 v[214:217], v155 offset:7168
	global_load_lds_dwordx4 v[218:219], off
	v_lshl_add_u64 v[218:219], s[40:41], 0, v[140:141]
	s_add_i32 m0, s48, 0xe000
	s_nop 0
	global_load_lds_dwordx4 v[218:219], off
	s_waitcnt vmcnt(8)
	s_waitcnt lgkmcnt(0)
	s_barrier
	s_setprio 1
	s_waitcnt lgkmcnt(0)
	v_mfma_f32_16x16x32_bf16 v[124:127], v[146:149], v[186:189], v[124:127]
	v_mfma_f32_16x16x32_bf16 v[120:123], v[162:165], v[186:189], v[120:123]
	v_mfma_f32_16x16x32_bf16 v[108:111], v[146:149], v[194:197], v[108:111]
	v_mfma_f32_16x16x32_bf16 v[104:107], v[162:165], v[194:197], v[104:107]
	v_mfma_f32_16x16x32_bf16 v[92:95], v[146:149], v[202:205], v[92:95]
	v_mfma_f32_16x16x32_bf16 v[88:91], v[162:165], v[202:205], v[88:91]
	v_mfma_f32_16x16x32_bf16 v[76:79], v[146:149], v[210:213], v[76:79]
	v_mfma_f32_16x16x32_bf16 v[72:75], v[162:165], v[210:213], v[72:75]
	v_mfma_f32_16x16x32_bf16 v[124:127], v[158:161], v[190:193], v[124:127]
	v_mfma_f32_16x16x32_bf16 v[120:123], v[166:169], v[190:193], v[120:123]
	v_mfma_f32_16x16x32_bf16 v[108:111], v[158:161], v[198:201], v[108:111]
	v_mfma_f32_16x16x32_bf16 v[104:107], v[166:169], v[198:201], v[104:107]
	v_mfma_f32_16x16x32_bf16 v[92:95], v[158:161], v[206:209], v[92:95]
	v_mfma_f32_16x16x32_bf16 v[88:91], v[166:169], v[206:209], v[88:91]
	v_mfma_f32_16x16x32_bf16 v[76:79], v[158:161], v[214:217], v[76:79]
	v_mfma_f32_16x16x32_bf16 v[72:75], v[166:169], v[214:217], v[72:75]
	s_setprio 0
	s_setprio 1
	v_mfma_f32_16x16x32_bf16 v[116:119], v[170:173], v[186:189], v[116:119]
	v_mfma_f32_16x16x32_bf16 v[112:115], v[178:181], v[186:189], v[112:115]
	v_mfma_f32_16x16x32_bf16 v[100:103], v[170:173], v[194:197], v[100:103]
	v_mfma_f32_16x16x32_bf16 v[96:99], v[178:181], v[194:197], v[96:99]
	v_mfma_f32_16x16x32_bf16 v[84:87], v[170:173], v[202:205], v[84:87]
	v_mfma_f32_16x16x32_bf16 v[80:83], v[178:181], v[202:205], v[80:83]
	v_mfma_f32_16x16x32_bf16 v[68:71], v[170:173], v[210:213], v[68:71]
	v_mfma_f32_16x16x32_bf16 v[64:67], v[178:181], v[210:213], v[64:67]
	v_mfma_f32_16x16x32_bf16 v[116:119], v[174:177], v[190:193], v[116:119]
	v_mfma_f32_16x16x32_bf16 v[112:115], v[182:185], v[190:193], v[112:115]
	v_mfma_f32_16x16x32_bf16 v[100:103], v[174:177], v[198:201], v[100:103]
	v_mfma_f32_16x16x32_bf16 v[96:99], v[182:185], v[198:201], v[96:99]
	v_mfma_f32_16x16x32_bf16 v[84:87], v[174:177], v[206:209], v[84:87]
	v_mfma_f32_16x16x32_bf16 v[80:83], v[182:185], v[206:209], v[80:83]
	v_mfma_f32_16x16x32_bf16 v[68:71], v[174:177], v[214:217], v[68:71]
	v_mfma_f32_16x16x32_bf16 v[64:67], v[182:185], v[214:217], v[64:67]
	s_setprio 0
	s_barrier
	s_add_i32 s34, s58, s47
	v_lshl_add_u64 v[218:219], s[42:43], 0, v[132:133]
	s_mov_b32 m0, s34
	ds_read_b128 v[186:189], v155 offset:16384
	ds_read_b128 v[190:193], v155 offset:17408
	ds_read_b128 v[194:197], v155 offset:18432
	ds_read_b128 v[198:201], v155 offset:19456
	ds_read_b128 v[202:205], v155 offset:20480
	ds_read_b128 v[206:209], v155 offset:21504
	ds_read_b128 v[210:213], v155 offset:22528
	ds_read_b128 v[214:217], v155 offset:23552
	global_load_lds_dwordx4 v[218:219], off
	s_add_i32 m0, s34, 0x2000
	s_add_u32 s34, s42, 0x40000
	v_lshl_add_u64 v[220:221], s[42:43], 0, v[136:137]
	s_addc_u32 s35, s43, 0
	s_add_i32 s63, s59, s47
	global_load_lds_dwordx4 v[220:221], off
	v_lshl_add_u64 v[222:223], s[34:35], 0, v[132:133]
	s_mov_b32 m0, s63
	v_lshl_add_u64 v[224:225], s[44:45], 0, v[134:135]
	global_load_lds_dwordx4 v[222:223], off
	v_lshl_add_u64 v[222:223], s[34:35], 0, v[136:137]
	s_add_i32 m0, s63, 0x2000
	s_nop 0
	global_load_lds_dwordx4 v[222:223], off
	v_lshl_add_u64 v[222:223], s[44:45], 0, v[130:131]
	s_mov_b32 m0, s48
	s_nop 0
	global_load_lds_dwordx4 v[222:223], off
	s_mov_b32 m0, s49
	s_nop 0
	global_load_lds_dwordx4 v[224:225], off
	s_waitcnt vmcnt(8)
	s_waitcnt lgkmcnt(0)
	s_barrier
	s_setprio 1
	s_waitcnt lgkmcnt(0)
	v_mfma_f32_16x16x32_bf16 v[60:63], v[146:149], v[186:189], v[60:63]
	v_mfma_f32_16x16x32_bf16 v[56:59], v[162:165], v[186:189], v[56:59]
	v_mfma_f32_16x16x32_bf16 v[44:47], v[146:149], v[194:197], v[44:47]
	v_mfma_f32_16x16x32_bf16 v[40:43], v[162:165], v[194:197], v[40:43]
	v_mfma_f32_16x16x32_bf16 v[28:31], v[146:149], v[202:205], v[28:31]
	v_mfma_f32_16x16x32_bf16 v[24:27], v[162:165], v[202:205], v[24:27]
	v_mfma_f32_16x16x32_bf16 v[12:15], v[146:149], v[210:213], v[12:15]
	v_mfma_f32_16x16x32_bf16 v[8:11], v[162:165], v[210:213], v[8:11]
	v_mfma_f32_16x16x32_bf16 v[60:63], v[158:161], v[190:193], v[60:63]
	v_mfma_f32_16x16x32_bf16 v[56:59], v[166:169], v[190:193], v[56:59]
	v_mfma_f32_16x16x32_bf16 v[44:47], v[158:161], v[198:201], v[44:47]
	v_mfma_f32_16x16x32_bf16 v[40:43], v[166:169], v[198:201], v[40:43]
	v_mfma_f32_16x16x32_bf16 v[28:31], v[158:161], v[206:209], v[28:31]
	v_mfma_f32_16x16x32_bf16 v[24:27], v[166:169], v[206:209], v[24:27]
	v_mfma_f32_16x16x32_bf16 v[12:15], v[158:161], v[214:217], v[12:15]
	v_mfma_f32_16x16x32_bf16 v[8:11], v[166:169], v[214:217], v[8:11]
	s_setprio 0
	s_setprio 1
	v_mfma_f32_16x16x32_bf16 v[52:55], v[170:173], v[186:189], v[52:55]
	v_mfma_f32_16x16x32_bf16 v[48:51], v[178:181], v[186:189], v[48:51]
	v_mfma_f32_16x16x32_bf16 v[36:39], v[170:173], v[194:197], v[36:39]
	v_mfma_f32_16x16x32_bf16 v[32:35], v[178:181], v[194:197], v[32:35]
	v_mfma_f32_16x16x32_bf16 v[20:23], v[170:173], v[202:205], v[20:23]
	v_mfma_f32_16x16x32_bf16 v[16:19], v[178:181], v[202:205], v[16:19]
	v_mfma_f32_16x16x32_bf16 v[4:7], v[170:173], v[210:213], v[4:7]
	v_mfma_f32_16x16x32_bf16 v[0:3], v[178:181], v[210:213], v[0:3]
	v_mfma_f32_16x16x32_bf16 v[52:55], v[174:177], v[190:193], v[52:55]
	v_mfma_f32_16x16x32_bf16 v[48:51], v[182:185], v[190:193], v[48:51]
	v_mfma_f32_16x16x32_bf16 v[36:39], v[174:177], v[198:201], v[36:39]
	v_mfma_f32_16x16x32_bf16 v[32:35], v[182:185], v[198:201], v[32:35]
	v_mfma_f32_16x16x32_bf16 v[20:23], v[174:177], v[206:209], v[20:23]
	v_mfma_f32_16x16x32_bf16 v[16:19], v[182:185], v[206:209], v[16:19]
	v_mfma_f32_16x16x32_bf16 v[4:7], v[174:177], v[214:217], v[4:7]
	v_mfma_f32_16x16x32_bf16 v[0:3], v[182:185], v[214:217], v[0:3]
	s_setprio 0
	s_barrier
	s_add_i32 s63, 0, 0x18000
	s_add_i32 s64, 0, 0x1c000
	v_add_u32_e32 v166, s63, v151
	v_add_u32_e32 v182, s64, v151
	ds_read_b128 v[146:149], v166
	ds_read_b128 v[158:161], v166 offset:1024
	ds_read_b128 v[162:165], v166 offset:2048
	ds_read_b128 v[166:169], v166 offset:3072
	ds_read_b128 v[170:173], v182
	ds_read_b128 v[174:177], v182 offset:1024
	ds_read_b128 v[178:181], v182 offset:2048
	ds_read_b128 v[182:185], v182 offset:3072
	s_add_u32 s34, s44, 0x40000
	s_addc_u32 s35, s45, 0
	s_mov_b32 m0, s50
	v_lshl_add_u64 v[226:227], s[34:35], 0, v[130:131]
	ds_read_b128 v[186:189], v155 offset:32768
	ds_read_b128 v[190:193], v155 offset:33792
	ds_read_b128 v[194:197], v155 offset:34816
	ds_read_b128 v[198:201], v155 offset:35840
	ds_read_b128 v[202:205], v155 offset:36864
	ds_read_b128 v[206:209], v155 offset:37888
	ds_read_b128 v[210:213], v155 offset:38912
	ds_read_b128 v[214:217], v155 offset:39936
	global_load_lds_dwordx4 v[226:227], off
	v_lshl_add_u64 v[226:227], s[34:35], 0, v[134:135]
	s_mov_b32 m0, s51
	s_nop 0
	global_load_lds_dwordx4 v[226:227], off
	s_waitcnt vmcnt(8)
	s_waitcnt lgkmcnt(0)
	s_barrier
	s_setprio 1
	s_waitcnt lgkmcnt(0)
	v_mfma_f32_16x16x32_bf16 v[124:127], v[146:149], v[186:189], v[124:127]
	v_mfma_f32_16x16x32_bf16 v[120:123], v[162:165], v[186:189], v[120:123]
	v_mfma_f32_16x16x32_bf16 v[108:111], v[146:149], v[194:197], v[108:111]
	v_mfma_f32_16x16x32_bf16 v[104:107], v[162:165], v[194:197], v[104:107]
	v_mfma_f32_16x16x32_bf16 v[92:95], v[146:149], v[202:205], v[92:95]
	v_mfma_f32_16x16x32_bf16 v[88:91], v[162:165], v[202:205], v[88:91]
	v_mfma_f32_16x16x32_bf16 v[76:79], v[146:149], v[210:213], v[76:79]
	v_mfma_f32_16x16x32_bf16 v[72:75], v[162:165], v[210:213], v[72:75]
	v_mfma_f32_16x16x32_bf16 v[124:127], v[158:161], v[190:193], v[124:127]
	v_mfma_f32_16x16x32_bf16 v[120:123], v[166:169], v[190:193], v[120:123]
	v_mfma_f32_16x16x32_bf16 v[108:111], v[158:161], v[198:201], v[108:111]
	v_mfma_f32_16x16x32_bf16 v[104:107], v[166:169], v[198:201], v[104:107]
	v_mfma_f32_16x16x32_bf16 v[92:95], v[158:161], v[206:209], v[92:95]
	v_mfma_f32_16x16x32_bf16 v[88:91], v[166:169], v[206:209], v[88:91]
	v_mfma_f32_16x16x32_bf16 v[76:79], v[158:161], v[214:217], v[76:79]
	v_mfma_f32_16x16x32_bf16 v[72:75], v[166:169], v[214:217], v[72:75]
	s_setprio 0
	s_setprio 1
	v_mfma_f32_16x16x32_bf16 v[116:119], v[170:173], v[186:189], v[116:119]
	v_mfma_f32_16x16x32_bf16 v[112:115], v[178:181], v[186:189], v[112:115]
	v_mfma_f32_16x16x32_bf16 v[100:103], v[170:173], v[194:197], v[100:103]
	v_mfma_f32_16x16x32_bf16 v[96:99], v[178:181], v[194:197], v[96:99]
	v_mfma_f32_16x16x32_bf16 v[84:87], v[170:173], v[202:205], v[84:87]
	v_mfma_f32_16x16x32_bf16 v[80:83], v[178:181], v[202:205], v[80:83]
	v_mfma_f32_16x16x32_bf16 v[68:71], v[170:173], v[210:213], v[68:71]
	v_mfma_f32_16x16x32_bf16 v[64:67], v[178:181], v[210:213], v[64:67]
	v_mfma_f32_16x16x32_bf16 v[116:119], v[174:177], v[190:193], v[116:119]
	v_mfma_f32_16x16x32_bf16 v[112:115], v[182:185], v[190:193], v[112:115]
	v_mfma_f32_16x16x32_bf16 v[100:103], v[174:177], v[198:201], v[100:103]
	v_mfma_f32_16x16x32_bf16 v[96:99], v[182:185], v[198:201], v[96:99]
	v_mfma_f32_16x16x32_bf16 v[84:87], v[174:177], v[206:209], v[84:87]
	v_mfma_f32_16x16x32_bf16 v[80:83], v[182:185], v[206:209], v[80:83]
	v_mfma_f32_16x16x32_bf16 v[68:71], v[174:177], v[214:217], v[68:71]
	v_mfma_f32_16x16x32_bf16 v[64:67], v[182:185], v[214:217], v[64:67]
	s_setprio 0
	s_barrier
	s_add_i32 s34, s63, s47
	v_lshl_add_u64 v[218:219], v[218:219], 0, s[10:11]
	s_mov_b32 m0, s34
	ds_read_b128 v[186:189], v155 offset:49152
	ds_read_b128 v[190:193], v155 offset:50176
	ds_read_b128 v[194:197], v155 offset:51200
	ds_read_b128 v[198:201], v155 offset:52224
	ds_read_b128 v[202:205], v155 offset:53248
	ds_read_b128 v[206:209], v155 offset:54272
	ds_read_b128 v[210:213], v155 offset:55296
	ds_read_b128 v[214:217], v155 offset:56320
	global_load_lds_dwordx4 v[218:219], off
	s_add_i32 m0, s34, 0x2000
	s_add_u32 s34, s42, 0x40080
	v_lshl_add_u64 v[218:219], v[220:221], 0, s[10:11]
	s_addc_u32 s35, s43, 0
	s_add_i32 s42, s64, s47
	global_load_lds_dwordx4 v[218:219], off
	v_lshl_add_u64 v[218:219], s[34:35], 0, v[132:133]
	s_mov_b32 m0, s42
	s_nop 0
	global_load_lds_dwordx4 v[218:219], off
	v_lshl_add_u64 v[218:219], s[34:35], 0, v[136:137]
	s_add_i32 m0, s42, 0x2000
	s_nop 0
	global_load_lds_dwordx4 v[218:219], off
	v_lshl_add_u64 v[218:219], v[222:223], 0, s[10:11]
	s_mov_b32 m0, s53
	s_nop 0
	global_load_lds_dwordx4 v[218:219], off
	v_lshl_add_u64 v[218:219], v[224:225], 0, s[10:11]
	s_mov_b32 m0, s54
	s_nop 0
	global_load_lds_dwordx4 v[218:219], off
	s_waitcnt vmcnt(8)
	s_waitcnt lgkmcnt(0)
	s_barrier
	s_setprio 1
	s_waitcnt lgkmcnt(0)
	v_mfma_f32_16x16x32_bf16 v[60:63], v[146:149], v[186:189], v[60:63]
	v_mfma_f32_16x16x32_bf16 v[56:59], v[162:165], v[186:189], v[56:59]
	v_mfma_f32_16x16x32_bf16 v[44:47], v[146:149], v[194:197], v[44:47]
	v_mfma_f32_16x16x32_bf16 v[40:43], v[162:165], v[194:197], v[40:43]
	v_mfma_f32_16x16x32_bf16 v[28:31], v[146:149], v[202:205], v[28:31]
	v_mfma_f32_16x16x32_bf16 v[24:27], v[162:165], v[202:205], v[24:27]
	v_mfma_f32_16x16x32_bf16 v[12:15], v[146:149], v[210:213], v[12:15]
	v_mfma_f32_16x16x32_bf16 v[8:11], v[162:165], v[210:213], v[8:11]
	v_mfma_f32_16x16x32_bf16 v[60:63], v[158:161], v[190:193], v[60:63]
	v_mfma_f32_16x16x32_bf16 v[56:59], v[166:169], v[190:193], v[56:59]
	v_mfma_f32_16x16x32_bf16 v[44:47], v[158:161], v[198:201], v[44:47]
	v_mfma_f32_16x16x32_bf16 v[40:43], v[166:169], v[198:201], v[40:43]
	v_mfma_f32_16x16x32_bf16 v[28:31], v[158:161], v[206:209], v[28:31]
	v_mfma_f32_16x16x32_bf16 v[24:27], v[166:169], v[206:209], v[24:27]
	v_mfma_f32_16x16x32_bf16 v[12:15], v[158:161], v[214:217], v[12:15]
	v_mfma_f32_16x16x32_bf16 v[8:11], v[166:169], v[214:217], v[8:11]
	s_setprio 0
	s_setprio 1
	v_mfma_f32_16x16x32_bf16 v[52:55], v[170:173], v[186:189], v[52:55]
	v_mfma_f32_16x16x32_bf16 v[48:51], v[178:181], v[186:189], v[48:51]
	v_mfma_f32_16x16x32_bf16 v[36:39], v[170:173], v[194:197], v[36:39]
	v_mfma_f32_16x16x32_bf16 v[32:35], v[178:181], v[194:197], v[32:35]
	v_mfma_f32_16x16x32_bf16 v[20:23], v[170:173], v[202:205], v[20:23]
	v_mfma_f32_16x16x32_bf16 v[16:19], v[178:181], v[202:205], v[16:19]
	v_mfma_f32_16x16x32_bf16 v[4:7], v[170:173], v[210:213], v[4:7]
	v_mfma_f32_16x16x32_bf16 v[0:3], v[178:181], v[210:213], v[0:3]
	v_mfma_f32_16x16x32_bf16 v[52:55], v[174:177], v[190:193], v[52:55]
	v_mfma_f32_16x16x32_bf16 v[48:51], v[182:185], v[190:193], v[48:51]
	v_mfma_f32_16x16x32_bf16 v[36:39], v[174:177], v[198:201], v[36:39]
	v_mfma_f32_16x16x32_bf16 v[32:35], v[182:185], v[198:201], v[32:35]
	v_mfma_f32_16x16x32_bf16 v[20:23], v[174:177], v[206:209], v[20:23]
	v_mfma_f32_16x16x32_bf16 v[16:19], v[182:185], v[206:209], v[16:19]
	v_mfma_f32_16x16x32_bf16 v[4:7], v[174:177], v[214:217], v[4:7]
	v_mfma_f32_16x16x32_bf16 v[0:3], v[182:185], v[214:217], v[0:3]
	s_setprio 0
	s_cmp_eq_u32 s62, s98
	s_cbranch_scc1 .Lmy_nobar_16
	s_barrier
.Lmy_nobar_16:
	s_add_i32 s62, s62, 2
	s_add_u32 s40, s40, 0x100
	s_addc_u32 s41, s41, 0
	s_add_u32 s39, s39, 0x100
	s_addc_u32 s61, s61, 0
	s_cmp_gt_u32 s62, 13
	s_cbranch_scc0 .LBB0_1557
	s_and_b64 vcc, exec, s[22:23]
	s_cbranch_vccz .LBB0_1560
	s_nop 0

.LBB0_1644:
	s_lshr_b32 s99, s91, 2
	s_cmp_eq_u32 s99, 1
	s_cselect_b32 s98, 12, 0x7fffffff
	s_add_i32 s56, s56, 1
	s_mul_i32 s4, s56, s42
	s_mul_hi_u32 s5, s56, s43
	s_add_i32 s5, s5, s4
	s_mul_i32 s4, s56, s43
	s_add_u32 s26, s4, s2
	s_addc_u32 s27, s5, s3
	v_cmp_gt_i64_e32 vcc, s[26:27], v[144:145]
	v_cmp_lt_i64_e64 s[4:5], s[26:27], v[142:143]
	s_cbranch_vccnz .LBB0_1646
	s_ashr_i32 s10, s26, 31
	s_lshr_b32 s10, s10, 29
	s_add_i32 s10, s26, s10
	s_ashr_i32 s11, s10, 3
	s_and_b32 s10, s10, -8
	s_sub_i32 s10, s26, s10
	s_cmp_lt_i32 s10, 0
	s_cselect_b32 s22, s47, 0x160
	s_mul_i32 s10, s10, s22
	s_add_i32 s10, s10, s11
	s_mul_hi_i32 s11, s10, 0x2e8ba2e9
	s_lshr_b32 s22, s11, 31
	s_ashr_i32 s11, s11, 5
	s_add_i32 s11, s11, s22
	s_lshl_b32 s22, s11, 3
	s_sub_i32 s23, 0x80, s22
	s_min_i32 s23, s23, 8
	s_abs_i32 s26, s23
	v_cvt_f32_u32_e32 v0, s26
	s_sub_i32 s28, 0, s26
	s_mulk_i32 s11, 0xb0
	s_sub_i32 s11, s10, s11
	v_rcp_iflag_f32_e32 v0, v0
	s_abs_i32 s10, s11
	s_xor_b32 s27, s11, s23
	s_ashr_i32 s27, s27, 31
	v_mul_f32_e32 v0, 0x4f7ffffe, v0
	v_cvt_u32_f32_e32 v0, v0
	s_mov_b32 s57, s56
	v_readfirstlane_b32 s29, v0
	s_mul_i32 s28, s28, s29
	s_mul_hi_u32 s28, s29, s28
	s_add_i32 s29, s29, s28
	s_mul_hi_u32 s28, s10, s29
	s_mul_i32 s29, s28, s26
	s_sub_i32 s10, s10, s29
	s_add_i32 s34, s28, 1
	s_sub_i32 s29, s10, s26
	s_cmp_ge_u32 s10, s26
	s_cselect_b32 s28, s34, s28
	s_cselect_b32 s10, s29, s10
	s_add_i32 s29, s28, 1
	s_cmp_ge_u32 s10, s26
	s_cselect_b32 s10, s29, s28
	s_xor_b32 s10, s10, s27
	s_sub_i32 s10, s10, s27
	s_mul_i32 s23, s10, s23
	s_sub_i32 s11, s11, s23
	s_add_i32 s22, s22, s11
.LBB0_1646:
	s_ashr_i32 s23, s22, 31
	s_lshl_b64 s[26:27], s[22:23], 19
	s_add_u32 s26, s14, s26
	s_addc_u32 s27, s15, s27
	s_and_b64 s[28:29], s[4:5], exec
	s_cselect_b32 s23, s27, s37
	s_cselect_b32 s58, s26, s36
	s_ashr_i32 s11, s10, 31
	s_lshl_b64 s[28:29], s[10:11], 19
	s_add_u32 s28, s45, s28
	s_addc_u32 s29, s46, s29
	s_and_b64 s[34:35], s[4:5], exec
	s_cselect_b32 s11, s29, s39
	s_cselect_b32 s59, s28, s38
	s_add_u32 s36, s36, 0x40080
	s_addc_u32 s37, s37, 0
	s_add_u32 s60, s38, 0x100
	v_mov_b32_e32 v0, 0
	s_addc_u32 s61, s39, 0
	s_mov_b32 s62, -2
	v_mov_b32_e32 v1, v0
	v_mov_b32_e32 v2, v0
	v_mov_b32_e32 v3, v0
	v_mov_b32_e32 v4, v0
	v_mov_b32_e32 v5, v0
	v_mov_b32_e32 v6, v0
	v_mov_b32_e32 v7, v0
	v_mov_b32_e32 v16, v0
	v_mov_b32_e32 v17, v0
	v_mov_b32_e32 v18, v0
	v_mov_b32_e32 v19, v0
	v_mov_b32_e32 v20, v0
	v_mov_b32_e32 v21, v0
	v_mov_b32_e32 v22, v0
	v_mov_b32_e32 v23, v0
	v_mov_b32_e32 v32, v0
	v_mov_b32_e32 v33, v0
	v_mov_b32_e32 v34, v0
	v_mov_b32_e32 v35, v0
	v_mov_b32_e32 v36, v0
	v_mov_b32_e32 v37, v0
	v_mov_b32_e32 v38, v0
	v_mov_b32_e32 v39, v0
	v_mov_b32_e32 v48, v0
	v_mov_b32_e32 v49, v0
	v_mov_b32_e32 v50, v0
	v_mov_b32_e32 v51, v0
	v_mov_b32_e32 v52, v0
	v_mov_b32_e32 v53, v0
	v_mov_b32_e32 v54, v0
	v_mov_b32_e32 v55, v0
	v_mov_b32_e32 v8, v0
	v_mov_b32_e32 v9, v0
	v_mov_b32_e32 v10, v0
	v_mov_b32_e32 v11, v0
	v_mov_b32_e32 v12, v0
	v_mov_b32_e32 v13, v0
	v_mov_b32_e32 v14, v0
	v_mov_b32_e32 v15, v0
	v_mov_b32_e32 v24, v0
	v_mov_b32_e32 v25, v0
	v_mov_b32_e32 v26, v0
	v_mov_b32_e32 v27, v0
	v_mov_b32_e32 v28, v0
	v_mov_b32_e32 v29, v0
	v_mov_b32_e32 v30, v0
	v_mov_b32_e32 v31, v0
	v_mov_b32_e32 v40, v0
	v_mov_b32_e32 v41, v0
	v_mov_b32_e32 v42, v0
	v_mov_b32_e32 v43, v0
	v_mov_b32_e32 v44, v0
	v_mov_b32_e32 v45, v0
	v_mov_b32_e32 v46, v0
	v_mov_b32_e32 v47, v0
	v_mov_b32_e32 v56, v0
	v_mov_b32_e32 v57, v0
	v_mov_b32_e32 v58, v0
	v_mov_b32_e32 v59, v0
	v_mov_b32_e32 v60, v0
	v_mov_b32_e32 v61, v0
	v_mov_b32_e32 v62, v0
	v_mov_b32_e32 v63, v0
	v_mov_b32_e32 v64, v0
	v_mov_b32_e32 v65, v0
	v_mov_b32_e32 v66, v0
	v_mov_b32_e32 v67, v0
	v_mov_b32_e32 v68, v0
	v_mov_b32_e32 v69, v0
	v_mov_b32_e32 v70, v0
	v_mov_b32_e32 v71, v0
	v_mov_b32_e32 v80, v0
	v_mov_b32_e32 v81, v0
	v_mov_b32_e32 v82, v0
	v_mov_b32_e32 v83, v0
	v_mov_b32_e32 v84, v0
	v_mov_b32_e32 v85, v0
	v_mov_b32_e32 v86, v0
	v_mov_b32_e32 v87, v0
	v_mov_b32_e32 v96, v0
	v_mov_b32_e32 v97, v0
	v_mov_b32_e32 v98, v0
	v_mov_b32_e32 v99, v0
	v_mov_b32_e32 v100, v0
	v_mov_b32_e32 v101, v0
	v_mov_b32_e32 v102, v0
	v_mov_b32_e32 v103, v0
	v_mov_b32_e32 v112, v0
	v_mov_b32_e32 v113, v0
	v_mov_b32_e32 v114, v0
	v_mov_b32_e32 v115, v0
	v_mov_b32_e32 v116, v0
	v_mov_b32_e32 v117, v0
	v_mov_b32_e32 v118, v0
	v_mov_b32_e32 v119, v0
	v_mov_b32_e32 v72, v0
	v_mov_b32_e32 v73, v0
	v_mov_b32_e32 v74, v0
	v_mov_b32_e32 v75, v0
	v_mov_b32_e32 v76, v0
	v_mov_b32_e32 v77, v0
	v_mov_b32_e32 v78, v0
	v_mov_b32_e32 v79, v0
	v_mov_b32_e32 v88, v0
	v_mov_b32_e32 v89, v0
	v_mov_b32_e32 v90, v0
	v_mov_b32_e32 v91, v0
	v_mov_b32_e32 v92, v0
	v_mov_b32_e32 v93, v0
	v_mov_b32_e32 v94, v0
	v_mov_b32_e32 v95, v0
	v_mov_b32_e32 v104, v0
	v_mov_b32_e32 v105, v0
	v_mov_b32_e32 v106, v0
	v_mov_b32_e32 v107, v0
	v_mov_b32_e32 v108, v0
	v_mov_b32_e32 v109, v0
	v_mov_b32_e32 v110, v0
	v_mov_b32_e32 v111, v0
	v_mov_b32_e32 v120, v0
	v_mov_b32_e32 v121, v0
	v_mov_b32_e32 v122, v0
	v_mov_b32_e32 v123, v0
	v_mov_b32_e32 v124, v0
	v_mov_b32_e32 v125, v0
	v_mov_b32_e32 v126, v0
	v_mov_b32_e32 v127, v0
	s_cmp_lg_u32 s56, 1
	s_cselect_b32 s100, s99, 0
	s_cmp_lg_u32 s100, 0
	s_cbranch_scc0 .Lmy_nobar2_17
	s_barrier
.Lmy_nobar2_17:
.LBB0_1647:
	ds_read_b128 v[146:149], v154
	ds_read_b128 v[158:161], v154 offset:1024
	ds_read_b128 v[162:165], v154 offset:2048
	ds_read_b128 v[166:169], v154 offset:3072
	ds_read_b128 v[170:173], v155
	ds_read_b128 v[174:177], v155 offset:1024
	ds_read_b128 v[178:181], v155 offset:2048
	ds_read_b128 v[182:185], v155 offset:3072
	s_add_u32 s34, s36, 0xfffc0080
	s_addc_u32 s35, s37, -1
	s_cmp_eq_u32 s62, 12
	s_cselect_b32 s41, s23, s35
	s_cselect_b32 s40, s58, s34
	s_cselect_b32 s39, s11, s61
	s_cselect_b32 s38, s59, s60
	v_lshl_add_u64 v[218:219], s[36:37], 0, v[138:139]
	s_add_i32 m0, s31, 0xc000
	ds_read_b128 v[186:189], v157
	ds_read_b128 v[190:193], v157 offset:1024
	ds_read_b128 v[194:197], v157 offset:2048
	ds_read_b128 v[198:201], v157 offset:3072
	ds_read_b128 v[202:205], v157 offset:4096
	ds_read_b128 v[206:209], v157 offset:5120
	ds_read_b128 v[210:213], v157 offset:6144
	ds_read_b128 v[214:217], v157 offset:7168
	global_load_lds_dwordx4 v[218:219], off
	v_lshl_add_u64 v[218:219], s[36:37], 0, v[140:141]
	s_add_i32 m0, s31, 0xe000
	s_nop 0
	global_load_lds_dwordx4 v[218:219], off
	s_waitcnt vmcnt(8)
	s_waitcnt lgkmcnt(0)
	s_barrier
	s_setprio 1
	s_waitcnt lgkmcnt(0)
	v_mfma_f32_16x16x32_bf16 v[124:127], v[146:149], v[186:189], v[124:127]
	v_mfma_f32_16x16x32_bf16 v[120:123], v[162:165], v[186:189], v[120:123]
	v_mfma_f32_16x16x32_bf16 v[108:111], v[146:149], v[194:197], v[108:111]
	v_mfma_f32_16x16x32_bf16 v[104:107], v[162:165], v[194:197], v[104:107]
	v_mfma_f32_16x16x32_bf16 v[92:95], v[146:149], v[202:205], v[92:95]
	v_mfma_f32_16x16x32_bf16 v[88:91], v[162:165], v[202:205], v[88:91]
	v_mfma_f32_16x16x32_bf16 v[76:79], v[146:149], v[210:213], v[76:79]
	v_mfma_f32_16x16x32_bf16 v[72:75], v[162:165], v[210:213], v[72:75]
	v_mfma_f32_16x16x32_bf16 v[124:127], v[158:161], v[190:193], v[124:127]
	v_mfma_f32_16x16x32_bf16 v[120:123], v[166:169], v[190:193], v[120:123]
	v_mfma_f32_16x16x32_bf16 v[108:111], v[158:161], v[198:201], v[108:111]
	v_mfma_f32_16x16x32_bf16 v[104:107], v[166:169], v[198:201], v[104:107]
	v_mfma_f32_16x16x32_bf16 v[92:95], v[158:161], v[206:209], v[92:95]
	v_mfma_f32_16x16x32_bf16 v[88:91], v[166:169], v[206:209], v[88:91]
	v_mfma_f32_16x16x32_bf16 v[76:79], v[158:161], v[214:217], v[76:79]
	v_mfma_f32_16x16x32_bf16 v[72:75], v[166:169], v[214:217], v[72:75]
	s_setprio 0
	s_setprio 1
	v_mfma_f32_16x16x32_bf16 v[116:119], v[170:173], v[186:189], v[116:119]
	v_mfma_f32_16x16x32_bf16 v[112:115], v[178:181], v[186:189], v[112:115]
	v_mfma_f32_16x16x32_bf16 v[100:103], v[170:173], v[194:197], v[100:103]
	v_mfma_f32_16x16x32_bf16 v[96:99], v[178:181], v[194:197], v[96:99]
	v_mfma_f32_16x16x32_bf16 v[84:87], v[170:173], v[202:205], v[84:87]
	v_mfma_f32_16x16x32_bf16 v[80:83], v[178:181], v[202:205], v[80:83]
	v_mfma_f32_16x16x32_bf16 v[68:71], v[170:173], v[210:213], v[68:71]
	v_mfma_f32_16x16x32_bf16 v[64:67], v[178:181], v[210:213], v[64:67]
	v_mfma_f32_16x16x32_bf16 v[116:119], v[174:177], v[190:193], v[116:119]
	v_mfma_f32_16x16x32_bf16 v[112:115], v[182:185], v[190:193], v[112:115]
	v_mfma_f32_16x16x32_bf16 v[100:103], v[174:177], v[198:201], v[100:103]
	v_mfma_f32_16x16x32_bf16 v[96:99], v[182:185], v[198:201], v[96:99]
	v_mfma_f32_16x16x32_bf16 v[84:87], v[174:177], v[206:209], v[84:87]
	v_mfma_f32_16x16x32_bf16 v[80:83], v[182:185], v[206:209], v[80:83]
	v_mfma_f32_16x16x32_bf16 v[68:71], v[174:177], v[214:217], v[68:71]
	v_mfma_f32_16x16x32_bf16 v[64:67], v[182:185], v[214:217], v[64:67]
	s_setprio 0
	s_barrier
	s_add_i32 s34, s53, s44
	v_lshl_add_u64 v[218:219], s[38:39], 0, v[134:135]
	s_mov_b32 m0, s34
	ds_read_b128 v[186:189], v157 offset:16384
	ds_read_b128 v[190:193], v157 offset:17408
	ds_read_b128 v[194:197], v157 offset:18432
	ds_read_b128 v[198:201], v157 offset:19456
	ds_read_b128 v[202:205], v157 offset:20480
	ds_read_b128 v[206:209], v157 offset:21504
	ds_read_b128 v[210:213], v157 offset:22528
	ds_read_b128 v[214:217], v157 offset:23552
	global_load_lds_dwordx4 v[218:219], off
	s_add_i32 m0, s34, 0x2000
	s_add_u32 s34, s38, 0x40000
	v_lshl_add_u64 v[220:221], s[38:39], 0, v[130:131]
	s_addc_u32 s35, s39, 0
	s_add_i32 s63, s54, s44
	global_load_lds_dwordx4 v[220:221], off
	v_lshl_add_u64 v[222:223], s[34:35], 0, v[134:135]
	s_mov_b32 m0, s63
	v_lshl_add_u64 v[224:225], s[40:41], 0, v[132:133]
	global_load_lds_dwordx4 v[222:223], off
	v_lshl_add_u64 v[222:223], s[34:35], 0, v[130:131]
	s_add_i32 m0, s63, 0x2000
	s_nop 0
	global_load_lds_dwordx4 v[222:223], off
	v_lshl_add_u64 v[222:223], s[40:41], 0, v[136:137]
	s_mov_b32 m0, s31
	s_nop 0
	global_load_lds_dwordx4 v[222:223], off
	s_mov_b32 m0, s48
	s_nop 0
	global_load_lds_dwordx4 v[224:225], off
	s_waitcnt vmcnt(8)
	s_waitcnt lgkmcnt(0)
	s_barrier
	s_setprio 1
	s_waitcnt lgkmcnt(0)
	v_mfma_f32_16x16x32_bf16 v[60:63], v[146:149], v[186:189], v[60:63]
	v_mfma_f32_16x16x32_bf16 v[56:59], v[162:165], v[186:189], v[56:59]
	v_mfma_f32_16x16x32_bf16 v[44:47], v[146:149], v[194:197], v[44:47]
	v_mfma_f32_16x16x32_bf16 v[40:43], v[162:165], v[194:197], v[40:43]
	v_mfma_f32_16x16x32_bf16 v[28:31], v[146:149], v[202:205], v[28:31]
	v_mfma_f32_16x16x32_bf16 v[24:27], v[162:165], v[202:205], v[24:27]
	v_mfma_f32_16x16x32_bf16 v[12:15], v[146:149], v[210:213], v[12:15]
	v_mfma_f32_16x16x32_bf16 v[8:11], v[162:165], v[210:213], v[8:11]
	v_mfma_f32_16x16x32_bf16 v[60:63], v[158:161], v[190:193], v[60:63]
	v_mfma_f32_16x16x32_bf16 v[56:59], v[166:169], v[190:193], v[56:59]
	v_mfma_f32_16x16x32_bf16 v[44:47], v[158:161], v[198:201], v[44:47]
	v_mfma_f32_16x16x32_bf16 v[40:43], v[166:169], v[198:201], v[40:43]
	v_mfma_f32_16x16x32_bf16 v[28:31], v[158:161], v[206:209], v[28:31]
	v_mfma_f32_16x16x32_bf16 v[24:27], v[166:169], v[206:209], v[24:27]
	v_mfma_f32_16x16x32_bf16 v[12:15], v[158:161], v[214:217], v[12:15]
	v_mfma_f32_16x16x32_bf16 v[8:11], v[166:169], v[214:217], v[8:11]
	s_setprio 0
	s_setprio 1
	v_mfma_f32_16x16x32_bf16 v[52:55], v[170:173], v[186:189], v[52:55]
	v_mfma_f32_16x16x32_bf16 v[48:51], v[178:181], v[186:189], v[48:51]
	v_mfma_f32_16x16x32_bf16 v[36:39], v[170:173], v[194:197], v[36:39]
	v_mfma_f32_16x16x32_bf16 v[32:35], v[178:181], v[194:197], v[32:35]
	v_mfma_f32_16x16x32_bf16 v[20:23], v[170:173], v[202:205], v[20:23]
	v_mfma_f32_16x16x32_bf16 v[16:19], v[178:181], v[202:205], v[16:19]
	v_mfma_f32_16x16x32_bf16 v[4:7], v[170:173], v[210:213], v[4:7]
	v_mfma_f32_16x16x32_bf16 v[0:3], v[178:181], v[210:213], v[0:3]
	v_mfma_f32_16x16x32_bf16 v[52:55], v[174:177], v[190:193], v[52:55]
	v_mfma_f32_16x16x32_bf16 v[48:51], v[182:185], v[190:193], v[48:51]
	v_mfma_f32_16x16x32_bf16 v[36:39], v[174:177], v[198:201], v[36:39]
	v_mfma_f32_16x16x32_bf16 v[32:35], v[182:185], v[198:201], v[32:35]
	v_mfma_f32_16x16x32_bf16 v[20:23], v[174:177], v[206:209], v[20:23]
	v_mfma_f32_16x16x32_bf16 v[16:19], v[182:185], v[206:209], v[16:19]
	v_mfma_f32_16x16x32_bf16 v[4:7], v[174:177], v[214:217], v[4:7]
	v_mfma_f32_16x16x32_bf16 v[0:3], v[182:185], v[214:217], v[0:3]
	s_setprio 0
	s_barrier
	s_add_i32 s63, 0, 0x18000
	s_add_i32 s64, 0, 0x1c000
	v_add_u32_e32 v166, s63, v151
	v_add_u32_e32 v182, s64, v151
	ds_read_b128 v[146:149], v166
	ds_read_b128 v[158:161], v166 offset:1024
	ds_read_b128 v[162:165], v166 offset:2048
	ds_read_b128 v[166:169], v166 offset:3072
	ds_read_b128 v[170:173], v182
	ds_read_b128 v[174:177], v182 offset:1024
	ds_read_b128 v[178:181], v182 offset:2048
	ds_read_b128 v[182:185], v182 offset:3072
	s_add_u32 s34, s40, 0x40000
	s_addc_u32 s35, s41, 0
	s_mov_b32 m0, s49
	v_lshl_add_u64 v[226:227], s[34:35], 0, v[136:137]
	ds_read_b128 v[186:189], v157 offset:32768
	ds_read_b128 v[190:193], v157 offset:33792
	ds_read_b128 v[194:197], v157 offset:34816
	ds_read_b128 v[198:201], v157 offset:35840
	ds_read_b128 v[202:205], v157 offset:36864
	ds_read_b128 v[206:209], v157 offset:37888
	ds_read_b128 v[210:213], v157 offset:38912
	ds_read_b128 v[214:217], v157 offset:39936
	global_load_lds_dwordx4 v[226:227], off
	v_lshl_add_u64 v[226:227], s[34:35], 0, v[132:133]
	s_mov_b32 m0, s50
	s_nop 0
	global_load_lds_dwordx4 v[226:227], off
	s_waitcnt vmcnt(8)
	s_waitcnt lgkmcnt(0)
	s_barrier
	s_setprio 1
	s_waitcnt lgkmcnt(0)
	v_mfma_f32_16x16x32_bf16 v[124:127], v[146:149], v[186:189], v[124:127]
	v_mfma_f32_16x16x32_bf16 v[120:123], v[162:165], v[186:189], v[120:123]
	v_mfma_f32_16x16x32_bf16 v[108:111], v[146:149], v[194:197], v[108:111]
	v_mfma_f32_16x16x32_bf16 v[104:107], v[162:165], v[194:197], v[104:107]
	v_mfma_f32_16x16x32_bf16 v[92:95], v[146:149], v[202:205], v[92:95]
	v_mfma_f32_16x16x32_bf16 v[88:91], v[162:165], v[202:205], v[88:91]
	v_mfma_f32_16x16x32_bf16 v[76:79], v[146:149], v[210:213], v[76:79]
	v_mfma_f32_16x16x32_bf16 v[72:75], v[162:165], v[210:213], v[72:75]
	v_mfma_f32_16x16x32_bf16 v[124:127], v[158:161], v[190:193], v[124:127]
	v_mfma_f32_16x16x32_bf16 v[120:123], v[166:169], v[190:193], v[120:123]
	v_mfma_f32_16x16x32_bf16 v[108:111], v[158:161], v[198:201], v[108:111]
	v_mfma_f32_16x16x32_bf16 v[104:107], v[166:169], v[198:201], v[104:107]
	v_mfma_f32_16x16x32_bf16 v[92:95], v[158:161], v[206:209], v[92:95]
	v_mfma_f32_16x16x32_bf16 v[88:91], v[166:169], v[206:209], v[88:91]
	v_mfma_f32_16x16x32_bf16 v[76:79], v[158:161], v[214:217], v[76:79]
	v_mfma_f32_16x16x32_bf16 v[72:75], v[166:169], v[214:217], v[72:75]
	s_setprio 0
	s_setprio 1
	v_mfma_f32_16x16x32_bf16 v[116:119], v[170:173], v[186:189], v[116:119]
	v_mfma_f32_16x16x32_bf16 v[112:115], v[178:181], v[186:189], v[112:115]
	v_mfma_f32_16x16x32_bf16 v[100:103], v[170:173], v[194:197], v[100:103]
	v_mfma_f32_16x16x32_bf16 v[96:99], v[178:181], v[194:197], v[96:99]
	v_mfma_f32_16x16x32_bf16 v[84:87], v[170:173], v[202:205], v[84:87]
	v_mfma_f32_16x16x32_bf16 v[80:83], v[178:181], v[202:205], v[80:83]
	v_mfma_f32_16x16x32_bf16 v[68:71], v[170:173], v[210:213], v[68:71]
	v_mfma_f32_16x16x32_bf16 v[64:67], v[178:181], v[210:213], v[64:67]
	v_mfma_f32_16x16x32_bf16 v[116:119], v[174:177], v[190:193], v[116:119]
	v_mfma_f32_16x16x32_bf16 v[112:115], v[182:185], v[190:193], v[112:115]
	v_mfma_f32_16x16x32_bf16 v[100:103], v[174:177], v[198:201], v[100:103]
	v_mfma_f32_16x16x32_bf16 v[96:99], v[182:185], v[198:201], v[96:99]
	v_mfma_f32_16x16x32_bf16 v[84:87], v[174:177], v[206:209], v[84:87]
	v_mfma_f32_16x16x32_bf16 v[80:83], v[182:185], v[206:209], v[80:83]
	v_mfma_f32_16x16x32_bf16 v[68:71], v[174:177], v[214:217], v[68:71]
	v_mfma_f32_16x16x32_bf16 v[64:67], v[182:185], v[214:217], v[64:67]
	s_setprio 0
	s_barrier
	s_add_i32 s34, s63, s44
	v_lshl_add_u64 v[218:219], v[218:219], 0, s[6:7]
	s_mov_b32 m0, s34
	ds_read_b128 v[186:189], v157 offset:49152
	ds_read_b128 v[190:193], v157 offset:50176
	ds_read_b128 v[194:197], v157 offset:51200
	ds_read_b128 v[198:201], v157 offset:52224
	ds_read_b128 v[202:205], v157 offset:53248
	ds_read_b128 v[206:209], v157 offset:54272
	ds_read_b128 v[210:213], v157 offset:55296
	ds_read_b128 v[214:217], v157 offset:56320
	global_load_lds_dwordx4 v[218:219], off
	s_add_i32 m0, s34, 0x2000
	s_add_u32 s34, s38, 0x40080
	v_lshl_add_u64 v[218:219], v[220:221], 0, s[6:7]
	s_addc_u32 s35, s39, 0
	s_add_i32 s38, s64, s44
	global_load_lds_dwordx4 v[218:219], off
	v_lshl_add_u64 v[218:219], s[34:35], 0, v[134:135]
	s_mov_b32 m0, s38
	s_nop 0
	global_load_lds_dwordx4 v[218:219], off
	v_lshl_add_u64 v[218:219], s[34:35], 0, v[130:131]
	s_add_i32 m0, s38, 0x2000
	s_nop 0
	global_load_lds_dwordx4 v[218:219], off
	v_lshl_add_u64 v[218:219], v[222:223], 0, s[6:7]
	s_mov_b32 m0, s51
	s_nop 0
	global_load_lds_dwordx4 v[218:219], off
	v_lshl_add_u64 v[218:219], v[224:225], 0, s[6:7]
	s_mov_b32 m0, s52
	s_nop 0
	global_load_lds_dwordx4 v[218:219], off
	s_waitcnt vmcnt(8)
	s_waitcnt lgkmcnt(0)
	s_barrier
	s_setprio 1
	s_waitcnt lgkmcnt(0)
	v_mfma_f32_16x16x32_bf16 v[60:63], v[146:149], v[186:189], v[60:63]
	v_mfma_f32_16x16x32_bf16 v[56:59], v[162:165], v[186:189], v[56:59]
	v_mfma_f32_16x16x32_bf16 v[44:47], v[146:149], v[194:197], v[44:47]
	v_mfma_f32_16x16x32_bf16 v[40:43], v[162:165], v[194:197], v[40:43]
	v_mfma_f32_16x16x32_bf16 v[28:31], v[146:149], v[202:205], v[28:31]
	v_mfma_f32_16x16x32_bf16 v[24:27], v[162:165], v[202:205], v[24:27]
	v_mfma_f32_16x16x32_bf16 v[12:15], v[146:149], v[210:213], v[12:15]
	v_mfma_f32_16x16x32_bf16 v[8:11], v[162:165], v[210:213], v[8:11]
	v_mfma_f32_16x16x32_bf16 v[60:63], v[158:161], v[190:193], v[60:63]
	v_mfma_f32_16x16x32_bf16 v[56:59], v[166:169], v[190:193], v[56:59]
	v_mfma_f32_16x16x32_bf16 v[44:47], v[158:161], v[198:201], v[44:47]
	v_mfma_f32_16x16x32_bf16 v[40:43], v[166:169], v[198:201], v[40:43]
	v_mfma_f32_16x16x32_bf16 v[28:31], v[158:161], v[206:209], v[28:31]
	v_mfma_f32_16x16x32_bf16 v[24:27], v[166:169], v[206:209], v[24:27]
	v_mfma_f32_16x16x32_bf16 v[12:15], v[158:161], v[214:217], v[12:15]
	v_mfma_f32_16x16x32_bf16 v[8:11], v[166:169], v[214:217], v[8:11]
	s_setprio 0
	s_setprio 1
	v_mfma_f32_16x16x32_bf16 v[52:55], v[170:173], v[186:189], v[52:55]
	v_mfma_f32_16x16x32_bf16 v[48:51], v[178:181], v[186:189], v[48:51]
	v_mfma_f32_16x16x32_bf16 v[36:39], v[170:173], v[194:197], v[36:39]
	v_mfma_f32_16x16x32_bf16 v[32:35], v[178:181], v[194:197], v[32:35]
	v_mfma_f32_16x16x32_bf16 v[20:23], v[170:173], v[202:205], v[20:23]
	v_mfma_f32_16x16x32_bf16 v[16:19], v[178:181], v[202:205], v[16:19]
	v_mfma_f32_16x16x32_bf16 v[4:7], v[170:173], v[210:213], v[4:7]
	v_mfma_f32_16x16x32_bf16 v[0:3], v[178:181], v[210:213], v[0:3]
	v_mfma_f32_16x16x32_bf16 v[52:55], v[174:177], v[190:193], v[52:55]
	v_mfma_f32_16x16x32_bf16 v[48:51], v[182:185], v[190:193], v[48:51]
	v_mfma_f32_16x16x32_bf16 v[36:39], v[174:177], v[198:201], v[36:39]
	v_mfma_f32_16x16x32_bf16 v[32:35], v[182:185], v[198:201], v[32:35]
	v_mfma_f32_16x16x32_bf16 v[20:23], v[174:177], v[206:209], v[20:23]
	v_mfma_f32_16x16x32_bf16 v[16:19], v[182:185], v[206:209], v[16:19]
	v_mfma_f32_16x16x32_bf16 v[4:7], v[174:177], v[214:217], v[4:7]
	v_mfma_f32_16x16x32_bf16 v[0:3], v[182:185], v[214:217], v[0:3]
	s_setprio 0
	s_cmp_eq_u32 s62, s98
	s_cbranch_scc1 .Lmy_nobar_17
	s_barrier
.Lmy_nobar_17:
	s_add_i32 s62, s62, 2
	s_add_u32 s36, s36, 0x100
	s_addc_u32 s37, s37, 0
	s_add_u32 s60, s60, 0x100
	s_addc_u32 s61, s61, 0
	s_cmp_gt_u32 s62, 13
	s_cbranch_scc0 .LBB0_1647
	s_and_b64 vcc, exec, s[8:9]
	s_cbranch_vccz .LBB0_1650
	s_nop 0
.LBB0_1650:
	v_lshl_add_u32 v159, s12, 10, v152
	ds_read_b32 v160, v159
	v_lshl_or_b32 v148, s13, 7, v153
	v_lshl_add_u32 v158, s30, 8, v150
	v_ashrrev_i32_e32 v149, 31, v148
	v_mov_b64_e32 v[146:147], s[16:17]
	s_waitcnt lgkmcnt(0)
	v_pk_mul_f32 v[124:125], v[124:125], v[160:161] op_sel_hi:[1,0]
	v_pk_mul_f32 v[126:127], v[126:127], v[160:161] op_sel_hi:[1,0]
	v_pk_mul_f32 v[122:123], v[122:123], v[160:161] op_sel_hi:[1,0]
	v_pk_mul_f32 v[120:121], v[120:121], v[160:161] op_sel_hi:[1,0]
	v_pk_mul_f32 v[118:119], v[118:119], v[160:161] op_sel_hi:[1,0]
	v_pk_mul_f32 v[116:117], v[116:117], v[160:161] op_sel_hi:[1,0]
	v_mul_f32_e32 v161, 0xbfb8aa3b, v124
	v_exp_f32_e32 v161, v161
	v_mul_f32_e32 v164, 0xbfb8aa3b, v125
	v_exp_f32_e32 v166, v164
	v_mad_i64_i32 v[162:163], s[12:13], v158, s55, v[146:147]
	v_pk_mul_f32 v[164:165], v[114:115], v[160:161] op_sel_hi:[1,0]
	v_add_f32_e32 v114, 1.0, v161
	v_rcp_f32_e32 v161, v114
	v_add_f32_e32 v114, 1.0, v166
	v_rcp_f32_e32 v166, v114
	v_lshlrev_b64 v[148:149], 1, v[148:149]
	v_pk_mul_f32 v[114:115], v[112:113], v[160:161] op_sel_hi:[1,0]
	v_mul_f32_e32 v112, v124, v161
	v_mul_f32_e32 v112, v116, v112
	v_mul_f32_e32 v116, 0xbfb8aa3b, v126
	v_mul_f32_e32 v124, 0xbfb8aa3b, v127
	v_exp_f32_e32 v116, v116
	v_exp_f32_e32 v124, v124
	v_mul_f32_e32 v113, v125, v166
	v_mul_f32_e32 v113, v117, v113
	v_add_f32_e32 v116, 1.0, v116
	v_add_f32_e32 v117, 1.0, v124
	v_rcp_f32_e32 v116, v116
	v_rcp_f32_e32 v117, v117
	v_cvt_pk_bf16_f32 v112, v112, v113
	v_lshl_add_u64 v[162:163], v[162:163], 0, v[148:149]
	v_mul_f32_e32 v113, v126, v116
	v_mul_f32_e32 v116, v127, v117
	v_mul_f32_e32 v117, 0xbfb8aa3b, v120
	v_mul_f32_e32 v113, v118, v113
	v_exp_f32_e32 v117, v117
	v_mul_f32_e32 v118, 0xbfb8aa3b, v121
	v_exp_f32_e32 v118, v118
	v_mul_f32_e32 v116, v119, v116
	v_add_f32_e32 v117, 1.0, v117
	v_rcp_f32_e32 v117, v117
	v_add_f32_e32 v118, 1.0, v118
	v_rcp_f32_e32 v118, v118
	v_cvt_pk_bf16_f32 v113, v113, v116
	v_mul_f32_e32 v116, v120, v117
	v_mul_f32_e32 v117, 0xbfb8aa3b, v122
	v_mul_f32_e32 v114, v114, v116
	v_mul_f32_e32 v116, v121, v118
	v_exp_f32_e32 v117, v117
	v_mul_f32_e32 v118, 0xbfb8aa3b, v123
	v_exp_f32_e32 v118, v118
	v_mul_f32_e32 v115, v115, v116
	v_add_f32_e32 v116, 1.0, v117
	v_rcp_f32_e32 v116, v116
	v_add_f32_e32 v117, 1.0, v118
	v_rcp_f32_e32 v117, v117
	v_cvt_pk_bf16_f32 v114, v114, v115
	v_mul_f32_e32 v115, v122, v116
	v_mul_f32_e32 v115, v164, v115
	v_mul_f32_e32 v116, v123, v117
	v_mul_f32_e32 v116, v165, v116
	v_cvt_pk_bf16_f32 v115, v115, v116
	global_store_dwordx4 v[162:163], v[112:115], off
	ds_read_b32 v112, v159 offset:64
	s_andn2_b64 vcc, exec, s[4:5]
	v_or_b32_e32 v113, 16, v158
	v_mad_i64_i32 v[114:115], s[12:13], v113, s55, v[146:147]
	s_waitcnt lgkmcnt(0)
	v_pk_mul_f32 v[108:109], v[108:109], v[112:113] op_sel_hi:[1,0]
	v_pk_mul_f32 v[110:111], v[110:111], v[112:113] op_sel_hi:[1,0]
	v_pk_mul_f32 v[106:107], v[106:107], v[112:113] op_sel_hi:[1,0]
	v_pk_mul_f32 v[104:105], v[104:105], v[112:113] op_sel_hi:[1,0]
	v_pk_mul_f32 v[102:103], v[102:103], v[112:113] op_sel_hi:[1,0]
	v_pk_mul_f32 v[100:101], v[100:101], v[112:113] op_sel_hi:[1,0]
	v_mul_f32_e32 v113, 0xbfb8aa3b, v108
	v_exp_f32_e32 v113, v113
	v_mul_f32_e32 v116, 0xbfb8aa3b, v109
	v_exp_f32_e32 v118, v116
	v_lshl_add_u64 v[114:115], v[114:115], 0, v[148:149]
	v_pk_mul_f32 v[116:117], v[98:99], v[112:113] op_sel_hi:[1,0]
	v_add_f32_e32 v98, 1.0, v113
	v_rcp_f32_e32 v113, v98
	v_add_f32_e32 v98, 1.0, v118
	v_rcp_f32_e32 v118, v98
	s_mov_b64 s[4:5], -1
	v_pk_mul_f32 v[98:99], v[96:97], v[112:113] op_sel_hi:[1,0]
	v_mul_f32_e32 v96, v108, v113
	v_mul_f32_e32 v96, v100, v96
	v_mul_f32_e32 v100, 0xbfb8aa3b, v110
	v_mul_f32_e32 v108, 0xbfb8aa3b, v111
	v_exp_f32_e32 v100, v100
	v_exp_f32_e32 v108, v108
	v_mul_f32_e32 v97, v109, v118
	v_mul_f32_e32 v97, v101, v97
	v_add_f32_e32 v100, 1.0, v100
	v_add_f32_e32 v101, 1.0, v108
	v_rcp_f32_e32 v100, v100
	v_rcp_f32_e32 v101, v101
	v_cvt_pk_bf16_f32 v96, v96, v97
	v_mul_f32_e32 v97, v110, v100
	v_mul_f32_e32 v100, v111, v101
	v_mul_f32_e32 v101, 0xbfb8aa3b, v104
	v_mul_f32_e32 v97, v102, v97
	v_exp_f32_e32 v101, v101
	v_mul_f32_e32 v102, 0xbfb8aa3b, v105
	v_exp_f32_e32 v102, v102
	v_mul_f32_e32 v100, v103, v100
	v_add_f32_e32 v101, 1.0, v101
	v_rcp_f32_e32 v101, v101
	v_add_f32_e32 v102, 1.0, v102
	v_rcp_f32_e32 v102, v102
	v_cvt_pk_bf16_f32 v97, v97, v100
	v_mul_f32_e32 v100, v104, v101
	v_mul_f32_e32 v101, 0xbfb8aa3b, v106
	v_mul_f32_e32 v98, v98, v100
	v_mul_f32_e32 v100, v105, v102
	v_exp_f32_e32 v101, v101
	v_mul_f32_e32 v102, 0xbfb8aa3b, v107
	v_exp_f32_e32 v102, v102
	v_mul_f32_e32 v99, v99, v100
	v_add_f32_e32 v100, 1.0, v101
	v_rcp_f32_e32 v100, v100
	v_add_f32_e32 v101, 1.0, v102
	v_rcp_f32_e32 v101, v101
	v_cvt_pk_bf16_f32 v98, v98, v99
	v_mul_f32_e32 v99, v106, v100
	v_mul_f32_e32 v99, v116, v99
	v_mul_f32_e32 v100, v107, v101
	v_mul_f32_e32 v100, v117, v100
	v_cvt_pk_bf16_f32 v99, v99, v100
	global_store_dwordx4 v[114:115], v[96:99], off
	ds_read_b32 v96, v159 offset:128
	s_nop 0
	v_or_b32_e32 v97, 32, v158
	v_mad_i64_i32 v[98:99], s[12:13], v97, s55, v[146:147]
	s_waitcnt lgkmcnt(0)
	v_pk_mul_f32 v[92:93], v[92:93], v[96:97] op_sel_hi:[1,0]
	v_pk_mul_f32 v[94:95], v[94:95], v[96:97] op_sel_hi:[1,0]
	v_pk_mul_f32 v[90:91], v[90:91], v[96:97] op_sel_hi:[1,0]
	v_pk_mul_f32 v[88:89], v[88:89], v[96:97] op_sel_hi:[1,0]
	v_pk_mul_f32 v[86:87], v[86:87], v[96:97] op_sel_hi:[1,0]
	v_pk_mul_f32 v[84:85], v[84:85], v[96:97] op_sel_hi:[1,0]
	v_mul_f32_e32 v97, 0xbfb8aa3b, v92
	v_exp_f32_e32 v97, v97
	v_mul_f32_e32 v100, 0xbfb8aa3b, v93
	v_exp_f32_e32 v102, v100
	v_lshl_add_u64 v[98:99], v[98:99], 0, v[148:149]
	v_pk_mul_f32 v[100:101], v[82:83], v[96:97] op_sel_hi:[1,0]
	v_add_f32_e32 v82, 1.0, v97
	v_rcp_f32_e32 v97, v82
	v_add_f32_e32 v82, 1.0, v102
	v_rcp_f32_e32 v102, v82
	v_pk_mul_f32 v[82:83], v[80:81], v[96:97] op_sel_hi:[1,0]
	v_mul_f32_e32 v80, v92, v97
	v_mul_f32_e32 v80, v84, v80
	v_mul_f32_e32 v84, 0xbfb8aa3b, v94
	v_mul_f32_e32 v92, 0xbfb8aa3b, v95
	v_exp_f32_e32 v84, v84
	v_exp_f32_e32 v92, v92
	v_mul_f32_e32 v81, v93, v102
	v_mul_f32_e32 v81, v85, v81
	v_add_f32_e32 v84, 1.0, v84
	v_add_f32_e32 v85, 1.0, v92
	v_rcp_f32_e32 v84, v84
	v_rcp_f32_e32 v85, v85
	v_cvt_pk_bf16_f32 v80, v80, v81
	v_mul_f32_e32 v81, v94, v84
	v_mul_f32_e32 v84, v95, v85
	v_mul_f32_e32 v85, 0xbfb8aa3b, v88
	v_mul_f32_e32 v81, v86, v81
	v_exp_f32_e32 v85, v85
	v_mul_f32_e32 v86, 0xbfb8aa3b, v89
	v_exp_f32_e32 v86, v86
	v_mul_f32_e32 v84, v87, v84
	v_add_f32_e32 v85, 1.0, v85
	v_rcp_f32_e32 v85, v85
	v_add_f32_e32 v86, 1.0, v86
	v_rcp_f32_e32 v86, v86
	v_cvt_pk_bf16_f32 v81, v81, v84
	v_mul_f32_e32 v84, v88, v85
	v_mul_f32_e32 v85, 0xbfb8aa3b, v90
	v_mul_f32_e32 v82, v82, v84
	v_mul_f32_e32 v84, v89, v86
	v_exp_f32_e32 v85, v85
	v_mul_f32_e32 v86, 0xbfb8aa3b, v91
	v_exp_f32_e32 v86, v86
	v_mul_f32_e32 v83, v83, v84
	v_add_f32_e32 v84, 1.0, v85
	v_rcp_f32_e32 v84, v84
	v_add_f32_e32 v85, 1.0, v86
	v_rcp_f32_e32 v85, v85
	v_cvt_pk_bf16_f32 v82, v82, v83
	v_mul_f32_e32 v83, v90, v84
	v_mul_f32_e32 v83, v100, v83
	v_mul_f32_e32 v84, v91, v85
	v_mul_f32_e32 v84, v101, v84
	v_cvt_pk_bf16_f32 v83, v83, v84
	global_store_dwordx4 v[98:99], v[80:83], off
	ds_read_b32 v80, v159 offset:192
	s_nop 0
	v_or_b32_e32 v81, 48, v158
	v_mad_i64_i32 v[82:83], s[12:13], v81, s55, v[146:147]
	s_waitcnt lgkmcnt(0)
	v_pk_mul_f32 v[76:77], v[76:77], v[80:81] op_sel_hi:[1,0]
	v_pk_mul_f32 v[78:79], v[78:79], v[80:81] op_sel_hi:[1,0]
	v_pk_mul_f32 v[74:75], v[74:75], v[80:81] op_sel_hi:[1,0]
	v_pk_mul_f32 v[72:73], v[72:73], v[80:81] op_sel_hi:[1,0]
	v_pk_mul_f32 v[70:71], v[70:71], v[80:81] op_sel_hi:[1,0]
	v_pk_mul_f32 v[68:69], v[68:69], v[80:81] op_sel_hi:[1,0]
	v_mul_f32_e32 v81, 0xbfb8aa3b, v76
	v_exp_f32_e32 v81, v81
	v_mul_f32_e32 v84, 0xbfb8aa3b, v77
	v_exp_f32_e32 v86, v84
	v_lshl_add_u64 v[82:83], v[82:83], 0, v[148:149]
	v_pk_mul_f32 v[84:85], v[66:67], v[80:81] op_sel_hi:[1,0]
	v_add_f32_e32 v66, 1.0, v81
	v_rcp_f32_e32 v81, v66
	v_add_f32_e32 v66, 1.0, v86
	v_rcp_f32_e32 v86, v66
	v_pk_mul_f32 v[66:67], v[64:65], v[80:81] op_sel_hi:[1,0]
	v_mul_f32_e32 v64, v76, v81
	v_mul_f32_e32 v64, v68, v64
	v_mul_f32_e32 v68, 0xbfb8aa3b, v78
	v_mul_f32_e32 v76, 0xbfb8aa3b, v79
	v_exp_f32_e32 v68, v68
	v_exp_f32_e32 v76, v76
	v_mul_f32_e32 v65, v77, v86
	v_mul_f32_e32 v65, v69, v65
	v_add_f32_e32 v68, 1.0, v68
	v_add_f32_e32 v69, 1.0, v76
	v_rcp_f32_e32 v68, v68
	v_rcp_f32_e32 v69, v69
	v_cvt_pk_bf16_f32 v64, v64, v65
	v_mul_f32_e32 v65, v78, v68
	v_mul_f32_e32 v68, v79, v69
	v_mul_f32_e32 v69, 0xbfb8aa3b, v72
	v_mul_f32_e32 v65, v70, v65
	v_exp_f32_e32 v69, v69
	v_mul_f32_e32 v70, 0xbfb8aa3b, v73
	v_exp_f32_e32 v70, v70
	v_mul_f32_e32 v68, v71, v68
	v_add_f32_e32 v69, 1.0, v69
	v_rcp_f32_e32 v69, v69
	v_add_f32_e32 v70, 1.0, v70
	v_rcp_f32_e32 v70, v70
	v_cvt_pk_bf16_f32 v65, v65, v68
	v_mul_f32_e32 v68, v72, v69
	v_mul_f32_e32 v69, 0xbfb8aa3b, v74
	v_mul_f32_e32 v66, v66, v68
	v_mul_f32_e32 v68, v73, v70
	v_exp_f32_e32 v69, v69
	v_mul_f32_e32 v70, 0xbfb8aa3b, v75
	v_exp_f32_e32 v70, v70
	v_mul_f32_e32 v67, v67, v68
	v_add_f32_e32 v68, 1.0, v69
	v_rcp_f32_e32 v68, v68
	v_add_f32_e32 v69, 1.0, v70
	v_rcp_f32_e32 v69, v69
	v_cvt_pk_bf16_f32 v66, v66, v67
	v_mul_f32_e32 v67, v74, v68
	v_mul_f32_e32 v67, v84, v67
	v_mul_f32_e32 v68, v75, v69
	v_mul_f32_e32 v68, v85, v68
	v_cvt_pk_bf16_f32 v67, v67, v68
	global_store_dwordx4 v[82:83], v[64:67], off
	ds_read_b32 v64, v159 offset:512
	s_nop 0
	v_add_u32_e32 v65, 0x80, v158
	v_mad_i64_i32 v[66:67], s[12:13], v65, s55, v[146:147]
	s_waitcnt lgkmcnt(0)
	v_pk_mul_f32 v[60:61], v[60:61], v[64:65] op_sel_hi:[1,0]
	v_pk_mul_f32 v[62:63], v[62:63], v[64:65] op_sel_hi:[1,0]
	v_pk_mul_f32 v[58:59], v[58:59], v[64:65] op_sel_hi:[1,0]
	v_pk_mul_f32 v[56:57], v[56:57], v[64:65] op_sel_hi:[1,0]
	v_pk_mul_f32 v[54:55], v[54:55], v[64:65] op_sel_hi:[1,0]
	v_pk_mul_f32 v[52:53], v[52:53], v[64:65] op_sel_hi:[1,0]
	v_mul_f32_e32 v65, 0xbfb8aa3b, v60
	v_exp_f32_e32 v65, v65
	v_mul_f32_e32 v68, 0xbfb8aa3b, v61
	v_exp_f32_e32 v70, v68
	v_lshl_add_u64 v[66:67], v[66:67], 0, v[148:149]
	v_pk_mul_f32 v[68:69], v[50:51], v[64:65] op_sel_hi:[1,0]
	v_add_f32_e32 v50, 1.0, v65
	v_rcp_f32_e32 v65, v50
	v_add_f32_e32 v50, 1.0, v70
	v_rcp_f32_e32 v70, v50
	v_pk_mul_f32 v[50:51], v[48:49], v[64:65] op_sel_hi:[1,0]
	v_mul_f32_e32 v48, v60, v65
	v_mul_f32_e32 v48, v52, v48
	v_mul_f32_e32 v52, 0xbfb8aa3b, v62
	v_mul_f32_e32 v60, 0xbfb8aa3b, v63
	v_exp_f32_e32 v52, v52
	v_exp_f32_e32 v60, v60
	v_mul_f32_e32 v49, v61, v70
	v_mul_f32_e32 v49, v53, v49
	v_add_f32_e32 v52, 1.0, v52
	v_add_f32_e32 v53, 1.0, v60
	v_rcp_f32_e32 v52, v52
	v_rcp_f32_e32 v53, v53
	v_cvt_pk_bf16_f32 v48, v48, v49
	v_mul_f32_e32 v49, v62, v52
	v_mul_f32_e32 v52, v63, v53
	v_mul_f32_e32 v53, 0xbfb8aa3b, v56
	v_mul_f32_e32 v49, v54, v49
	v_exp_f32_e32 v53, v53
	v_mul_f32_e32 v54, 0xbfb8aa3b, v57
	v_exp_f32_e32 v54, v54
	v_mul_f32_e32 v52, v55, v52
	v_add_f32_e32 v53, 1.0, v53
	v_rcp_f32_e32 v53, v53
	v_add_f32_e32 v54, 1.0, v54
	v_rcp_f32_e32 v54, v54
	v_cvt_pk_bf16_f32 v49, v49, v52
	v_mul_f32_e32 v52, v56, v53
	v_mul_f32_e32 v53, 0xbfb8aa3b, v58
	v_mul_f32_e32 v50, v50, v52
	v_mul_f32_e32 v52, v57, v54
	v_exp_f32_e32 v53, v53
	v_mul_f32_e32 v54, 0xbfb8aa3b, v59
	v_exp_f32_e32 v54, v54
	v_mul_f32_e32 v51, v51, v52
	v_add_f32_e32 v52, 1.0, v53
	v_rcp_f32_e32 v52, v52
	v_add_f32_e32 v53, 1.0, v54
	v_rcp_f32_e32 v53, v53
	v_cvt_pk_bf16_f32 v50, v50, v51
	v_mul_f32_e32 v51, v58, v52
	v_mul_f32_e32 v51, v68, v51
	v_mul_f32_e32 v52, v59, v53
	v_mul_f32_e32 v52, v69, v52
	v_cvt_pk_bf16_f32 v51, v51, v52
	global_store_dwordx4 v[66:67], v[48:51], off
	ds_read_b32 v48, v159 offset:576
	s_nop 0
	v_add_u32_e32 v49, 0x90, v158
	v_mad_i64_i32 v[50:51], s[12:13], v49, s55, v[146:147]
	s_waitcnt lgkmcnt(0)
	v_pk_mul_f32 v[44:45], v[44:45], v[48:49] op_sel_hi:[1,0]
	v_pk_mul_f32 v[46:47], v[46:47], v[48:49] op_sel_hi:[1,0]
	v_pk_mul_f32 v[42:43], v[42:43], v[48:49] op_sel_hi:[1,0]
	v_pk_mul_f32 v[40:41], v[40:41], v[48:49] op_sel_hi:[1,0]
	v_pk_mul_f32 v[38:39], v[38:39], v[48:49] op_sel_hi:[1,0]
	v_pk_mul_f32 v[36:37], v[36:37], v[48:49] op_sel_hi:[1,0]
	v_mul_f32_e32 v49, 0xbfb8aa3b, v44
	v_exp_f32_e32 v49, v49
	v_mul_f32_e32 v52, 0xbfb8aa3b, v45
	v_exp_f32_e32 v54, v52
	v_lshl_add_u64 v[50:51], v[50:51], 0, v[148:149]
	v_pk_mul_f32 v[52:53], v[34:35], v[48:49] op_sel_hi:[1,0]
	v_add_f32_e32 v34, 1.0, v49
	v_rcp_f32_e32 v49, v34
	v_add_f32_e32 v34, 1.0, v54
	v_rcp_f32_e32 v54, v34
	v_pk_mul_f32 v[34:35], v[32:33], v[48:49] op_sel_hi:[1,0]
	v_mul_f32_e32 v32, v44, v49
	v_mul_f32_e32 v32, v36, v32
	v_mul_f32_e32 v36, 0xbfb8aa3b, v46
	v_mul_f32_e32 v44, 0xbfb8aa3b, v47
	v_exp_f32_e32 v36, v36
	v_exp_f32_e32 v44, v44
	v_mul_f32_e32 v33, v45, v54
	v_mul_f32_e32 v33, v37, v33
	v_add_f32_e32 v36, 1.0, v36
	v_add_f32_e32 v37, 1.0, v44
	v_rcp_f32_e32 v36, v36
	v_rcp_f32_e32 v37, v37
	v_cvt_pk_bf16_f32 v32, v32, v33
	v_mul_f32_e32 v33, v46, v36
	v_mul_f32_e32 v36, v47, v37
	v_mul_f32_e32 v37, 0xbfb8aa3b, v40
	v_mul_f32_e32 v33, v38, v33
	v_exp_f32_e32 v37, v37
	v_mul_f32_e32 v38, 0xbfb8aa3b, v41
	v_exp_f32_e32 v38, v38
	v_mul_f32_e32 v36, v39, v36
	v_add_f32_e32 v37, 1.0, v37
	v_rcp_f32_e32 v37, v37
	v_add_f32_e32 v38, 1.0, v38
	v_rcp_f32_e32 v38, v38
	v_cvt_pk_bf16_f32 v33, v33, v36
	v_mul_f32_e32 v36, v40, v37
	v_mul_f32_e32 v37, 0xbfb8aa3b, v42
	v_mul_f32_e32 v34, v34, v36
	v_mul_f32_e32 v36, v41, v38
	v_exp_f32_e32 v37, v37
	v_mul_f32_e32 v38, 0xbfb8aa3b, v43
	v_exp_f32_e32 v38, v38
	v_mul_f32_e32 v35, v35, v36
	v_add_f32_e32 v36, 1.0, v37
	v_rcp_f32_e32 v36, v36
	v_add_f32_e32 v37, 1.0, v38
	v_rcp_f32_e32 v37, v37
	v_cvt_pk_bf16_f32 v34, v34, v35
	v_mul_f32_e32 v35, v42, v36
	v_mul_f32_e32 v35, v52, v35
	v_mul_f32_e32 v36, v43, v37
	v_mul_f32_e32 v36, v53, v36
	v_cvt_pk_bf16_f32 v35, v35, v36
	global_store_dwordx4 v[50:51], v[32:35], off
	ds_read_b32 v32, v159 offset:640
	s_nop 0
	v_add_u32_e32 v33, 0xa0, v158
	v_mad_i64_i32 v[34:35], s[12:13], v33, s55, v[146:147]
	s_waitcnt lgkmcnt(0)
	v_pk_mul_f32 v[28:29], v[28:29], v[32:33] op_sel_hi:[1,0]
	v_pk_mul_f32 v[30:31], v[30:31], v[32:33] op_sel_hi:[1,0]
	v_pk_mul_f32 v[26:27], v[26:27], v[32:33] op_sel_hi:[1,0]
	v_pk_mul_f32 v[24:25], v[24:25], v[32:33] op_sel_hi:[1,0]
	v_pk_mul_f32 v[22:23], v[22:23], v[32:33] op_sel_hi:[1,0]
	v_pk_mul_f32 v[20:21], v[20:21], v[32:33] op_sel_hi:[1,0]
	v_mul_f32_e32 v33, 0xbfb8aa3b, v28
	v_exp_f32_e32 v33, v33
	v_mul_f32_e32 v36, 0xbfb8aa3b, v29
	v_exp_f32_e32 v38, v36
	v_lshl_add_u64 v[34:35], v[34:35], 0, v[148:149]
	v_pk_mul_f32 v[36:37], v[18:19], v[32:33] op_sel_hi:[1,0]
	v_add_f32_e32 v18, 1.0, v33
	v_rcp_f32_e32 v33, v18
	v_add_f32_e32 v18, 1.0, v38
	v_rcp_f32_e32 v38, v18
	v_pk_mul_f32 v[18:19], v[16:17], v[32:33] op_sel_hi:[1,0]
	v_mul_f32_e32 v16, v28, v33
	v_mul_f32_e32 v16, v20, v16
	v_mul_f32_e32 v20, 0xbfb8aa3b, v30
	v_mul_f32_e32 v28, 0xbfb8aa3b, v31
	v_exp_f32_e32 v20, v20
	v_exp_f32_e32 v28, v28
	v_mul_f32_e32 v17, v29, v38
	v_mul_f32_e32 v17, v21, v17
	v_add_f32_e32 v20, 1.0, v20
	v_add_f32_e32 v21, 1.0, v28
	v_rcp_f32_e32 v20, v20
	v_rcp_f32_e32 v21, v21
	v_cvt_pk_bf16_f32 v16, v16, v17
	v_mul_f32_e32 v17, v30, v20
	v_mul_f32_e32 v20, v31, v21
	v_mul_f32_e32 v21, 0xbfb8aa3b, v24
	v_mul_f32_e32 v17, v22, v17
	v_exp_f32_e32 v21, v21
	v_mul_f32_e32 v22, 0xbfb8aa3b, v25
	v_exp_f32_e32 v22, v22
	v_mul_f32_e32 v20, v23, v20
	v_add_f32_e32 v21, 1.0, v21
	v_rcp_f32_e32 v21, v21
	v_add_f32_e32 v22, 1.0, v22
	v_rcp_f32_e32 v22, v22
	v_cvt_pk_bf16_f32 v17, v17, v20
	v_mul_f32_e32 v20, v24, v21
	v_mul_f32_e32 v21, 0xbfb8aa3b, v26
	v_mul_f32_e32 v18, v18, v20
	v_mul_f32_e32 v20, v25, v22
	v_exp_f32_e32 v21, v21
	v_mul_f32_e32 v22, 0xbfb8aa3b, v27
	v_exp_f32_e32 v22, v22
	v_mul_f32_e32 v19, v19, v20
	v_add_f32_e32 v20, 1.0, v21
	v_rcp_f32_e32 v20, v20
	v_add_f32_e32 v21, 1.0, v22
	v_rcp_f32_e32 v21, v21
	v_cvt_pk_bf16_f32 v18, v18, v19
	v_mul_f32_e32 v19, v26, v20
	v_mul_f32_e32 v19, v36, v19
	v_mul_f32_e32 v20, v27, v21
	v_mul_f32_e32 v20, v37, v20
	v_cvt_pk_bf16_f32 v19, v19, v20
	global_store_dwordx4 v[34:35], v[16:19], off
	ds_read_b32 v16, v159 offset:704
	s_nop 0
	v_add_u32_e32 v17, 0xb0, v158
	v_mad_i64_i32 v[18:19], s[12:13], v17, s55, v[146:147]
	s_waitcnt lgkmcnt(0)
	v_pk_mul_f32 v[12:13], v[12:13], v[16:17] op_sel_hi:[1,0]
	v_pk_mul_f32 v[14:15], v[14:15], v[16:17] op_sel_hi:[1,0]
	v_pk_mul_f32 v[10:11], v[10:11], v[16:17] op_sel_hi:[1,0]
	v_pk_mul_f32 v[8:9], v[8:9], v[16:17] op_sel_hi:[1,0]
	v_pk_mul_f32 v[6:7], v[6:7], v[16:17] op_sel_hi:[1,0]
	v_pk_mul_f32 v[4:5], v[4:5], v[16:17] op_sel_hi:[1,0]
	v_mul_f32_e32 v17, 0xbfb8aa3b, v12
	v_exp_f32_e32 v17, v17
	v_mul_f32_e32 v20, 0xbfb8aa3b, v13
	v_exp_f32_e32 v22, v20
	v_lshl_add_u64 v[18:19], v[18:19], 0, v[148:149]
	v_pk_mul_f32 v[20:21], v[2:3], v[16:17] op_sel_hi:[1,0]
	v_add_f32_e32 v2, 1.0, v17
	v_rcp_f32_e32 v17, v2
	v_add_f32_e32 v2, 1.0, v22
	v_rcp_f32_e32 v22, v2
	v_pk_mul_f32 v[2:3], v[0:1], v[16:17] op_sel_hi:[1,0]
	v_mul_f32_e32 v0, v12, v17
	v_mul_f32_e32 v0, v4, v0
	v_mul_f32_e32 v4, 0xbfb8aa3b, v14
	v_mul_f32_e32 v12, 0xbfb8aa3b, v15
	v_exp_f32_e32 v4, v4
	v_exp_f32_e32 v12, v12
	v_mul_f32_e32 v1, v13, v22
	v_mul_f32_e32 v1, v5, v1
	v_add_f32_e32 v4, 1.0, v4
	v_add_f32_e32 v5, 1.0, v12
	v_rcp_f32_e32 v4, v4
	v_rcp_f32_e32 v5, v5
	v_cvt_pk_bf16_f32 v0, v0, v1
	v_mul_f32_e32 v1, v14, v4
	v_mul_f32_e32 v4, v15, v5
	v_mul_f32_e32 v5, 0xbfb8aa3b, v8
	v_mul_f32_e32 v1, v6, v1
	v_exp_f32_e32 v5, v5
	v_mul_f32_e32 v6, 0xbfb8aa3b, v9
	v_exp_f32_e32 v6, v6
	v_mul_f32_e32 v4, v7, v4
	v_add_f32_e32 v5, 1.0, v5
	v_rcp_f32_e32 v5, v5
	v_add_f32_e32 v6, 1.0, v6
	v_rcp_f32_e32 v6, v6
	v_cvt_pk_bf16_f32 v1, v1, v4
	v_mul_f32_e32 v4, v8, v5
	v_mul_f32_e32 v5, 0xbfb8aa3b, v10
	v_mul_f32_e32 v2, v2, v4
	v_mul_f32_e32 v4, v9, v6
	v_exp_f32_e32 v5, v5
	v_mul_f32_e32 v6, 0xbfb8aa3b, v11
	v_exp_f32_e32 v6, v6
	v_mul_f32_e32 v3, v3, v4
	v_add_f32_e32 v4, 1.0, v5
	v_rcp_f32_e32 v4, v4
	v_add_f32_e32 v5, 1.0, v6
	v_rcp_f32_e32 v5, v5
	v_cvt_pk_bf16_f32 v2, v2, v3
	v_mul_f32_e32 v3, v10, v4
	v_mul_f32_e32 v3, v20, v3
	v_mul_f32_e32 v4, v11, v5
	v_mul_f32_e32 v4, v21, v4
	v_cvt_pk_bf16_f32 v3, v3, v4
	global_store_dwordx4 v[18:19], v[0:3], off
	s_cbranch_vccnz .LBB0_1643
	s_andn2_b64 vcc, exec, s[0:1]
	s_cbranch_vccnz .LBB0_1642
	s_nop 0
	s_branch .LBB0_1642

.LBB0_1722:
	s_lshr_b32 s99, s91, 2
	s_cmp_eq_u32 s99, 1
	s_cselect_b32 s98, 40, 0x7fffffff
	s_add_i32 s54, s54, 1
	s_mul_i32 s0, s54, s49
	s_mul_hi_u32 s1, s54, s50
	s_add_i32 s1, s1, s0
	s_mul_i32 s0, s54, s50
	s_add_u32 s6, s0, s2
	s_addc_u32 s7, s1, s51
	v_cmp_gt_i64_e32 vcc, s[6:7], v[144:145]
	v_cmp_lt_i64_e64 s[0:1], s[6:7], v[142:143]
	s_cbranch_vccnz .LBB0_1728
	s_ashr_i32 s7, s6, 31
	s_lshr_b32 s7, s7, 29
	s_add_i32 s13, s6, s7
	s_and_b32 s7, s13, -8
	s_sub_i32 s28, s6, s7
	s_cmp_gt_i32 s28, -1
	s_mov_b64 s[6:7], -1
	s_cbranch_scc0 .LBB0_1725
	s_lshl_b32 s29, s28, 6
	s_mov_b64 s[6:7], 0

.LBB0_1732:
	s_add_u32 s30, s30, 0xb0080
	s_addc_u32 s31, s31, 0
	s_add_u32 s13, s36, 0x100
	v_mov_b32_e32 v0, 0
	s_addc_u32 s57, s37, 0
	s_mov_b32 s58, -2
	s_waitcnt lgkmcnt(0)
	v_mov_b32_e32 v1, v0
	v_mov_b32_e32 v2, v0
	v_mov_b32_e32 v3, v0
	v_mov_b32_e32 v4, v0
	v_mov_b32_e32 v5, v0
	v_mov_b32_e32 v6, v0
	v_mov_b32_e32 v7, v0
	v_mov_b32_e32 v16, v0
	v_mov_b32_e32 v17, v0
	v_mov_b32_e32 v18, v0
	v_mov_b32_e32 v19, v0
	v_mov_b32_e32 v20, v0
	v_mov_b32_e32 v21, v0
	v_mov_b32_e32 v22, v0
	v_mov_b32_e32 v23, v0
	v_mov_b32_e32 v32, v0
	v_mov_b32_e32 v33, v0
	v_mov_b32_e32 v34, v0
	v_mov_b32_e32 v35, v0
	v_mov_b32_e32 v36, v0
	v_mov_b32_e32 v37, v0
	v_mov_b32_e32 v38, v0
	v_mov_b32_e32 v39, v0
	v_mov_b32_e32 v48, v0
	v_mov_b32_e32 v49, v0
	v_mov_b32_e32 v50, v0
	v_mov_b32_e32 v51, v0
	v_mov_b32_e32 v52, v0
	v_mov_b32_e32 v53, v0
	v_mov_b32_e32 v54, v0
	v_mov_b32_e32 v55, v0
	v_mov_b32_e32 v8, v0
	v_mov_b32_e32 v9, v0
	v_mov_b32_e32 v10, v0
	v_mov_b32_e32 v11, v0
	v_mov_b32_e32 v12, v0
	v_mov_b32_e32 v13, v0
	v_mov_b32_e32 v14, v0
	v_mov_b32_e32 v15, v0
	v_mov_b32_e32 v24, v0
	v_mov_b32_e32 v25, v0
	v_mov_b32_e32 v26, v0
	v_mov_b32_e32 v27, v0
	v_mov_b32_e32 v28, v0
	v_mov_b32_e32 v29, v0
	v_mov_b32_e32 v30, v0
	v_mov_b32_e32 v31, v0
	v_mov_b32_e32 v40, v0
	v_mov_b32_e32 v41, v0
	v_mov_b32_e32 v42, v0
	v_mov_b32_e32 v43, v0
	v_mov_b32_e32 v44, v0
	v_mov_b32_e32 v45, v0
	v_mov_b32_e32 v46, v0
	v_mov_b32_e32 v47, v0
	v_mov_b32_e32 v56, v0
	v_mov_b32_e32 v57, v0
	v_mov_b32_e32 v58, v0
	v_mov_b32_e32 v59, v0
	v_mov_b32_e32 v60, v0
	v_mov_b32_e32 v61, v0
	v_mov_b32_e32 v62, v0
	v_mov_b32_e32 v63, v0
	v_mov_b32_e32 v64, v0
	v_mov_b32_e32 v65, v0
	v_mov_b32_e32 v66, v0
	v_mov_b32_e32 v67, v0
	v_mov_b32_e32 v68, v0
	v_mov_b32_e32 v69, v0
	v_mov_b32_e32 v70, v0
	v_mov_b32_e32 v71, v0
	v_mov_b32_e32 v80, v0
	v_mov_b32_e32 v81, v0
	v_mov_b32_e32 v82, v0
	v_mov_b32_e32 v83, v0
	v_mov_b32_e32 v84, v0
	v_mov_b32_e32 v85, v0
	v_mov_b32_e32 v86, v0
	v_mov_b32_e32 v87, v0
	v_mov_b32_e32 v96, v0
	v_mov_b32_e32 v97, v0
	v_mov_b32_e32 v98, v0
	v_mov_b32_e32 v99, v0
	v_mov_b32_e32 v100, v0
	v_mov_b32_e32 v101, v0
	v_mov_b32_e32 v102, v0
	v_mov_b32_e32 v103, v0
	v_mov_b32_e32 v112, v0
	v_mov_b32_e32 v113, v0
	v_mov_b32_e32 v114, v0
	v_mov_b32_e32 v115, v0
	v_mov_b32_e32 v116, v0
	v_mov_b32_e32 v117, v0
	v_mov_b32_e32 v118, v0
	v_mov_b32_e32 v119, v0
	v_mov_b32_e32 v72, v0
	v_mov_b32_e32 v73, v0
	v_mov_b32_e32 v74, v0
	v_mov_b32_e32 v75, v0
	v_mov_b32_e32 v76, v0
	v_mov_b32_e32 v77, v0
	v_mov_b32_e32 v78, v0
	v_mov_b32_e32 v79, v0
	v_mov_b32_e32 v88, v0
	v_mov_b32_e32 v89, v0
	v_mov_b32_e32 v90, v0
	v_mov_b32_e32 v91, v0
	v_mov_b32_e32 v92, v0
	v_mov_b32_e32 v93, v0
	v_mov_b32_e32 v94, v0
	v_mov_b32_e32 v95, v0
	v_mov_b32_e32 v104, v0
	v_mov_b32_e32 v105, v0
	v_mov_b32_e32 v106, v0
	v_mov_b32_e32 v107, v0
	v_mov_b32_e32 v108, v0
	v_mov_b32_e32 v109, v0
	v_mov_b32_e32 v110, v0
	v_mov_b32_e32 v111, v0
	v_mov_b32_e32 v120, v0
	v_mov_b32_e32 v121, v0
	v_mov_b32_e32 v122, v0
	v_mov_b32_e32 v123, v0
	v_mov_b32_e32 v124, v0
	v_mov_b32_e32 v125, v0
	v_mov_b32_e32 v126, v0
	v_mov_b32_e32 v127, v0
	s_cmp_lg_u32 s54, 1
	s_cselect_b32 s100, s99, 0
	s_cmp_lg_u32 s100, 0
	s_cbranch_scc0 .Lmy_nobar2_18
	s_barrier
.Lmy_nobar2_18:
.LBB0_1733:
	ds_read_b128 v[146:149], v153
	ds_read_b128 v[158:161], v153 offset:1024
	ds_read_b128 v[162:165], v153 offset:2048
	ds_read_b128 v[166:169], v153 offset:3072
	ds_read_b128 v[170:173], v154
	ds_read_b128 v[174:177], v154 offset:1024
	ds_read_b128 v[178:181], v154 offset:2048
	ds_read_b128 v[182:185], v154 offset:3072
	s_add_u32 s34, s30, 0xfff50080
	s_addc_u32 s35, s31, -1
	s_cmp_eq_u32 s58, 40
	s_cselect_b32 s39, s1, s35
	s_cselect_b32 s38, s0, s34
	s_cselect_b32 s37, s29, s57
	s_cselect_b32 s36, s28, s13
	v_lshl_add_u64 v[218:219], s[30:31], 0, v[138:139]
	s_add_i32 m0, s42, 0xc000
	ds_read_b128 v[186:189], v155
	ds_read_b128 v[190:193], v155 offset:1024
	ds_read_b128 v[194:197], v155 offset:2048
	ds_read_b128 v[198:201], v155 offset:3072
	ds_read_b128 v[202:205], v155 offset:4096
	ds_read_b128 v[206:209], v155 offset:5120
	ds_read_b128 v[210:213], v155 offset:6144
	ds_read_b128 v[214:217], v155 offset:7168
	global_load_lds_dwordx4 v[218:219], off
	v_lshl_add_u64 v[218:219], s[30:31], 0, v[140:141]
	s_add_i32 m0, s42, 0xe000
	s_nop 0
	global_load_lds_dwordx4 v[218:219], off
	s_waitcnt vmcnt(8)
	s_waitcnt lgkmcnt(0)
	s_barrier
	s_setprio 1
	s_waitcnt lgkmcnt(0)
	v_mfma_f32_16x16x32_bf16 v[124:127], v[146:149], v[186:189], v[124:127]
	v_mfma_f32_16x16x32_bf16 v[120:123], v[162:165], v[186:189], v[120:123]
	v_mfma_f32_16x16x32_bf16 v[108:111], v[146:149], v[194:197], v[108:111]
	v_mfma_f32_16x16x32_bf16 v[104:107], v[162:165], v[194:197], v[104:107]
	v_mfma_f32_16x16x32_bf16 v[92:95], v[146:149], v[202:205], v[92:95]
	v_mfma_f32_16x16x32_bf16 v[88:91], v[162:165], v[202:205], v[88:91]
	v_mfma_f32_16x16x32_bf16 v[76:79], v[146:149], v[210:213], v[76:79]
	v_mfma_f32_16x16x32_bf16 v[72:75], v[162:165], v[210:213], v[72:75]
	v_mfma_f32_16x16x32_bf16 v[124:127], v[158:161], v[190:193], v[124:127]
	v_mfma_f32_16x16x32_bf16 v[120:123], v[166:169], v[190:193], v[120:123]
	v_mfma_f32_16x16x32_bf16 v[108:111], v[158:161], v[198:201], v[108:111]
	v_mfma_f32_16x16x32_bf16 v[104:107], v[166:169], v[198:201], v[104:107]
	v_mfma_f32_16x16x32_bf16 v[92:95], v[158:161], v[206:209], v[92:95]
	v_mfma_f32_16x16x32_bf16 v[88:91], v[166:169], v[206:209], v[88:91]
	v_mfma_f32_16x16x32_bf16 v[76:79], v[158:161], v[214:217], v[76:79]
	v_mfma_f32_16x16x32_bf16 v[72:75], v[166:169], v[214:217], v[72:75]
	s_setprio 0
	s_setprio 1
	v_mfma_f32_16x16x32_bf16 v[116:119], v[170:173], v[186:189], v[116:119]
	v_mfma_f32_16x16x32_bf16 v[112:115], v[178:181], v[186:189], v[112:115]
	v_mfma_f32_16x16x32_bf16 v[100:103], v[170:173], v[194:197], v[100:103]
	v_mfma_f32_16x16x32_bf16 v[96:99], v[178:181], v[194:197], v[96:99]
	v_mfma_f32_16x16x32_bf16 v[84:87], v[170:173], v[202:205], v[84:87]
	v_mfma_f32_16x16x32_bf16 v[80:83], v[178:181], v[202:205], v[80:83]
	v_mfma_f32_16x16x32_bf16 v[68:71], v[170:173], v[210:213], v[68:71]
	v_mfma_f32_16x16x32_bf16 v[64:67], v[178:181], v[210:213], v[64:67]
	v_mfma_f32_16x16x32_bf16 v[116:119], v[174:177], v[190:193], v[116:119]
	v_mfma_f32_16x16x32_bf16 v[112:115], v[182:185], v[190:193], v[112:115]
	v_mfma_f32_16x16x32_bf16 v[100:103], v[174:177], v[198:201], v[100:103]
	v_mfma_f32_16x16x32_bf16 v[96:99], v[182:185], v[198:201], v[96:99]
	v_mfma_f32_16x16x32_bf16 v[84:87], v[174:177], v[206:209], v[84:87]
	v_mfma_f32_16x16x32_bf16 v[80:83], v[182:185], v[206:209], v[80:83]
	v_mfma_f32_16x16x32_bf16 v[68:71], v[174:177], v[214:217], v[68:71]
	v_mfma_f32_16x16x32_bf16 v[64:67], v[182:185], v[214:217], v[64:67]
	s_setprio 0
	s_barrier
	s_add_i32 s34, s52, s41
	v_lshl_add_u64 v[218:219], s[36:37], 0, v[132:133]
	s_mov_b32 m0, s34
	ds_read_b128 v[186:189], v155 offset:16384
	ds_read_b128 v[190:193], v155 offset:17408
	ds_read_b128 v[194:197], v155 offset:18432
	ds_read_b128 v[198:201], v155 offset:19456
	ds_read_b128 v[202:205], v155 offset:20480
	ds_read_b128 v[206:209], v155 offset:21504
	ds_read_b128 v[210:213], v155 offset:22528
	ds_read_b128 v[214:217], v155 offset:23552
	global_load_lds_dwordx4 v[218:219], off
	s_add_i32 m0, s34, 0x2000
	s_add_u32 s34, s36, 0xb0000
	v_lshl_add_u64 v[220:221], s[36:37], 0, v[136:137]
	s_addc_u32 s35, s37, 0
	s_add_i32 s59, s53, s41
	global_load_lds_dwordx4 v[220:221], off
	v_lshl_add_u64 v[222:223], s[34:35], 0, v[132:133]
	s_mov_b32 m0, s59
	v_lshl_add_u64 v[224:225], s[38:39], 0, v[134:135]
	global_load_lds_dwordx4 v[222:223], off
	v_lshl_add_u64 v[222:223], s[34:35], 0, v[136:137]
	s_add_i32 m0, s59, 0x2000
	s_nop 0
	global_load_lds_dwordx4 v[222:223], off
	v_lshl_add_u64 v[222:223], s[38:39], 0, v[130:131]
	s_mov_b32 m0, s42
	s_nop 0
	global_load_lds_dwordx4 v[222:223], off
	s_mov_b32 m0, s43
	s_nop 0
	global_load_lds_dwordx4 v[224:225], off
	s_waitcnt vmcnt(8)
	s_waitcnt lgkmcnt(0)
	s_barrier
	s_setprio 1
	s_waitcnt lgkmcnt(0)
	v_mfma_f32_16x16x32_bf16 v[60:63], v[146:149], v[186:189], v[60:63]
	v_mfma_f32_16x16x32_bf16 v[56:59], v[162:165], v[186:189], v[56:59]
	v_mfma_f32_16x16x32_bf16 v[44:47], v[146:149], v[194:197], v[44:47]
	v_mfma_f32_16x16x32_bf16 v[40:43], v[162:165], v[194:197], v[40:43]
	v_mfma_f32_16x16x32_bf16 v[28:31], v[146:149], v[202:205], v[28:31]
	v_mfma_f32_16x16x32_bf16 v[24:27], v[162:165], v[202:205], v[24:27]
	v_mfma_f32_16x16x32_bf16 v[12:15], v[146:149], v[210:213], v[12:15]
	v_mfma_f32_16x16x32_bf16 v[8:11], v[162:165], v[210:213], v[8:11]
	v_mfma_f32_16x16x32_bf16 v[60:63], v[158:161], v[190:193], v[60:63]
	v_mfma_f32_16x16x32_bf16 v[56:59], v[166:169], v[190:193], v[56:59]
	v_mfma_f32_16x16x32_bf16 v[44:47], v[158:161], v[198:201], v[44:47]
	v_mfma_f32_16x16x32_bf16 v[40:43], v[166:169], v[198:201], v[40:43]
	v_mfma_f32_16x16x32_bf16 v[28:31], v[158:161], v[206:209], v[28:31]
	v_mfma_f32_16x16x32_bf16 v[24:27], v[166:169], v[206:209], v[24:27]
	v_mfma_f32_16x16x32_bf16 v[12:15], v[158:161], v[214:217], v[12:15]
	v_mfma_f32_16x16x32_bf16 v[8:11], v[166:169], v[214:217], v[8:11]
	s_setprio 0
	s_setprio 1
	v_mfma_f32_16x16x32_bf16 v[52:55], v[170:173], v[186:189], v[52:55]
	v_mfma_f32_16x16x32_bf16 v[48:51], v[178:181], v[186:189], v[48:51]
	v_mfma_f32_16x16x32_bf16 v[36:39], v[170:173], v[194:197], v[36:39]
	v_mfma_f32_16x16x32_bf16 v[32:35], v[178:181], v[194:197], v[32:35]
	v_mfma_f32_16x16x32_bf16 v[20:23], v[170:173], v[202:205], v[20:23]
	v_mfma_f32_16x16x32_bf16 v[16:19], v[178:181], v[202:205], v[16:19]
	v_mfma_f32_16x16x32_bf16 v[4:7], v[170:173], v[210:213], v[4:7]
	v_mfma_f32_16x16x32_bf16 v[0:3], v[178:181], v[210:213], v[0:3]
	v_mfma_f32_16x16x32_bf16 v[52:55], v[174:177], v[190:193], v[52:55]
	v_mfma_f32_16x16x32_bf16 v[48:51], v[182:185], v[190:193], v[48:51]
	v_mfma_f32_16x16x32_bf16 v[36:39], v[174:177], v[198:201], v[36:39]
	v_mfma_f32_16x16x32_bf16 v[32:35], v[182:185], v[198:201], v[32:35]
	v_mfma_f32_16x16x32_bf16 v[20:23], v[174:177], v[206:209], v[20:23]
	v_mfma_f32_16x16x32_bf16 v[16:19], v[182:185], v[206:209], v[16:19]
	v_mfma_f32_16x16x32_bf16 v[4:7], v[174:177], v[214:217], v[4:7]
	v_mfma_f32_16x16x32_bf16 v[0:3], v[182:185], v[214:217], v[0:3]
	s_setprio 0
	s_barrier
	s_add_i32 s59, 0, 0x18000
	s_add_i32 s60, 0, 0x1c000
	v_add_u32_e32 v166, s59, v151
	v_add_u32_e32 v182, s60, v151
	ds_read_b128 v[146:149], v166
	ds_read_b128 v[158:161], v166 offset:1024
	ds_read_b128 v[162:165], v166 offset:2048
	ds_read_b128 v[166:169], v166 offset:3072
	ds_read_b128 v[170:173], v182
	ds_read_b128 v[174:177], v182 offset:1024
	ds_read_b128 v[178:181], v182 offset:2048
	ds_read_b128 v[182:185], v182 offset:3072
	s_add_u32 s34, s38, 0xb0000
	s_addc_u32 s35, s39, 0
	s_mov_b32 m0, s44
	v_lshl_add_u64 v[226:227], s[34:35], 0, v[130:131]
	ds_read_b128 v[186:189], v155 offset:32768
	ds_read_b128 v[190:193], v155 offset:33792
	ds_read_b128 v[194:197], v155 offset:34816
	ds_read_b128 v[198:201], v155 offset:35840
	ds_read_b128 v[202:205], v155 offset:36864
	ds_read_b128 v[206:209], v155 offset:37888
	ds_read_b128 v[210:213], v155 offset:38912
	ds_read_b128 v[214:217], v155 offset:39936
	global_load_lds_dwordx4 v[226:227], off
	v_lshl_add_u64 v[226:227], s[34:35], 0, v[134:135]
	s_mov_b32 m0, s45
	s_nop 0
	global_load_lds_dwordx4 v[226:227], off
	s_waitcnt vmcnt(8)
	s_waitcnt lgkmcnt(0)
	s_barrier
	s_setprio 1
	s_waitcnt lgkmcnt(0)
	v_mfma_f32_16x16x32_bf16 v[124:127], v[146:149], v[186:189], v[124:127]
	v_mfma_f32_16x16x32_bf16 v[120:123], v[162:165], v[186:189], v[120:123]
	v_mfma_f32_16x16x32_bf16 v[108:111], v[146:149], v[194:197], v[108:111]
	v_mfma_f32_16x16x32_bf16 v[104:107], v[162:165], v[194:197], v[104:107]
	v_mfma_f32_16x16x32_bf16 v[92:95], v[146:149], v[202:205], v[92:95]
	v_mfma_f32_16x16x32_bf16 v[88:91], v[162:165], v[202:205], v[88:91]
	v_mfma_f32_16x16x32_bf16 v[76:79], v[146:149], v[210:213], v[76:79]
	v_mfma_f32_16x16x32_bf16 v[72:75], v[162:165], v[210:213], v[72:75]
	v_mfma_f32_16x16x32_bf16 v[124:127], v[158:161], v[190:193], v[124:127]
	v_mfma_f32_16x16x32_bf16 v[120:123], v[166:169], v[190:193], v[120:123]
	v_mfma_f32_16x16x32_bf16 v[108:111], v[158:161], v[198:201], v[108:111]
	v_mfma_f32_16x16x32_bf16 v[104:107], v[166:169], v[198:201], v[104:107]
	v_mfma_f32_16x16x32_bf16 v[92:95], v[158:161], v[206:209], v[92:95]
	v_mfma_f32_16x16x32_bf16 v[88:91], v[166:169], v[206:209], v[88:91]
	v_mfma_f32_16x16x32_bf16 v[76:79], v[158:161], v[214:217], v[76:79]
	v_mfma_f32_16x16x32_bf16 v[72:75], v[166:169], v[214:217], v[72:75]
	s_setprio 0
	s_setprio 1
	v_mfma_f32_16x16x32_bf16 v[116:119], v[170:173], v[186:189], v[116:119]
	v_mfma_f32_16x16x32_bf16 v[112:115], v[178:181], v[186:189], v[112:115]
	v_mfma_f32_16x16x32_bf16 v[100:103], v[170:173], v[194:197], v[100:103]
	v_mfma_f32_16x16x32_bf16 v[96:99], v[178:181], v[194:197], v[96:99]
	v_mfma_f32_16x16x32_bf16 v[84:87], v[170:173], v[202:205], v[84:87]
	v_mfma_f32_16x16x32_bf16 v[80:83], v[178:181], v[202:205], v[80:83]
	v_mfma_f32_16x16x32_bf16 v[68:71], v[170:173], v[210:213], v[68:71]
	v_mfma_f32_16x16x32_bf16 v[64:67], v[178:181], v[210:213], v[64:67]
	v_mfma_f32_16x16x32_bf16 v[116:119], v[174:177], v[190:193], v[116:119]
	v_mfma_f32_16x16x32_bf16 v[112:115], v[182:185], v[190:193], v[112:115]
	v_mfma_f32_16x16x32_bf16 v[100:103], v[174:177], v[198:201], v[100:103]
	v_mfma_f32_16x16x32_bf16 v[96:99], v[182:185], v[198:201], v[96:99]
	v_mfma_f32_16x16x32_bf16 v[84:87], v[174:177], v[206:209], v[84:87]
	v_mfma_f32_16x16x32_bf16 v[80:83], v[182:185], v[206:209], v[80:83]
	v_mfma_f32_16x16x32_bf16 v[68:71], v[174:177], v[214:217], v[68:71]
	v_mfma_f32_16x16x32_bf16 v[64:67], v[182:185], v[214:217], v[64:67]
	s_setprio 0
	s_barrier
	s_add_i32 s34, s59, s41
	v_lshl_add_u64 v[218:219], v[218:219], 0, s[22:23]
	s_mov_b32 m0, s34
	ds_read_b128 v[186:189], v155 offset:49152
	ds_read_b128 v[190:193], v155 offset:50176
	ds_read_b128 v[194:197], v155 offset:51200
	ds_read_b128 v[198:201], v155 offset:52224
	ds_read_b128 v[202:205], v155 offset:53248
	ds_read_b128 v[206:209], v155 offset:54272
	ds_read_b128 v[210:213], v155 offset:55296
	ds_read_b128 v[214:217], v155 offset:56320
	global_load_lds_dwordx4 v[218:219], off
	s_add_i32 m0, s34, 0x2000
	s_add_u32 s34, s36, 0xb0080
	v_lshl_add_u64 v[218:219], v[220:221], 0, s[22:23]
	s_addc_u32 s35, s37, 0
	s_add_i32 s36, s60, s41
	global_load_lds_dwordx4 v[218:219], off
	v_lshl_add_u64 v[218:219], s[34:35], 0, v[132:133]
	s_mov_b32 m0, s36
	s_nop 0
	global_load_lds_dwordx4 v[218:219], off
	v_lshl_add_u64 v[218:219], s[34:35], 0, v[136:137]
	s_add_i32 m0, s36, 0x2000
	s_nop 0
	global_load_lds_dwordx4 v[218:219], off
	v_lshl_add_u64 v[218:219], v[222:223], 0, s[22:23]
	s_mov_b32 m0, s47
	s_nop 0
	global_load_lds_dwordx4 v[218:219], off
	v_lshl_add_u64 v[218:219], v[224:225], 0, s[22:23]
	s_mov_b32 m0, s48
	s_nop 0
	global_load_lds_dwordx4 v[218:219], off
	s_waitcnt vmcnt(8)
	s_waitcnt lgkmcnt(0)
	s_barrier
	s_setprio 1
	s_waitcnt lgkmcnt(0)
	v_mfma_f32_16x16x32_bf16 v[60:63], v[146:149], v[186:189], v[60:63]
	v_mfma_f32_16x16x32_bf16 v[56:59], v[162:165], v[186:189], v[56:59]
	v_mfma_f32_16x16x32_bf16 v[44:47], v[146:149], v[194:197], v[44:47]
	v_mfma_f32_16x16x32_bf16 v[40:43], v[162:165], v[194:197], v[40:43]
	v_mfma_f32_16x16x32_bf16 v[28:31], v[146:149], v[202:205], v[28:31]
	v_mfma_f32_16x16x32_bf16 v[24:27], v[162:165], v[202:205], v[24:27]
	v_mfma_f32_16x16x32_bf16 v[12:15], v[146:149], v[210:213], v[12:15]
	v_mfma_f32_16x16x32_bf16 v[8:11], v[162:165], v[210:213], v[8:11]
	v_mfma_f32_16x16x32_bf16 v[60:63], v[158:161], v[190:193], v[60:63]
	v_mfma_f32_16x16x32_bf16 v[56:59], v[166:169], v[190:193], v[56:59]
	v_mfma_f32_16x16x32_bf16 v[44:47], v[158:161], v[198:201], v[44:47]
	v_mfma_f32_16x16x32_bf16 v[40:43], v[166:169], v[198:201], v[40:43]
	v_mfma_f32_16x16x32_bf16 v[28:31], v[158:161], v[206:209], v[28:31]
	v_mfma_f32_16x16x32_bf16 v[24:27], v[166:169], v[206:209], v[24:27]
	v_mfma_f32_16x16x32_bf16 v[12:15], v[158:161], v[214:217], v[12:15]
	v_mfma_f32_16x16x32_bf16 v[8:11], v[166:169], v[214:217], v[8:11]
	s_setprio 0
	s_setprio 1
	v_mfma_f32_16x16x32_bf16 v[52:55], v[170:173], v[186:189], v[52:55]
	v_mfma_f32_16x16x32_bf16 v[48:51], v[178:181], v[186:189], v[48:51]
	v_mfma_f32_16x16x32_bf16 v[36:39], v[170:173], v[194:197], v[36:39]
	v_mfma_f32_16x16x32_bf16 v[32:35], v[178:181], v[194:197], v[32:35]
	v_mfma_f32_16x16x32_bf16 v[20:23], v[170:173], v[202:205], v[20:23]
	v_mfma_f32_16x16x32_bf16 v[16:19], v[178:181], v[202:205], v[16:19]
	v_mfma_f32_16x16x32_bf16 v[4:7], v[170:173], v[210:213], v[4:7]
	v_mfma_f32_16x16x32_bf16 v[0:3], v[178:181], v[210:213], v[0:3]
	v_mfma_f32_16x16x32_bf16 v[52:55], v[174:177], v[190:193], v[52:55]
	v_mfma_f32_16x16x32_bf16 v[48:51], v[182:185], v[190:193], v[48:51]
	v_mfma_f32_16x16x32_bf16 v[36:39], v[174:177], v[198:201], v[36:39]
	v_mfma_f32_16x16x32_bf16 v[32:35], v[182:185], v[198:201], v[32:35]
	v_mfma_f32_16x16x32_bf16 v[20:23], v[174:177], v[206:209], v[20:23]
	v_mfma_f32_16x16x32_bf16 v[16:19], v[182:185], v[206:209], v[16:19]
	v_mfma_f32_16x16x32_bf16 v[4:7], v[174:177], v[214:217], v[4:7]
	v_mfma_f32_16x16x32_bf16 v[0:3], v[182:185], v[214:217], v[0:3]
	s_setprio 0
	s_cmp_eq_u32 s58, s98
	s_cbranch_scc1 .Lmy_nobar_18
	s_barrier
.Lmy_nobar_18:
	s_add_i32 s58, s58, 2
	s_add_u32 s30, s30, 0x100
	s_addc_u32 s31, s31, 0
	s_add_u32 s13, s13, 0x100
	s_addc_u32 s57, s57, 0
	s_cmp_gt_u32 s58, 41
	s_cbranch_scc0 .LBB0_1733
	s_and_b64 vcc, exec, s[26:27]
	s_cbranch_vccz .LBB0_1736
	s_nop 0

.LBB0_1823:
	s_lshr_b32 s99, s91, 2
	s_cmp_eq_u32 s99, 1
	s_cselect_b32 s98, 12, 0x7fffffff
	s_add_i32 s63, s63, 1
	s_mul_i32 s4, s63, s48
	s_mul_hi_u32 s5, s63, s49
	s_add_i32 s5, s5, s4
	s_mul_i32 s4, s63, s49
	s_add_u32 s38, s4, s2
	s_addc_u32 s39, s5, s3
	v_cmp_gt_i64_e32 vcc, s[38:39], v[148:149]
	v_cmp_lt_i64_e64 s[4:5], s[38:39], v[146:147]
	s_cbranch_vccnz .LBB0_1825
	s_ashr_i32 s7, s38, 31
	s_lshr_b32 s7, s7, 29
	s_add_i32 s7, s38, s7
	s_ashr_i32 s8, s7, 3
	s_and_b32 s7, s7, -8
	s_sub_i32 s7, s38, s7
	s_cmp_lt_i32 s7, 0
	s_cselect_b32 s12, s60, 0xc0
	s_mul_i32 s7, s7, s12
	s_add_i32 s7, s7, s8
	s_mul_hi_i32 s8, s7, 0x2aaaaaab
	s_lshr_b32 s12, s8, 31
	s_ashr_i32 s8, s8, 4
	s_add_i32 s8, s8, s12
	s_lshl_b32 s12, s8, 3
	s_sub_i32 s13, 0x80, s12
	s_min_i32 s13, s13, 8
	s_abs_i32 s30, s13
	v_cvt_f32_u32_e32 v0, s30
	s_sub_i32 s34, 0, s30
	s_mulk_i32 s8, 0x60
	s_sub_i32 s7, s7, s8
	v_rcp_iflag_f32_e32 v0, v0
	s_abs_i32 s8, s7
	s_xor_b32 s31, s7, s13
	s_ashr_i32 s31, s31, 31
	v_mul_f32_e32 v0, 0x4f7ffffe, v0
	v_cvt_u32_f32_e32 v0, v0
	s_mov_b32 s64, s63
	v_readfirstlane_b32 s35, v0
	s_mul_i32 s34, s34, s35
	s_mul_hi_u32 s34, s35, s34
	s_add_i32 s35, s35, s34
	s_mul_hi_u32 s34, s8, s35
	s_mul_i32 s35, s34, s30
	s_sub_i32 s8, s8, s35
	s_add_i32 s36, s34, 1
	s_sub_i32 s35, s8, s30
	s_cmp_ge_u32 s8, s30
	s_cselect_b32 s34, s36, s34
	s_cselect_b32 s8, s35, s8
	s_add_i32 s35, s34, 1
	s_cmp_ge_u32 s8, s30
	s_cselect_b32 s8, s35, s34
	s_xor_b32 s8, s8, s31
	s_sub_i32 s30, s8, s31
	s_mul_i32 s8, s30, s13
	s_sub_i32 s7, s7, s8
	s_add_i32 s36, s12, s7
.LBB0_1825:
	s_ashr_i32 s37, s36, 31
	s_lshl_b64 s[12:13], s[36:37], 19
	s_add_u32 s38, s14, s12
	s_addc_u32 s39, s15, s13
	s_and_b64 s[12:13], s[4:5], exec
	s_cselect_b32 s7, s39, s43
	s_cselect_b32 s8, s38, s42
	s_ashr_i32 s31, s30, 31
	s_lshl_b64 s[12:13], s[30:31], 19
	s_add_u32 s40, s51, s12
	s_addc_u32 s41, s52, s13
	s_and_b64 s[12:13], s[4:5], exec
	s_cselect_b32 s12, s41, s45
	s_cselect_b32 s13, s40, s44
	s_add_u32 s42, s42, 0x40080
	s_addc_u32 s43, s43, 0
	s_add_u32 s31, s44, 0x100
	v_mov_b32_e32 v0, 0
	s_addc_u32 s37, s45, 0
	s_mov_b32 s65, -2
	v_mov_b32_e32 v1, v0
	v_mov_b32_e32 v2, v0
	v_mov_b32_e32 v3, v0
	v_mov_b32_e32 v4, v0
	v_mov_b32_e32 v5, v0
	v_mov_b32_e32 v6, v0
	v_mov_b32_e32 v7, v0
	v_mov_b32_e32 v16, v0
	v_mov_b32_e32 v17, v0
	s_waitcnt lgkmcnt(0)
	v_mov_b32_e32 v18, v0
	v_mov_b32_e32 v19, v0
	v_mov_b32_e32 v20, v0
	v_mov_b32_e32 v21, v0
	v_mov_b32_e32 v22, v0
	v_mov_b32_e32 v23, v0
	v_mov_b32_e32 v32, v0
	v_mov_b32_e32 v33, v0
	v_mov_b32_e32 v34, v0
	v_mov_b32_e32 v35, v0
	v_mov_b32_e32 v36, v0
	v_mov_b32_e32 v37, v0
	v_mov_b32_e32 v38, v0
	v_mov_b32_e32 v39, v0
	v_mov_b32_e32 v48, v0
	v_mov_b32_e32 v49, v0
	v_mov_b32_e32 v50, v0
	v_mov_b32_e32 v51, v0
	v_mov_b32_e32 v52, v0
	v_mov_b32_e32 v53, v0
	v_mov_b32_e32 v54, v0
	v_mov_b32_e32 v55, v0
	v_mov_b32_e32 v8, v0
	v_mov_b32_e32 v9, v0
	v_mov_b32_e32 v10, v0
	v_mov_b32_e32 v11, v0
	v_mov_b32_e32 v12, v0
	v_mov_b32_e32 v13, v0
	v_mov_b32_e32 v14, v0
	v_mov_b32_e32 v15, v0
	v_mov_b32_e32 v24, v0
	v_mov_b32_e32 v25, v0
	v_mov_b32_e32 v26, v0
	v_mov_b32_e32 v27, v0
	v_mov_b32_e32 v28, v0
	v_mov_b32_e32 v29, v0
	v_mov_b32_e32 v30, v0
	v_mov_b32_e32 v31, v0
	v_mov_b32_e32 v40, v0
	v_mov_b32_e32 v41, v0
	v_mov_b32_e32 v42, v0
	v_mov_b32_e32 v43, v0
	v_mov_b32_e32 v44, v0
	v_mov_b32_e32 v45, v0
	v_mov_b32_e32 v46, v0
	v_mov_b32_e32 v47, v0
	v_mov_b32_e32 v56, v0
	v_mov_b32_e32 v57, v0
	v_mov_b32_e32 v58, v0
	v_mov_b32_e32 v59, v0
	v_mov_b32_e32 v60, v0
	v_mov_b32_e32 v61, v0
	v_mov_b32_e32 v62, v0
	v_mov_b32_e32 v63, v0
	v_mov_b32_e32 v64, v0
	v_mov_b32_e32 v65, v0
	v_mov_b32_e32 v66, v0
	v_mov_b32_e32 v67, v0
	v_mov_b32_e32 v68, v0
	v_mov_b32_e32 v69, v0
	v_mov_b32_e32 v70, v0
	v_mov_b32_e32 v71, v0
	v_mov_b32_e32 v80, v0
	v_mov_b32_e32 v81, v0
	v_mov_b32_e32 v82, v0
	v_mov_b32_e32 v83, v0
	v_mov_b32_e32 v84, v0
	v_mov_b32_e32 v85, v0
	v_mov_b32_e32 v86, v0
	v_mov_b32_e32 v87, v0
	v_mov_b32_e32 v96, v0
	v_mov_b32_e32 v97, v0
	v_mov_b32_e32 v98, v0
	v_mov_b32_e32 v99, v0
	v_mov_b32_e32 v100, v0
	v_mov_b32_e32 v101, v0
	v_mov_b32_e32 v102, v0
	v_mov_b32_e32 v103, v0
	v_mov_b32_e32 v112, v0
	v_mov_b32_e32 v113, v0
	v_mov_b32_e32 v114, v0
	v_mov_b32_e32 v115, v0
	v_mov_b32_e32 v116, v0
	v_mov_b32_e32 v117, v0
	v_mov_b32_e32 v118, v0
	v_mov_b32_e32 v119, v0
	v_mov_b32_e32 v72, v0
	v_mov_b32_e32 v73, v0
	v_mov_b32_e32 v74, v0
	v_mov_b32_e32 v75, v0
	v_mov_b32_e32 v76, v0
	v_mov_b32_e32 v77, v0
	v_mov_b32_e32 v78, v0
	v_mov_b32_e32 v79, v0
	v_mov_b32_e32 v88, v0
	v_mov_b32_e32 v89, v0
	v_mov_b32_e32 v90, v0
	v_mov_b32_e32 v91, v0
	v_mov_b32_e32 v92, v0
	v_mov_b32_e32 v93, v0
	v_mov_b32_e32 v94, v0
	v_mov_b32_e32 v95, v0
	v_mov_b32_e32 v104, v0
	v_mov_b32_e32 v105, v0
	v_mov_b32_e32 v106, v0
	v_mov_b32_e32 v107, v0
	v_mov_b32_e32 v108, v0
	v_mov_b32_e32 v109, v0
	v_mov_b32_e32 v110, v0
	v_mov_b32_e32 v111, v0
	v_mov_b32_e32 v120, v0
	v_mov_b32_e32 v121, v0
	v_mov_b32_e32 v122, v0
	v_mov_b32_e32 v123, v0
	v_mov_b32_e32 v124, v0
	v_mov_b32_e32 v125, v0
	v_mov_b32_e32 v126, v0
	v_mov_b32_e32 v127, v0
	s_cmp_lg_u32 s63, 1
	s_cselect_b32 s100, s99, 0
	s_cmp_lg_u32 s100, 0
	s_cbranch_scc0 .Lmy_nobar2_19
	s_barrier
.Lmy_nobar2_19:
.LBB0_1826:
	ds_read_b128 v[150:153], v157
	ds_read_b128 v[160:163], v157 offset:1024
	ds_read_b128 v[164:167], v157 offset:2048
	ds_read_b128 v[168:171], v157 offset:3072
	ds_read_b128 v[172:175], v158
	ds_read_b128 v[176:179], v158 offset:1024
	ds_read_b128 v[180:183], v158 offset:2048
	ds_read_b128 v[184:187], v158 offset:3072
	s_add_u32 s34, s42, 0xfffc0080
	s_addc_u32 s35, s43, -1
	s_cmp_eq_u32 s65, 12
	s_cselect_b32 s47, s7, s35
	s_cselect_b32 s46, s8, s34
	s_cselect_b32 s45, s12, s37
	s_cselect_b32 s44, s13, s31
	v_lshl_add_u64 v[220:221], s[42:43], 0, v[142:143]
	s_add_i32 m0, s53, 0xc000
	ds_read_b128 v[188:191], v159
	ds_read_b128 v[192:195], v159 offset:1024
	ds_read_b128 v[196:199], v159 offset:2048
	ds_read_b128 v[200:203], v159 offset:3072
	ds_read_b128 v[204:207], v159 offset:4096
	ds_read_b128 v[208:211], v159 offset:5120
	ds_read_b128 v[212:215], v159 offset:6144
	ds_read_b128 v[216:219], v159 offset:7168
	global_load_lds_dwordx4 v[220:221], off
	v_lshl_add_u64 v[220:221], s[42:43], 0, v[144:145]
	s_add_i32 m0, s53, 0xe000
	s_nop 0
	global_load_lds_dwordx4 v[220:221], off
	s_waitcnt vmcnt(8)
	s_waitcnt lgkmcnt(0)
	s_barrier
	s_setprio 1
	s_waitcnt lgkmcnt(0)
	v_mfma_f32_16x16x32_bf16 v[124:127], v[150:153], v[188:191], v[124:127]
	v_mfma_f32_16x16x32_bf16 v[120:123], v[164:167], v[188:191], v[120:123]
	v_mfma_f32_16x16x32_bf16 v[108:111], v[150:153], v[196:199], v[108:111]
	v_mfma_f32_16x16x32_bf16 v[104:107], v[164:167], v[196:199], v[104:107]
	v_mfma_f32_16x16x32_bf16 v[92:95], v[150:153], v[204:207], v[92:95]
	v_mfma_f32_16x16x32_bf16 v[88:91], v[164:167], v[204:207], v[88:91]
	v_mfma_f32_16x16x32_bf16 v[76:79], v[150:153], v[212:215], v[76:79]
	v_mfma_f32_16x16x32_bf16 v[72:75], v[164:167], v[212:215], v[72:75]
	v_mfma_f32_16x16x32_bf16 v[124:127], v[160:163], v[192:195], v[124:127]
	v_mfma_f32_16x16x32_bf16 v[120:123], v[168:171], v[192:195], v[120:123]
	v_mfma_f32_16x16x32_bf16 v[108:111], v[160:163], v[200:203], v[108:111]
	v_mfma_f32_16x16x32_bf16 v[104:107], v[168:171], v[200:203], v[104:107]
	v_mfma_f32_16x16x32_bf16 v[92:95], v[160:163], v[208:211], v[92:95]
	v_mfma_f32_16x16x32_bf16 v[88:91], v[168:171], v[208:211], v[88:91]
	v_mfma_f32_16x16x32_bf16 v[76:79], v[160:163], v[216:219], v[76:79]
	v_mfma_f32_16x16x32_bf16 v[72:75], v[168:171], v[216:219], v[72:75]
	s_setprio 0
	s_setprio 1
	v_mfma_f32_16x16x32_bf16 v[116:119], v[172:175], v[188:191], v[116:119]
	v_mfma_f32_16x16x32_bf16 v[112:115], v[180:183], v[188:191], v[112:115]
	v_mfma_f32_16x16x32_bf16 v[100:103], v[172:175], v[196:199], v[100:103]
	v_mfma_f32_16x16x32_bf16 v[96:99], v[180:183], v[196:199], v[96:99]
	v_mfma_f32_16x16x32_bf16 v[84:87], v[172:175], v[204:207], v[84:87]
	v_mfma_f32_16x16x32_bf16 v[80:83], v[180:183], v[204:207], v[80:83]
	v_mfma_f32_16x16x32_bf16 v[68:71], v[172:175], v[212:215], v[68:71]
	v_mfma_f32_16x16x32_bf16 v[64:67], v[180:183], v[212:215], v[64:67]
	v_mfma_f32_16x16x32_bf16 v[116:119], v[176:179], v[192:195], v[116:119]
	v_mfma_f32_16x16x32_bf16 v[112:115], v[184:187], v[192:195], v[112:115]
	v_mfma_f32_16x16x32_bf16 v[100:103], v[176:179], v[200:203], v[100:103]
	v_mfma_f32_16x16x32_bf16 v[96:99], v[184:187], v[200:203], v[96:99]
	v_mfma_f32_16x16x32_bf16 v[84:87], v[176:179], v[208:211], v[84:87]
	v_mfma_f32_16x16x32_bf16 v[80:83], v[184:187], v[208:211], v[80:83]
	v_mfma_f32_16x16x32_bf16 v[68:71], v[176:179], v[216:219], v[68:71]
	v_mfma_f32_16x16x32_bf16 v[64:67], v[184:187], v[216:219], v[64:67]
	s_setprio 0
	s_barrier
	s_add_i32 s34, s61, s50
	v_lshl_add_u64 v[220:221], s[44:45], 0, v[134:135]
	s_mov_b32 m0, s34
	ds_read_b128 v[188:191], v159 offset:16384
	ds_read_b128 v[192:195], v159 offset:17408
	ds_read_b128 v[196:199], v159 offset:18432
	ds_read_b128 v[200:203], v159 offset:19456
	ds_read_b128 v[204:207], v159 offset:20480
	ds_read_b128 v[208:211], v159 offset:21504
	ds_read_b128 v[212:215], v159 offset:22528
	ds_read_b128 v[216:219], v159 offset:23552
	global_load_lds_dwordx4 v[220:221], off
	s_add_i32 m0, s34, 0x2000
	s_add_u32 s34, s44, 0x40000
	v_lshl_add_u64 v[222:223], s[44:45], 0, v[138:139]
	s_addc_u32 s35, s45, 0
	s_add_i32 s66, s62, s50
	global_load_lds_dwordx4 v[222:223], off
	v_lshl_add_u64 v[224:225], s[34:35], 0, v[134:135]
	s_mov_b32 m0, s66
	v_lshl_add_u64 v[226:227], s[46:47], 0, v[136:137]
	global_load_lds_dwordx4 v[224:225], off
	v_lshl_add_u64 v[224:225], s[34:35], 0, v[138:139]
	s_add_i32 m0, s66, 0x2000
	s_nop 0
	global_load_lds_dwordx4 v[224:225], off
	v_lshl_add_u64 v[224:225], s[46:47], 0, v[132:133]
	s_mov_b32 m0, s53
	s_nop 0
	global_load_lds_dwordx4 v[224:225], off
	s_mov_b32 m0, s54
	s_nop 0
	global_load_lds_dwordx4 v[226:227], off
	s_waitcnt vmcnt(8)
	s_waitcnt lgkmcnt(0)
	s_barrier
	s_setprio 1
	s_waitcnt lgkmcnt(0)
	v_mfma_f32_16x16x32_bf16 v[60:63], v[150:153], v[188:191], v[60:63]
	v_mfma_f32_16x16x32_bf16 v[56:59], v[164:167], v[188:191], v[56:59]
	v_mfma_f32_16x16x32_bf16 v[44:47], v[150:153], v[196:199], v[44:47]
	v_mfma_f32_16x16x32_bf16 v[40:43], v[164:167], v[196:199], v[40:43]
	v_mfma_f32_16x16x32_bf16 v[28:31], v[150:153], v[204:207], v[28:31]
	v_mfma_f32_16x16x32_bf16 v[24:27], v[164:167], v[204:207], v[24:27]
	v_mfma_f32_16x16x32_bf16 v[12:15], v[150:153], v[212:215], v[12:15]
	v_mfma_f32_16x16x32_bf16 v[8:11], v[164:167], v[212:215], v[8:11]
	v_mfma_f32_16x16x32_bf16 v[60:63], v[160:163], v[192:195], v[60:63]
	v_mfma_f32_16x16x32_bf16 v[56:59], v[168:171], v[192:195], v[56:59]
	v_mfma_f32_16x16x32_bf16 v[44:47], v[160:163], v[200:203], v[44:47]
	v_mfma_f32_16x16x32_bf16 v[40:43], v[168:171], v[200:203], v[40:43]
	v_mfma_f32_16x16x32_bf16 v[28:31], v[160:163], v[208:211], v[28:31]
	v_mfma_f32_16x16x32_bf16 v[24:27], v[168:171], v[208:211], v[24:27]
	v_mfma_f32_16x16x32_bf16 v[12:15], v[160:163], v[216:219], v[12:15]
	v_mfma_f32_16x16x32_bf16 v[8:11], v[168:171], v[216:219], v[8:11]
	s_setprio 0
	s_setprio 1
	v_mfma_f32_16x16x32_bf16 v[52:55], v[172:175], v[188:191], v[52:55]
	v_mfma_f32_16x16x32_bf16 v[48:51], v[180:183], v[188:191], v[48:51]
	v_mfma_f32_16x16x32_bf16 v[36:39], v[172:175], v[196:199], v[36:39]
	v_mfma_f32_16x16x32_bf16 v[32:35], v[180:183], v[196:199], v[32:35]
	v_mfma_f32_16x16x32_bf16 v[20:23], v[172:175], v[204:207], v[20:23]
	v_mfma_f32_16x16x32_bf16 v[16:19], v[180:183], v[204:207], v[16:19]
	v_mfma_f32_16x16x32_bf16 v[4:7], v[172:175], v[212:215], v[4:7]
	v_mfma_f32_16x16x32_bf16 v[0:3], v[180:183], v[212:215], v[0:3]
	v_mfma_f32_16x16x32_bf16 v[52:55], v[176:179], v[192:195], v[52:55]
	v_mfma_f32_16x16x32_bf16 v[48:51], v[184:187], v[192:195], v[48:51]
	v_mfma_f32_16x16x32_bf16 v[36:39], v[176:179], v[200:203], v[36:39]
	v_mfma_f32_16x16x32_bf16 v[32:35], v[184:187], v[200:203], v[32:35]
	v_mfma_f32_16x16x32_bf16 v[20:23], v[176:179], v[208:211], v[20:23]
	v_mfma_f32_16x16x32_bf16 v[16:19], v[184:187], v[208:211], v[16:19]
	v_mfma_f32_16x16x32_bf16 v[4:7], v[176:179], v[216:219], v[4:7]
	v_mfma_f32_16x16x32_bf16 v[0:3], v[184:187], v[216:219], v[0:3]
	s_setprio 0
	s_barrier
	s_add_i32 s66, 0, 0x18000
	v_add_u32_e32 v140, s66, v154
	s_add_i32 s67, 0, 0x1c000
	ds_read_b128 v[150:153], v140
	ds_read_b128 v[160:163], v140 offset:1024
	ds_read_b128 v[164:167], v140 offset:2048
	ds_read_b128 v[168:171], v140 offset:3072
	v_add_u32_e32 v140, s67, v154
	ds_read_b128 v[172:175], v140
	ds_read_b128 v[176:179], v140 offset:1024
	ds_read_b128 v[180:183], v140 offset:2048
	ds_read_b128 v[184:187], v140 offset:3072
	s_add_u32 s34, s46, 0x40000
	s_addc_u32 s35, s47, 0
	s_mov_b32 m0, s55
	v_lshl_add_u64 v[228:229], s[34:35], 0, v[132:133]
	ds_read_b128 v[188:191], v159 offset:32768
	ds_read_b128 v[192:195], v159 offset:33792
	ds_read_b128 v[196:199], v159 offset:34816
	ds_read_b128 v[200:203], v159 offset:35840
	ds_read_b128 v[204:207], v159 offset:36864
	ds_read_b128 v[208:211], v159 offset:37888
	ds_read_b128 v[212:215], v159 offset:38912
	ds_read_b128 v[216:219], v159 offset:39936
	global_load_lds_dwordx4 v[228:229], off
	v_lshl_add_u64 v[228:229], s[34:35], 0, v[136:137]
	s_mov_b32 m0, s56
	s_nop 0
	global_load_lds_dwordx4 v[228:229], off
	s_waitcnt vmcnt(8)
	s_waitcnt lgkmcnt(0)
	s_barrier
	s_setprio 1
	s_waitcnt lgkmcnt(0)
	v_mfma_f32_16x16x32_bf16 v[124:127], v[150:153], v[188:191], v[124:127]
	v_mfma_f32_16x16x32_bf16 v[120:123], v[164:167], v[188:191], v[120:123]
	v_mfma_f32_16x16x32_bf16 v[108:111], v[150:153], v[196:199], v[108:111]
	v_mfma_f32_16x16x32_bf16 v[104:107], v[164:167], v[196:199], v[104:107]
	v_mfma_f32_16x16x32_bf16 v[92:95], v[150:153], v[204:207], v[92:95]
	v_mfma_f32_16x16x32_bf16 v[88:91], v[164:167], v[204:207], v[88:91]
	v_mfma_f32_16x16x32_bf16 v[76:79], v[150:153], v[212:215], v[76:79]
	v_mfma_f32_16x16x32_bf16 v[72:75], v[164:167], v[212:215], v[72:75]
	v_mfma_f32_16x16x32_bf16 v[124:127], v[160:163], v[192:195], v[124:127]
	v_mfma_f32_16x16x32_bf16 v[120:123], v[168:171], v[192:195], v[120:123]
	v_mfma_f32_16x16x32_bf16 v[108:111], v[160:163], v[200:203], v[108:111]
	v_mfma_f32_16x16x32_bf16 v[104:107], v[168:171], v[200:203], v[104:107]
	v_mfma_f32_16x16x32_bf16 v[92:95], v[160:163], v[208:211], v[92:95]
	v_mfma_f32_16x16x32_bf16 v[88:91], v[168:171], v[208:211], v[88:91]
	v_mfma_f32_16x16x32_bf16 v[76:79], v[160:163], v[216:219], v[76:79]
	v_mfma_f32_16x16x32_bf16 v[72:75], v[168:171], v[216:219], v[72:75]
	s_setprio 0
	s_setprio 1
	v_mfma_f32_16x16x32_bf16 v[116:119], v[172:175], v[188:191], v[116:119]
	v_mfma_f32_16x16x32_bf16 v[112:115], v[180:183], v[188:191], v[112:115]
	v_mfma_f32_16x16x32_bf16 v[100:103], v[172:175], v[196:199], v[100:103]
	v_mfma_f32_16x16x32_bf16 v[96:99], v[180:183], v[196:199], v[96:99]
	v_mfma_f32_16x16x32_bf16 v[84:87], v[172:175], v[204:207], v[84:87]
	v_mfma_f32_16x16x32_bf16 v[80:83], v[180:183], v[204:207], v[80:83]
	v_mfma_f32_16x16x32_bf16 v[68:71], v[172:175], v[212:215], v[68:71]
	v_mfma_f32_16x16x32_bf16 v[64:67], v[180:183], v[212:215], v[64:67]
	v_mfma_f32_16x16x32_bf16 v[116:119], v[176:179], v[192:195], v[116:119]
	v_mfma_f32_16x16x32_bf16 v[112:115], v[184:187], v[192:195], v[112:115]
	v_mfma_f32_16x16x32_bf16 v[100:103], v[176:179], v[200:203], v[100:103]
	v_mfma_f32_16x16x32_bf16 v[96:99], v[184:187], v[200:203], v[96:99]
	v_mfma_f32_16x16x32_bf16 v[84:87], v[176:179], v[208:211], v[84:87]
	v_mfma_f32_16x16x32_bf16 v[80:83], v[184:187], v[208:211], v[80:83]
	v_mfma_f32_16x16x32_bf16 v[68:71], v[176:179], v[216:219], v[68:71]
	v_mfma_f32_16x16x32_bf16 v[64:67], v[184:187], v[216:219], v[64:67]
	s_setprio 0
	s_barrier
	s_add_i32 s34, s66, s50
	v_lshl_add_u64 v[220:221], v[220:221], 0, s[26:27]
	s_mov_b32 m0, s34
	ds_read_b128 v[188:191], v159 offset:49152
	ds_read_b128 v[192:195], v159 offset:50176
	ds_read_b128 v[196:199], v159 offset:51200
	ds_read_b128 v[200:203], v159 offset:52224
	ds_read_b128 v[204:207], v159 offset:53248
	ds_read_b128 v[208:211], v159 offset:54272
	ds_read_b128 v[212:215], v159 offset:55296
	ds_read_b128 v[216:219], v159 offset:56320
	global_load_lds_dwordx4 v[220:221], off
	s_add_i32 m0, s34, 0x2000
	s_add_u32 s34, s44, 0x40080
	v_lshl_add_u64 v[220:221], v[222:223], 0, s[26:27]
	s_addc_u32 s35, s45, 0
	s_add_i32 s44, s67, s50
	global_load_lds_dwordx4 v[220:221], off
	v_lshl_add_u64 v[220:221], s[34:35], 0, v[134:135]
	s_mov_b32 m0, s44
	s_nop 0
	global_load_lds_dwordx4 v[220:221], off
	v_lshl_add_u64 v[220:221], s[34:35], 0, v[138:139]
	s_add_i32 m0, s44, 0x2000
	s_nop 0
	global_load_lds_dwordx4 v[220:221], off
	v_lshl_add_u64 v[220:221], v[224:225], 0, s[26:27]
	s_mov_b32 m0, s58
	s_nop 0
	global_load_lds_dwordx4 v[220:221], off
	v_lshl_add_u64 v[220:221], v[226:227], 0, s[26:27]
	s_mov_b32 m0, s59
	s_nop 0
	global_load_lds_dwordx4 v[220:221], off
	s_waitcnt vmcnt(8)
	s_waitcnt lgkmcnt(0)
	s_barrier
	s_setprio 1
	s_waitcnt lgkmcnt(0)
	v_mfma_f32_16x16x32_bf16 v[60:63], v[150:153], v[188:191], v[60:63]
	v_mfma_f32_16x16x32_bf16 v[56:59], v[164:167], v[188:191], v[56:59]
	v_mfma_f32_16x16x32_bf16 v[44:47], v[150:153], v[196:199], v[44:47]
	v_mfma_f32_16x16x32_bf16 v[40:43], v[164:167], v[196:199], v[40:43]
	v_mfma_f32_16x16x32_bf16 v[28:31], v[150:153], v[204:207], v[28:31]
	v_mfma_f32_16x16x32_bf16 v[24:27], v[164:167], v[204:207], v[24:27]
	v_mfma_f32_16x16x32_bf16 v[12:15], v[150:153], v[212:215], v[12:15]
	v_mfma_f32_16x16x32_bf16 v[8:11], v[164:167], v[212:215], v[8:11]
	v_mfma_f32_16x16x32_bf16 v[60:63], v[160:163], v[192:195], v[60:63]
	v_mfma_f32_16x16x32_bf16 v[56:59], v[168:171], v[192:195], v[56:59]
	v_mfma_f32_16x16x32_bf16 v[44:47], v[160:163], v[200:203], v[44:47]
	v_mfma_f32_16x16x32_bf16 v[40:43], v[168:171], v[200:203], v[40:43]
	v_mfma_f32_16x16x32_bf16 v[28:31], v[160:163], v[208:211], v[28:31]
	v_mfma_f32_16x16x32_bf16 v[24:27], v[168:171], v[208:211], v[24:27]
	v_mfma_f32_16x16x32_bf16 v[12:15], v[160:163], v[216:219], v[12:15]
	v_mfma_f32_16x16x32_bf16 v[8:11], v[168:171], v[216:219], v[8:11]
	s_setprio 0
	s_setprio 1
	v_mfma_f32_16x16x32_bf16 v[52:55], v[172:175], v[188:191], v[52:55]
	v_mfma_f32_16x16x32_bf16 v[48:51], v[180:183], v[188:191], v[48:51]
	v_mfma_f32_16x16x32_bf16 v[36:39], v[172:175], v[196:199], v[36:39]
	v_mfma_f32_16x16x32_bf16 v[32:35], v[180:183], v[196:199], v[32:35]
	v_mfma_f32_16x16x32_bf16 v[20:23], v[172:175], v[204:207], v[20:23]
	v_mfma_f32_16x16x32_bf16 v[16:19], v[180:183], v[204:207], v[16:19]
	v_mfma_f32_16x16x32_bf16 v[4:7], v[172:175], v[212:215], v[4:7]
	v_mfma_f32_16x16x32_bf16 v[0:3], v[180:183], v[212:215], v[0:3]
	v_mfma_f32_16x16x32_bf16 v[52:55], v[176:179], v[192:195], v[52:55]
	v_mfma_f32_16x16x32_bf16 v[48:51], v[184:187], v[192:195], v[48:51]
	v_mfma_f32_16x16x32_bf16 v[36:39], v[176:179], v[200:203], v[36:39]
	v_mfma_f32_16x16x32_bf16 v[32:35], v[184:187], v[200:203], v[32:35]
	v_mfma_f32_16x16x32_bf16 v[20:23], v[176:179], v[208:211], v[20:23]
	v_mfma_f32_16x16x32_bf16 v[16:19], v[184:187], v[208:211], v[16:19]
	v_mfma_f32_16x16x32_bf16 v[4:7], v[176:179], v[216:219], v[4:7]
	v_mfma_f32_16x16x32_bf16 v[0:3], v[184:187], v[216:219], v[0:3]
	s_setprio 0
	s_cmp_eq_u32 s65, s98
	s_cbranch_scc1 .Lmy_nobar_19
	s_barrier
.Lmy_nobar_19:
	s_add_i32 s65, s65, 2
	s_add_u32 s42, s42, 0x100
	s_addc_u32 s43, s43, 0
	s_add_u32 s31, s31, 0x100
	s_addc_u32 s37, s37, 0
	s_cmp_gt_u32 s65, 13
	s_cbranch_scc0 .LBB0_1826
	s_and_b64 vcc, exec, s[28:29]
	s_cbranch_vccz .LBB0_1829
	s_nop 0

.LBB0_1994:
	s_lshr_b32 s99, s91, 2
	s_cmp_eq_u32 s99, 1
	s_cselect_b32 s98, 12, 0x7fffffff
	s_add_i32 s58, s58, 1
	s_mul_i32 s6, s58, s53
	s_mul_hi_u32 s7, s58, s54
	s_add_i32 s7, s7, s6
	s_mul_i32 s6, s58, s54
	s_add_u32 s28, s6, s2
	s_addc_u32 s29, s7, s55
	v_cmp_gt_i64_e32 vcc, s[28:29], v[144:145]
	v_cmp_lt_i64_e64 s[6:7], s[28:29], v[142:143]
	s_cbranch_vccnz .LBB0_2000
	s_ashr_i32 s12, s28, 31
	s_lshr_b32 s12, s12, 29
	s_add_i32 s12, s28, s12
	s_and_b32 s13, s12, -8
	s_sub_i32 s13, s28, s13
	s_cmp_gt_i32 s13, -1
	s_mov_b64 s[24:25], -1
	s_cbranch_scc0 .LBB0_1997
	s_lshl_b32 s26, s13, 6
	s_mov_b64 s[24:25], 0

.LBB0_2000:
	s_ashr_i32 s27, s26, 31
	s_lshl_b64 s[12:13], s[26:27], 19
	s_add_u32 s28, s20, s12
	s_addc_u32 s29, s21, s13
	s_and_b64 s[12:13], s[6:7], exec
	s_cselect_b32 s12, s29, s39
	s_cselect_b32 s13, s28, s38
	s_ashr_i32 s25, s24, 31
	s_lshl_b64 s[30:31], s[24:25], 19
	s_add_u32 s30, s3, s30
	s_addc_u32 s31, s44, s31
	s_and_b64 s[34:35], s[6:7], exec
	s_cselect_b32 s25, s31, s41
	s_cselect_b32 s27, s30, s40
	s_add_u32 s38, s38, 0x40080
	s_addc_u32 s39, s39, 0
	s_add_u32 s37, s40, 0x100
	v_mov_b32_e32 v0, 0
	s_addc_u32 s59, s41, 0
	s_mov_b32 s60, -2
	s_waitcnt lgkmcnt(0)
	v_mov_b32_e32 v1, v0
	v_mov_b32_e32 v2, v0
	v_mov_b32_e32 v3, v0
	v_mov_b32_e32 v4, v0
	v_mov_b32_e32 v5, v0
	v_mov_b32_e32 v6, v0
	v_mov_b32_e32 v7, v0
	v_mov_b32_e32 v16, v0
	v_mov_b32_e32 v17, v0
	v_mov_b32_e32 v18, v0
	v_mov_b32_e32 v19, v0
	v_mov_b32_e32 v20, v0
	v_mov_b32_e32 v21, v0
	v_mov_b32_e32 v22, v0
	v_mov_b32_e32 v23, v0
	v_mov_b32_e32 v32, v0
	v_mov_b32_e32 v33, v0
	v_mov_b32_e32 v34, v0
	v_mov_b32_e32 v35, v0
	v_mov_b32_e32 v36, v0
	v_mov_b32_e32 v37, v0
	v_mov_b32_e32 v38, v0
	v_mov_b32_e32 v39, v0
	v_mov_b32_e32 v48, v0
	v_mov_b32_e32 v49, v0
	v_mov_b32_e32 v50, v0
	v_mov_b32_e32 v51, v0
	v_mov_b32_e32 v52, v0
	v_mov_b32_e32 v53, v0
	v_mov_b32_e32 v54, v0
	v_mov_b32_e32 v55, v0
	v_mov_b32_e32 v8, v0
	v_mov_b32_e32 v9, v0
	v_mov_b32_e32 v10, v0
	v_mov_b32_e32 v11, v0
	v_mov_b32_e32 v12, v0
	v_mov_b32_e32 v13, v0
	v_mov_b32_e32 v14, v0
	v_mov_b32_e32 v15, v0
	v_mov_b32_e32 v24, v0
	v_mov_b32_e32 v25, v0
	v_mov_b32_e32 v26, v0
	v_mov_b32_e32 v27, v0
	v_mov_b32_e32 v28, v0
	v_mov_b32_e32 v29, v0
	v_mov_b32_e32 v30, v0
	v_mov_b32_e32 v31, v0
	v_mov_b32_e32 v40, v0
	v_mov_b32_e32 v41, v0
	v_mov_b32_e32 v42, v0
	v_mov_b32_e32 v43, v0
	v_mov_b32_e32 v44, v0
	v_mov_b32_e32 v45, v0
	v_mov_b32_e32 v46, v0
	v_mov_b32_e32 v47, v0
	v_mov_b32_e32 v56, v0
	v_mov_b32_e32 v57, v0
	v_mov_b32_e32 v58, v0
	v_mov_b32_e32 v59, v0
	v_mov_b32_e32 v60, v0
	v_mov_b32_e32 v61, v0
	v_mov_b32_e32 v62, v0
	v_mov_b32_e32 v63, v0
	v_mov_b32_e32 v64, v0
	v_mov_b32_e32 v65, v0
	v_mov_b32_e32 v66, v0
	v_mov_b32_e32 v67, v0
	v_mov_b32_e32 v68, v0
	v_mov_b32_e32 v69, v0
	v_mov_b32_e32 v70, v0
	v_mov_b32_e32 v71, v0
	v_mov_b32_e32 v80, v0
	v_mov_b32_e32 v81, v0
	v_mov_b32_e32 v82, v0
	v_mov_b32_e32 v83, v0
	v_mov_b32_e32 v84, v0
	v_mov_b32_e32 v85, v0
	v_mov_b32_e32 v86, v0
	v_mov_b32_e32 v87, v0
	v_mov_b32_e32 v96, v0
	v_mov_b32_e32 v97, v0
	v_mov_b32_e32 v98, v0
	v_mov_b32_e32 v99, v0
	v_mov_b32_e32 v100, v0
	v_mov_b32_e32 v101, v0
	v_mov_b32_e32 v102, v0
	v_mov_b32_e32 v103, v0
	v_mov_b32_e32 v112, v0
	v_mov_b32_e32 v113, v0
	v_mov_b32_e32 v114, v0
	v_mov_b32_e32 v115, v0
	v_mov_b32_e32 v116, v0
	v_mov_b32_e32 v117, v0
	v_mov_b32_e32 v118, v0
	v_mov_b32_e32 v119, v0
	v_mov_b32_e32 v72, v0
	v_mov_b32_e32 v73, v0
	v_mov_b32_e32 v74, v0
	v_mov_b32_e32 v75, v0
	v_mov_b32_e32 v76, v0
	v_mov_b32_e32 v77, v0
	v_mov_b32_e32 v78, v0
	v_mov_b32_e32 v79, v0
	v_mov_b32_e32 v88, v0
	v_mov_b32_e32 v89, v0
	v_mov_b32_e32 v90, v0
	v_mov_b32_e32 v91, v0
	v_mov_b32_e32 v92, v0
	v_mov_b32_e32 v93, v0
	v_mov_b32_e32 v94, v0
	v_mov_b32_e32 v95, v0
	v_mov_b32_e32 v104, v0
	v_mov_b32_e32 v105, v0
	v_mov_b32_e32 v106, v0
	v_mov_b32_e32 v107, v0
	v_mov_b32_e32 v108, v0
	v_mov_b32_e32 v109, v0
	v_mov_b32_e32 v110, v0
	v_mov_b32_e32 v111, v0
	v_mov_b32_e32 v120, v0
	v_mov_b32_e32 v121, v0
	v_mov_b32_e32 v122, v0
	v_mov_b32_e32 v123, v0
	v_mov_b32_e32 v124, v0
	v_mov_b32_e32 v125, v0
	v_mov_b32_e32 v126, v0
	v_mov_b32_e32 v127, v0
	s_cmp_lg_u32 s58, 1
	s_cselect_b32 s100, s99, 0
	s_cmp_lg_u32 s100, 0
	s_cbranch_scc0 .Lmy_nobar2_21
	s_barrier
.Lmy_nobar2_21:
.LBB0_2001:
	ds_read_b128 v[146:149], v153
	ds_read_b128 v[158:161], v153 offset:1024
	ds_read_b128 v[162:165], v153 offset:2048
	ds_read_b128 v[166:169], v153 offset:3072
	ds_read_b128 v[170:173], v154
	ds_read_b128 v[174:177], v154 offset:1024
	ds_read_b128 v[178:181], v154 offset:2048
	ds_read_b128 v[182:185], v154 offset:3072
	s_add_u32 s34, s38, 0xfffc0080
	s_addc_u32 s35, s39, -1
	s_cmp_eq_u32 s60, 12
	s_cselect_b32 s43, s12, s35
	s_cselect_b32 s42, s13, s34
	s_cselect_b32 s41, s25, s59
	s_cselect_b32 s40, s27, s37
	v_lshl_add_u64 v[218:219], s[38:39], 0, v[138:139]
	s_add_i32 m0, s46, 0xc000
	ds_read_b128 v[186:189], v155
	ds_read_b128 v[190:193], v155 offset:1024
	ds_read_b128 v[194:197], v155 offset:2048
	ds_read_b128 v[198:201], v155 offset:3072
	ds_read_b128 v[202:205], v155 offset:4096
	ds_read_b128 v[206:209], v155 offset:5120
	ds_read_b128 v[210:213], v155 offset:6144
	ds_read_b128 v[214:217], v155 offset:7168
	global_load_lds_dwordx4 v[218:219], off
	v_lshl_add_u64 v[218:219], s[38:39], 0, v[140:141]
	s_add_i32 m0, s46, 0xe000
	s_nop 0
	global_load_lds_dwordx4 v[218:219], off
	s_waitcnt vmcnt(8)
	s_waitcnt lgkmcnt(0)
	s_barrier
	s_setprio 1
	s_waitcnt lgkmcnt(0)
	v_mfma_f32_16x16x32_bf16 v[124:127], v[146:149], v[186:189], v[124:127]
	v_mfma_f32_16x16x32_bf16 v[120:123], v[162:165], v[186:189], v[120:123]
	v_mfma_f32_16x16x32_bf16 v[108:111], v[146:149], v[194:197], v[108:111]
	v_mfma_f32_16x16x32_bf16 v[104:107], v[162:165], v[194:197], v[104:107]
	v_mfma_f32_16x16x32_bf16 v[92:95], v[146:149], v[202:205], v[92:95]
	v_mfma_f32_16x16x32_bf16 v[88:91], v[162:165], v[202:205], v[88:91]
	v_mfma_f32_16x16x32_bf16 v[76:79], v[146:149], v[210:213], v[76:79]
	v_mfma_f32_16x16x32_bf16 v[72:75], v[162:165], v[210:213], v[72:75]
	v_mfma_f32_16x16x32_bf16 v[124:127], v[158:161], v[190:193], v[124:127]
	v_mfma_f32_16x16x32_bf16 v[120:123], v[166:169], v[190:193], v[120:123]
	v_mfma_f32_16x16x32_bf16 v[108:111], v[158:161], v[198:201], v[108:111]
	v_mfma_f32_16x16x32_bf16 v[104:107], v[166:169], v[198:201], v[104:107]
	v_mfma_f32_16x16x32_bf16 v[92:95], v[158:161], v[206:209], v[92:95]
	v_mfma_f32_16x16x32_bf16 v[88:91], v[166:169], v[206:209], v[88:91]
	v_mfma_f32_16x16x32_bf16 v[76:79], v[158:161], v[214:217], v[76:79]
	v_mfma_f32_16x16x32_bf16 v[72:75], v[166:169], v[214:217], v[72:75]
	s_setprio 0
	s_setprio 1
	v_mfma_f32_16x16x32_bf16 v[116:119], v[170:173], v[186:189], v[116:119]
	v_mfma_f32_16x16x32_bf16 v[112:115], v[178:181], v[186:189], v[112:115]
	v_mfma_f32_16x16x32_bf16 v[100:103], v[170:173], v[194:197], v[100:103]
	v_mfma_f32_16x16x32_bf16 v[96:99], v[178:181], v[194:197], v[96:99]
	v_mfma_f32_16x16x32_bf16 v[84:87], v[170:173], v[202:205], v[84:87]
	v_mfma_f32_16x16x32_bf16 v[80:83], v[178:181], v[202:205], v[80:83]
	v_mfma_f32_16x16x32_bf16 v[68:71], v[170:173], v[210:213], v[68:71]
	v_mfma_f32_16x16x32_bf16 v[64:67], v[178:181], v[210:213], v[64:67]
	v_mfma_f32_16x16x32_bf16 v[116:119], v[174:177], v[190:193], v[116:119]
	v_mfma_f32_16x16x32_bf16 v[112:115], v[182:185], v[190:193], v[112:115]
	v_mfma_f32_16x16x32_bf16 v[100:103], v[174:177], v[198:201], v[100:103]
	v_mfma_f32_16x16x32_bf16 v[96:99], v[182:185], v[198:201], v[96:99]
	v_mfma_f32_16x16x32_bf16 v[84:87], v[174:177], v[206:209], v[84:87]
	v_mfma_f32_16x16x32_bf16 v[80:83], v[182:185], v[206:209], v[80:83]
	v_mfma_f32_16x16x32_bf16 v[68:71], v[174:177], v[214:217], v[68:71]
	v_mfma_f32_16x16x32_bf16 v[64:67], v[182:185], v[214:217], v[64:67]
	s_setprio 0
	s_barrier
	s_add_i32 s34, s56, s45
	v_lshl_add_u64 v[218:219], s[40:41], 0, v[132:133]
	s_mov_b32 m0, s34
	ds_read_b128 v[186:189], v155 offset:16384
	ds_read_b128 v[190:193], v155 offset:17408
	ds_read_b128 v[194:197], v155 offset:18432
	ds_read_b128 v[198:201], v155 offset:19456
	ds_read_b128 v[202:205], v155 offset:20480
	ds_read_b128 v[206:209], v155 offset:21504
	ds_read_b128 v[210:213], v155 offset:22528
	ds_read_b128 v[214:217], v155 offset:23552
	global_load_lds_dwordx4 v[218:219], off
	s_add_i32 m0, s34, 0x2000
	s_add_u32 s34, s40, 0x40000
	v_lshl_add_u64 v[220:221], s[40:41], 0, v[136:137]
	s_addc_u32 s35, s41, 0
	s_add_i32 s61, s57, s45
	global_load_lds_dwordx4 v[220:221], off
	v_lshl_add_u64 v[222:223], s[34:35], 0, v[132:133]
	s_mov_b32 m0, s61
	v_lshl_add_u64 v[224:225], s[42:43], 0, v[134:135]
	global_load_lds_dwordx4 v[222:223], off
	v_lshl_add_u64 v[222:223], s[34:35], 0, v[136:137]
	s_add_i32 m0, s61, 0x2000
	s_nop 0
	global_load_lds_dwordx4 v[222:223], off
	v_lshl_add_u64 v[222:223], s[42:43], 0, v[130:131]
	s_mov_b32 m0, s46
	s_nop 0
	global_load_lds_dwordx4 v[222:223], off
	s_mov_b32 m0, s47
	s_nop 0
	global_load_lds_dwordx4 v[224:225], off
	s_waitcnt vmcnt(8)
	s_waitcnt lgkmcnt(0)
	s_barrier
	s_setprio 1
	s_waitcnt lgkmcnt(0)
	v_mfma_f32_16x16x32_bf16 v[60:63], v[146:149], v[186:189], v[60:63]
	v_mfma_f32_16x16x32_bf16 v[56:59], v[162:165], v[186:189], v[56:59]
	v_mfma_f32_16x16x32_bf16 v[44:47], v[146:149], v[194:197], v[44:47]
	v_mfma_f32_16x16x32_bf16 v[40:43], v[162:165], v[194:197], v[40:43]
	v_mfma_f32_16x16x32_bf16 v[28:31], v[146:149], v[202:205], v[28:31]
	v_mfma_f32_16x16x32_bf16 v[24:27], v[162:165], v[202:205], v[24:27]
	v_mfma_f32_16x16x32_bf16 v[12:15], v[146:149], v[210:213], v[12:15]
	v_mfma_f32_16x16x32_bf16 v[8:11], v[162:165], v[210:213], v[8:11]
	v_mfma_f32_16x16x32_bf16 v[60:63], v[158:161], v[190:193], v[60:63]
	v_mfma_f32_16x16x32_bf16 v[56:59], v[166:169], v[190:193], v[56:59]
	v_mfma_f32_16x16x32_bf16 v[44:47], v[158:161], v[198:201], v[44:47]
	v_mfma_f32_16x16x32_bf16 v[40:43], v[166:169], v[198:201], v[40:43]
	v_mfma_f32_16x16x32_bf16 v[28:31], v[158:161], v[206:209], v[28:31]
	v_mfma_f32_16x16x32_bf16 v[24:27], v[166:169], v[206:209], v[24:27]
	v_mfma_f32_16x16x32_bf16 v[12:15], v[158:161], v[214:217], v[12:15]
	v_mfma_f32_16x16x32_bf16 v[8:11], v[166:169], v[214:217], v[8:11]
	s_setprio 0
	s_setprio 1
	v_mfma_f32_16x16x32_bf16 v[52:55], v[170:173], v[186:189], v[52:55]
	v_mfma_f32_16x16x32_bf16 v[48:51], v[178:181], v[186:189], v[48:51]
	v_mfma_f32_16x16x32_bf16 v[36:39], v[170:173], v[194:197], v[36:39]
	v_mfma_f32_16x16x32_bf16 v[32:35], v[178:181], v[194:197], v[32:35]
	v_mfma_f32_16x16x32_bf16 v[20:23], v[170:173], v[202:205], v[20:23]
	v_mfma_f32_16x16x32_bf16 v[16:19], v[178:181], v[202:205], v[16:19]
	v_mfma_f32_16x16x32_bf16 v[4:7], v[170:173], v[210:213], v[4:7]
	v_mfma_f32_16x16x32_bf16 v[0:3], v[178:181], v[210:213], v[0:3]
	v_mfma_f32_16x16x32_bf16 v[52:55], v[174:177], v[190:193], v[52:55]
	v_mfma_f32_16x16x32_bf16 v[48:51], v[182:185], v[190:193], v[48:51]
	v_mfma_f32_16x16x32_bf16 v[36:39], v[174:177], v[198:201], v[36:39]
	v_mfma_f32_16x16x32_bf16 v[32:35], v[182:185], v[198:201], v[32:35]
	v_mfma_f32_16x16x32_bf16 v[20:23], v[174:177], v[206:209], v[20:23]
	v_mfma_f32_16x16x32_bf16 v[16:19], v[182:185], v[206:209], v[16:19]
	v_mfma_f32_16x16x32_bf16 v[4:7], v[174:177], v[214:217], v[4:7]
	v_mfma_f32_16x16x32_bf16 v[0:3], v[182:185], v[214:217], v[0:3]
	s_setprio 0
	s_barrier
	s_add_i32 s61, 0, 0x18000
	v_add_u32_e32 v157, s61, v151
	s_add_i32 s62, 0, 0x1c000
	ds_read_b128 v[146:149], v157
	ds_read_b128 v[158:161], v157 offset:1024
	ds_read_b128 v[162:165], v157 offset:2048
	ds_read_b128 v[166:169], v157 offset:3072
	v_add_u32_e32 v157, s62, v151
	ds_read_b128 v[170:173], v157
	ds_read_b128 v[174:177], v157 offset:1024
	ds_read_b128 v[178:181], v157 offset:2048
	ds_read_b128 v[182:185], v157 offset:3072
	s_add_u32 s34, s42, 0x40000
	s_addc_u32 s35, s43, 0
	s_mov_b32 m0, s48
	v_lshl_add_u64 v[226:227], s[34:35], 0, v[130:131]
	ds_read_b128 v[186:189], v155 offset:32768
	ds_read_b128 v[190:193], v155 offset:33792
	ds_read_b128 v[194:197], v155 offset:34816
	ds_read_b128 v[198:201], v155 offset:35840
	ds_read_b128 v[202:205], v155 offset:36864
	ds_read_b128 v[206:209], v155 offset:37888
	ds_read_b128 v[210:213], v155 offset:38912
	ds_read_b128 v[214:217], v155 offset:39936
	global_load_lds_dwordx4 v[226:227], off
	v_lshl_add_u64 v[226:227], s[34:35], 0, v[134:135]
	s_mov_b32 m0, s49
	s_nop 0
	global_load_lds_dwordx4 v[226:227], off
	s_waitcnt vmcnt(8)
	s_waitcnt lgkmcnt(0)
	s_barrier
	s_setprio 1
	s_waitcnt lgkmcnt(0)
	v_mfma_f32_16x16x32_bf16 v[124:127], v[146:149], v[186:189], v[124:127]
	v_mfma_f32_16x16x32_bf16 v[120:123], v[162:165], v[186:189], v[120:123]
	v_mfma_f32_16x16x32_bf16 v[108:111], v[146:149], v[194:197], v[108:111]
	v_mfma_f32_16x16x32_bf16 v[104:107], v[162:165], v[194:197], v[104:107]
	v_mfma_f32_16x16x32_bf16 v[92:95], v[146:149], v[202:205], v[92:95]
	v_mfma_f32_16x16x32_bf16 v[88:91], v[162:165], v[202:205], v[88:91]
	v_mfma_f32_16x16x32_bf16 v[76:79], v[146:149], v[210:213], v[76:79]
	v_mfma_f32_16x16x32_bf16 v[72:75], v[162:165], v[210:213], v[72:75]
	v_mfma_f32_16x16x32_bf16 v[124:127], v[158:161], v[190:193], v[124:127]
	v_mfma_f32_16x16x32_bf16 v[120:123], v[166:169], v[190:193], v[120:123]
	v_mfma_f32_16x16x32_bf16 v[108:111], v[158:161], v[198:201], v[108:111]
	v_mfma_f32_16x16x32_bf16 v[104:107], v[166:169], v[198:201], v[104:107]
	v_mfma_f32_16x16x32_bf16 v[92:95], v[158:161], v[206:209], v[92:95]
	v_mfma_f32_16x16x32_bf16 v[88:91], v[166:169], v[206:209], v[88:91]
	v_mfma_f32_16x16x32_bf16 v[76:79], v[158:161], v[214:217], v[76:79]
	v_mfma_f32_16x16x32_bf16 v[72:75], v[166:169], v[214:217], v[72:75]
	s_setprio 0
	s_setprio 1
	v_mfma_f32_16x16x32_bf16 v[116:119], v[170:173], v[186:189], v[116:119]
	v_mfma_f32_16x16x32_bf16 v[112:115], v[178:181], v[186:189], v[112:115]
	v_mfma_f32_16x16x32_bf16 v[100:103], v[170:173], v[194:197], v[100:103]
	v_mfma_f32_16x16x32_bf16 v[96:99], v[178:181], v[194:197], v[96:99]
	v_mfma_f32_16x16x32_bf16 v[84:87], v[170:173], v[202:205], v[84:87]
	v_mfma_f32_16x16x32_bf16 v[80:83], v[178:181], v[202:205], v[80:83]
	v_mfma_f32_16x16x32_bf16 v[68:71], v[170:173], v[210:213], v[68:71]
	v_mfma_f32_16x16x32_bf16 v[64:67], v[178:181], v[210:213], v[64:67]
	v_mfma_f32_16x16x32_bf16 v[116:119], v[174:177], v[190:193], v[116:119]
	v_mfma_f32_16x16x32_bf16 v[112:115], v[182:185], v[190:193], v[112:115]
	v_mfma_f32_16x16x32_bf16 v[100:103], v[174:177], v[198:201], v[100:103]
	v_mfma_f32_16x16x32_bf16 v[96:99], v[182:185], v[198:201], v[96:99]
	v_mfma_f32_16x16x32_bf16 v[84:87], v[174:177], v[206:209], v[84:87]
	v_mfma_f32_16x16x32_bf16 v[80:83], v[182:185], v[206:209], v[80:83]
	v_mfma_f32_16x16x32_bf16 v[68:71], v[174:177], v[214:217], v[68:71]
	v_mfma_f32_16x16x32_bf16 v[64:67], v[182:185], v[214:217], v[64:67]
	s_setprio 0
	s_barrier
	s_add_i32 s34, s61, s45
	v_lshl_add_u64 v[218:219], v[218:219], 0, s[10:11]
	s_mov_b32 m0, s34
	ds_read_b128 v[186:189], v155 offset:49152
	ds_read_b128 v[190:193], v155 offset:50176
	ds_read_b128 v[194:197], v155 offset:51200
	ds_read_b128 v[198:201], v155 offset:52224
	ds_read_b128 v[202:205], v155 offset:53248
	ds_read_b128 v[206:209], v155 offset:54272
	ds_read_b128 v[210:213], v155 offset:55296
	ds_read_b128 v[214:217], v155 offset:56320
	global_load_lds_dwordx4 v[218:219], off
	s_add_i32 m0, s34, 0x2000
	s_add_u32 s34, s40, 0x40080
	v_lshl_add_u64 v[218:219], v[220:221], 0, s[10:11]
	s_addc_u32 s35, s41, 0
	s_add_i32 s40, s62, s45
	global_load_lds_dwordx4 v[218:219], off
	v_lshl_add_u64 v[218:219], s[34:35], 0, v[132:133]
	s_mov_b32 m0, s40
	s_nop 0
	global_load_lds_dwordx4 v[218:219], off
	v_lshl_add_u64 v[218:219], s[34:35], 0, v[136:137]
	s_add_i32 m0, s40, 0x2000
	s_nop 0
	global_load_lds_dwordx4 v[218:219], off
	v_lshl_add_u64 v[218:219], v[222:223], 0, s[10:11]
	s_mov_b32 m0, s51
	s_nop 0
	global_load_lds_dwordx4 v[218:219], off
	v_lshl_add_u64 v[218:219], v[224:225], 0, s[10:11]
	s_mov_b32 m0, s52
	s_nop 0
	global_load_lds_dwordx4 v[218:219], off
	s_waitcnt vmcnt(8)
	s_waitcnt lgkmcnt(0)
	s_barrier
	s_setprio 1
	s_waitcnt lgkmcnt(0)
	v_mfma_f32_16x16x32_bf16 v[60:63], v[146:149], v[186:189], v[60:63]
	v_mfma_f32_16x16x32_bf16 v[56:59], v[162:165], v[186:189], v[56:59]
	v_mfma_f32_16x16x32_bf16 v[44:47], v[146:149], v[194:197], v[44:47]
	v_mfma_f32_16x16x32_bf16 v[40:43], v[162:165], v[194:197], v[40:43]
	v_mfma_f32_16x16x32_bf16 v[28:31], v[146:149], v[202:205], v[28:31]
	v_mfma_f32_16x16x32_bf16 v[24:27], v[162:165], v[202:205], v[24:27]
	v_mfma_f32_16x16x32_bf16 v[12:15], v[146:149], v[210:213], v[12:15]
	v_mfma_f32_16x16x32_bf16 v[8:11], v[162:165], v[210:213], v[8:11]
	v_mfma_f32_16x16x32_bf16 v[60:63], v[158:161], v[190:193], v[60:63]
	v_mfma_f32_16x16x32_bf16 v[56:59], v[166:169], v[190:193], v[56:59]
	v_mfma_f32_16x16x32_bf16 v[44:47], v[158:161], v[198:201], v[44:47]
	v_mfma_f32_16x16x32_bf16 v[40:43], v[166:169], v[198:201], v[40:43]
	v_mfma_f32_16x16x32_bf16 v[28:31], v[158:161], v[206:209], v[28:31]
	v_mfma_f32_16x16x32_bf16 v[24:27], v[166:169], v[206:209], v[24:27]
	v_mfma_f32_16x16x32_bf16 v[12:15], v[158:161], v[214:217], v[12:15]
	v_mfma_f32_16x16x32_bf16 v[8:11], v[166:169], v[214:217], v[8:11]
	s_setprio 0
	s_setprio 1
	v_mfma_f32_16x16x32_bf16 v[52:55], v[170:173], v[186:189], v[52:55]
	v_mfma_f32_16x16x32_bf16 v[48:51], v[178:181], v[186:189], v[48:51]
	v_mfma_f32_16x16x32_bf16 v[36:39], v[170:173], v[194:197], v[36:39]
	v_mfma_f32_16x16x32_bf16 v[32:35], v[178:181], v[194:197], v[32:35]
	v_mfma_f32_16x16x32_bf16 v[20:23], v[170:173], v[202:205], v[20:23]
	v_mfma_f32_16x16x32_bf16 v[16:19], v[178:181], v[202:205], v[16:19]
	v_mfma_f32_16x16x32_bf16 v[4:7], v[170:173], v[210:213], v[4:7]
	v_mfma_f32_16x16x32_bf16 v[0:3], v[178:181], v[210:213], v[0:3]
	v_mfma_f32_16x16x32_bf16 v[52:55], v[174:177], v[190:193], v[52:55]
	v_mfma_f32_16x16x32_bf16 v[48:51], v[182:185], v[190:193], v[48:51]
	v_mfma_f32_16x16x32_bf16 v[36:39], v[174:177], v[198:201], v[36:39]
	v_mfma_f32_16x16x32_bf16 v[32:35], v[182:185], v[198:201], v[32:35]
	v_mfma_f32_16x16x32_bf16 v[20:23], v[174:177], v[206:209], v[20:23]
	v_mfma_f32_16x16x32_bf16 v[16:19], v[182:185], v[206:209], v[16:19]
	v_mfma_f32_16x16x32_bf16 v[4:7], v[174:177], v[214:217], v[4:7]
	v_mfma_f32_16x16x32_bf16 v[0:3], v[182:185], v[214:217], v[0:3]
	s_setprio 0
	s_cmp_eq_u32 s60, s98
	s_cbranch_scc1 .Lmy_nobar_21
	s_barrier
.Lmy_nobar_21:
	s_add_i32 s60, s60, 2
	s_add_u32 s38, s38, 0x100
	s_addc_u32 s39, s39, 0
	s_add_u32 s37, s37, 0x100
	s_addc_u32 s59, s59, 0
	s_cmp_gt_u32 s60, 13
	s_cbranch_scc0 .LBB0_2001
	s_and_b64 vcc, exec, s[22:23]
	s_cbranch_vccz .LBB0_2004
	s_nop 0

.LBB0_2020:
	s_or_b64 exec, exec, s[38:39]
	s_andn2_b64 vcc, exec, s[6:7]
	s_mov_b64 s[6:7], -1
	s_cbranch_vccnz .LBB0_1993
	s_andn2_b64 vcc, exec, s[8:9]
	s_cbranch_vccnz .LBB0_1992
	s_nop 0
	s_branch .LBB0_1992

.LBB0_2088:
	s_lshr_b32 s99, s91, 2
	s_cmp_eq_u32 s99, 1
	s_cselect_b32 s98, 12, 0x7fffffff
	s_add_i32 s50, s50, 1
	s_mul_i32 s4, s50, s36
	s_mul_hi_u32 s5, s50, s37
	s_add_i32 s5, s5, s4
	s_mul_i32 s4, s50, s37
	s_add_u32 s20, s4, s2
	s_addc_u32 s21, s5, s3
	v_cmp_gt_i64_e32 vcc, s[20:21], v[144:145]
	v_cmp_lt_i64_e64 s[4:5], s[20:21], v[142:143]
	s_cbranch_vccnz .LBB0_2090
	s_ashr_i32 s10, s20, 31
	s_lshr_b32 s10, s10, 29
	s_add_i32 s10, s20, s10
	s_ashr_i32 s11, s10, 3
	s_and_b32 s10, s10, -8
	s_sub_i32 s10, s20, s10
	s_cmp_lt_i32 s10, 0
	s_cselect_b32 s18, s41, 0x160
	s_mul_i32 s10, s10, s18
	s_add_i32 s10, s10, s11
	s_mul_hi_i32 s11, s10, 0x2e8ba2e9
	s_lshr_b32 s18, s11, 31
	s_ashr_i32 s11, s11, 5
	s_add_i32 s11, s11, s18
	s_lshl_b32 s18, s11, 3
	s_sub_i32 s19, 0x80, s18
	s_min_i32 s19, s19, 8
	s_abs_i32 s20, s19
	v_cvt_f32_u32_e32 v0, s20
	s_sub_i32 s22, 0, s20
	s_mulk_i32 s11, 0xb0
	s_sub_i32 s11, s10, s11
	v_rcp_iflag_f32_e32 v0, v0
	s_abs_i32 s10, s11
	s_xor_b32 s21, s11, s19
	s_ashr_i32 s21, s21, 31
	v_mul_f32_e32 v0, 0x4f7ffffe, v0
	v_cvt_u32_f32_e32 v0, v0
	s_mov_b32 s51, s50
	v_readfirstlane_b32 s23, v0
	s_mul_i32 s22, s22, s23
	s_mul_hi_u32 s22, s23, s22
	s_add_i32 s23, s23, s22
	s_mul_hi_u32 s22, s10, s23
	s_mul_i32 s23, s22, s20
	s_sub_i32 s10, s10, s23
	s_add_i32 s30, s22, 1
	s_sub_i32 s23, s10, s20
	s_cmp_ge_u32 s10, s20
	s_cselect_b32 s22, s30, s22
	s_cselect_b32 s10, s23, s10
	s_add_i32 s23, s22, 1
	s_cmp_ge_u32 s10, s20
	s_cselect_b32 s10, s23, s22
	s_xor_b32 s10, s10, s21
	s_sub_i32 s10, s10, s21
	s_mul_i32 s19, s10, s19
	s_sub_i32 s11, s11, s19
	s_add_i32 s18, s18, s11
.LBB0_2090:
	s_ashr_i32 s19, s18, 31
	s_lshl_b64 s[20:21], s[18:19], 19
	s_add_u32 s20, s14, s20
	s_addc_u32 s21, s15, s21
	s_and_b64 s[22:23], s[4:5], exec
	s_cselect_b32 s19, s21, s27
	s_cselect_b32 s52, s20, s26
	s_ashr_i32 s11, s10, 31
	s_lshl_b64 s[22:23], s[10:11], 19
	s_add_u32 s22, s39, s22
	s_addc_u32 s23, s40, s23
	s_and_b64 s[30:31], s[4:5], exec
	s_cselect_b32 s11, s23, s29
	s_cselect_b32 s53, s22, s28
	s_add_u32 s26, s26, 0x40080
	s_addc_u32 s27, s27, 0
	s_add_u32 s54, s28, 0x100
	v_mov_b32_e32 v0, 0
	s_addc_u32 s55, s29, 0
	s_mov_b32 s56, -2
	v_mov_b32_e32 v1, v0
	v_mov_b32_e32 v2, v0
	v_mov_b32_e32 v3, v0
	v_mov_b32_e32 v4, v0
	v_mov_b32_e32 v5, v0
	v_mov_b32_e32 v6, v0
	v_mov_b32_e32 v7, v0
	v_mov_b32_e32 v16, v0
	v_mov_b32_e32 v17, v0
	v_mov_b32_e32 v18, v0
	v_mov_b32_e32 v19, v0
	v_mov_b32_e32 v20, v0
	v_mov_b32_e32 v21, v0
	v_mov_b32_e32 v22, v0
	v_mov_b32_e32 v23, v0
	v_mov_b32_e32 v32, v0
	v_mov_b32_e32 v33, v0
	v_mov_b32_e32 v34, v0
	v_mov_b32_e32 v35, v0
	v_mov_b32_e32 v36, v0
	v_mov_b32_e32 v37, v0
	v_mov_b32_e32 v38, v0
	v_mov_b32_e32 v39, v0
	v_mov_b32_e32 v48, v0
	v_mov_b32_e32 v49, v0
	v_mov_b32_e32 v50, v0
	v_mov_b32_e32 v51, v0
	v_mov_b32_e32 v52, v0
	v_mov_b32_e32 v53, v0
	v_mov_b32_e32 v54, v0
	v_mov_b32_e32 v55, v0
	v_mov_b32_e32 v8, v0
	v_mov_b32_e32 v9, v0
	v_mov_b32_e32 v10, v0
	v_mov_b32_e32 v11, v0
	v_mov_b32_e32 v12, v0
	v_mov_b32_e32 v13, v0
	v_mov_b32_e32 v14, v0
	v_mov_b32_e32 v15, v0
	v_mov_b32_e32 v24, v0
	v_mov_b32_e32 v25, v0
	v_mov_b32_e32 v26, v0
	v_mov_b32_e32 v27, v0
	v_mov_b32_e32 v28, v0
	v_mov_b32_e32 v29, v0
	v_mov_b32_e32 v30, v0
	v_mov_b32_e32 v31, v0
	v_mov_b32_e32 v40, v0
	v_mov_b32_e32 v41, v0
	v_mov_b32_e32 v42, v0
	v_mov_b32_e32 v43, v0
	v_mov_b32_e32 v44, v0
	v_mov_b32_e32 v45, v0
	v_mov_b32_e32 v46, v0
	v_mov_b32_e32 v47, v0
	v_mov_b32_e32 v56, v0
	v_mov_b32_e32 v57, v0
	v_mov_b32_e32 v58, v0
	v_mov_b32_e32 v59, v0
	v_mov_b32_e32 v60, v0
	v_mov_b32_e32 v61, v0
	v_mov_b32_e32 v62, v0
	v_mov_b32_e32 v63, v0
	v_mov_b32_e32 v64, v0
	v_mov_b32_e32 v65, v0
	v_mov_b32_e32 v66, v0
	v_mov_b32_e32 v67, v0
	v_mov_b32_e32 v68, v0
	v_mov_b32_e32 v69, v0
	v_mov_b32_e32 v70, v0
	v_mov_b32_e32 v71, v0
	v_mov_b32_e32 v80, v0
	v_mov_b32_e32 v81, v0
	v_mov_b32_e32 v82, v0
	v_mov_b32_e32 v83, v0
	v_mov_b32_e32 v84, v0
	v_mov_b32_e32 v85, v0
	v_mov_b32_e32 v86, v0
	v_mov_b32_e32 v87, v0
	v_mov_b32_e32 v96, v0
	v_mov_b32_e32 v97, v0
	v_mov_b32_e32 v98, v0
	v_mov_b32_e32 v99, v0
	v_mov_b32_e32 v100, v0
	v_mov_b32_e32 v101, v0
	v_mov_b32_e32 v102, v0
	v_mov_b32_e32 v103, v0
	v_mov_b32_e32 v112, v0
	v_mov_b32_e32 v113, v0
	v_mov_b32_e32 v114, v0
	v_mov_b32_e32 v115, v0
	v_mov_b32_e32 v116, v0
	v_mov_b32_e32 v117, v0
	v_mov_b32_e32 v118, v0
	v_mov_b32_e32 v119, v0
	v_mov_b32_e32 v72, v0
	v_mov_b32_e32 v73, v0
	v_mov_b32_e32 v74, v0
	v_mov_b32_e32 v75, v0
	v_mov_b32_e32 v76, v0
	v_mov_b32_e32 v77, v0
	v_mov_b32_e32 v78, v0
	v_mov_b32_e32 v79, v0
	v_mov_b32_e32 v88, v0
	v_mov_b32_e32 v89, v0
	v_mov_b32_e32 v90, v0
	v_mov_b32_e32 v91, v0
	v_mov_b32_e32 v92, v0
	v_mov_b32_e32 v93, v0
	v_mov_b32_e32 v94, v0
	v_mov_b32_e32 v95, v0
	v_mov_b32_e32 v104, v0
	v_mov_b32_e32 v105, v0
	v_mov_b32_e32 v106, v0
	v_mov_b32_e32 v107, v0
	v_mov_b32_e32 v108, v0
	v_mov_b32_e32 v109, v0
	v_mov_b32_e32 v110, v0
	v_mov_b32_e32 v111, v0
	v_mov_b32_e32 v120, v0
	v_mov_b32_e32 v121, v0
	v_mov_b32_e32 v122, v0
	v_mov_b32_e32 v123, v0
	v_mov_b32_e32 v124, v0
	v_mov_b32_e32 v125, v0
	v_mov_b32_e32 v126, v0
	v_mov_b32_e32 v127, v0
	s_cmp_lg_u32 s50, 1
	s_cselect_b32 s100, s99, 0
	s_cmp_lg_u32 s100, 0
	s_cbranch_scc0 .Lmy_nobar2_22
	s_barrier
.Lmy_nobar2_22:
.LBB0_2091:
	ds_read_b128 v[146:149], v153
	ds_read_b128 v[156:159], v153 offset:1024
	ds_read_b128 v[160:163], v153 offset:2048
	ds_read_b128 v[164:167], v153 offset:3072
	ds_read_b128 v[168:171], v154
	ds_read_b128 v[172:175], v154 offset:1024
	ds_read_b128 v[176:179], v154 offset:2048
	ds_read_b128 v[180:183], v154 offset:3072
	s_add_u32 s28, s26, 0xfffc0080
	s_addc_u32 s29, s27, -1
	s_cmp_eq_u32 s56, 12
	s_cselect_b32 s31, s19, s29
	s_cselect_b32 s30, s52, s28
	s_cselect_b32 s29, s11, s55
	s_cselect_b32 s28, s53, s54
	v_lshl_add_u64 v[216:217], s[26:27], 0, v[138:139]
	s_add_i32 m0, s25, 0xc000
	ds_read_b128 v[184:187], v155
	ds_read_b128 v[188:191], v155 offset:1024
	ds_read_b128 v[192:195], v155 offset:2048
	ds_read_b128 v[196:199], v155 offset:3072
	ds_read_b128 v[200:203], v155 offset:4096
	ds_read_b128 v[204:207], v155 offset:5120
	ds_read_b128 v[208:211], v155 offset:6144
	ds_read_b128 v[212:215], v155 offset:7168
	global_load_lds_dwordx4 v[216:217], off
	v_lshl_add_u64 v[216:217], s[26:27], 0, v[140:141]
	s_add_i32 m0, s25, 0xe000
	s_nop 0
	global_load_lds_dwordx4 v[216:217], off
	s_waitcnt vmcnt(8)
	s_waitcnt lgkmcnt(0)
	s_barrier
	s_setprio 1
	s_waitcnt lgkmcnt(0)
	v_mfma_f32_16x16x32_bf16 v[124:127], v[146:149], v[184:187], v[124:127]
	v_mfma_f32_16x16x32_bf16 v[120:123], v[160:163], v[184:187], v[120:123]
	v_mfma_f32_16x16x32_bf16 v[108:111], v[146:149], v[192:195], v[108:111]
	v_mfma_f32_16x16x32_bf16 v[104:107], v[160:163], v[192:195], v[104:107]
	v_mfma_f32_16x16x32_bf16 v[92:95], v[146:149], v[200:203], v[92:95]
	v_mfma_f32_16x16x32_bf16 v[88:91], v[160:163], v[200:203], v[88:91]
	v_mfma_f32_16x16x32_bf16 v[76:79], v[146:149], v[208:211], v[76:79]
	v_mfma_f32_16x16x32_bf16 v[72:75], v[160:163], v[208:211], v[72:75]
	v_mfma_f32_16x16x32_bf16 v[124:127], v[156:159], v[188:191], v[124:127]
	v_mfma_f32_16x16x32_bf16 v[120:123], v[164:167], v[188:191], v[120:123]
	v_mfma_f32_16x16x32_bf16 v[108:111], v[156:159], v[196:199], v[108:111]
	v_mfma_f32_16x16x32_bf16 v[104:107], v[164:167], v[196:199], v[104:107]
	v_mfma_f32_16x16x32_bf16 v[92:95], v[156:159], v[204:207], v[92:95]
	v_mfma_f32_16x16x32_bf16 v[88:91], v[164:167], v[204:207], v[88:91]
	v_mfma_f32_16x16x32_bf16 v[76:79], v[156:159], v[212:215], v[76:79]
	v_mfma_f32_16x16x32_bf16 v[72:75], v[164:167], v[212:215], v[72:75]
	s_setprio 0
	s_setprio 1
	v_mfma_f32_16x16x32_bf16 v[116:119], v[168:171], v[184:187], v[116:119]
	v_mfma_f32_16x16x32_bf16 v[112:115], v[176:179], v[184:187], v[112:115]
	v_mfma_f32_16x16x32_bf16 v[100:103], v[168:171], v[192:195], v[100:103]
	v_mfma_f32_16x16x32_bf16 v[96:99], v[176:179], v[192:195], v[96:99]
	v_mfma_f32_16x16x32_bf16 v[84:87], v[168:171], v[200:203], v[84:87]
	v_mfma_f32_16x16x32_bf16 v[80:83], v[176:179], v[200:203], v[80:83]
	v_mfma_f32_16x16x32_bf16 v[68:71], v[168:171], v[208:211], v[68:71]
	v_mfma_f32_16x16x32_bf16 v[64:67], v[176:179], v[208:211], v[64:67]
	v_mfma_f32_16x16x32_bf16 v[116:119], v[172:175], v[188:191], v[116:119]
	v_mfma_f32_16x16x32_bf16 v[112:115], v[180:183], v[188:191], v[112:115]
	v_mfma_f32_16x16x32_bf16 v[100:103], v[172:175], v[196:199], v[100:103]
	v_mfma_f32_16x16x32_bf16 v[96:99], v[180:183], v[196:199], v[96:99]
	v_mfma_f32_16x16x32_bf16 v[84:87], v[172:175], v[204:207], v[84:87]
	v_mfma_f32_16x16x32_bf16 v[80:83], v[180:183], v[204:207], v[80:83]
	v_mfma_f32_16x16x32_bf16 v[68:71], v[172:175], v[212:215], v[68:71]
	v_mfma_f32_16x16x32_bf16 v[64:67], v[180:183], v[212:215], v[64:67]
	s_setprio 0
	s_barrier
	s_add_i32 s34, s47, s38
	v_lshl_add_u64 v[216:217], s[28:29], 0, v[134:135]
	s_mov_b32 m0, s34
	ds_read_b128 v[184:187], v155 offset:16384
	ds_read_b128 v[188:191], v155 offset:17408
	ds_read_b128 v[192:195], v155 offset:18432
	ds_read_b128 v[196:199], v155 offset:19456
	ds_read_b128 v[200:203], v155 offset:20480
	ds_read_b128 v[204:207], v155 offset:21504
	ds_read_b128 v[208:211], v155 offset:22528
	ds_read_b128 v[212:215], v155 offset:23552
	global_load_lds_dwordx4 v[216:217], off
	s_add_i32 m0, s34, 0x2000
	s_add_u32 s34, s28, 0x40000
	v_lshl_add_u64 v[218:219], s[28:29], 0, v[130:131]
	s_addc_u32 s35, s29, 0
	s_add_i32 s57, s48, s38
	global_load_lds_dwordx4 v[218:219], off
	v_lshl_add_u64 v[220:221], s[34:35], 0, v[134:135]
	s_mov_b32 m0, s57
	v_lshl_add_u64 v[222:223], s[30:31], 0, v[132:133]
	global_load_lds_dwordx4 v[220:221], off
	v_lshl_add_u64 v[220:221], s[34:35], 0, v[130:131]
	s_add_i32 m0, s57, 0x2000
	s_nop 0
	global_load_lds_dwordx4 v[220:221], off
	v_lshl_add_u64 v[220:221], s[30:31], 0, v[136:137]
	s_mov_b32 m0, s25
	s_nop 0
	global_load_lds_dwordx4 v[220:221], off
	s_mov_b32 m0, s42
	s_nop 0
	global_load_lds_dwordx4 v[222:223], off
	s_waitcnt vmcnt(8)
	s_waitcnt lgkmcnt(0)
	s_barrier
	s_setprio 1
	s_waitcnt lgkmcnt(0)
	v_mfma_f32_16x16x32_bf16 v[60:63], v[146:149], v[184:187], v[60:63]
	v_mfma_f32_16x16x32_bf16 v[56:59], v[160:163], v[184:187], v[56:59]
	v_mfma_f32_16x16x32_bf16 v[44:47], v[146:149], v[192:195], v[44:47]
	v_mfma_f32_16x16x32_bf16 v[40:43], v[160:163], v[192:195], v[40:43]
	v_mfma_f32_16x16x32_bf16 v[28:31], v[146:149], v[200:203], v[28:31]
	v_mfma_f32_16x16x32_bf16 v[24:27], v[160:163], v[200:203], v[24:27]
	v_mfma_f32_16x16x32_bf16 v[12:15], v[146:149], v[208:211], v[12:15]
	v_mfma_f32_16x16x32_bf16 v[8:11], v[160:163], v[208:211], v[8:11]
	v_mfma_f32_16x16x32_bf16 v[60:63], v[156:159], v[188:191], v[60:63]
	v_mfma_f32_16x16x32_bf16 v[56:59], v[164:167], v[188:191], v[56:59]
	v_mfma_f32_16x16x32_bf16 v[44:47], v[156:159], v[196:199], v[44:47]
	v_mfma_f32_16x16x32_bf16 v[40:43], v[164:167], v[196:199], v[40:43]
	v_mfma_f32_16x16x32_bf16 v[28:31], v[156:159], v[204:207], v[28:31]
	v_mfma_f32_16x16x32_bf16 v[24:27], v[164:167], v[204:207], v[24:27]
	v_mfma_f32_16x16x32_bf16 v[12:15], v[156:159], v[212:215], v[12:15]
	v_mfma_f32_16x16x32_bf16 v[8:11], v[164:167], v[212:215], v[8:11]
	s_setprio 0
	s_setprio 1
	v_mfma_f32_16x16x32_bf16 v[52:55], v[168:171], v[184:187], v[52:55]
	v_mfma_f32_16x16x32_bf16 v[48:51], v[176:179], v[184:187], v[48:51]
	v_mfma_f32_16x16x32_bf16 v[36:39], v[168:171], v[192:195], v[36:39]
	v_mfma_f32_16x16x32_bf16 v[32:35], v[176:179], v[192:195], v[32:35]
	v_mfma_f32_16x16x32_bf16 v[20:23], v[168:171], v[200:203], v[20:23]
	v_mfma_f32_16x16x32_bf16 v[16:19], v[176:179], v[200:203], v[16:19]
	v_mfma_f32_16x16x32_bf16 v[4:7], v[168:171], v[208:211], v[4:7]
	v_mfma_f32_16x16x32_bf16 v[0:3], v[176:179], v[208:211], v[0:3]
	v_mfma_f32_16x16x32_bf16 v[52:55], v[172:175], v[188:191], v[52:55]
	v_mfma_f32_16x16x32_bf16 v[48:51], v[180:183], v[188:191], v[48:51]
	v_mfma_f32_16x16x32_bf16 v[36:39], v[172:175], v[196:199], v[36:39]
	v_mfma_f32_16x16x32_bf16 v[32:35], v[180:183], v[196:199], v[32:35]
	v_mfma_f32_16x16x32_bf16 v[20:23], v[172:175], v[204:207], v[20:23]
	v_mfma_f32_16x16x32_bf16 v[16:19], v[180:183], v[204:207], v[16:19]
	v_mfma_f32_16x16x32_bf16 v[4:7], v[172:175], v[212:215], v[4:7]
	v_mfma_f32_16x16x32_bf16 v[0:3], v[180:183], v[212:215], v[0:3]
	s_setprio 0
	s_barrier
	s_add_i32 s34, 0, 0x18000
	s_add_i32 s35, 0, 0x1c000
	v_add_u32_e32 v164, s34, v150
	v_add_u32_e32 v180, s35, v150
	ds_read_b128 v[146:149], v164
	ds_read_b128 v[156:159], v164 offset:1024
	ds_read_b128 v[160:163], v164 offset:2048
	ds_read_b128 v[164:167], v164 offset:3072
	ds_read_b128 v[168:171], v180
	ds_read_b128 v[172:175], v180 offset:1024
	ds_read_b128 v[176:179], v180 offset:2048
	ds_read_b128 v[180:183], v180 offset:3072
	s_add_u32 s30, s30, 0x40000
	s_addc_u32 s31, s31, 0
	s_mov_b32 m0, s43
	v_lshl_add_u64 v[224:225], s[30:31], 0, v[136:137]
	ds_read_b128 v[184:187], v155 offset:32768
	ds_read_b128 v[188:191], v155 offset:33792
	ds_read_b128 v[192:195], v155 offset:34816
	ds_read_b128 v[196:199], v155 offset:35840
	ds_read_b128 v[200:203], v155 offset:36864
	ds_read_b128 v[204:207], v155 offset:37888
	ds_read_b128 v[208:211], v155 offset:38912
	ds_read_b128 v[212:215], v155 offset:39936
	global_load_lds_dwordx4 v[224:225], off
	v_lshl_add_u64 v[224:225], s[30:31], 0, v[132:133]
	s_mov_b32 m0, s44
	s_nop 0
	global_load_lds_dwordx4 v[224:225], off
	s_waitcnt vmcnt(8)
	s_waitcnt lgkmcnt(0)
	s_barrier
	s_setprio 1
	s_waitcnt lgkmcnt(0)
	v_mfma_f32_16x16x32_bf16 v[124:127], v[146:149], v[184:187], v[124:127]
	v_mfma_f32_16x16x32_bf16 v[120:123], v[160:163], v[184:187], v[120:123]
	v_mfma_f32_16x16x32_bf16 v[108:111], v[146:149], v[192:195], v[108:111]
	v_mfma_f32_16x16x32_bf16 v[104:107], v[160:163], v[192:195], v[104:107]
	v_mfma_f32_16x16x32_bf16 v[92:95], v[146:149], v[200:203], v[92:95]
	v_mfma_f32_16x16x32_bf16 v[88:91], v[160:163], v[200:203], v[88:91]
	v_mfma_f32_16x16x32_bf16 v[76:79], v[146:149], v[208:211], v[76:79]
	v_mfma_f32_16x16x32_bf16 v[72:75], v[160:163], v[208:211], v[72:75]
	v_mfma_f32_16x16x32_bf16 v[124:127], v[156:159], v[188:191], v[124:127]
	v_mfma_f32_16x16x32_bf16 v[120:123], v[164:167], v[188:191], v[120:123]
	v_mfma_f32_16x16x32_bf16 v[108:111], v[156:159], v[196:199], v[108:111]
	v_mfma_f32_16x16x32_bf16 v[104:107], v[164:167], v[196:199], v[104:107]
	v_mfma_f32_16x16x32_bf16 v[92:95], v[156:159], v[204:207], v[92:95]
	v_mfma_f32_16x16x32_bf16 v[88:91], v[164:167], v[204:207], v[88:91]
	v_mfma_f32_16x16x32_bf16 v[76:79], v[156:159], v[212:215], v[76:79]
	v_mfma_f32_16x16x32_bf16 v[72:75], v[164:167], v[212:215], v[72:75]
	s_setprio 0
	s_setprio 1
	v_mfma_f32_16x16x32_bf16 v[116:119], v[168:171], v[184:187], v[116:119]
	v_mfma_f32_16x16x32_bf16 v[112:115], v[176:179], v[184:187], v[112:115]
	v_mfma_f32_16x16x32_bf16 v[100:103], v[168:171], v[192:195], v[100:103]
	v_mfma_f32_16x16x32_bf16 v[96:99], v[176:179], v[192:195], v[96:99]
	v_mfma_f32_16x16x32_bf16 v[84:87], v[168:171], v[200:203], v[84:87]
	v_mfma_f32_16x16x32_bf16 v[80:83], v[176:179], v[200:203], v[80:83]
	v_mfma_f32_16x16x32_bf16 v[68:71], v[168:171], v[208:211], v[68:71]
	v_mfma_f32_16x16x32_bf16 v[64:67], v[176:179], v[208:211], v[64:67]
	v_mfma_f32_16x16x32_bf16 v[116:119], v[172:175], v[188:191], v[116:119]
	v_mfma_f32_16x16x32_bf16 v[112:115], v[180:183], v[188:191], v[112:115]
	v_mfma_f32_16x16x32_bf16 v[100:103], v[172:175], v[196:199], v[100:103]
	v_mfma_f32_16x16x32_bf16 v[96:99], v[180:183], v[196:199], v[96:99]
	v_mfma_f32_16x16x32_bf16 v[84:87], v[172:175], v[204:207], v[84:87]
	v_mfma_f32_16x16x32_bf16 v[80:83], v[180:183], v[204:207], v[80:83]
	v_mfma_f32_16x16x32_bf16 v[68:71], v[172:175], v[212:215], v[68:71]
	v_mfma_f32_16x16x32_bf16 v[64:67], v[180:183], v[212:215], v[64:67]
	s_setprio 0
	s_barrier
	s_add_i32 s30, s34, s38
	v_lshl_add_u64 v[216:217], v[216:217], 0, s[6:7]
	s_mov_b32 m0, s30
	ds_read_b128 v[184:187], v155 offset:49152
	ds_read_b128 v[188:191], v155 offset:50176
	ds_read_b128 v[192:195], v155 offset:51200
	ds_read_b128 v[196:199], v155 offset:52224
	ds_read_b128 v[200:203], v155 offset:53248
	ds_read_b128 v[204:207], v155 offset:54272
	ds_read_b128 v[208:211], v155 offset:55296
	ds_read_b128 v[212:215], v155 offset:56320
	global_load_lds_dwordx4 v[216:217], off
	s_add_i32 m0, s30, 0x2000
	s_add_u32 s28, s28, 0x40080
	v_lshl_add_u64 v[216:217], v[218:219], 0, s[6:7]
	s_addc_u32 s29, s29, 0
	s_add_i32 s30, s35, s38
	global_load_lds_dwordx4 v[216:217], off
	v_lshl_add_u64 v[216:217], s[28:29], 0, v[134:135]
	s_mov_b32 m0, s30
	s_nop 0
	global_load_lds_dwordx4 v[216:217], off
	v_lshl_add_u64 v[216:217], s[28:29], 0, v[130:131]
	s_add_i32 m0, s30, 0x2000
	s_nop 0
	global_load_lds_dwordx4 v[216:217], off
	v_lshl_add_u64 v[216:217], v[220:221], 0, s[6:7]
	s_mov_b32 m0, s45
	s_nop 0
	global_load_lds_dwordx4 v[216:217], off
	v_lshl_add_u64 v[216:217], v[222:223], 0, s[6:7]
	s_mov_b32 m0, s46
	s_nop 0
	global_load_lds_dwordx4 v[216:217], off
	s_waitcnt vmcnt(8)
	s_waitcnt lgkmcnt(0)
	s_barrier
	s_setprio 1
	s_waitcnt lgkmcnt(0)
	v_mfma_f32_16x16x32_bf16 v[60:63], v[146:149], v[184:187], v[60:63]
	v_mfma_f32_16x16x32_bf16 v[56:59], v[160:163], v[184:187], v[56:59]
	v_mfma_f32_16x16x32_bf16 v[44:47], v[146:149], v[192:195], v[44:47]
	v_mfma_f32_16x16x32_bf16 v[40:43], v[160:163], v[192:195], v[40:43]
	v_mfma_f32_16x16x32_bf16 v[28:31], v[146:149], v[200:203], v[28:31]
	v_mfma_f32_16x16x32_bf16 v[24:27], v[160:163], v[200:203], v[24:27]
	v_mfma_f32_16x16x32_bf16 v[12:15], v[146:149], v[208:211], v[12:15]
	v_mfma_f32_16x16x32_bf16 v[8:11], v[160:163], v[208:211], v[8:11]
	v_mfma_f32_16x16x32_bf16 v[60:63], v[156:159], v[188:191], v[60:63]
	v_mfma_f32_16x16x32_bf16 v[56:59], v[164:167], v[188:191], v[56:59]
	v_mfma_f32_16x16x32_bf16 v[44:47], v[156:159], v[196:199], v[44:47]
	v_mfma_f32_16x16x32_bf16 v[40:43], v[164:167], v[196:199], v[40:43]
	v_mfma_f32_16x16x32_bf16 v[28:31], v[156:159], v[204:207], v[28:31]
	v_mfma_f32_16x16x32_bf16 v[24:27], v[164:167], v[204:207], v[24:27]
	v_mfma_f32_16x16x32_bf16 v[12:15], v[156:159], v[212:215], v[12:15]
	v_mfma_f32_16x16x32_bf16 v[8:11], v[164:167], v[212:215], v[8:11]
	s_setprio 0
	s_setprio 1
	v_mfma_f32_16x16x32_bf16 v[52:55], v[168:171], v[184:187], v[52:55]
	v_mfma_f32_16x16x32_bf16 v[48:51], v[176:179], v[184:187], v[48:51]
	v_mfma_f32_16x16x32_bf16 v[36:39], v[168:171], v[192:195], v[36:39]
	v_mfma_f32_16x16x32_bf16 v[32:35], v[176:179], v[192:195], v[32:35]
	v_mfma_f32_16x16x32_bf16 v[20:23], v[168:171], v[200:203], v[20:23]
	v_mfma_f32_16x16x32_bf16 v[16:19], v[176:179], v[200:203], v[16:19]
	v_mfma_f32_16x16x32_bf16 v[4:7], v[168:171], v[208:211], v[4:7]
	v_mfma_f32_16x16x32_bf16 v[0:3], v[176:179], v[208:211], v[0:3]
	v_mfma_f32_16x16x32_bf16 v[52:55], v[172:175], v[188:191], v[52:55]
	v_mfma_f32_16x16x32_bf16 v[48:51], v[180:183], v[188:191], v[48:51]
	v_mfma_f32_16x16x32_bf16 v[36:39], v[172:175], v[196:199], v[36:39]
	v_mfma_f32_16x16x32_bf16 v[32:35], v[180:183], v[196:199], v[32:35]
	v_mfma_f32_16x16x32_bf16 v[20:23], v[172:175], v[204:207], v[20:23]
	v_mfma_f32_16x16x32_bf16 v[16:19], v[180:183], v[204:207], v[16:19]
	v_mfma_f32_16x16x32_bf16 v[4:7], v[172:175], v[212:215], v[4:7]
	v_mfma_f32_16x16x32_bf16 v[0:3], v[180:183], v[212:215], v[0:3]
	s_setprio 0
	s_cmp_eq_u32 s56, s98
	s_cbranch_scc1 .Lmy_nobar_22
	s_barrier
.Lmy_nobar_22:
	s_add_i32 s56, s56, 2
	s_add_u32 s26, s26, 0x100
	s_addc_u32 s27, s27, 0
	s_add_u32 s54, s54, 0x100
	s_addc_u32 s55, s55, 0
	s_cmp_gt_u32 s56, 13
	s_cbranch_scc0 .LBB0_2091
	s_and_b64 vcc, exec, s[8:9]
	s_cbranch_vccz .LBB0_2094
	s_nop 0
.LBB0_2094:
	v_lshl_add_u32 v157, s12, 10, v151
	ds_read_b32 v158, v157
	v_lshl_or_b32 v148, s13, 7, v152
	v_lshl_add_u32 v156, s24, 8, v129
	v_ashrrev_i32_e32 v149, 31, v148
	v_mov_b64_e32 v[146:147], s[16:17]
	s_waitcnt lgkmcnt(0)
	v_pk_mul_f32 v[124:125], v[124:125], v[158:159] op_sel_hi:[1,0]
	v_pk_mul_f32 v[126:127], v[126:127], v[158:159] op_sel_hi:[1,0]
	v_pk_mul_f32 v[122:123], v[122:123], v[158:159] op_sel_hi:[1,0]
	v_pk_mul_f32 v[120:121], v[120:121], v[158:159] op_sel_hi:[1,0]
	v_pk_mul_f32 v[118:119], v[118:119], v[158:159] op_sel_hi:[1,0]
	v_pk_mul_f32 v[116:117], v[116:117], v[158:159] op_sel_hi:[1,0]
	v_mul_f32_e32 v159, 0xbfb8aa3b, v124
	v_exp_f32_e32 v159, v159
	v_mul_f32_e32 v162, 0xbfb8aa3b, v125
	v_exp_f32_e32 v164, v162
	v_mad_i64_i32 v[160:161], s[12:13], v156, s49, v[146:147]
	v_pk_mul_f32 v[162:163], v[114:115], v[158:159] op_sel_hi:[1,0]
	v_add_f32_e32 v114, 1.0, v159
	v_rcp_f32_e32 v159, v114
	v_add_f32_e32 v114, 1.0, v164
	v_rcp_f32_e32 v164, v114
	v_lshlrev_b64 v[148:149], 1, v[148:149]
	v_pk_mul_f32 v[114:115], v[112:113], v[158:159] op_sel_hi:[1,0]
	v_mul_f32_e32 v112, v124, v159
	v_mul_f32_e32 v112, v116, v112
	v_mul_f32_e32 v116, 0xbfb8aa3b, v126
	v_mul_f32_e32 v124, 0xbfb8aa3b, v127
	v_exp_f32_e32 v116, v116
	v_exp_f32_e32 v124, v124
	v_mul_f32_e32 v113, v125, v164
	v_mul_f32_e32 v113, v117, v113
	v_add_f32_e32 v116, 1.0, v116
	v_add_f32_e32 v117, 1.0, v124
	v_rcp_f32_e32 v116, v116
	v_rcp_f32_e32 v117, v117
	v_cvt_pk_bf16_f32 v112, v112, v113
	v_lshl_add_u64 v[160:161], v[160:161], 0, v[148:149]
	v_mul_f32_e32 v113, v126, v116
	v_mul_f32_e32 v116, v127, v117
	v_mul_f32_e32 v117, 0xbfb8aa3b, v120
	v_mul_f32_e32 v113, v118, v113
	v_exp_f32_e32 v117, v117
	v_mul_f32_e32 v118, 0xbfb8aa3b, v121
	v_exp_f32_e32 v118, v118
	v_mul_f32_e32 v116, v119, v116
	v_add_f32_e32 v117, 1.0, v117
	v_rcp_f32_e32 v117, v117
	v_add_f32_e32 v118, 1.0, v118
	v_rcp_f32_e32 v118, v118
	v_cvt_pk_bf16_f32 v113, v113, v116
	v_mul_f32_e32 v116, v120, v117
	v_mul_f32_e32 v117, 0xbfb8aa3b, v122
	v_mul_f32_e32 v114, v114, v116
	v_mul_f32_e32 v116, v121, v118
	v_exp_f32_e32 v117, v117
	v_mul_f32_e32 v118, 0xbfb8aa3b, v123
	v_exp_f32_e32 v118, v118
	v_mul_f32_e32 v115, v115, v116
	v_add_f32_e32 v116, 1.0, v117
	v_rcp_f32_e32 v116, v116
	v_add_f32_e32 v117, 1.0, v118
	v_rcp_f32_e32 v117, v117
	v_cvt_pk_bf16_f32 v114, v114, v115
	v_mul_f32_e32 v115, v122, v116
	v_mul_f32_e32 v115, v162, v115
	v_mul_f32_e32 v116, v123, v117
	v_mul_f32_e32 v116, v163, v116
	v_cvt_pk_bf16_f32 v115, v115, v116
	global_store_dwordx4 v[160:161], v[112:115], off
	ds_read_b32 v112, v157 offset:64
	s_andn2_b64 vcc, exec, s[4:5]
	v_or_b32_e32 v113, 16, v156
	v_mad_i64_i32 v[114:115], s[12:13], v113, s49, v[146:147]
	s_waitcnt lgkmcnt(0)
	v_pk_mul_f32 v[108:109], v[108:109], v[112:113] op_sel_hi:[1,0]
	v_pk_mul_f32 v[110:111], v[110:111], v[112:113] op_sel_hi:[1,0]
	v_pk_mul_f32 v[106:107], v[106:107], v[112:113] op_sel_hi:[1,0]
	v_pk_mul_f32 v[104:105], v[104:105], v[112:113] op_sel_hi:[1,0]
	v_pk_mul_f32 v[102:103], v[102:103], v[112:113] op_sel_hi:[1,0]
	v_pk_mul_f32 v[100:101], v[100:101], v[112:113] op_sel_hi:[1,0]
	v_mul_f32_e32 v113, 0xbfb8aa3b, v108
	v_exp_f32_e32 v113, v113
	v_mul_f32_e32 v116, 0xbfb8aa3b, v109
	v_exp_f32_e32 v118, v116
	v_lshl_add_u64 v[114:115], v[114:115], 0, v[148:149]
	v_pk_mul_f32 v[116:117], v[98:99], v[112:113] op_sel_hi:[1,0]
	v_add_f32_e32 v98, 1.0, v113
	v_rcp_f32_e32 v113, v98
	v_add_f32_e32 v98, 1.0, v118
	v_rcp_f32_e32 v118, v98
	s_mov_b64 s[4:5], -1
	v_pk_mul_f32 v[98:99], v[96:97], v[112:113] op_sel_hi:[1,0]
	v_mul_f32_e32 v96, v108, v113
	v_mul_f32_e32 v96, v100, v96
	v_mul_f32_e32 v100, 0xbfb8aa3b, v110
	v_mul_f32_e32 v108, 0xbfb8aa3b, v111
	v_exp_f32_e32 v100, v100
	v_exp_f32_e32 v108, v108
	v_mul_f32_e32 v97, v109, v118
	v_mul_f32_e32 v97, v101, v97
	v_add_f32_e32 v100, 1.0, v100
	v_add_f32_e32 v101, 1.0, v108
	v_rcp_f32_e32 v100, v100
	v_rcp_f32_e32 v101, v101
	v_cvt_pk_bf16_f32 v96, v96, v97
	v_mul_f32_e32 v97, v110, v100
	v_mul_f32_e32 v100, v111, v101
	v_mul_f32_e32 v101, 0xbfb8aa3b, v104
	v_mul_f32_e32 v97, v102, v97
	v_exp_f32_e32 v101, v101
	v_mul_f32_e32 v102, 0xbfb8aa3b, v105
	v_exp_f32_e32 v102, v102
	v_mul_f32_e32 v100, v103, v100
	v_add_f32_e32 v101, 1.0, v101
	v_rcp_f32_e32 v101, v101
	v_add_f32_e32 v102, 1.0, v102
	v_rcp_f32_e32 v102, v102
	v_cvt_pk_bf16_f32 v97, v97, v100
	v_mul_f32_e32 v100, v104, v101
	v_mul_f32_e32 v101, 0xbfb8aa3b, v106
	v_mul_f32_e32 v98, v98, v100
	v_mul_f32_e32 v100, v105, v102
	v_exp_f32_e32 v101, v101
	v_mul_f32_e32 v102, 0xbfb8aa3b, v107
	v_exp_f32_e32 v102, v102
	v_mul_f32_e32 v99, v99, v100
	v_add_f32_e32 v100, 1.0, v101
	v_rcp_f32_e32 v100, v100
	v_add_f32_e32 v101, 1.0, v102
	v_rcp_f32_e32 v101, v101
	v_cvt_pk_bf16_f32 v98, v98, v99
	v_mul_f32_e32 v99, v106, v100
	v_mul_f32_e32 v99, v116, v99
	v_mul_f32_e32 v100, v107, v101
	v_mul_f32_e32 v100, v117, v100
	v_cvt_pk_bf16_f32 v99, v99, v100
	global_store_dwordx4 v[114:115], v[96:99], off
	ds_read_b32 v96, v157 offset:128
	s_nop 0
	v_or_b32_e32 v97, 32, v156
	v_mad_i64_i32 v[98:99], s[12:13], v97, s49, v[146:147]
	s_waitcnt lgkmcnt(0)
	v_pk_mul_f32 v[92:93], v[92:93], v[96:97] op_sel_hi:[1,0]
	v_pk_mul_f32 v[94:95], v[94:95], v[96:97] op_sel_hi:[1,0]
	v_pk_mul_f32 v[90:91], v[90:91], v[96:97] op_sel_hi:[1,0]
	v_pk_mul_f32 v[88:89], v[88:89], v[96:97] op_sel_hi:[1,0]
	v_pk_mul_f32 v[86:87], v[86:87], v[96:97] op_sel_hi:[1,0]
	v_pk_mul_f32 v[84:85], v[84:85], v[96:97] op_sel_hi:[1,0]
	v_mul_f32_e32 v97, 0xbfb8aa3b, v92
	v_exp_f32_e32 v97, v97
	v_mul_f32_e32 v100, 0xbfb8aa3b, v93
	v_exp_f32_e32 v102, v100
	v_lshl_add_u64 v[98:99], v[98:99], 0, v[148:149]
	v_pk_mul_f32 v[100:101], v[82:83], v[96:97] op_sel_hi:[1,0]
	v_add_f32_e32 v82, 1.0, v97
	v_rcp_f32_e32 v97, v82
	v_add_f32_e32 v82, 1.0, v102
	v_rcp_f32_e32 v102, v82
	v_pk_mul_f32 v[82:83], v[80:81], v[96:97] op_sel_hi:[1,0]
	v_mul_f32_e32 v80, v92, v97
	v_mul_f32_e32 v80, v84, v80
	v_mul_f32_e32 v84, 0xbfb8aa3b, v94
	v_mul_f32_e32 v92, 0xbfb8aa3b, v95
	v_exp_f32_e32 v84, v84
	v_exp_f32_e32 v92, v92
	v_mul_f32_e32 v81, v93, v102
	v_mul_f32_e32 v81, v85, v81
	v_add_f32_e32 v84, 1.0, v84
	v_add_f32_e32 v85, 1.0, v92
	v_rcp_f32_e32 v84, v84
	v_rcp_f32_e32 v85, v85
	v_cvt_pk_bf16_f32 v80, v80, v81
	v_mul_f32_e32 v81, v94, v84
	v_mul_f32_e32 v84, v95, v85
	v_mul_f32_e32 v85, 0xbfb8aa3b, v88
	v_mul_f32_e32 v81, v86, v81
	v_exp_f32_e32 v85, v85
	v_mul_f32_e32 v86, 0xbfb8aa3b, v89
	v_exp_f32_e32 v86, v86
	v_mul_f32_e32 v84, v87, v84
	v_add_f32_e32 v85, 1.0, v85
	v_rcp_f32_e32 v85, v85
	v_add_f32_e32 v86, 1.0, v86
	v_rcp_f32_e32 v86, v86
	v_cvt_pk_bf16_f32 v81, v81, v84
	v_mul_f32_e32 v84, v88, v85
	v_mul_f32_e32 v85, 0xbfb8aa3b, v90
	v_mul_f32_e32 v82, v82, v84
	v_mul_f32_e32 v84, v89, v86
	v_exp_f32_e32 v85, v85
	v_mul_f32_e32 v86, 0xbfb8aa3b, v91
	v_exp_f32_e32 v86, v86
	v_mul_f32_e32 v83, v83, v84
	v_add_f32_e32 v84, 1.0, v85
	v_rcp_f32_e32 v84, v84
	v_add_f32_e32 v85, 1.0, v86
	v_rcp_f32_e32 v85, v85
	v_cvt_pk_bf16_f32 v82, v82, v83
	v_mul_f32_e32 v83, v90, v84
	v_mul_f32_e32 v83, v100, v83
	v_mul_f32_e32 v84, v91, v85
	v_mul_f32_e32 v84, v101, v84
	v_cvt_pk_bf16_f32 v83, v83, v84
	global_store_dwordx4 v[98:99], v[80:83], off
	ds_read_b32 v80, v157 offset:192
	s_nop 0
	v_or_b32_e32 v81, 48, v156
	v_mad_i64_i32 v[82:83], s[12:13], v81, s49, v[146:147]
	s_waitcnt lgkmcnt(0)
	v_pk_mul_f32 v[76:77], v[76:77], v[80:81] op_sel_hi:[1,0]
	v_pk_mul_f32 v[78:79], v[78:79], v[80:81] op_sel_hi:[1,0]
	v_pk_mul_f32 v[74:75], v[74:75], v[80:81] op_sel_hi:[1,0]
	v_pk_mul_f32 v[72:73], v[72:73], v[80:81] op_sel_hi:[1,0]
	v_pk_mul_f32 v[70:71], v[70:71], v[80:81] op_sel_hi:[1,0]
	v_pk_mul_f32 v[68:69], v[68:69], v[80:81] op_sel_hi:[1,0]
	v_mul_f32_e32 v81, 0xbfb8aa3b, v76
	v_exp_f32_e32 v81, v81
	v_mul_f32_e32 v84, 0xbfb8aa3b, v77
	v_exp_f32_e32 v86, v84
	v_lshl_add_u64 v[82:83], v[82:83], 0, v[148:149]
	v_pk_mul_f32 v[84:85], v[66:67], v[80:81] op_sel_hi:[1,0]
	v_add_f32_e32 v66, 1.0, v81
	v_rcp_f32_e32 v81, v66
	v_add_f32_e32 v66, 1.0, v86
	v_rcp_f32_e32 v86, v66
	v_pk_mul_f32 v[66:67], v[64:65], v[80:81] op_sel_hi:[1,0]
	v_mul_f32_e32 v64, v76, v81
	v_mul_f32_e32 v64, v68, v64
	v_mul_f32_e32 v68, 0xbfb8aa3b, v78
	v_mul_f32_e32 v76, 0xbfb8aa3b, v79
	v_exp_f32_e32 v68, v68
	v_exp_f32_e32 v76, v76
	v_mul_f32_e32 v65, v77, v86
	v_mul_f32_e32 v65, v69, v65
	v_add_f32_e32 v68, 1.0, v68
	v_add_f32_e32 v69, 1.0, v76
	v_rcp_f32_e32 v68, v68
	v_rcp_f32_e32 v69, v69
	v_cvt_pk_bf16_f32 v64, v64, v65
	v_mul_f32_e32 v65, v78, v68
	v_mul_f32_e32 v68, v79, v69
	v_mul_f32_e32 v69, 0xbfb8aa3b, v72
	v_mul_f32_e32 v65, v70, v65
	v_exp_f32_e32 v69, v69
	v_mul_f32_e32 v70, 0xbfb8aa3b, v73
	v_exp_f32_e32 v70, v70
	v_mul_f32_e32 v68, v71, v68
	v_add_f32_e32 v69, 1.0, v69
	v_rcp_f32_e32 v69, v69
	v_add_f32_e32 v70, 1.0, v70
	v_rcp_f32_e32 v70, v70
	v_cvt_pk_bf16_f32 v65, v65, v68
	v_mul_f32_e32 v68, v72, v69
	v_mul_f32_e32 v69, 0xbfb8aa3b, v74
	v_mul_f32_e32 v66, v66, v68
	v_mul_f32_e32 v68, v73, v70
	v_exp_f32_e32 v69, v69
	v_mul_f32_e32 v70, 0xbfb8aa3b, v75
	v_exp_f32_e32 v70, v70
	v_mul_f32_e32 v67, v67, v68
	v_add_f32_e32 v68, 1.0, v69
	v_rcp_f32_e32 v68, v68
	v_add_f32_e32 v69, 1.0, v70
	v_rcp_f32_e32 v69, v69
	v_cvt_pk_bf16_f32 v66, v66, v67
	v_mul_f32_e32 v67, v74, v68
	v_mul_f32_e32 v67, v84, v67
	v_mul_f32_e32 v68, v75, v69
	v_mul_f32_e32 v68, v85, v68
	v_cvt_pk_bf16_f32 v67, v67, v68
	global_store_dwordx4 v[82:83], v[64:67], off
	ds_read_b32 v64, v157 offset:512
	s_nop 0
	v_add_u32_e32 v65, 0x80, v156
	v_mad_i64_i32 v[66:67], s[12:13], v65, s49, v[146:147]
	s_waitcnt lgkmcnt(0)
	v_pk_mul_f32 v[60:61], v[60:61], v[64:65] op_sel_hi:[1,0]
	v_pk_mul_f32 v[62:63], v[62:63], v[64:65] op_sel_hi:[1,0]
	v_pk_mul_f32 v[58:59], v[58:59], v[64:65] op_sel_hi:[1,0]
	v_pk_mul_f32 v[56:57], v[56:57], v[64:65] op_sel_hi:[1,0]
	v_pk_mul_f32 v[54:55], v[54:55], v[64:65] op_sel_hi:[1,0]
	v_pk_mul_f32 v[52:53], v[52:53], v[64:65] op_sel_hi:[1,0]
	v_mul_f32_e32 v65, 0xbfb8aa3b, v60
	v_exp_f32_e32 v65, v65
	v_mul_f32_e32 v68, 0xbfb8aa3b, v61
	v_exp_f32_e32 v70, v68
	v_lshl_add_u64 v[66:67], v[66:67], 0, v[148:149]
	v_pk_mul_f32 v[68:69], v[50:51], v[64:65] op_sel_hi:[1,0]
	v_add_f32_e32 v50, 1.0, v65
	v_rcp_f32_e32 v65, v50
	v_add_f32_e32 v50, 1.0, v70
	v_rcp_f32_e32 v70, v50
	v_pk_mul_f32 v[50:51], v[48:49], v[64:65] op_sel_hi:[1,0]
	v_mul_f32_e32 v48, v60, v65
	v_mul_f32_e32 v48, v52, v48
	v_mul_f32_e32 v52, 0xbfb8aa3b, v62
	v_mul_f32_e32 v60, 0xbfb8aa3b, v63
	v_exp_f32_e32 v52, v52
	v_exp_f32_e32 v60, v60
	v_mul_f32_e32 v49, v61, v70
	v_mul_f32_e32 v49, v53, v49
	v_add_f32_e32 v52, 1.0, v52
	v_add_f32_e32 v53, 1.0, v60
	v_rcp_f32_e32 v52, v52
	v_rcp_f32_e32 v53, v53
	v_cvt_pk_bf16_f32 v48, v48, v49
	v_mul_f32_e32 v49, v62, v52
	v_mul_f32_e32 v52, v63, v53
	v_mul_f32_e32 v53, 0xbfb8aa3b, v56
	v_mul_f32_e32 v49, v54, v49
	v_exp_f32_e32 v53, v53
	v_mul_f32_e32 v54, 0xbfb8aa3b, v57
	v_exp_f32_e32 v54, v54
	v_mul_f32_e32 v52, v55, v52
	v_add_f32_e32 v53, 1.0, v53
	v_rcp_f32_e32 v53, v53
	v_add_f32_e32 v54, 1.0, v54
	v_rcp_f32_e32 v54, v54
	v_cvt_pk_bf16_f32 v49, v49, v52
	v_mul_f32_e32 v52, v56, v53
	v_mul_f32_e32 v53, 0xbfb8aa3b, v58
	v_mul_f32_e32 v50, v50, v52
	v_mul_f32_e32 v52, v57, v54
	v_exp_f32_e32 v53, v53
	v_mul_f32_e32 v54, 0xbfb8aa3b, v59
	v_exp_f32_e32 v54, v54
	v_mul_f32_e32 v51, v51, v52
	v_add_f32_e32 v52, 1.0, v53
	v_rcp_f32_e32 v52, v52
	v_add_f32_e32 v53, 1.0, v54
	v_rcp_f32_e32 v53, v53
	v_cvt_pk_bf16_f32 v50, v50, v51
	v_mul_f32_e32 v51, v58, v52
	v_mul_f32_e32 v51, v68, v51
	v_mul_f32_e32 v52, v59, v53
	v_mul_f32_e32 v52, v69, v52
	v_cvt_pk_bf16_f32 v51, v51, v52
	global_store_dwordx4 v[66:67], v[48:51], off
	ds_read_b32 v48, v157 offset:576
	s_nop 0
	v_add_u32_e32 v49, 0x90, v156
	v_mad_i64_i32 v[50:51], s[12:13], v49, s49, v[146:147]
	s_waitcnt lgkmcnt(0)
	v_pk_mul_f32 v[44:45], v[44:45], v[48:49] op_sel_hi:[1,0]
	v_pk_mul_f32 v[46:47], v[46:47], v[48:49] op_sel_hi:[1,0]
	v_pk_mul_f32 v[42:43], v[42:43], v[48:49] op_sel_hi:[1,0]
	v_pk_mul_f32 v[40:41], v[40:41], v[48:49] op_sel_hi:[1,0]
	v_pk_mul_f32 v[38:39], v[38:39], v[48:49] op_sel_hi:[1,0]
	v_pk_mul_f32 v[36:37], v[36:37], v[48:49] op_sel_hi:[1,0]
	v_mul_f32_e32 v49, 0xbfb8aa3b, v44
	v_exp_f32_e32 v49, v49
	v_mul_f32_e32 v52, 0xbfb8aa3b, v45
	v_exp_f32_e32 v54, v52
	v_lshl_add_u64 v[50:51], v[50:51], 0, v[148:149]
	v_pk_mul_f32 v[52:53], v[34:35], v[48:49] op_sel_hi:[1,0]
	v_add_f32_e32 v34, 1.0, v49
	v_rcp_f32_e32 v49, v34
	v_add_f32_e32 v34, 1.0, v54
	v_rcp_f32_e32 v54, v34
	v_pk_mul_f32 v[34:35], v[32:33], v[48:49] op_sel_hi:[1,0]
	v_mul_f32_e32 v32, v44, v49
	v_mul_f32_e32 v32, v36, v32
	v_mul_f32_e32 v36, 0xbfb8aa3b, v46
	v_mul_f32_e32 v44, 0xbfb8aa3b, v47
	v_exp_f32_e32 v36, v36
	v_exp_f32_e32 v44, v44
	v_mul_f32_e32 v33, v45, v54
	v_mul_f32_e32 v33, v37, v33
	v_add_f32_e32 v36, 1.0, v36
	v_add_f32_e32 v37, 1.0, v44
	v_rcp_f32_e32 v36, v36
	v_rcp_f32_e32 v37, v37
	v_cvt_pk_bf16_f32 v32, v32, v33
	v_mul_f32_e32 v33, v46, v36
	v_mul_f32_e32 v36, v47, v37
	v_mul_f32_e32 v37, 0xbfb8aa3b, v40
	v_mul_f32_e32 v33, v38, v33
	v_exp_f32_e32 v37, v37
	v_mul_f32_e32 v38, 0xbfb8aa3b, v41
	v_exp_f32_e32 v38, v38
	v_mul_f32_e32 v36, v39, v36
	v_add_f32_e32 v37, 1.0, v37
	v_rcp_f32_e32 v37, v37
	v_add_f32_e32 v38, 1.0, v38
	v_rcp_f32_e32 v38, v38
	v_cvt_pk_bf16_f32 v33, v33, v36
	v_mul_f32_e32 v36, v40, v37
	v_mul_f32_e32 v37, 0xbfb8aa3b, v42
	v_mul_f32_e32 v34, v34, v36
	v_mul_f32_e32 v36, v41, v38
	v_exp_f32_e32 v37, v37
	v_mul_f32_e32 v38, 0xbfb8aa3b, v43
	v_exp_f32_e32 v38, v38
	v_mul_f32_e32 v35, v35, v36
	v_add_f32_e32 v36, 1.0, v37
	v_rcp_f32_e32 v36, v36
	v_add_f32_e32 v37, 1.0, v38
	v_rcp_f32_e32 v37, v37
	v_cvt_pk_bf16_f32 v34, v34, v35
	v_mul_f32_e32 v35, v42, v36
	v_mul_f32_e32 v35, v52, v35
	v_mul_f32_e32 v36, v43, v37
	v_mul_f32_e32 v36, v53, v36
	v_cvt_pk_bf16_f32 v35, v35, v36
	global_store_dwordx4 v[50:51], v[32:35], off
	ds_read_b32 v32, v157 offset:640
	s_nop 0
	v_add_u32_e32 v33, 0xa0, v156
	v_mad_i64_i32 v[34:35], s[12:13], v33, s49, v[146:147]
	s_waitcnt lgkmcnt(0)
	v_pk_mul_f32 v[28:29], v[28:29], v[32:33] op_sel_hi:[1,0]
	v_pk_mul_f32 v[30:31], v[30:31], v[32:33] op_sel_hi:[1,0]
	v_pk_mul_f32 v[26:27], v[26:27], v[32:33] op_sel_hi:[1,0]
	v_pk_mul_f32 v[24:25], v[24:25], v[32:33] op_sel_hi:[1,0]
	v_pk_mul_f32 v[22:23], v[22:23], v[32:33] op_sel_hi:[1,0]
	v_pk_mul_f32 v[20:21], v[20:21], v[32:33] op_sel_hi:[1,0]
	v_mul_f32_e32 v33, 0xbfb8aa3b, v28
	v_exp_f32_e32 v33, v33
	v_mul_f32_e32 v36, 0xbfb8aa3b, v29
	v_exp_f32_e32 v38, v36
	v_lshl_add_u64 v[34:35], v[34:35], 0, v[148:149]
	v_pk_mul_f32 v[36:37], v[18:19], v[32:33] op_sel_hi:[1,0]
	v_add_f32_e32 v18, 1.0, v33
	v_rcp_f32_e32 v33, v18
	v_add_f32_e32 v18, 1.0, v38
	v_rcp_f32_e32 v38, v18
	v_pk_mul_f32 v[18:19], v[16:17], v[32:33] op_sel_hi:[1,0]
	v_mul_f32_e32 v16, v28, v33
	v_mul_f32_e32 v16, v20, v16
	v_mul_f32_e32 v20, 0xbfb8aa3b, v30
	v_mul_f32_e32 v28, 0xbfb8aa3b, v31
	v_exp_f32_e32 v20, v20
	v_exp_f32_e32 v28, v28
	v_mul_f32_e32 v17, v29, v38
	v_mul_f32_e32 v17, v21, v17
	v_add_f32_e32 v20, 1.0, v20
	v_add_f32_e32 v21, 1.0, v28
	v_rcp_f32_e32 v20, v20
	v_rcp_f32_e32 v21, v21
	v_cvt_pk_bf16_f32 v16, v16, v17
	v_mul_f32_e32 v17, v30, v20
	v_mul_f32_e32 v20, v31, v21
	v_mul_f32_e32 v21, 0xbfb8aa3b, v24
	v_mul_f32_e32 v17, v22, v17
	v_exp_f32_e32 v21, v21
	v_mul_f32_e32 v22, 0xbfb8aa3b, v25
	v_exp_f32_e32 v22, v22
	v_mul_f32_e32 v20, v23, v20
	v_add_f32_e32 v21, 1.0, v21
	v_rcp_f32_e32 v21, v21
	v_add_f32_e32 v22, 1.0, v22
	v_rcp_f32_e32 v22, v22
	v_cvt_pk_bf16_f32 v17, v17, v20
	v_mul_f32_e32 v20, v24, v21
	v_mul_f32_e32 v21, 0xbfb8aa3b, v26
	v_mul_f32_e32 v18, v18, v20
	v_mul_f32_e32 v20, v25, v22
	v_exp_f32_e32 v21, v21
	v_mul_f32_e32 v22, 0xbfb8aa3b, v27
	v_exp_f32_e32 v22, v22
	v_mul_f32_e32 v19, v19, v20
	v_add_f32_e32 v20, 1.0, v21
	v_rcp_f32_e32 v20, v20
	v_add_f32_e32 v21, 1.0, v22
	v_rcp_f32_e32 v21, v21
	v_cvt_pk_bf16_f32 v18, v18, v19
	v_mul_f32_e32 v19, v26, v20
	v_mul_f32_e32 v19, v36, v19
	v_mul_f32_e32 v20, v27, v21
	v_mul_f32_e32 v20, v37, v20
	v_cvt_pk_bf16_f32 v19, v19, v20
	global_store_dwordx4 v[34:35], v[16:19], off
	ds_read_b32 v16, v157 offset:704
	s_nop 0
	v_add_u32_e32 v17, 0xb0, v156
	v_mad_i64_i32 v[18:19], s[12:13], v17, s49, v[146:147]
	s_waitcnt lgkmcnt(0)
	v_pk_mul_f32 v[12:13], v[12:13], v[16:17] op_sel_hi:[1,0]
	v_pk_mul_f32 v[14:15], v[14:15], v[16:17] op_sel_hi:[1,0]
	v_pk_mul_f32 v[10:11], v[10:11], v[16:17] op_sel_hi:[1,0]
	v_pk_mul_f32 v[8:9], v[8:9], v[16:17] op_sel_hi:[1,0]
	v_pk_mul_f32 v[6:7], v[6:7], v[16:17] op_sel_hi:[1,0]
	v_pk_mul_f32 v[4:5], v[4:5], v[16:17] op_sel_hi:[1,0]
	v_mul_f32_e32 v17, 0xbfb8aa3b, v12
	v_exp_f32_e32 v17, v17
	v_mul_f32_e32 v20, 0xbfb8aa3b, v13
	v_exp_f32_e32 v22, v20
	v_lshl_add_u64 v[18:19], v[18:19], 0, v[148:149]
	v_pk_mul_f32 v[20:21], v[2:3], v[16:17] op_sel_hi:[1,0]
	v_add_f32_e32 v2, 1.0, v17
	v_rcp_f32_e32 v17, v2
	v_add_f32_e32 v2, 1.0, v22
	v_rcp_f32_e32 v22, v2
	v_pk_mul_f32 v[2:3], v[0:1], v[16:17] op_sel_hi:[1,0]
	v_mul_f32_e32 v0, v12, v17
	v_mul_f32_e32 v0, v4, v0
	v_mul_f32_e32 v4, 0xbfb8aa3b, v14
	v_mul_f32_e32 v12, 0xbfb8aa3b, v15
	v_exp_f32_e32 v4, v4
	v_exp_f32_e32 v12, v12
	v_mul_f32_e32 v1, v13, v22
	v_mul_f32_e32 v1, v5, v1
	v_add_f32_e32 v4, 1.0, v4
	v_add_f32_e32 v5, 1.0, v12
	v_rcp_f32_e32 v4, v4
	v_rcp_f32_e32 v5, v5
	v_cvt_pk_bf16_f32 v0, v0, v1
	v_mul_f32_e32 v1, v14, v4
	v_mul_f32_e32 v4, v15, v5
	v_mul_f32_e32 v5, 0xbfb8aa3b, v8
	v_mul_f32_e32 v1, v6, v1
	v_exp_f32_e32 v5, v5
	v_mul_f32_e32 v6, 0xbfb8aa3b, v9
	v_exp_f32_e32 v6, v6
	v_mul_f32_e32 v4, v7, v4
	v_add_f32_e32 v5, 1.0, v5
	v_rcp_f32_e32 v5, v5
	v_add_f32_e32 v6, 1.0, v6
	v_rcp_f32_e32 v6, v6
	v_cvt_pk_bf16_f32 v1, v1, v4
	v_mul_f32_e32 v4, v8, v5
	v_mul_f32_e32 v5, 0xbfb8aa3b, v10
	v_mul_f32_e32 v2, v2, v4
	v_mul_f32_e32 v4, v9, v6
	v_exp_f32_e32 v5, v5
	v_mul_f32_e32 v6, 0xbfb8aa3b, v11
	v_exp_f32_e32 v6, v6
	v_mul_f32_e32 v3, v3, v4
	v_add_f32_e32 v4, 1.0, v5
	v_rcp_f32_e32 v4, v4
	v_add_f32_e32 v5, 1.0, v6
	v_rcp_f32_e32 v5, v5
	v_cvt_pk_bf16_f32 v2, v2, v3
	v_mul_f32_e32 v3, v10, v4
	v_mul_f32_e32 v3, v20, v3
	v_mul_f32_e32 v4, v11, v5
	v_mul_f32_e32 v4, v21, v4
	v_cvt_pk_bf16_f32 v3, v3, v4
	global_store_dwordx4 v[18:19], v[0:3], off
	s_cbranch_vccnz .LBB0_2087
	s_andn2_b64 vcc, exec, s[0:1]
	s_cbranch_vccnz .LBB0_2086
	s_nop 0
	s_branch .LBB0_2086

.LBB0_2163:
	s_lshr_b32 s99, s91, 2
	s_cmp_eq_u32 s99, 1
	s_cselect_b32 s98, 40, 0x7fffffff
	s_add_i32 s45, s45, 1
	s_mul_i32 s0, s45, s48
	s_mul_hi_u32 s1, s45, s49
	s_add_i32 s1, s1, s0
	s_mul_i32 s0, s45, s49
	s_add_u32 s4, s0, s2
	s_addc_u32 s5, s1, s3
	v_cmp_gt_i64_e32 vcc, s[4:5], v[142:143]
	v_cmp_lt_i64_e64 s[0:1], s[4:5], v[140:141]
	s_cbranch_vccnz .LBB0_2169
	s_ashr_i32 s5, s4, 31
	s_lshr_b32 s5, s5, 29
	s_add_i32 s26, s4, s5
	s_and_b32 s5, s26, -8
	s_sub_i32 s27, s4, s5
	s_cmp_gt_i32 s27, -1
	s_mov_b64 s[4:5], -1
	s_cbranch_scc0 .LBB0_2166
	s_lshl_b32 s34, s27, 6
	s_mov_b64 s[4:5], 0

.LBB0_2173:
	s_add_u32 s28, s28, 0xb0080
	s_addc_u32 s29, s29, 0
	s_add_u32 s54, s30, 0x100
	v_mov_b32_e32 v0, 0
	s_addc_u32 s55, s31, 0
	s_mov_b32 s56, -2
	v_mov_b32_e32 v1, v0
	v_mov_b32_e32 v2, v0
	v_mov_b32_e32 v3, v0
	v_mov_b32_e32 v4, v0
	v_mov_b32_e32 v5, v0
	v_mov_b32_e32 v6, v0
	v_mov_b32_e32 v7, v0
	v_mov_b32_e32 v16, v0
	v_mov_b32_e32 v17, v0
	v_mov_b32_e32 v18, v0
	v_mov_b32_e32 v19, v0
	v_mov_b32_e32 v20, v0
	v_mov_b32_e32 v21, v0
	v_mov_b32_e32 v22, v0
	v_mov_b32_e32 v23, v0
	v_mov_b32_e32 v32, v0
	v_mov_b32_e32 v33, v0
	v_mov_b32_e32 v34, v0
	v_mov_b32_e32 v35, v0
	v_mov_b32_e32 v36, v0
	v_mov_b32_e32 v37, v0
	v_mov_b32_e32 v38, v0
	v_mov_b32_e32 v39, v0
	v_mov_b32_e32 v48, v0
	v_mov_b32_e32 v49, v0
	v_mov_b32_e32 v50, v0
	v_mov_b32_e32 v51, v0
	v_mov_b32_e32 v52, v0
	v_mov_b32_e32 v53, v0
	v_mov_b32_e32 v54, v0
	v_mov_b32_e32 v55, v0
	v_mov_b32_e32 v8, v0
	v_mov_b32_e32 v9, v0
	v_mov_b32_e32 v10, v0
	v_mov_b32_e32 v11, v0
	v_mov_b32_e32 v12, v0
	v_mov_b32_e32 v13, v0
	v_mov_b32_e32 v14, v0
	v_mov_b32_e32 v15, v0
	v_mov_b32_e32 v24, v0
	v_mov_b32_e32 v25, v0
	v_mov_b32_e32 v26, v0
	v_mov_b32_e32 v27, v0
	v_mov_b32_e32 v28, v0
	v_mov_b32_e32 v29, v0
	v_mov_b32_e32 v30, v0
	v_mov_b32_e32 v31, v0
	v_mov_b32_e32 v40, v0
	v_mov_b32_e32 v41, v0
	v_mov_b32_e32 v42, v0
	v_mov_b32_e32 v43, v0
	v_mov_b32_e32 v44, v0
	v_mov_b32_e32 v45, v0
	v_mov_b32_e32 v46, v0
	v_mov_b32_e32 v47, v0
	v_mov_b32_e32 v56, v0
	v_mov_b32_e32 v57, v0
	v_mov_b32_e32 v58, v0
	v_mov_b32_e32 v59, v0
	v_mov_b32_e32 v60, v0
	v_mov_b32_e32 v61, v0
	v_mov_b32_e32 v62, v0
	v_mov_b32_e32 v63, v0
	v_mov_b32_e32 v64, v0
	v_mov_b32_e32 v65, v0
	v_mov_b32_e32 v66, v0
	v_mov_b32_e32 v67, v0
	v_mov_b32_e32 v68, v0
	v_mov_b32_e32 v69, v0
	v_mov_b32_e32 v70, v0
	v_mov_b32_e32 v71, v0
	v_mov_b32_e32 v80, v0
	v_mov_b32_e32 v81, v0
	v_mov_b32_e32 v82, v0
	v_mov_b32_e32 v83, v0
	v_mov_b32_e32 v84, v0
	v_mov_b32_e32 v85, v0
	v_mov_b32_e32 v86, v0
	v_mov_b32_e32 v87, v0
	v_mov_b32_e32 v96, v0
	v_mov_b32_e32 v97, v0
	v_mov_b32_e32 v98, v0
	v_mov_b32_e32 v99, v0
	v_mov_b32_e32 v100, v0
	v_mov_b32_e32 v101, v0
	v_mov_b32_e32 v102, v0
	v_mov_b32_e32 v103, v0
	v_mov_b32_e32 v112, v0
	v_mov_b32_e32 v113, v0
	v_mov_b32_e32 v114, v0
	v_mov_b32_e32 v115, v0
	v_mov_b32_e32 v116, v0
	v_mov_b32_e32 v117, v0
	v_mov_b32_e32 v118, v0
	v_mov_b32_e32 v119, v0
	v_mov_b32_e32 v72, v0
	v_mov_b32_e32 v73, v0
	v_mov_b32_e32 v74, v0
	v_mov_b32_e32 v75, v0
	v_mov_b32_e32 v76, v0
	v_mov_b32_e32 v77, v0
	v_mov_b32_e32 v78, v0
	v_mov_b32_e32 v79, v0
	v_mov_b32_e32 v88, v0
	v_mov_b32_e32 v89, v0
	v_mov_b32_e32 v90, v0
	v_mov_b32_e32 v91, v0
	v_mov_b32_e32 v92, v0
	v_mov_b32_e32 v93, v0
	v_mov_b32_e32 v94, v0
	v_mov_b32_e32 v95, v0
	v_mov_b32_e32 v104, v0
	v_mov_b32_e32 v105, v0
	v_mov_b32_e32 v106, v0
	v_mov_b32_e32 v107, v0
	v_mov_b32_e32 v108, v0
	v_mov_b32_e32 v109, v0
	v_mov_b32_e32 v110, v0
	v_mov_b32_e32 v111, v0
	v_mov_b32_e32 v120, v0
	v_mov_b32_e32 v121, v0
	v_mov_b32_e32 v122, v0
	v_mov_b32_e32 v123, v0
	v_mov_b32_e32 v124, v0
	v_mov_b32_e32 v125, v0
	v_mov_b32_e32 v126, v0
	v_mov_b32_e32 v127, v0
	s_cmp_lg_u32 s45, 1
	s_cselect_b32 s100, s99, 0
	s_cmp_lg_u32 s100, 0
	s_cbranch_scc0 .Lmy_nobar2_23
	s_barrier
.Lmy_nobar2_23:
.LBB0_2174:
	ds_read_b128 v[144:147], v153
	ds_read_b128 v[156:159], v153 offset:1024
	ds_read_b128 v[160:163], v153 offset:2048
	ds_read_b128 v[164:167], v153 offset:3072
	ds_read_b128 v[168:171], v154
	ds_read_b128 v[172:175], v154 offset:1024
	ds_read_b128 v[176:179], v154 offset:2048
	ds_read_b128 v[180:183], v154 offset:3072
	s_add_u32 s30, s28, 0xfff50080
	s_addc_u32 s31, s29, -1
	s_cmp_eq_u32 s56, 40
	s_cselect_b32 s37, s1, s31
	s_cselect_b32 s36, s0, s30
	s_cselect_b32 s31, s27, s55
	s_cselect_b32 s30, s26, s54
	v_lshl_add_u64 v[148:149], s[28:29], 0, v[128:129]
	s_add_i32 m0, s41, 0xc000
	ds_read_b128 v[184:187], v155
	ds_read_b128 v[188:191], v155 offset:1024
	ds_read_b128 v[192:195], v155 offset:2048
	ds_read_b128 v[196:199], v155 offset:3072
	ds_read_b128 v[200:203], v155 offset:4096
	ds_read_b128 v[204:207], v155 offset:5120
	ds_read_b128 v[208:211], v155 offset:6144
	ds_read_b128 v[212:215], v155 offset:7168
	global_load_lds_dwordx4 v[148:149], off
	v_lshl_add_u64 v[148:149], s[28:29], 0, v[138:139]
	s_add_i32 m0, s41, 0xe000
	s_nop 0
	global_load_lds_dwordx4 v[148:149], off
	s_waitcnt vmcnt(8)
	s_waitcnt lgkmcnt(0)
	s_barrier
	s_setprio 1
	s_waitcnt lgkmcnt(0)
	v_mfma_f32_16x16x32_bf16 v[124:127], v[144:147], v[184:187], v[124:127]
	v_mfma_f32_16x16x32_bf16 v[120:123], v[160:163], v[184:187], v[120:123]
	v_mfma_f32_16x16x32_bf16 v[108:111], v[144:147], v[192:195], v[108:111]
	v_mfma_f32_16x16x32_bf16 v[104:107], v[160:163], v[192:195], v[104:107]
	v_mfma_f32_16x16x32_bf16 v[92:95], v[144:147], v[200:203], v[92:95]
	v_mfma_f32_16x16x32_bf16 v[88:91], v[160:163], v[200:203], v[88:91]
	v_mfma_f32_16x16x32_bf16 v[76:79], v[144:147], v[208:211], v[76:79]
	v_mfma_f32_16x16x32_bf16 v[72:75], v[160:163], v[208:211], v[72:75]
	v_mfma_f32_16x16x32_bf16 v[124:127], v[156:159], v[188:191], v[124:127]
	v_mfma_f32_16x16x32_bf16 v[120:123], v[164:167], v[188:191], v[120:123]
	v_mfma_f32_16x16x32_bf16 v[108:111], v[156:159], v[196:199], v[108:111]
	v_mfma_f32_16x16x32_bf16 v[104:107], v[164:167], v[196:199], v[104:107]
	v_mfma_f32_16x16x32_bf16 v[92:95], v[156:159], v[204:207], v[92:95]
	v_mfma_f32_16x16x32_bf16 v[88:91], v[164:167], v[204:207], v[88:91]
	v_mfma_f32_16x16x32_bf16 v[76:79], v[156:159], v[212:215], v[76:79]
	v_mfma_f32_16x16x32_bf16 v[72:75], v[164:167], v[212:215], v[72:75]
	s_setprio 0
	s_setprio 1
	v_mfma_f32_16x16x32_bf16 v[116:119], v[168:171], v[184:187], v[116:119]
	v_mfma_f32_16x16x32_bf16 v[112:115], v[176:179], v[184:187], v[112:115]
	v_mfma_f32_16x16x32_bf16 v[100:103], v[168:171], v[192:195], v[100:103]
	v_mfma_f32_16x16x32_bf16 v[96:99], v[176:179], v[192:195], v[96:99]
	v_mfma_f32_16x16x32_bf16 v[84:87], v[168:171], v[200:203], v[84:87]
	v_mfma_f32_16x16x32_bf16 v[80:83], v[176:179], v[200:203], v[80:83]
	v_mfma_f32_16x16x32_bf16 v[68:71], v[168:171], v[208:211], v[68:71]
	v_mfma_f32_16x16x32_bf16 v[64:67], v[176:179], v[208:211], v[64:67]
	v_mfma_f32_16x16x32_bf16 v[116:119], v[172:175], v[188:191], v[116:119]
	v_mfma_f32_16x16x32_bf16 v[112:115], v[180:183], v[188:191], v[112:115]
	v_mfma_f32_16x16x32_bf16 v[100:103], v[172:175], v[196:199], v[100:103]
	v_mfma_f32_16x16x32_bf16 v[96:99], v[180:183], v[196:199], v[96:99]
	v_mfma_f32_16x16x32_bf16 v[84:87], v[172:175], v[204:207], v[84:87]
	v_mfma_f32_16x16x32_bf16 v[80:83], v[180:183], v[204:207], v[80:83]
	v_mfma_f32_16x16x32_bf16 v[68:71], v[172:175], v[212:215], v[68:71]
	v_mfma_f32_16x16x32_bf16 v[64:67], v[180:183], v[212:215], v[64:67]
	s_setprio 0
	s_barrier
	s_add_i32 s34, s50, s40
	v_lshl_add_u64 v[148:149], s[30:31], 0, v[132:133]
	s_mov_b32 m0, s34
	ds_read_b128 v[184:187], v155 offset:16384
	ds_read_b128 v[188:191], v155 offset:17408
	ds_read_b128 v[192:195], v155 offset:18432
	ds_read_b128 v[196:199], v155 offset:19456
	ds_read_b128 v[200:203], v155 offset:20480
	ds_read_b128 v[204:207], v155 offset:21504
	ds_read_b128 v[208:211], v155 offset:22528
	ds_read_b128 v[212:215], v155 offset:23552
	global_load_lds_dwordx4 v[148:149], off
	s_add_i32 m0, s34, 0x2000
	s_add_u32 s34, s30, 0xb0000
	v_lshl_add_u64 v[216:217], s[30:31], 0, v[136:137]
	s_addc_u32 s35, s31, 0
	s_add_i32 s57, s51, s40
	global_load_lds_dwordx4 v[216:217], off
	v_lshl_add_u64 v[218:219], s[34:35], 0, v[132:133]
	s_mov_b32 m0, s57
	v_lshl_add_u64 v[220:221], s[36:37], 0, v[134:135]
	global_load_lds_dwordx4 v[218:219], off
	v_lshl_add_u64 v[218:219], s[34:35], 0, v[136:137]
	s_add_i32 m0, s57, 0x2000
	s_nop 0
	global_load_lds_dwordx4 v[218:219], off
	v_lshl_add_u64 v[218:219], s[36:37], 0, v[130:131]
	s_mov_b32 m0, s41
	s_nop 0
	global_load_lds_dwordx4 v[218:219], off
	s_mov_b32 m0, s42
	s_nop 0
	global_load_lds_dwordx4 v[220:221], off
	s_waitcnt vmcnt(8)
	s_waitcnt lgkmcnt(0)
	s_barrier
	s_setprio 1
	s_waitcnt lgkmcnt(0)
	v_mfma_f32_16x16x32_bf16 v[60:63], v[144:147], v[184:187], v[60:63]
	v_mfma_f32_16x16x32_bf16 v[56:59], v[160:163], v[184:187], v[56:59]
	v_mfma_f32_16x16x32_bf16 v[44:47], v[144:147], v[192:195], v[44:47]
	v_mfma_f32_16x16x32_bf16 v[40:43], v[160:163], v[192:195], v[40:43]
	v_mfma_f32_16x16x32_bf16 v[28:31], v[144:147], v[200:203], v[28:31]
	v_mfma_f32_16x16x32_bf16 v[24:27], v[160:163], v[200:203], v[24:27]
	v_mfma_f32_16x16x32_bf16 v[12:15], v[144:147], v[208:211], v[12:15]
	v_mfma_f32_16x16x32_bf16 v[8:11], v[160:163], v[208:211], v[8:11]
	v_mfma_f32_16x16x32_bf16 v[60:63], v[156:159], v[188:191], v[60:63]
	v_mfma_f32_16x16x32_bf16 v[56:59], v[164:167], v[188:191], v[56:59]
	v_mfma_f32_16x16x32_bf16 v[44:47], v[156:159], v[196:199], v[44:47]
	v_mfma_f32_16x16x32_bf16 v[40:43], v[164:167], v[196:199], v[40:43]
	v_mfma_f32_16x16x32_bf16 v[28:31], v[156:159], v[204:207], v[28:31]
	v_mfma_f32_16x16x32_bf16 v[24:27], v[164:167], v[204:207], v[24:27]
	v_mfma_f32_16x16x32_bf16 v[12:15], v[156:159], v[212:215], v[12:15]
	v_mfma_f32_16x16x32_bf16 v[8:11], v[164:167], v[212:215], v[8:11]
	s_setprio 0
	s_setprio 1
	v_mfma_f32_16x16x32_bf16 v[52:55], v[168:171], v[184:187], v[52:55]
	v_mfma_f32_16x16x32_bf16 v[48:51], v[176:179], v[184:187], v[48:51]
	v_mfma_f32_16x16x32_bf16 v[36:39], v[168:171], v[192:195], v[36:39]
	v_mfma_f32_16x16x32_bf16 v[32:35], v[176:179], v[192:195], v[32:35]
	v_mfma_f32_16x16x32_bf16 v[20:23], v[168:171], v[200:203], v[20:23]
	v_mfma_f32_16x16x32_bf16 v[16:19], v[176:179], v[200:203], v[16:19]
	v_mfma_f32_16x16x32_bf16 v[4:7], v[168:171], v[208:211], v[4:7]
	v_mfma_f32_16x16x32_bf16 v[0:3], v[176:179], v[208:211], v[0:3]
	v_mfma_f32_16x16x32_bf16 v[52:55], v[172:175], v[188:191], v[52:55]
	v_mfma_f32_16x16x32_bf16 v[48:51], v[180:183], v[188:191], v[48:51]
	v_mfma_f32_16x16x32_bf16 v[36:39], v[172:175], v[196:199], v[36:39]
	v_mfma_f32_16x16x32_bf16 v[32:35], v[180:183], v[196:199], v[32:35]
	v_mfma_f32_16x16x32_bf16 v[20:23], v[172:175], v[204:207], v[20:23]
	v_mfma_f32_16x16x32_bf16 v[16:19], v[180:183], v[204:207], v[16:19]
	v_mfma_f32_16x16x32_bf16 v[4:7], v[172:175], v[212:215], v[4:7]
	v_mfma_f32_16x16x32_bf16 v[0:3], v[180:183], v[212:215], v[0:3]
	s_setprio 0
	s_barrier
	s_add_i32 s57, 0, 0x18000
	s_add_i32 s58, 0, 0x1c000
	v_add_u32_e32 v164, s57, v151
	v_add_u32_e32 v180, s58, v151
	ds_read_b128 v[144:147], v164
	ds_read_b128 v[156:159], v164 offset:1024
	ds_read_b128 v[160:163], v164 offset:2048
	ds_read_b128 v[164:167], v164 offset:3072
	ds_read_b128 v[168:171], v180
	ds_read_b128 v[172:175], v180 offset:1024
	ds_read_b128 v[176:179], v180 offset:2048
	ds_read_b128 v[180:183], v180 offset:3072
	s_add_u32 s34, s36, 0xb0000
	s_addc_u32 s35, s37, 0
	s_mov_b32 m0, s43
	v_lshl_add_u64 v[222:223], s[34:35], 0, v[130:131]
	ds_read_b128 v[184:187], v155 offset:32768
	ds_read_b128 v[188:191], v155 offset:33792
	ds_read_b128 v[192:195], v155 offset:34816
	ds_read_b128 v[196:199], v155 offset:35840
	ds_read_b128 v[200:203], v155 offset:36864
	ds_read_b128 v[204:207], v155 offset:37888
	ds_read_b128 v[208:211], v155 offset:38912
	ds_read_b128 v[212:215], v155 offset:39936
	global_load_lds_dwordx4 v[222:223], off
	v_lshl_add_u64 v[222:223], s[34:35], 0, v[134:135]
	s_mov_b32 m0, s44
	s_nop 0
	global_load_lds_dwordx4 v[222:223], off
	s_waitcnt vmcnt(8)
	s_waitcnt lgkmcnt(0)
	s_barrier
	s_setprio 1
	s_waitcnt lgkmcnt(0)
	v_mfma_f32_16x16x32_bf16 v[124:127], v[144:147], v[184:187], v[124:127]
	v_mfma_f32_16x16x32_bf16 v[120:123], v[160:163], v[184:187], v[120:123]
	v_mfma_f32_16x16x32_bf16 v[108:111], v[144:147], v[192:195], v[108:111]
	v_mfma_f32_16x16x32_bf16 v[104:107], v[160:163], v[192:195], v[104:107]
	v_mfma_f32_16x16x32_bf16 v[92:95], v[144:147], v[200:203], v[92:95]
	v_mfma_f32_16x16x32_bf16 v[88:91], v[160:163], v[200:203], v[88:91]
	v_mfma_f32_16x16x32_bf16 v[76:79], v[144:147], v[208:211], v[76:79]
	v_mfma_f32_16x16x32_bf16 v[72:75], v[160:163], v[208:211], v[72:75]
	v_mfma_f32_16x16x32_bf16 v[124:127], v[156:159], v[188:191], v[124:127]
	v_mfma_f32_16x16x32_bf16 v[120:123], v[164:167], v[188:191], v[120:123]
	v_mfma_f32_16x16x32_bf16 v[108:111], v[156:159], v[196:199], v[108:111]
	v_mfma_f32_16x16x32_bf16 v[104:107], v[164:167], v[196:199], v[104:107]
	v_mfma_f32_16x16x32_bf16 v[92:95], v[156:159], v[204:207], v[92:95]
	v_mfma_f32_16x16x32_bf16 v[88:91], v[164:167], v[204:207], v[88:91]
	v_mfma_f32_16x16x32_bf16 v[76:79], v[156:159], v[212:215], v[76:79]
	v_mfma_f32_16x16x32_bf16 v[72:75], v[164:167], v[212:215], v[72:75]
	s_setprio 0
	s_setprio 1
	v_mfma_f32_16x16x32_bf16 v[116:119], v[168:171], v[184:187], v[116:119]
	v_mfma_f32_16x16x32_bf16 v[112:115], v[176:179], v[184:187], v[112:115]
	v_mfma_f32_16x16x32_bf16 v[100:103], v[168:171], v[192:195], v[100:103]
	v_mfma_f32_16x16x32_bf16 v[96:99], v[176:179], v[192:195], v[96:99]
	v_mfma_f32_16x16x32_bf16 v[84:87], v[168:171], v[200:203], v[84:87]
	v_mfma_f32_16x16x32_bf16 v[80:83], v[176:179], v[200:203], v[80:83]
	v_mfma_f32_16x16x32_bf16 v[68:71], v[168:171], v[208:211], v[68:71]
	v_mfma_f32_16x16x32_bf16 v[64:67], v[176:179], v[208:211], v[64:67]
	v_mfma_f32_16x16x32_bf16 v[116:119], v[172:175], v[188:191], v[116:119]
	v_mfma_f32_16x16x32_bf16 v[112:115], v[180:183], v[188:191], v[112:115]
	v_mfma_f32_16x16x32_bf16 v[100:103], v[172:175], v[196:199], v[100:103]
	v_mfma_f32_16x16x32_bf16 v[96:99], v[180:183], v[196:199], v[96:99]
	v_mfma_f32_16x16x32_bf16 v[84:87], v[172:175], v[204:207], v[84:87]
	v_mfma_f32_16x16x32_bf16 v[80:83], v[180:183], v[204:207], v[80:83]
	v_mfma_f32_16x16x32_bf16 v[68:71], v[172:175], v[212:215], v[68:71]
	v_mfma_f32_16x16x32_bf16 v[64:67], v[180:183], v[212:215], v[64:67]
	s_setprio 0
	s_barrier
	s_add_i32 s34, s57, s40
	v_lshl_add_u64 v[148:149], v[148:149], 0, s[8:9]
	s_mov_b32 m0, s34
	ds_read_b128 v[184:187], v155 offset:49152
	ds_read_b128 v[188:191], v155 offset:50176
	ds_read_b128 v[192:195], v155 offset:51200
	ds_read_b128 v[196:199], v155 offset:52224
	ds_read_b128 v[200:203], v155 offset:53248
	ds_read_b128 v[204:207], v155 offset:54272
	ds_read_b128 v[208:211], v155 offset:55296
	ds_read_b128 v[212:215], v155 offset:56320
	global_load_lds_dwordx4 v[148:149], off
	s_add_i32 m0, s34, 0x2000
	s_add_u32 s30, s30, 0xb0080
	v_lshl_add_u64 v[148:149], v[216:217], 0, s[8:9]
	s_addc_u32 s31, s31, 0
	s_add_i32 s34, s58, s40
	global_load_lds_dwordx4 v[148:149], off
	v_lshl_add_u64 v[148:149], s[30:31], 0, v[132:133]
	s_mov_b32 m0, s34
	s_nop 0
	global_load_lds_dwordx4 v[148:149], off
	v_lshl_add_u64 v[148:149], s[30:31], 0, v[136:137]
	s_add_i32 m0, s34, 0x2000
	s_nop 0
	global_load_lds_dwordx4 v[148:149], off
	v_lshl_add_u64 v[148:149], v[218:219], 0, s[8:9]
	s_mov_b32 m0, s46
	s_nop 0
	global_load_lds_dwordx4 v[148:149], off
	v_lshl_add_u64 v[148:149], v[220:221], 0, s[8:9]
	s_mov_b32 m0, s47
	s_nop 0
	global_load_lds_dwordx4 v[148:149], off
	s_waitcnt vmcnt(8)
	s_waitcnt lgkmcnt(0)
	s_barrier
	s_setprio 1
	s_waitcnt lgkmcnt(0)
	v_mfma_f32_16x16x32_bf16 v[60:63], v[144:147], v[184:187], v[60:63]
	v_mfma_f32_16x16x32_bf16 v[56:59], v[160:163], v[184:187], v[56:59]
	v_mfma_f32_16x16x32_bf16 v[44:47], v[144:147], v[192:195], v[44:47]
	v_mfma_f32_16x16x32_bf16 v[40:43], v[160:163], v[192:195], v[40:43]
	v_mfma_f32_16x16x32_bf16 v[28:31], v[144:147], v[200:203], v[28:31]
	v_mfma_f32_16x16x32_bf16 v[24:27], v[160:163], v[200:203], v[24:27]
	v_mfma_f32_16x16x32_bf16 v[12:15], v[144:147], v[208:211], v[12:15]
	v_mfma_f32_16x16x32_bf16 v[8:11], v[160:163], v[208:211], v[8:11]
	v_mfma_f32_16x16x32_bf16 v[60:63], v[156:159], v[188:191], v[60:63]
	v_mfma_f32_16x16x32_bf16 v[56:59], v[164:167], v[188:191], v[56:59]
	v_mfma_f32_16x16x32_bf16 v[44:47], v[156:159], v[196:199], v[44:47]
	v_mfma_f32_16x16x32_bf16 v[40:43], v[164:167], v[196:199], v[40:43]
	v_mfma_f32_16x16x32_bf16 v[28:31], v[156:159], v[204:207], v[28:31]
	v_mfma_f32_16x16x32_bf16 v[24:27], v[164:167], v[204:207], v[24:27]
	v_mfma_f32_16x16x32_bf16 v[12:15], v[156:159], v[212:215], v[12:15]
	v_mfma_f32_16x16x32_bf16 v[8:11], v[164:167], v[212:215], v[8:11]
	s_setprio 0
	s_setprio 1
	v_mfma_f32_16x16x32_bf16 v[52:55], v[168:171], v[184:187], v[52:55]
	v_mfma_f32_16x16x32_bf16 v[48:51], v[176:179], v[184:187], v[48:51]
	v_mfma_f32_16x16x32_bf16 v[36:39], v[168:171], v[192:195], v[36:39]
	v_mfma_f32_16x16x32_bf16 v[32:35], v[176:179], v[192:195], v[32:35]
	v_mfma_f32_16x16x32_bf16 v[20:23], v[168:171], v[200:203], v[20:23]
	v_mfma_f32_16x16x32_bf16 v[16:19], v[176:179], v[200:203], v[16:19]
	v_mfma_f32_16x16x32_bf16 v[4:7], v[168:171], v[208:211], v[4:7]
	v_mfma_f32_16x16x32_bf16 v[0:3], v[176:179], v[208:211], v[0:3]
	v_mfma_f32_16x16x32_bf16 v[52:55], v[172:175], v[188:191], v[52:55]
	v_mfma_f32_16x16x32_bf16 v[48:51], v[180:183], v[188:191], v[48:51]
	v_mfma_f32_16x16x32_bf16 v[36:39], v[172:175], v[196:199], v[36:39]
	v_mfma_f32_16x16x32_bf16 v[32:35], v[180:183], v[196:199], v[32:35]
	v_mfma_f32_16x16x32_bf16 v[20:23], v[172:175], v[204:207], v[20:23]
	v_mfma_f32_16x16x32_bf16 v[16:19], v[180:183], v[204:207], v[16:19]
	v_mfma_f32_16x16x32_bf16 v[4:7], v[172:175], v[212:215], v[4:7]
	v_mfma_f32_16x16x32_bf16 v[0:3], v[180:183], v[212:215], v[0:3]
	s_setprio 0
	s_cmp_eq_u32 s56, s98
	s_cbranch_scc1 .Lmy_nobar_23
	s_barrier
.Lmy_nobar_23:
	s_add_i32 s56, s56, 2
	s_add_u32 s28, s28, 0x100
	s_addc_u32 s29, s29, 0
	s_add_u32 s54, s54, 0x100
	s_addc_u32 s55, s55, 0
	s_cmp_gt_u32 s56, 41
	s_cbranch_scc0 .LBB0_2174
	s_and_b64 vcc, exec, s[10:11]
	s_cbranch_vccz .LBB0_2177
	s_nop 0
.LBB0_2177:
	v_lshl_add_u32 v148, s12, 8, v150
	v_lshl_or_b32 v146, s13, 8, v152
	v_ashrrev_i32_e32 v149, 31, v148
	v_ashrrev_i32_e32 v147, 31, v146
	v_lshlrev_b64 v[144:145], 10, v[148:149]
	v_lshl_add_u64 v[144:145], v[144:145], 0, v[146:147]
	v_lshlrev_b64 v[160:161], 1, v[144:145]
	v_lshl_add_u64 v[156:157], s[14:15], 0, v[160:161]
	global_load_dwordx4 v[156:159], v[156:157], off
	v_lshl_add_u64 v[162:163], v[144:145], 2, s[68:69]
	v_or_b32_e32 v160, 0x100, v160
	v_lshl_add_u64 v[160:161], s[14:15], 0, v[160:161]
	s_and_b64 vcc, exec, s[4:5]
	s_mov_b64 s[4:5], -1
	s_waitcnt vmcnt(0)
	v_lshlrev_b32_e32 v164, 16, v156
	v_and_b32_e32 v165, 0xffff0000, v156
	v_lshlrev_b32_e32 v156, 16, v157
	v_and_b32_e32 v157, 0xffff0000, v157
	v_lshlrev_b32_e32 v166, 16, v158
	v_and_b32_e32 v167, 0xffff0000, v158
	v_lshlrev_b32_e32 v158, 16, v159
	v_and_b32_e32 v159, 0xffff0000, v159
	v_pk_add_f32 v[124:125], v[124:125], v[164:165]
	v_pk_add_f32 v[126:127], v[126:127], v[156:157]
	v_pk_add_f32 v[120:121], v[120:121], v[166:167]
	v_pk_add_f32 v[122:123], v[122:123], v[158:159]
	global_store_dwordx4 v[162:163], v[124:127], off
	global_store_dwordx4 v[162:163], v[120:123], off offset:16
	global_load_dwordx4 v[120:123], v[160:161], off
	v_or_b32_e32 v124, 16, v148
	v_ashrrev_i32_e32 v125, 31, v124
	v_lshlrev_b64 v[124:125], 10, v[124:125]
	v_lshl_add_u64 v[124:125], v[124:125], 0, v[146:147]
	v_lshlrev_b64 v[126:127], 1, v[124:125]
	v_lshl_add_u64 v[156:157], s[14:15], 0, v[126:127]
	v_or_b32_e32 v126, 0x100, v126
	s_waitcnt vmcnt(0)
	v_lshlrev_b32_e32 v158, 16, v120
	v_and_b32_e32 v159, 0xffff0000, v120
	v_lshlrev_b32_e32 v120, 16, v121
	v_and_b32_e32 v121, 0xffff0000, v121
	v_lshlrev_b32_e32 v160, 16, v122
	v_and_b32_e32 v161, 0xffff0000, v122
	v_lshlrev_b32_e32 v122, 16, v123
	v_and_b32_e32 v123, 0xffff0000, v123
	v_pk_add_f32 v[116:117], v[116:117], v[158:159]
	v_pk_add_f32 v[118:119], v[118:119], v[120:121]
	v_pk_add_f32 v[112:113], v[112:113], v[160:161]
	v_pk_add_f32 v[114:115], v[114:115], v[122:123]
	global_store_dwordx4 v[162:163], v[116:119], off offset:512
	global_store_dwordx4 v[162:163], v[112:115], off offset:528
	global_load_dwordx4 v[112:115], v[156:157], off
	v_lshl_add_u64 v[116:117], v[124:125], 2, s[68:69]
	v_lshl_add_u64 v[118:119], s[14:15], 0, v[126:127]
	s_waitcnt vmcnt(0)
	v_lshlrev_b32_e32 v120, 16, v112
	v_and_b32_e32 v121, 0xffff0000, v112
	v_lshlrev_b32_e32 v112, 16, v113
	v_and_b32_e32 v113, 0xffff0000, v113
	v_lshlrev_b32_e32 v122, 16, v114
	v_and_b32_e32 v123, 0xffff0000, v114
	v_lshlrev_b32_e32 v114, 16, v115
	v_and_b32_e32 v115, 0xffff0000, v115
	v_pk_add_f32 v[108:109], v[108:109], v[120:121]
	v_pk_add_f32 v[110:111], v[110:111], v[112:113]
	v_pk_add_f32 v[104:105], v[104:105], v[122:123]
	v_pk_add_f32 v[106:107], v[106:107], v[114:115]
	global_store_dwordx4 v[116:117], v[108:111], off
	global_store_dwordx4 v[116:117], v[104:107], off offset:16
	global_load_dwordx4 v[104:107], v[118:119], off
	v_or_b32_e32 v108, 32, v148
	v_ashrrev_i32_e32 v109, 31, v108
	v_lshlrev_b64 v[108:109], 10, v[108:109]
	v_lshl_add_u64 v[108:109], v[108:109], 0, v[146:147]
	v_lshlrev_b64 v[110:111], 1, v[108:109]
	v_lshl_add_u64 v[112:113], s[14:15], 0, v[110:111]
	v_or_b32_e32 v110, 0x100, v110
	s_waitcnt vmcnt(0)
	v_lshlrev_b32_e32 v114, 16, v104
	v_and_b32_e32 v115, 0xffff0000, v104
	v_lshlrev_b32_e32 v104, 16, v105
	v_and_b32_e32 v105, 0xffff0000, v105
	v_lshlrev_b32_e32 v118, 16, v106
	v_and_b32_e32 v119, 0xffff0000, v106
	v_lshlrev_b32_e32 v106, 16, v107
	v_and_b32_e32 v107, 0xffff0000, v107
	v_pk_add_f32 v[100:101], v[100:101], v[114:115]
	v_pk_add_f32 v[102:103], v[102:103], v[104:105]
	v_pk_add_f32 v[96:97], v[96:97], v[118:119]
	v_pk_add_f32 v[98:99], v[98:99], v[106:107]
	global_store_dwordx4 v[116:117], v[100:103], off offset:512
	global_store_dwordx4 v[116:117], v[96:99], off offset:528
	global_load_dwordx4 v[96:99], v[112:113], off
	v_lshl_add_u64 v[100:101], v[108:109], 2, s[68:69]
	v_lshl_add_u64 v[102:103], s[14:15], 0, v[110:111]
	s_waitcnt vmcnt(0)
	v_lshlrev_b32_e32 v104, 16, v96
	v_and_b32_e32 v105, 0xffff0000, v96
	v_lshlrev_b32_e32 v96, 16, v97
	v_and_b32_e32 v97, 0xffff0000, v97
	v_lshlrev_b32_e32 v106, 16, v98
	v_and_b32_e32 v107, 0xffff0000, v98
	v_lshlrev_b32_e32 v98, 16, v99
	v_and_b32_e32 v99, 0xffff0000, v99
	v_pk_add_f32 v[92:93], v[92:93], v[104:105]
	v_pk_add_f32 v[94:95], v[94:95], v[96:97]
	v_pk_add_f32 v[88:89], v[88:89], v[106:107]
	v_pk_add_f32 v[90:91], v[90:91], v[98:99]
	global_store_dwordx4 v[100:101], v[92:95], off
	global_store_dwordx4 v[100:101], v[88:91], off offset:16
	global_load_dwordx4 v[88:91], v[102:103], off
	v_or_b32_e32 v92, 48, v148
	v_ashrrev_i32_e32 v93, 31, v92
	v_lshlrev_b64 v[92:93], 10, v[92:93]
	v_lshl_add_u64 v[92:93], v[92:93], 0, v[146:147]
	v_lshlrev_b64 v[94:95], 1, v[92:93]
	v_lshl_add_u64 v[96:97], s[14:15], 0, v[94:95]
	v_or_b32_e32 v94, 0x100, v94
	s_waitcnt vmcnt(0)
	v_lshlrev_b32_e32 v98, 16, v88
	v_and_b32_e32 v99, 0xffff0000, v88
	v_lshlrev_b32_e32 v88, 16, v89
	v_and_b32_e32 v89, 0xffff0000, v89
	v_lshlrev_b32_e32 v102, 16, v90
	v_and_b32_e32 v103, 0xffff0000, v90
	v_lshlrev_b32_e32 v90, 16, v91
	v_and_b32_e32 v91, 0xffff0000, v91
	v_pk_add_f32 v[84:85], v[84:85], v[98:99]
	v_pk_add_f32 v[86:87], v[86:87], v[88:89]
	v_pk_add_f32 v[80:81], v[80:81], v[102:103]
	v_pk_add_f32 v[82:83], v[82:83], v[90:91]
	global_store_dwordx4 v[100:101], v[84:87], off offset:512
	global_store_dwordx4 v[100:101], v[80:83], off offset:528
	global_load_dwordx4 v[80:83], v[96:97], off
	v_lshl_add_u64 v[84:85], v[92:93], 2, s[68:69]
	v_lshl_add_u64 v[86:87], s[14:15], 0, v[94:95]
	s_waitcnt vmcnt(0)
	v_lshlrev_b32_e32 v88, 16, v80
	v_and_b32_e32 v89, 0xffff0000, v80
	v_lshlrev_b32_e32 v80, 16, v81
	v_and_b32_e32 v81, 0xffff0000, v81
	v_lshlrev_b32_e32 v90, 16, v82
	v_and_b32_e32 v91, 0xffff0000, v82
	v_lshlrev_b32_e32 v82, 16, v83
	v_and_b32_e32 v83, 0xffff0000, v83
	v_pk_add_f32 v[76:77], v[76:77], v[88:89]
	v_pk_add_f32 v[78:79], v[78:79], v[80:81]
	v_pk_add_f32 v[72:73], v[72:73], v[90:91]
	v_pk_add_f32 v[74:75], v[74:75], v[82:83]
	global_store_dwordx4 v[84:85], v[76:79], off
	global_store_dwordx4 v[84:85], v[72:75], off offset:16
	global_load_dwordx4 v[72:75], v[86:87], off
	v_lshl_add_u64 v[76:77], v[144:145], 0, s[18:19]
	v_lshlrev_b64 v[78:79], 1, v[76:77]
	v_lshl_add_u64 v[80:81], s[14:15], 0, v[78:79]
	v_or_b32_e32 v78, 0x100, v78
	s_waitcnt vmcnt(0)
	v_lshlrev_b32_e32 v82, 16, v72
	v_and_b32_e32 v83, 0xffff0000, v72
	v_lshlrev_b32_e32 v72, 16, v73
	v_and_b32_e32 v73, 0xffff0000, v73
	v_lshlrev_b32_e32 v86, 16, v74
	v_and_b32_e32 v87, 0xffff0000, v74
	v_lshlrev_b32_e32 v74, 16, v75
	v_and_b32_e32 v75, 0xffff0000, v75
	v_pk_add_f32 v[68:69], v[68:69], v[82:83]
	v_pk_add_f32 v[70:71], v[70:71], v[72:73]
	v_pk_add_f32 v[64:65], v[64:65], v[86:87]
	v_pk_add_f32 v[66:67], v[66:67], v[74:75]
	global_store_dwordx4 v[84:85], v[68:71], off offset:512
	global_store_dwordx4 v[84:85], v[64:67], off offset:528
	global_load_dwordx4 v[64:67], v[80:81], off
	v_lshl_add_u64 v[68:69], v[76:77], 2, s[68:69]
	v_lshl_add_u64 v[70:71], s[14:15], 0, v[78:79]
	s_waitcnt vmcnt(0)
	v_lshlrev_b32_e32 v72, 16, v64
	v_and_b32_e32 v73, 0xffff0000, v64
	v_lshlrev_b32_e32 v64, 16, v65
	v_and_b32_e32 v65, 0xffff0000, v65
	v_lshlrev_b32_e32 v74, 16, v66
	v_and_b32_e32 v75, 0xffff0000, v66
	v_lshlrev_b32_e32 v66, 16, v67
	v_and_b32_e32 v67, 0xffff0000, v67
	v_pk_add_f32 v[60:61], v[60:61], v[72:73]
	v_pk_add_f32 v[62:63], v[62:63], v[64:65]
	v_pk_add_f32 v[56:57], v[56:57], v[74:75]
	v_pk_add_f32 v[58:59], v[58:59], v[66:67]
	global_store_dwordx4 v[68:69], v[60:63], off
	global_store_dwordx4 v[68:69], v[56:59], off offset:16
	global_load_dwordx4 v[56:59], v[70:71], off
	v_lshl_add_u64 v[60:61], v[144:145], 0, s[20:21]
	v_lshlrev_b64 v[62:63], 1, v[60:61]
	v_lshl_add_u64 v[64:65], s[14:15], 0, v[62:63]
	v_or_b32_e32 v62, 0x100, v62
	s_waitcnt vmcnt(0)
	v_lshlrev_b32_e32 v66, 16, v56
	v_and_b32_e32 v67, 0xffff0000, v56
	v_lshlrev_b32_e32 v56, 16, v57
	v_and_b32_e32 v57, 0xffff0000, v57
	v_lshlrev_b32_e32 v70, 16, v58
	v_and_b32_e32 v71, 0xffff0000, v58
	v_lshlrev_b32_e32 v58, 16, v59
	v_and_b32_e32 v59, 0xffff0000, v59
	v_pk_add_f32 v[52:53], v[52:53], v[66:67]
	v_pk_add_f32 v[54:55], v[54:55], v[56:57]
	v_pk_add_f32 v[48:49], v[48:49], v[70:71]
	v_pk_add_f32 v[50:51], v[50:51], v[58:59]
	global_store_dwordx4 v[68:69], v[52:55], off offset:512
	global_store_dwordx4 v[68:69], v[48:51], off offset:528
	global_load_dwordx4 v[48:51], v[64:65], off
	v_lshl_add_u64 v[52:53], v[60:61], 2, s[68:69]
	v_lshl_add_u64 v[54:55], s[14:15], 0, v[62:63]
	s_waitcnt vmcnt(0)
	v_lshlrev_b32_e32 v56, 16, v48
	v_and_b32_e32 v57, 0xffff0000, v48
	v_lshlrev_b32_e32 v48, 16, v49
	v_and_b32_e32 v49, 0xffff0000, v49
	v_lshlrev_b32_e32 v58, 16, v50
	v_and_b32_e32 v59, 0xffff0000, v50
	v_lshlrev_b32_e32 v50, 16, v51
	v_and_b32_e32 v51, 0xffff0000, v51
	v_pk_add_f32 v[44:45], v[44:45], v[56:57]
	v_pk_add_f32 v[46:47], v[46:47], v[48:49]
	v_pk_add_f32 v[40:41], v[40:41], v[58:59]
	v_pk_add_f32 v[42:43], v[42:43], v[50:51]
	global_store_dwordx4 v[52:53], v[44:47], off
	global_store_dwordx4 v[52:53], v[40:43], off offset:16
	global_load_dwordx4 v[40:43], v[54:55], off
	v_lshl_add_u64 v[44:45], v[144:145], 0, s[22:23]
	v_lshlrev_b64 v[46:47], 1, v[44:45]
	v_lshl_add_u64 v[48:49], s[14:15], 0, v[46:47]
	v_or_b32_e32 v46, 0x100, v46
	s_waitcnt vmcnt(0)
	v_lshlrev_b32_e32 v50, 16, v40
	v_and_b32_e32 v51, 0xffff0000, v40
	v_lshlrev_b32_e32 v40, 16, v41
	v_and_b32_e32 v41, 0xffff0000, v41
	v_lshlrev_b32_e32 v54, 16, v42
	v_and_b32_e32 v55, 0xffff0000, v42
	v_lshlrev_b32_e32 v42, 16, v43
	v_and_b32_e32 v43, 0xffff0000, v43
	v_pk_add_f32 v[36:37], v[36:37], v[50:51]
	v_pk_add_f32 v[38:39], v[38:39], v[40:41]
	v_pk_add_f32 v[32:33], v[32:33], v[54:55]
	v_pk_add_f32 v[34:35], v[34:35], v[42:43]
	global_store_dwordx4 v[52:53], v[36:39], off offset:512
	global_store_dwordx4 v[52:53], v[32:35], off offset:528
	global_load_dwordx4 v[32:35], v[48:49], off
	v_lshl_add_u64 v[36:37], v[44:45], 2, s[68:69]
	v_lshl_add_u64 v[38:39], s[14:15], 0, v[46:47]
	s_waitcnt vmcnt(0)
	v_lshlrev_b32_e32 v40, 16, v32
	v_and_b32_e32 v41, 0xffff0000, v32
	v_lshlrev_b32_e32 v32, 16, v33
	v_and_b32_e32 v33, 0xffff0000, v33
	v_lshlrev_b32_e32 v42, 16, v34
	v_and_b32_e32 v43, 0xffff0000, v34
	v_lshlrev_b32_e32 v34, 16, v35
	v_and_b32_e32 v35, 0xffff0000, v35
	v_pk_add_f32 v[28:29], v[28:29], v[40:41]
	v_pk_add_f32 v[30:31], v[30:31], v[32:33]
	v_pk_add_f32 v[24:25], v[24:25], v[42:43]
	v_pk_add_f32 v[26:27], v[26:27], v[34:35]
	global_store_dwordx4 v[36:37], v[28:31], off
	global_store_dwordx4 v[36:37], v[24:27], off offset:16
	global_load_dwordx4 v[24:27], v[38:39], off
	v_lshl_add_u64 v[28:29], v[144:145], 0, s[24:25]
	v_lshlrev_b64 v[30:31], 1, v[28:29]
	v_lshl_add_u64 v[32:33], s[14:15], 0, v[30:31]
	v_or_b32_e32 v30, 0x100, v30
	s_waitcnt vmcnt(0)
	v_lshlrev_b32_e32 v34, 16, v24
	v_and_b32_e32 v35, 0xffff0000, v24
	v_lshlrev_b32_e32 v24, 16, v25
	v_and_b32_e32 v25, 0xffff0000, v25
	v_lshlrev_b32_e32 v38, 16, v26
	v_and_b32_e32 v39, 0xffff0000, v26
	v_lshlrev_b32_e32 v26, 16, v27
	v_and_b32_e32 v27, 0xffff0000, v27
	v_pk_add_f32 v[20:21], v[20:21], v[34:35]
	v_pk_add_f32 v[22:23], v[22:23], v[24:25]
	v_pk_add_f32 v[16:17], v[16:17], v[38:39]
	v_pk_add_f32 v[18:19], v[18:19], v[26:27]
	global_store_dwordx4 v[36:37], v[20:23], off offset:512
	global_store_dwordx4 v[36:37], v[16:19], off offset:528
	global_load_dwordx4 v[16:19], v[32:33], off
	v_lshl_add_u64 v[20:21], v[28:29], 2, s[68:69]
	v_lshl_add_u64 v[22:23], s[14:15], 0, v[30:31]
	s_waitcnt vmcnt(0)
	v_lshlrev_b32_e32 v24, 16, v16
	v_and_b32_e32 v25, 0xffff0000, v16
	v_lshlrev_b32_e32 v16, 16, v17
	v_and_b32_e32 v17, 0xffff0000, v17
	v_lshlrev_b32_e32 v26, 16, v18
	v_and_b32_e32 v27, 0xffff0000, v18
	v_lshlrev_b32_e32 v18, 16, v19
	v_and_b32_e32 v19, 0xffff0000, v19
	v_pk_add_f32 v[12:13], v[12:13], v[24:25]
	v_pk_add_f32 v[14:15], v[14:15], v[16:17]
	v_pk_add_f32 v[8:9], v[8:9], v[26:27]
	v_pk_add_f32 v[10:11], v[10:11], v[18:19]
	global_store_dwordx4 v[20:21], v[12:15], off
	global_store_dwordx4 v[20:21], v[8:11], off offset:16
	global_load_dwordx4 v[8:11], v[22:23], off
	s_waitcnt vmcnt(0)
	v_lshlrev_b32_e32 v12, 16, v8
	v_and_b32_e32 v13, 0xffff0000, v8
	v_lshlrev_b32_e32 v8, 16, v9
	v_and_b32_e32 v9, 0xffff0000, v9
	v_lshlrev_b32_e32 v14, 16, v10
	v_and_b32_e32 v15, 0xffff0000, v10
	v_lshlrev_b32_e32 v10, 16, v11
	v_and_b32_e32 v11, 0xffff0000, v11
	v_pk_add_f32 v[4:5], v[4:5], v[12:13]
	v_pk_add_f32 v[6:7], v[6:7], v[8:9]
	v_pk_add_f32 v[0:1], v[0:1], v[14:15]
	v_pk_add_f32 v[2:3], v[2:3], v[10:11]
	global_store_dwordx4 v[20:21], v[4:7], off offset:512
	global_store_dwordx4 v[20:21], v[0:3], off offset:528
	s_cbranch_vccnz .LBB0_2162
	s_andn2_b64 vcc, exec, s[6:7]
	s_cbranch_vccnz .LBB0_2161
	s_nop 0
	s_branch .LBB0_2161

	.amdhsa_kernel _Z6mk_fwd4Args
		.amdhsa_group_segment_fixed_size 0
		.amdhsa_private_segment_fixed_size 0
		.amdhsa_kernarg_size 472
		.amdhsa_user_sgpr_count 2
		.amdhsa_user_sgpr_dispatch_ptr 0
		.amdhsa_user_sgpr_queue_ptr 0
		.amdhsa_user_sgpr_kernarg_segment_ptr 1
		.amdhsa_user_sgpr_dispatch_id 0
		.amdhsa_user_sgpr_kernarg_preload_length 0
		.amdhsa_user_sgpr_kernarg_preload_offset 0
		.amdhsa_user_sgpr_private_segment_size 0
		.amdhsa_uses_dynamic_stack 0
		.amdhsa_enable_private_segment 0
		.amdhsa_system_sgpr_workgroup_id_x 1
		.amdhsa_system_sgpr_workgroup_id_y 0
		.amdhsa_system_sgpr_workgroup_id_z 0
		.amdhsa_system_sgpr_workgroup_info 0
		.amdhsa_system_vgpr_workitem_id 2
		.amdhsa_next_free_vgpr 239
		.amdhsa_next_free_sgpr 102
		.amdhsa_accum_offset 240
		.amdhsa_reserve_vcc 1
		.amdhsa_float_round_mode_32 0
		.amdhsa_float_round_mode_16_64 0
		.amdhsa_float_denorm_mode_32 3
		.amdhsa_float_denorm_mode_16_64 3
		.amdhsa_dx10_clamp 1
		.amdhsa_ieee_mode 1
		.amdhsa_fp16_overflow 0
		.amdhsa_tg_split 0
		.amdhsa_exception_fp_ieee_invalid_op 0
		.amdhsa_exception_fp_denorm_src 0
		.amdhsa_exception_fp_ieee_div_zero 0
		.amdhsa_exception_fp_ieee_overflow 0
		.amdhsa_exception_fp_ieee_underflow 0
		.amdhsa_exception_fp_ieee_inexact 0
		.amdhsa_exception_int_div_zero 0
	.end_amdhsa_kernel

amdhsa.kernels:
  - .agpr_count:     0
    .args:
      - .offset:         0
        .size:           216
        .value_kind:     by_value
      - .offset:         216
        .size:           4
        .value_kind:     hidden_block_count_x
      - .offset:         220
        .size:           4
        .value_kind:     hidden_block_count_y
      - .offset:         224
        .size:           4
        .value_kind:     hidden_block_count_z
      - .offset:         228
        .size:           2
        .value_kind:     hidden_group_size_x
      - .offset:         230
        .size:           2
        .value_kind:     hidden_group_size_y
      - .offset:         232
        .size:           2
        .value_kind:     hidden_group_size_z
      - .offset:         234
        .size:           2
        .value_kind:     hidden_remainder_x
      - .offset:         236
        .size:           2
        .value_kind:     hidden_remainder_y
      - .offset:         238
        .size:           2
        .value_kind:     hidden_remainder_z
      - .offset:         256
        .size:           8
        .value_kind:     hidden_global_offset_x
      - .offset:         264
        .size:           8
        .value_kind:     hidden_global_offset_y
      - .offset:         272
        .size:           8
        .value_kind:     hidden_global_offset_z
      - .offset:         280
        .size:           2
        .value_kind:     hidden_grid_dims
      - .offset:         304
        .size:           8
        .value_kind:     hidden_multigrid_sync_arg
      - .offset:         336
        .size:           4
        .value_kind:     hidden_dynamic_lds_size
    .group_segment_fixed_size: 0
    .kernarg_segment_align: 8
    .kernarg_segment_size: 472
    .language:       OpenCL C
    .language_version:
      - 2
      - 0
    .max_flat_workgroup_size: 512
    .name:           _Z6mk_fwd4Args
    .private_segment_fixed_size: 0
    .sgpr_count:     108
    .sgpr_spill_count: 17
    .symbol:         _Z6mk_fwd4Args.kd
    .uniform_work_group_size: 1
    .uses_dynamic_stack: false
    .vgpr_count:     239
    .vgpr_spill_count: 0
    .wavefront_size: 64
